# U expert tables f32->fp4 conversion moved out of PRO (HBM-bound) into the top-k phases (VALU-bound, memory idle): one 4-KB chunk in flight per wave, 8 conversion points per unit
# speedup vs baseline: 1.1300x; 1.0197x over previous
.LBB0_83:
	s_or_b64 exec, exec, s[6:7]
	v_writelane_b32 v248, s62, 12
	v_writelane_b32 v248, s63, 13
	v_writelane_b32 v248, s40, 14
	v_writelane_b32 v248, s41, 15
	s_ashr_i32 s1, s33, 1
	s_cmpk_lt_i32 s1, 0x4000
	s_mov_b64 s[26:27], 0
	s_lshl_b32 s1, s1, 11
	s_and_b32 s16, s1, 0x1fff800
	v_readlane_b32 s1, v248, 3
	s_lshl_b32 s1, s1, 10
	s_and_b32 s17, s1, 0x400
	s_add_i32 s1, s33, s90
	s_cmp_lt_i32 s1, 0x10000
	s_cselect_b32 s1, s1, s33
	s_ashr_i32 s4, s1, 1
	s_cmpk_lt_i32 s4, 0x4000
	s_mov_b64 s[30:31], 0
	s_lshl_b32 s4, s4, 11
	s_lshl_b32 s1, s1, 10
	s_and_b32 s28, s4, 0x1fff800
	s_and_b32 s38, s1, 0x400
	s_cmp_lt_i32 s33, 0x10000
	v_readlane_b32 s34, v248, 0
	s_cselect_b64 s[14:15], -1, 0
	v_lshlrev_b32_e32 v68, 1, v80
	s_waitcnt vmcnt(31)
	v_and_b32_e32 v2, 7, v80
	v_lshrrev_b32_e32 v1, 1, v80
	s_bfe_u32 s70, s34, 0x10006
	s_lshl_b32 s1, s58, 4
	v_ashrrev_i32_e32 v73, 31, v72
	v_and_b32_e32 v74, 0xffffffe0, v68
	v_lshlrev_b32_e32 v76, 3, v2
	v_mov_b32_e32 v77, 0
	v_and_b32_e32 v78, 4, v1
	v_lshlrev_b32_e32 v1, 2, v2
	v_cmp_gt_u32_e64 s[6:7], 4, v2
	v_cmp_eq_u32_e64 s[8:9], 3, v2
	v_cmp_eq_u32_e64 s[10:11], 2, v2
	v_cmp_eq_u32_e64 s[12:13], 1, v2
	s_lshl_b32 s39, s70, 10
	s_mul_i32 s34, s58, 24
	v_cndmask_b32_e64 v2, 0, 1, s[14:15]
	s_mov_b32 s29, 0
	v_cmp_eq_u32_e64 s[4:5], 0, v80
	v_ashrrev_i32_e32 v75, 31, v74
	v_mov_b32_e32 v79, v77
	v_ashrrev_i32_e32 v69, 31, v68
	s_lshl_b32 s71, s70, 23
	s_add_i32 s76, s0, s34
	s_add_i32 s77, s0, s90
	s_add_i32 s78, s0, s1
	s_mov_b64 s[34:35], -1
	v_cmp_ne_u32_e64 s[14:15], 1, v2
	v_lshlrev_b64 v[72:73], 2, v[72:73]
	s_lshl_b32 s79, s28, 2
	s_lshl_b32 s80, s38, 2
	s_lshl_b32 s81, s16, 2
	s_lshl_b32 s82, s17, 2
	s_lshl_b32 s38, s39, 2
	s_mov_b32 s83, 0xda24260
	s_mov_b32 s16, 0
	s_branch .LBB0_85

.LBB0_85:
	s_and_b64 vcc, exec, s[14:15]
	s_cbranch_vccnz .LBB0_84
	s_lshl_b32 s28, s16, 25
	s_lshl_b64 s[42:43], s[28:29], 2
	s_add_u32 s84, s62, s42
	s_addc_u32 s85, s63, s43
	s_add_u32 s17, s64, s42
	s_addc_u32 s28, s65, s43
	s_sub_u32 s42, s17, s84
	s_subb_u32 s43, s28, s85
	s_ashr_i64 s[42:43], s[42:43], 2
	s_and_b64 s[44:45], s[34:35], exec
	s_brev_b32 s17, 16
	s_cselect_b32 s17, s17, 0x10000000
	s_add_u32 s86, s54, s17
	s_addc_u32 s87, s55, 0
	s_lshl_b32 s28, s16, 15
	s_lshl_b64 s[44:45], s[28:29], 2
	s_add_u32 s88, s74, s44
	s_addc_u32 s89, s75, s45
	s_lshl_b32 s28, s16, 11
	s_lshl_b64 s[16:17], s[28:29], 2
	s_add_u32 s16, s40, s16
	s_addc_u32 s17, s41, s17
	s_and_b64 s[44:45], s[30:31], exec
	s_cselect_b32 s45, 0, s43
	s_cselect_b32 s44, 0, s42
	s_lshl_b64 s[44:45], s[44:45], 2
	s_add_u32 s28, s84, s44
	s_addc_u32 s39, s85, s45
	s_add_u32 s28, s28, s79
	s_addc_u32 s39, s39, 0
	s_add_u32 s44, s28, s80
	s_addc_u32 s45, s39, 0
	s_waitcnt vmcnt(18)
	v_lshl_add_u64 v[14:15], s[44:45], 0, v[72:73]
	s_and_b64 s[44:45], s[26:27], exec
	s_cselect_b32 s45, 0, s43
	s_cselect_b32 s44, 0, s42
	s_lshl_b64 s[44:45], s[44:45], 2
	s_add_u32 s28, s84, s44
	s_addc_u32 s39, s85, s45
	s_add_u32 s28, s28, s81
	s_addc_u32 s39, s39, 0
	s_add_u32 s44, s28, s82
	s_addc_u32 s45, s39, 0
	global_load_dwordx4 v[2:5], v[14:15], off offset:3072
	global_load_dwordx4 v[6:9], v[14:15], off offset:2048
	global_load_dwordx4 v[10:13], v[14:15], off offset:1024
	global_load_dwordx4 v[46:49], v[14:15], off
	v_lshl_add_u64 v[14:15], s[44:45], 0, v[72:73]
	global_load_dwordx4 v[50:53], v[14:15], off offset:3072
	global_load_dwordx4 v[54:57], v[14:15], off offset:2048
	global_load_dwordx4 v[58:61], v[14:15], off offset:1024
	global_load_dwordx4 v[62:65], v[14:15], off
	v_lshl_add_u64 v[14:15], s[16:17], 0, v[72:73]
	s_add_u32 s16, s16, s38
	s_mov_b32 s39, s29
	s_addc_u32 s17, s17, 0
	v_lshl_add_u64 v[80:81], v[14:15], 0, s[38:39]
	v_lshl_add_u64 v[82:83], s[16:17], 0, v[72:73]
	global_load_dwordx4 v[140:143], v[80:81], off
	global_load_dwordx4 v[144:147], v[82:83], off offset:1024
	global_load_dwordx4 v[148:151], v[82:83], off offset:2048
	global_load_dwordx4 v[152:155], v[82:83], off offset:3072
	v_readlane_b32 s28, v248, 3
	s_add_i32 s28, s28, 0x8000
	s_branch .LBB0_88

.LBB0_485:
	s_cmp_lt_i32 s56, 7
	s_cselect_b64 s[0:1], -1, 0
	s_and_b64 s[44:45], s[0:1], s[4:5]
	s_andn2_b64 vcc, exec, s[44:45]
	s_cbranch_vccnz .LBB0_540
	v_mbcnt_lo_u32_b32 v246, -1, 0
	v_mbcnt_hi_u32_b32 v246, -1, v246
	v_readlane_b32 s21, v248, 0
	s_andn2_b32 s26, s21, 63
	v_add_u32_e32 v242, s26, v246
	s_lshr_b32 s21, s21, 6
	s_mov_b32 s4, 0
	s_mov_b32 s5, -1
	s_mov_b32 s6, 0xffffff80
	s_mov_b32 s7, 0xffffffc0
	v_lshrrev_b32_e32 v245, 5, v246
	v_and_b32_e32 v247, 31, v246
	v_lshlrev_b32_e32 v239, 12, v247
	v_lshl_or_b32 v239, v245, 4, v239
	v_lshlrev_b32_e32 v241, 9, v247
	v_lshl_or_b32 v241, v245, 5, v241
	v_lshlrev_b32_e32 v240, 4, v247
	s_lshl_b32 s26, s21, 11
	s_add_i32 s26, s26, 0x10000
	v_add_u32_e32 v240, s26, v240
	v_and_b32_e32 v231, 15, v246
	v_xor_b32_e32 v231, v231, v245
	v_lshlrev_b32_e32 v231, 4, v231
	v_lshl_or_b32 v231, v247, 8, v231
	v_xor_b32_e32 v232, 32, v231
	v_xor_b32_e32 v233, 64, v231
	v_xor_b32_e32 v234, 0x60, v231
	v_xor_b32_e32 v235, 0x80, v231
	v_xor_b32_e32 v236, 0xa0, v231
	v_xor_b32_e32 v237, 0xc0, v231
	v_xor_b32_e32 v238, 0xe0, v231
	v_lshlrev_b32_e32 v247, 2, v245
	v_xor_b32_e32 v211, 4, v247
	v_lshrrev_b32_e32 v243, 4, v242
	v_xor_b32_e32 v247, v243, v242
	v_lshlrev_b32_e32 v242, 4, v242
	v_and_b32_e32 v247, 15, v247
	v_lshlrev_b32_e32 v247, 4, v247
	v_lshl_or_b32 v243, v243, 8, v247
	v_mov_b32_e32 v244, 0xff800000
	v_mov_b32_e32 v247, 0x14000
	v_mov_b32_e32 v128, 0x20021001
	ds_write_b32 v247, v128 offset:0
	v_mov_b32_e32 v128, 0x40043003
	ds_write_b32 v247, v128 offset:4
	v_mov_b32_e32 v128, 0x60065005
	ds_write_b32 v247, v128 offset:8
	v_mov_b32_e32 v128, 0x80087007
	ds_write_b32 v247, v128 offset:12
	v_mov_b32_e32 v128, 0xa00a9009
	ds_write_b32 v247, v128 offset:16
	v_mov_b32_e32 v128, 0xc00cb00b
	ds_write_b32 v247, v128 offset:20
	v_mov_b32_e32 v128, 0xe00ed00d
	ds_write_b32 v247, v128 offset:24
	v_mov_b32_e32 v128, 0x2112f00f
	ds_write_b32 v247, v128 offset:28
	v_mov_b32_e32 v128, 0x41143113
	ds_write_b32 v247, v128 offset:32
	v_mov_b32_e32 v128, 0x61165115
	ds_write_b32 v247, v128 offset:36
	v_mov_b32_e32 v128, 0x32237117
	ds_write_b32 v247, v128 offset:40
	v_mov_b32_e32 v128, 0x4224
	ds_write_b32 v247, v128 offset:44
	v_mov_b32_e32 v128, 0x22221111
	ds_write_b32 v247, v128 offset:48
	v_mov_b32_e32 v128, 0x3333
	ds_write_b32 v247, v128 offset:52
	v_mov_b32_e32 v128, 0
	ds_write_b32 v247, v128 offset:56
	v_mov_b32_e32 v128, 0
	ds_write_b32 v247, v128 offset:60
	s_and_b32 s25, s2, 7
	s_lshl_b32 s25, s25, 3
	s_bfe_u32 s26, s2, 0x30003
	s_add_i32 s25, s25, s26
	s_lshl_b32 s23, s25, 8
	s_lshl_b32 s26, s21, 5
	s_add_i32 s23, s23, s26
	v_lshlrev_b32_e32 v212, 4, v246
	v_lshlrev_b32_e32 v213, 1, v246
	v_mov_b32_e32 v214, 0
	s_lshl_b32 s14, s2, 3
	s_add_i32 s14, s14, s21
	s_and_b32 s15, s14, 1
	s_lshr_b32 s14, s14, 1
	v_readlane_b32 s8, v248, 12
	v_readlane_b32 s9, v248, 13
	s_lshl_b32 s26, s14, 13
	s_lshl_b32 s34, s15, 12
	s_add_i32 s26, s26, s34
	s_add_u32 s8, s8, s26
	s_addc_u32 s9, s9, 0
	v_readlane_b32 s12, v248, 14
	v_readlane_b32 s13, v248, 15
	s_add_u32 s12, s12, s34
	s_addc_u32 s13, s13, 0
	global_load_dwordx4 v[176:179], v212, s[12:13] offset:0
	global_load_dwordx4 v[180:183], v212, s[12:13] offset:1024
	global_load_dwordx4 v[184:187], v212, s[12:13] offset:2048
	global_load_dwordx4 v[188:191], v212, s[12:13] offset:3072
	s_lshl_b32 s26, s15, 23
	s_lshl_b32 s34, s14, 7
	s_add_i32 s26, s26, s34
	s_add_i32 s26, s26, 0x8000000
	s_add_u32 s10, s54, s26
	s_addc_u32 s11, s55, 0
	s_lshl_b32 s26, s14, 3
	s_lshl_b32 s34, s15, 2
	s_add_i32 s26, s26, s34
	s_add_i32 s26, s26, 0x80000
	s_add_u32 s12, s54, s26
	s_addc_u32 s13, s55, 0
	global_load_dwordx4 v[160:163], v212, s[8:9] offset:0 nt
	global_load_dwordx4 v[164:167], v212, s[8:9] offset:1024 nt
	global_load_dwordx4 v[168:171], v212, s[8:9] offset:2048 nt
	global_load_dwordx4 v[172:175], v212, s[8:9] offset:3072 nt
	s_add_u32 s8, s8, 0x800000
	s_addc_u32 s9, s9, 0
	v_mov_b32_e32 v246, 0x14000
	s_lshr_b32 s24, s2, 6
	s_mov_b32 s22, 0
.Ltk0_unit:
	s_lshl_b32 s26, s24, 9
	s_lshl_b32 s20, s23, 12
	s_add_i32 s26, s26, s20
	s_add_i32 s26, s26, 0x1c000000
	s_add_u32 s16, s54, s26
	s_addc_u32 s17, s55, 0
	s_lshl_b32 s26, s24, 16
	s_add_i32 s26, s26, 0x300000
	s_add_u32 s18, s54, s26
	s_addc_u32 s19, s55, 0
	s_lshl_b32 s20, s23, 9
	s_lshl_b32 s26, s24, 6
	s_add_i32 s20, s20, s26
	s_add_i32 s26, s20, 0x28000000
	s_add_u32 s28, s54, s26
	s_addc_u32 s29, s55, 0
	s_add_i32 s26, s20, 0x28800000
	s_add_u32 s30, s54, s26
	s_addc_u32 s31, s55, 0
	s_barrier
	global_load_dwordx4 v[0:3], v242, s[18:19]
	v_add_u32_e32 v247, 0x2000, v242
	global_load_dwordx4 v[4:7], v247, s[18:19]
	v_add_u32_e32 v247, 0x4000, v242
	global_load_dwordx4 v[8:11], v247, s[18:19]
	v_add_u32_e32 v247, 0x6000, v242
	global_load_dwordx4 v[12:15], v247, s[18:19]
	v_add_u32_e32 v247, 0x8000, v242
	global_load_dwordx4 v[16:19], v247, s[18:19]
	v_add_u32_e32 v247, 0xa000, v242
	global_load_dwordx4 v[20:23], v247, s[18:19]
	v_add_u32_e32 v247, 0xc000, v242
	global_load_dwordx4 v[24:27], v247, s[18:19]
	v_add_u32_e32 v247, 0xe000, v242
	global_load_dwordx4 v[28:31], v247, s[18:19]
	global_load_dwordx4 v[64:67], v239, s[16:17] offset:0
	global_load_dwordx4 v[68:71], v239, s[16:17] offset:32
	global_load_dwordx4 v[72:75], v239, s[16:17] offset:64
	global_load_dwordx4 v[76:79], v239, s[16:17] offset:96
	global_load_dwordx4 v[80:83], v239, s[16:17] offset:128
	global_load_dwordx4 v[84:87], v239, s[16:17] offset:160
	global_load_dwordx4 v[88:91], v239, s[16:17] offset:192
	global_load_dwordx4 v[92:95], v239, s[16:17] offset:224
	s_waitcnt vmcnt(15)
	ds_write_b128 v243, v[0:3] offset:0
	s_waitcnt vmcnt(14)
	ds_write_b128 v243, v[4:7] offset:8192
	s_waitcnt vmcnt(13)
	ds_write_b128 v243, v[8:11] offset:16384
	s_waitcnt vmcnt(12)
	ds_write_b128 v243, v[12:15] offset:24576
	s_waitcnt vmcnt(11)
	ds_write_b128 v243, v[16:19] offset:32768
	s_waitcnt vmcnt(10)
	ds_write_b128 v243, v[20:23] offset:40960
	s_waitcnt vmcnt(9)
	ds_write_b128 v243, v[24:27] offset:49152
	s_waitcnt vmcnt(8)
	ds_write_b128 v243, v[28:31] offset:57344
	s_waitcnt lgkmcnt(0)
	s_barrier
	ds_read_b128 v[96:99], v231 offset:0
	ds_read_b128 v[100:103], v232 offset:0
	ds_read_b128 v[104:107], v233 offset:0
	ds_read_b128 v[108:111], v234 offset:0
	ds_read_b128 v[112:115], v235 offset:0
	ds_read_b128 v[116:119], v236 offset:0
	ds_read_b128 v[120:123], v237 offset:0
	ds_read_b128 v[124:127], v238 offset:0
	s_waitcnt vmcnt(0)
	s_waitcnt lgkmcnt(4)
	v_mfma_f32_32x32x16_bf16 v[0:15], v[96:99], v[64:67], 0
	v_mfma_f32_32x32x16_bf16 v[0:15], v[100:103], v[68:71], v[0:15]
	v_mfma_f32_32x32x16_bf16 v[0:15], v[104:107], v[72:75], v[0:15]
	v_mfma_f32_32x32x16_bf16 v[0:15], v[108:111], v[76:79], v[0:15]
	ds_read_b128 v[96:99], v231 offset:8192
	ds_read_b128 v[100:103], v232 offset:8192
	ds_read_b128 v[104:107], v233 offset:8192
	ds_read_b128 v[108:111], v234 offset:8192
	s_waitcnt lgkmcnt(4)
	v_mfma_f32_32x32x16_bf16 v[0:15], v[112:115], v[80:83], v[0:15]
	v_mfma_f32_32x32x16_bf16 v[0:15], v[116:119], v[84:87], v[0:15]
	v_mfma_f32_32x32x16_bf16 v[0:15], v[120:123], v[88:91], v[0:15]
	v_mfma_f32_32x32x16_bf16 v[0:15], v[124:127], v[92:95], v[0:15]
	ds_read_b128 v[112:115], v235 offset:8192
	ds_read_b128 v[116:119], v236 offset:8192
	ds_read_b128 v[120:123], v237 offset:8192
	ds_read_b128 v[124:127], v238 offset:8192
	s_waitcnt lgkmcnt(4)
	v_mfma_f32_32x32x16_bf16 v[16:31], v[96:99], v[64:67], 0
	v_mfma_f32_32x32x16_bf16 v[16:31], v[100:103], v[68:71], v[16:31]
	v_mfma_f32_32x32x16_bf16 v[16:31], v[104:107], v[72:75], v[16:31]
	v_mfma_f32_32x32x16_bf16 v[16:31], v[108:111], v[76:79], v[16:31]
	ds_read_b128 v[96:99], v231 offset:16384
	ds_read_b128 v[100:103], v232 offset:16384
	ds_read_b128 v[104:107], v233 offset:16384
	ds_read_b128 v[108:111], v234 offset:16384
	s_waitcnt lgkmcnt(4)
	v_mfma_f32_32x32x16_bf16 v[16:31], v[112:115], v[80:83], v[16:31]
	v_mfma_f32_32x32x16_bf16 v[16:31], v[116:119], v[84:87], v[16:31]
	v_mfma_f32_32x32x16_bf16 v[16:31], v[120:123], v[88:91], v[16:31]
	v_mfma_f32_32x32x16_bf16 v[16:31], v[124:127], v[92:95], v[16:31]
	ds_read_b128 v[112:115], v235 offset:16384
	ds_read_b128 v[116:119], v236 offset:16384
	ds_read_b128 v[120:123], v237 offset:16384
	ds_read_b128 v[124:127], v238 offset:16384
	s_waitcnt lgkmcnt(4)
	v_mfma_f32_32x32x16_bf16 v[32:47], v[96:99], v[64:67], 0
	v_mfma_f32_32x32x16_bf16 v[32:47], v[100:103], v[68:71], v[32:47]
	v_mfma_f32_32x32x16_bf16 v[32:47], v[104:107], v[72:75], v[32:47]
	v_mfma_f32_32x32x16_bf16 v[32:47], v[108:111], v[76:79], v[32:47]
	ds_read_b128 v[96:99], v231 offset:24576
	ds_read_b128 v[100:103], v232 offset:24576
	ds_read_b128 v[104:107], v233 offset:24576
	ds_read_b128 v[108:111], v234 offset:24576
	s_waitcnt lgkmcnt(4)
	v_mfma_f32_32x32x16_bf16 v[32:47], v[112:115], v[80:83], v[32:47]
	v_mfma_f32_32x32x16_bf16 v[32:47], v[116:119], v[84:87], v[32:47]
	v_mfma_f32_32x32x16_bf16 v[32:47], v[120:123], v[88:91], v[32:47]
	v_mfma_f32_32x32x16_bf16 v[32:47], v[124:127], v[92:95], v[32:47]
	ds_read_b128 v[112:115], v235 offset:24576
	ds_read_b128 v[116:119], v236 offset:24576
	ds_read_b128 v[120:123], v237 offset:24576
	ds_read_b128 v[124:127], v238 offset:24576
	s_waitcnt lgkmcnt(4)
	v_mfma_f32_32x32x16_bf16 v[48:63], v[96:99], v[64:67], 0
	v_mfma_f32_32x32x16_bf16 v[48:63], v[100:103], v[68:71], v[48:63]
	v_mfma_f32_32x32x16_bf16 v[48:63], v[104:107], v[72:75], v[48:63]
	v_mfma_f32_32x32x16_bf16 v[48:63], v[108:111], v[76:79], v[48:63]
	s_waitcnt lgkmcnt(0)
	v_mfma_f32_32x32x16_bf16 v[48:63], v[112:115], v[80:83], v[48:63]
	v_mfma_f32_32x32x16_bf16 v[48:63], v[116:119], v[84:87], v[48:63]
	v_mfma_f32_32x32x16_bf16 v[48:63], v[120:123], v[88:91], v[48:63]
	v_mfma_f32_32x32x16_bf16 v[48:63], v[124:127], v[92:95], v[48:63]
	global_load_dwordx4 v[64:67], v239, s[16:17] offset:256
	global_load_dwordx4 v[68:71], v239, s[16:17] offset:288
	global_load_dwordx4 v[72:75], v239, s[16:17] offset:320
	global_load_dwordx4 v[76:79], v239, s[16:17] offset:352
	global_load_dwordx4 v[80:83], v239, s[16:17] offset:384
	global_load_dwordx4 v[84:87], v239, s[16:17] offset:416
	global_load_dwordx4 v[88:91], v239, s[16:17] offset:448
	global_load_dwordx4 v[92:95], v239, s[16:17] offset:480
	s_nop 11
	v_and_or_b32 v0, v0, s6, v211
	v_or_b32_e32 v0, 0x7b, v0
	v_and_or_b32 v1, v1, s6, v211
	v_or_b32_e32 v1, 0x7a, v1
	v_and_or_b32 v2, v2, s6, v211
	v_or_b32_e32 v2, 0x79, v2
	v_and_or_b32 v3, v3, s6, v211
	v_or_b32_e32 v3, 0x78, v3
	v_and_or_b32 v4, v4, s6, v211
	v_or_b32_e32 v4, 0x73, v4
	v_and_or_b32 v5, v5, s6, v211
	v_or_b32_e32 v5, 0x72, v5
	v_and_or_b32 v6, v6, s6, v211
	v_or_b32_e32 v6, 0x71, v6
	v_and_or_b32 v7, v7, s6, v211
	v_or_b32_e32 v7, 0x70, v7
	v_and_or_b32 v8, v8, s6, v211
	v_or_b32_e32 v8, 0x6b, v8
	v_and_or_b32 v9, v9, s6, v211
	v_or_b32_e32 v9, 0x6a, v9
	v_and_or_b32 v10, v10, s6, v211
	v_or_b32_e32 v10, 0x69, v10
	v_and_or_b32 v11, v11, s6, v211
	v_or_b32_e32 v11, 0x68, v11
	v_and_or_b32 v12, v12, s6, v211
	v_or_b32_e32 v12, 0x63, v12
	v_and_or_b32 v13, v13, s6, v211
	v_or_b32_e32 v13, 0x62, v13
	v_and_or_b32 v14, v14, s6, v211
	v_or_b32_e32 v14, 0x61, v14
	v_and_or_b32 v15, v15, s6, v211
	v_or_b32_e32 v15, 0x60, v15
	v_and_or_b32 v16, v16, s6, v211
	v_or_b32_e32 v16, 0x5b, v16
	v_and_or_b32 v17, v17, s6, v211
	v_or_b32_e32 v17, 0x5a, v17
	v_and_or_b32 v18, v18, s6, v211
	v_or_b32_e32 v18, 0x59, v18
	v_and_or_b32 v19, v19, s6, v211
	v_or_b32_e32 v19, 0x58, v19
	v_and_or_b32 v20, v20, s6, v211
	v_or_b32_e32 v20, 0x53, v20
	v_and_or_b32 v21, v21, s6, v211
	v_or_b32_e32 v21, 0x52, v21
	v_and_or_b32 v22, v22, s6, v211
	v_or_b32_e32 v22, 0x51, v22
	v_and_or_b32 v23, v23, s6, v211
	v_or_b32_e32 v23, 0x50, v23
	v_and_or_b32 v24, v24, s6, v211
	v_or_b32_e32 v24, 0x4b, v24
	v_and_or_b32 v25, v25, s6, v211
	v_or_b32_e32 v25, 0x4a, v25
	v_and_or_b32 v26, v26, s6, v211
	v_or_b32_e32 v26, 0x49, v26
	v_and_or_b32 v27, v27, s6, v211
	v_or_b32_e32 v27, 0x48, v27
	v_and_or_b32 v28, v28, s6, v211
	v_or_b32_e32 v28, 0x43, v28
	v_and_or_b32 v29, v29, s6, v211
	v_or_b32_e32 v29, 0x42, v29
	v_and_or_b32 v30, v30, s6, v211
	v_or_b32_e32 v30, 0x41, v30
	v_and_or_b32 v31, v31, s6, v211
	v_or_b32_e32 v31, 64, v31
	v_and_or_b32 v32, v32, s6, v211
	v_or_b32_e32 v32, 59, v32
	v_and_or_b32 v33, v33, s6, v211
	v_or_b32_e32 v33, 58, v33
	v_and_or_b32 v34, v34, s6, v211
	v_or_b32_e32 v34, 57, v34
	v_and_or_b32 v35, v35, s6, v211
	v_or_b32_e32 v35, 56, v35
	v_and_or_b32 v36, v36, s6, v211
	v_or_b32_e32 v36, 51, v36
	v_and_or_b32 v37, v37, s6, v211
	v_or_b32_e32 v37, 50, v37
	v_and_or_b32 v38, v38, s6, v211
	v_or_b32_e32 v38, 49, v38
	v_and_or_b32 v39, v39, s6, v211
	v_or_b32_e32 v39, 48, v39
	v_and_or_b32 v40, v40, s6, v211
	v_or_b32_e32 v40, 43, v40
	v_and_or_b32 v41, v41, s6, v211
	v_or_b32_e32 v41, 42, v41
	v_and_or_b32 v42, v42, s6, v211
	v_or_b32_e32 v42, 41, v42
	v_and_or_b32 v43, v43, s6, v211
	v_or_b32_e32 v43, 40, v43
	v_and_or_b32 v44, v44, s6, v211
	v_or_b32_e32 v44, 35, v44
	v_and_or_b32 v45, v45, s6, v211
	v_or_b32_e32 v45, 34, v45
	v_and_or_b32 v46, v46, s6, v211
	v_or_b32_e32 v46, 33, v46
	v_and_or_b32 v47, v47, s6, v211
	v_or_b32_e32 v47, 32, v47
	v_and_or_b32 v48, v48, s6, v211
	v_or_b32_e32 v48, 27, v48
	v_and_or_b32 v49, v49, s6, v211
	v_or_b32_e32 v49, 26, v49
	v_and_or_b32 v50, v50, s6, v211
	v_or_b32_e32 v50, 25, v50
	v_and_or_b32 v51, v51, s6, v211
	v_or_b32_e32 v51, 24, v51
	v_and_or_b32 v52, v52, s6, v211
	v_or_b32_e32 v52, 19, v52
	v_and_or_b32 v53, v53, s6, v211
	v_or_b32_e32 v53, 18, v53
	v_and_or_b32 v54, v54, s6, v211
	v_or_b32_e32 v54, 17, v54
	v_and_or_b32 v55, v55, s6, v211
	v_or_b32_e32 v55, 16, v55
	v_and_or_b32 v56, v56, s6, v211
	v_or_b32_e32 v56, 11, v56
	v_and_or_b32 v57, v57, s6, v211
	v_or_b32_e32 v57, 10, v57
	v_and_or_b32 v58, v58, s6, v211
	v_or_b32_e32 v58, 9, v58
	v_and_or_b32 v59, v59, s6, v211
	v_or_b32_e32 v59, 8, v59
	v_and_or_b32 v60, v60, s6, v211
	v_or_b32_e32 v60, 3, v60
	v_and_or_b32 v61, v61, s6, v211
	v_or_b32_e32 v61, 2, v61
	v_and_or_b32 v62, v62, s6, v211
	v_or_b32_e32 v62, 1, v62
	v_and_or_b32 v63, v63, s6, v211
	v_or_b32_e32 v63, 0, v63
	v_max_f32_e32 v144, v0, v13
	v_min_f32_e32 v13, v0, v13
	v_max_f32_e32 v145, v1, v12
	v_min_f32_e32 v12, v1, v12
	v_max_f32_e32 v146, v2, v15
	v_min_f32_e32 v15, v2, v15
	v_max_f32_e32 v147, v3, v14
	v_min_f32_e32 v14, v3, v14
	v_max_f32_e32 v148, v4, v8
	v_min_f32_e32 v8, v4, v8
	v_max_f32_e32 v149, v5, v6
	v_min_f32_e32 v6, v5, v6
	v_max_f32_e32 v150, v7, v11
	v_min_f32_e32 v11, v7, v11
	v_max_f32_e32 v151, v9, v10
	v_min_f32_e32 v10, v9, v10
	v_max_f32_e32 v249, v144, v149
	v_min_f32_e32 v149, v144, v149
	v_max_f32_e32 v250, v145, v150
	v_min_f32_e32 v150, v145, v150
	v_max_f32_e32 v251, v146, v151
	v_min_f32_e32 v151, v146, v151
	v_max_f32_e32 v252, v147, v148
	v_min_f32_e32 v148, v147, v148
	v_max_f32_e32 v253, v6, v13
	v_min_f32_e32 v13, v6, v13
	v_max_f32_e32 v254, v8, v14
	v_min_f32_e32 v14, v8, v14
	v_max_f32_e32 v255, v10, v15
	v_min_f32_e32 v15, v10, v15
	v_max_f32_e32 v96, v11, v12
	v_min_f32_e32 v12, v11, v12
	v_max_f32_e32 v97, v249, v250
	v_min_f32_e32 v250, v249, v250
	v_max_f32_e32 v98, v251, v252
	v_min_f32_e32 v252, v251, v252
	v_max_f32_e32 v99, v148, v149
	v_min_f32_e32 v149, v148, v149
	v_max_f32_e32 v100, v253, v254
	v_min_f32_e32 v254, v253, v254
	v_max_f32_e32 v101, v150, v151
	v_min_f32_e32 v151, v150, v151
	v_max_f32_e32 v102, v255, v96
	v_min_f32_e32 v96, v255, v96
	v_max_f32_e32 v103, v12, v13
	v_min_f32_e32 v13, v12, v13
	v_max_f32_e32 v104, v14, v15
	v_min_f32_e32 v15, v14, v15
	v_max_f32_e32 v105, v97, v98
	v_min_f32_e32 v98, v97, v98
	v_max_f32_e32 v106, v250, v252
	v_min_f32_e32 v252, v250, v252
	v_max_f32_e32 v107, v99, v102
	v_min_f32_e32 v102, v99, v102
	v_max_f32_e32 v108, v149, v96
	v_min_f32_e32 v96, v149, v96
	v_max_f32_e32 v109, v100, v101
	v_min_f32_e32 v101, v100, v101
	v_max_f32_e32 v110, v254, v151
	v_min_f32_e32 v151, v254, v151
	v_max_f32_e32 v111, v103, v104
	v_min_f32_e32 v104, v103, v104
	v_max_f32_e32 v112, v13, v15
	v_min_f32_e32 v15, v13, v15
	v_max_f32_e32 v113, v106, v98
	v_min_f32_e32 v98, v106, v98
	v_max_f32_e32 v114, v252, v111
	v_min_f32_e32 v111, v252, v111
	v_max_f32_e32 v115, v107, v109
	v_min_f32_e32 v109, v107, v109
	v_max_f32_e32 v116, v108, v101
	v_min_f32_e32 v101, v108, v101
	v_max_f32_e32 v117, v110, v102
	v_min_f32_e32 v102, v110, v102
	v_max_f32_e32 v118, v151, v96
	v_min_f32_e32 v96, v151, v96
	v_max_f32_e32 v119, v112, v104
	v_min_f32_e32 v104, v112, v104
	v_max_f32_e32 v120, v113, v115
	v_min_f32_e32 v115, v113, v115
	v_max_f32_e32 v121, v98, v109
	v_min_f32_e32 v109, v98, v109
	v_max_f32_e32 v122, v116, v117
	v_min_f32_e32 v117, v116, v117
	v_max_f32_e32 v123, v101, v102
	v_min_f32_e32 v102, v101, v102
	v_max_f32_e32 v124, v118, v119
	v_min_f32_e32 v119, v118, v119
	v_max_f32_e32 v125, v96, v104
	v_min_f32_e32 v104, v96, v104
	v_max_f32_e32 v126, v121, v115
	v_min_f32_e32 v115, v121, v115
	v_max_f32_e32 v127, v114, v109
	v_min_f32_e32 v109, v114, v109
	v_max_f32_e32 v0, v124, v111
	v_min_f32_e32 v111, v124, v111
	v_max_f32_e32 v1, v125, v119
	v_min_f32_e32 v119, v125, v119
	v_max_f32_e32 v2, v127, v122
	v_min_f32_e32 v122, v127, v122
	v_max_f32_e32 v3, v109, v117
	v_min_f32_e32 v117, v109, v117
	v_max_f32_e32 v4, v123, v0
	v_min_f32_e32 v0, v123, v0
	v_max_f32_e32 v5, v102, v111
	v_min_f32_e32 v111, v102, v111
	v_max_f32_e32 v7, v2, v115
	v_min_f32_e32 v115, v2, v115
	v_max_f32_e32 v9, v122, v3
	v_min_f32_e32 v3, v122, v3
	v_max_f32_e32 v144, v4, v117
	v_min_f32_e32 v117, v4, v117
	v_max_f32_e32 v145, v0, v5
	v_min_f32_e32 v5, v0, v5
	v_max_f32_e32 v146, v1, v111
	v_min_f32_e32 v111, v1, v111
	v_max_f32_e32 v147, v3, v144
	v_min_f32_e32 v144, v3, v144
	v_max_f32_e32 v6, v117, v145
	v_min_f32_e32 v145, v117, v145
	v_max_f32_e32 v8, v16, v29
	v_min_f32_e32 v29, v16, v29
	v_max_f32_e32 v10, v17, v28
	v_min_f32_e32 v28, v17, v28
	v_max_f32_e32 v11, v18, v31
	v_min_f32_e32 v31, v18, v31
	v_max_f32_e32 v249, v19, v30
	v_min_f32_e32 v30, v19, v30
	v_max_f32_e32 v251, v20, v24
	v_min_f32_e32 v24, v20, v24
	v_max_f32_e32 v148, v21, v22
	v_min_f32_e32 v22, v21, v22
	v_max_f32_e32 v253, v23, v27
	v_min_f32_e32 v27, v23, v27
	v_max_f32_e32 v150, v25, v26
	v_min_f32_e32 v26, v25, v26
	v_max_f32_e32 v255, v8, v148
	v_min_f32_e32 v148, v8, v148
	v_max_f32_e32 v12, v10, v253
	v_min_f32_e32 v253, v10, v253
	v_max_f32_e32 v14, v11, v150
	v_min_f32_e32 v150, v11, v150
	v_max_f32_e32 v97, v249, v251
	v_min_f32_e32 v251, v249, v251
	v_max_f32_e32 v250, v22, v29
	v_min_f32_e32 v29, v22, v29
	v_max_f32_e32 v99, v24, v30
	v_min_f32_e32 v30, v24, v30
	v_max_f32_e32 v149, v26, v31
	v_min_f32_e32 v31, v26, v31
	v_max_f32_e32 v100, v27, v28
	v_min_f32_e32 v28, v27, v28
	v_max_f32_e32 v254, v255, v12
	v_min_f32_e32 v12, v255, v12
	v_max_f32_e32 v103, v14, v97
	v_min_f32_e32 v97, v14, v97
	v_max_f32_e32 v13, v251, v148
	v_min_f32_e32 v148, v251, v148
	v_max_f32_e32 v106, v250, v99
	v_min_f32_e32 v99, v250, v99
	v_max_f32_e32 v252, v253, v150
	v_min_f32_e32 v150, v253, v150
	v_max_f32_e32 v107, v149, v100
	v_min_f32_e32 v100, v149, v100
	v_max_f32_e32 v108, v28, v29
	v_min_f32_e32 v29, v28, v29
	v_max_f32_e32 v110, v30, v31
	v_min_f32_e32 v31, v30, v31
	v_max_f32_e32 v151, v254, v103
	v_min_f32_e32 v103, v254, v103
	v_max_f32_e32 v112, v12, v97
	v_min_f32_e32 v97, v12, v97
	v_max_f32_e32 v113, v13, v107
	v_min_f32_e32 v107, v13, v107
	v_max_f32_e32 v98, v148, v100
	v_min_f32_e32 v100, v148, v100
	v_max_f32_e32 v116, v106, v252
	v_min_f32_e32 v252, v106, v252
	v_max_f32_e32 v101, v99, v150
	v_min_f32_e32 v150, v99, v150
	v_max_f32_e32 v118, v108, v110
	v_min_f32_e32 v110, v108, v110
	v_max_f32_e32 v96, v29, v31
	v_min_f32_e32 v31, v29, v31
	v_max_f32_e32 v121, v112, v103
	v_min_f32_e32 v103, v112, v103
	v_max_f32_e32 v114, v97, v118
	v_min_f32_e32 v118, v97, v118
	v_max_f32_e32 v124, v113, v116
	v_min_f32_e32 v116, v113, v116
	v_max_f32_e32 v125, v98, v252
	v_min_f32_e32 v252, v98, v252
	v_max_f32_e32 v127, v101, v107
	v_min_f32_e32 v107, v101, v107
	v_max_f32_e32 v109, v150, v100
	v_min_f32_e32 v100, v150, v100
	v_max_f32_e32 v123, v96, v110
	v_min_f32_e32 v110, v96, v110
	v_max_f32_e32 v102, v121, v124
	v_min_f32_e32 v124, v121, v124
	v_max_f32_e32 v2, v103, v116
	v_min_f32_e32 v116, v103, v116
	v_max_f32_e32 v122, v125, v127
	v_min_f32_e32 v127, v125, v127
	v_max_f32_e32 v4, v252, v107
	v_min_f32_e32 v107, v252, v107
	v_max_f32_e32 v0, v109, v123
	v_min_f32_e32 v123, v109, v123
	v_max_f32_e32 v1, v100, v110
	v_min_f32_e32 v110, v100, v110
	v_max_f32_e32 v3, v2, v124
	v_min_f32_e32 v124, v2, v124
	v_max_f32_e32 v117, v114, v116
	v_min_f32_e32 v116, v114, v116
	v_max_f32_e32 v16, v0, v118
	v_min_f32_e32 v118, v0, v118
	v_max_f32_e32 v17, v1, v123
	v_min_f32_e32 v123, v1, v123
	v_max_f32_e32 v18, v117, v122
	v_min_f32_e32 v122, v117, v122
	v_max_f32_e32 v19, v116, v127
	v_min_f32_e32 v127, v116, v127
	v_max_f32_e32 v20, v4, v16
	v_min_f32_e32 v16, v4, v16
	v_max_f32_e32 v21, v107, v118
	v_min_f32_e32 v118, v107, v118
	v_max_f32_e32 v23, v18, v124
	v_min_f32_e32 v124, v18, v124
	v_max_f32_e32 v25, v122, v19
	v_min_f32_e32 v19, v122, v19
	v_max_f32_e32 v8, v20, v127
	v_min_f32_e32 v127, v20, v127
	v_max_f32_e32 v10, v16, v21
	v_min_f32_e32 v21, v16, v21
	v_max_f32_e32 v11, v17, v118
	v_min_f32_e32 v118, v17, v118
	v_max_f32_e32 v249, v19, v8
	v_min_f32_e32 v8, v19, v8
	v_max_f32_e32 v22, v127, v10
	v_min_f32_e32 v10, v127, v10
	s_waitcnt vmcnt(24)
	v_pk_mul_f32 v[160:161], v[160:161], v[176:177]
	v_pk_mul_f32 v[162:163], v[162:163], v[178:179]
	v_pk_mul_f32 v[164:165], v[164:165], v[180:181]
	v_pk_mul_f32 v[166:167], v[166:167], v[182:183]
	v_pk_mul_f32 v[168:169], v[168:169], v[184:185]
	v_pk_mul_f32 v[170:171], v[170:171], v[186:187]
	v_pk_mul_f32 v[172:173], v[172:173], v[188:189]
	v_pk_mul_f32 v[174:175], v[174:175], v[190:191]
	v_max3_f32 v192, |v160|, |v161|, |v162|
	v_max3_f32 v192, |v163|, |v164|, v192
	v_max3_f32 v192, |v165|, |v166|, v192
	v_max3_f32 v192, |v167|, |v168|, v192
	v_max3_f32 v192, |v169|, |v170|, v192
	v_max3_f32 v192, |v171|, |v172|, v192
	v_max3_f32 v192, |v173|, |v174|, v192
	v_max_f32_e64 v192, |v175|, v192
	s_nop 1
	v_mov_b32_dpp v193, v192 quad_perm:[1,0,3,2] row_mask:0xf bank_mask:0xf bound_ctrl:1
	v_max_f32_e32 v192, v192, v193
	s_nop 1
	v_mov_b32_dpp v193, v192 quad_perm:[2,3,0,1] row_mask:0xf bank_mask:0xf bound_ctrl:1
	v_max_f32_e32 v192, v192, v193
	s_nop 1
	v_mov_b32_dpp v193, v192 row_half_mirror row_mask:0xf bank_mask:0xf bound_ctrl:1
	v_max_f32_e32 v192, v192, v193
	s_nop 1
	v_mov_b32_dpp v193, v192 row_mirror row_mask:0xf bank_mask:0xf bound_ctrl:1
	v_max_f32_e32 v192, v192, v193
	v_mov_b32_e32 v193, v192
	s_nop 1
	v_permlane16_swap_b32_e32 v192, v193
	s_nop 1
	v_max_f32_e32 v192, v192, v193
	v_mov_b32_e32 v193, v192
	s_nop 1
	v_permlane32_swap_b32_e32 v192, v193
	s_nop 1
	v_max_f32_e32 v192, v192, v193
	v_max_f32_e32 v192, 0xda24260, v192
	v_mul_f32_e32 v194, 0x3e2aaaab, v192
	global_store_dword v214, v194, s[12:13]
	v_div_scale_f32 v195, s[26:27], v194, v194, 1.0
	v_rcp_f32_e32 v196, v195
	v_div_scale_f32 v204, vcc, 1.0, v194, 1.0
	v_fma_f32 v205, -v195, v196, 1.0
	v_fmac_f32_e32 v196, v205, v196
	v_mul_f32_e32 v205, v204, v196
	v_fma_f32 v206, -v195, v205, v204
	v_fmac_f32_e32 v205, v206, v196
	v_fma_f32 v195, -v195, v205, v204
	s_nop 0
	v_div_fmas_f32 v195, v195, v196, v205
	v_div_fixup_f32 v207, v195, v194, 1.0
	v_mul_f32_e32 v160, v207, v160
	v_mul_f32_e32 v161, v207, v161
	v_mul_f32_e32 v162, v207, v162
	v_mul_f32_e32 v163, v207, v163
	v_mul_f32_e32 v164, v207, v164
	v_mul_f32_e32 v165, v207, v165
	v_mul_f32_e32 v166, v207, v166
	v_mul_f32_e32 v167, v207, v167
	v_mul_f32_e32 v168, v207, v168
	v_mul_f32_e32 v169, v207, v169
	v_mul_f32_e32 v170, v207, v170
	v_mul_f32_e32 v171, v207, v171
	v_mul_f32_e32 v172, v207, v172
	v_mul_f32_e32 v173, v207, v173
	v_mul_f32_e32 v174, v207, v174
	v_mul_f32_e32 v175, v207, v175
	v_mov_b32_e32 v208, 0
	v_mov_b32_e32 v209, 0
	v_mov_b32_e32 v210, 0
	v_mov_b32_e32 v193, 0
	v_cvt_scalef32_pk_fp4_f32 v208, v160, v161, 1.0
	v_cvt_scalef32_pk_fp4_f32 v209, v164, v165, 1.0
	v_cvt_scalef32_pk_fp4_f32 v210, v168, v169, 1.0
	v_cvt_scalef32_pk_fp4_f32 v193, v172, v173, 1.0
	v_cvt_scalef32_pk_fp4_f32 v208, v162, v163, 1.0 op_sel:[0,0,1,0]
	v_cvt_scalef32_pk_fp4_f32 v209, v166, v167, 1.0 op_sel:[0,0,1,0]
	v_cvt_scalef32_pk_fp4_f32 v210, v170, v171, 1.0 op_sel:[0,0,1,0]
	v_cvt_scalef32_pk_fp4_f32 v193, v174, v175, 1.0 op_sel:[0,0,1,0]
	global_store_short v213, v208, s[10:11] nt
	s_add_u32 s14, s10, 0x200000
	s_addc_u32 s15, s11, 0
	global_store_short v213, v209, s[14:15] nt
	s_add_u32 s14, s10, 0x400000
	s_addc_u32 s15, s11, 0
	global_store_short v213, v210, s[14:15] nt
	s_add_u32 s14, s10, 0x600000
	s_addc_u32 s15, s11, 0
	global_store_short v213, v193, s[14:15] nt
	s_add_u32 s10, s10, 0x20000
	s_addc_u32 s11, s11, 0
	s_add_u32 s12, s12, 0x2000
	s_addc_u32 s13, s13, 0
	global_load_dwordx4 v[160:163], v212, s[8:9] offset:0 nt
	global_load_dwordx4 v[164:167], v212, s[8:9] offset:1024 nt
	global_load_dwordx4 v[168:171], v212, s[8:9] offset:2048 nt
	global_load_dwordx4 v[172:175], v212, s[8:9] offset:3072 nt
	s_add_u32 s8, s8, 0x800000
	s_addc_u32 s9, s9, 0
	v_max_f32_e32 v24, v32, v45
	v_min_f32_e32 v45, v32, v45
	v_max_f32_e32 v26, v33, v44
	v_min_f32_e32 v44, v33, v44
	v_max_f32_e32 v27, v34, v47
	v_min_f32_e32 v47, v34, v47
	v_max_f32_e32 v255, v35, v46
	v_min_f32_e32 v46, v35, v46
	v_max_f32_e32 v14, v36, v40
	v_min_f32_e32 v40, v36, v40
	v_max_f32_e32 v251, v37, v38
	v_min_f32_e32 v38, v37, v38
	v_max_f32_e32 v250, v39, v43
	v_min_f32_e32 v43, v39, v43
	v_max_f32_e32 v253, v41, v42
	v_min_f32_e32 v42, v41, v42
	v_max_f32_e32 v149, v24, v251
	v_min_f32_e32 v251, v24, v251
	v_max_f32_e32 v28, v26, v250
	v_min_f32_e32 v250, v26, v250
	v_max_f32_e32 v30, v27, v253
	v_min_f32_e32 v253, v27, v253
	v_max_f32_e32 v254, v255, v14
	v_min_f32_e32 v14, v255, v14
	v_max_f32_e32 v12, v38, v45
	v_min_f32_e32 v45, v38, v45
	v_max_f32_e32 v13, v40, v46
	v_min_f32_e32 v46, v40, v46
	v_max_f32_e32 v148, v42, v47
	v_min_f32_e32 v47, v42, v47
	v_max_f32_e32 v106, v43, v44
	v_min_f32_e32 v44, v43, v44
	v_max_f32_e32 v99, v149, v28
	v_min_f32_e32 v28, v149, v28
	v_max_f32_e32 v108, v30, v254
	v_min_f32_e32 v254, v30, v254
	v_max_f32_e32 v29, v14, v251
	v_min_f32_e32 v251, v14, v251
	v_max_f32_e32 v112, v12, v13
	v_min_f32_e32 v13, v12, v13
	v_max_f32_e32 v97, v250, v253
	v_min_f32_e32 v253, v250, v253
	v_max_f32_e32 v113, v148, v106
	v_min_f32_e32 v106, v148, v106
	v_max_f32_e32 v98, v44, v45
	v_min_f32_e32 v45, v44, v45
	v_max_f32_e32 v101, v46, v47
	v_min_f32_e32 v47, v46, v47
	v_max_f32_e32 v150, v99, v108
	v_min_f32_e32 v108, v99, v108
	v_max_f32_e32 v96, v28, v254
	v_min_f32_e32 v254, v28, v254
	v_max_f32_e32 v121, v29, v113
	v_min_f32_e32 v113, v29, v113
	v_max_f32_e32 v103, v251, v106
	v_min_f32_e32 v106, v251, v106
	v_max_f32_e32 v125, v112, v97
	v_min_f32_e32 v97, v112, v97
	v_max_f32_e32 v252, v13, v253
	v_min_f32_e32 v253, v13, v253
	v_max_f32_e32 v109, v98, v101
	v_min_f32_e32 v101, v98, v101
	v_max_f32_e32 v100, v45, v47
	v_min_f32_e32 v47, v45, v47
	v_max_f32_e32 v2, v96, v108
	v_min_f32_e32 v108, v96, v108
	v_max_f32_e32 v114, v254, v109
	v_min_f32_e32 v109, v254, v109
	v_max_f32_e32 v0, v121, v125
	v_min_f32_e32 v125, v121, v125
	v_max_f32_e32 v1, v103, v97
	v_min_f32_e32 v97, v103, v97
	v_max_f32_e32 v117, v252, v113
	v_min_f32_e32 v113, v252, v113
	v_max_f32_e32 v116, v253, v106
	v_min_f32_e32 v106, v253, v106
	v_max_f32_e32 v4, v100, v101
	v_min_f32_e32 v101, v100, v101
	v_max_f32_e32 v107, v2, v0
	v_min_f32_e32 v0, v2, v0
	v_max_f32_e32 v18, v108, v125
	v_min_f32_e32 v125, v108, v125
	v_max_f32_e32 v122, v1, v117
	v_min_f32_e32 v117, v1, v117
	v_max_f32_e32 v20, v97, v113
	v_min_f32_e32 v113, v97, v113
	v_max_f32_e32 v16, v116, v4
	v_min_f32_e32 v4, v116, v4
	v_max_f32_e32 v17, v106, v101
	v_min_f32_e32 v101, v106, v101
	v_max_f32_e32 v19, v18, v0
	v_min_f32_e32 v0, v18, v0
	v_max_f32_e32 v127, v114, v125
	v_min_f32_e32 v125, v114, v125
	v_max_f32_e32 v32, v16, v109
	v_min_f32_e32 v109, v16, v109
	v_max_f32_e32 v33, v17, v4
	v_min_f32_e32 v4, v17, v4
	v_max_f32_e32 v34, v127, v122
	v_min_f32_e32 v122, v127, v122
	v_max_f32_e32 v35, v125, v117
	v_min_f32_e32 v117, v125, v117
	v_max_f32_e32 v36, v20, v32
	v_min_f32_e32 v32, v20, v32
	v_max_f32_e32 v37, v113, v109
	v_min_f32_e32 v109, v113, v109
	v_max_f32_e32 v39, v34, v0
	v_min_f32_e32 v0, v34, v0
	v_max_f32_e32 v41, v122, v35
	v_min_f32_e32 v35, v122, v35
	v_max_f32_e32 v24, v36, v117
	v_min_f32_e32 v117, v36, v117
	v_max_f32_e32 v26, v32, v37
	v_min_f32_e32 v37, v32, v37
	v_max_f32_e32 v27, v33, v109
	v_min_f32_e32 v109, v33, v109
	v_max_f32_e32 v255, v35, v24
	v_min_f32_e32 v24, v35, v24
	v_max_f32_e32 v38, v117, v26
	v_min_f32_e32 v26, v117, v26
	v_max_f32_e32 v40, v48, v61
	v_min_f32_e32 v61, v48, v61
	v_max_f32_e32 v42, v49, v60
	v_min_f32_e32 v60, v49, v60
	v_max_f32_e32 v43, v50, v63
	v_min_f32_e32 v63, v50, v63
	v_max_f32_e32 v149, v51, v62
	v_min_f32_e32 v62, v51, v62
	v_max_f32_e32 v30, v52, v56
	v_min_f32_e32 v56, v52, v56
	v_max_f32_e32 v14, v53, v54
	v_min_f32_e32 v54, v53, v54
	v_max_f32_e32 v12, v55, v59
	v_min_f32_e32 v59, v55, v59
	v_max_f32_e32 v250, v57, v58
	v_min_f32_e32 v58, v57, v58
	v_max_f32_e32 v148, v40, v14
	v_min_f32_e32 v14, v40, v14
	v_max_f32_e32 v44, v42, v12
	v_min_f32_e32 v12, v42, v12
	v_max_f32_e32 v46, v43, v250
	v_min_f32_e32 v250, v43, v250
	v_max_f32_e32 v99, v149, v30
	v_min_f32_e32 v30, v149, v30
	v_max_f32_e32 v28, v54, v61
	v_min_f32_e32 v61, v54, v61
	v_max_f32_e32 v29, v56, v62
	v_min_f32_e32 v62, v56, v62
	v_max_f32_e32 v251, v58, v63
	v_min_f32_e32 v63, v58, v63
	v_max_f32_e32 v112, v59, v60
	v_min_f32_e32 v60, v59, v60
	v_max_f32_e32 v13, v148, v44
	v_min_f32_e32 v44, v148, v44
	v_max_f32_e32 v98, v46, v99
	v_min_f32_e32 v99, v46, v99
	v_max_f32_e32 v45, v30, v14
	v_min_f32_e32 v14, v30, v14
	v_max_f32_e32 v96, v28, v29
	v_min_f32_e32 v29, v28, v29
	v_max_f32_e32 v254, v12, v250
	v_min_f32_e32 v250, v12, v250
	v_max_f32_e32 v121, v251, v112
	v_min_f32_e32 v112, v251, v112
	v_max_f32_e32 v103, v60, v61
	v_min_f32_e32 v61, v60, v61
	v_max_f32_e32 v252, v62, v63
	v_min_f32_e32 v63, v62, v63
	v_max_f32_e32 v253, v13, v98
	v_min_f32_e32 v98, v13, v98
	v_max_f32_e32 v100, v44, v99
	v_min_f32_e32 v99, v44, v99
	v_max_f32_e32 v2, v45, v121
	v_min_f32_e32 v121, v45, v121
	v_max_f32_e32 v108, v14, v112
	v_min_f32_e32 v112, v14, v112
	v_max_f32_e32 v1, v96, v254
	v_min_f32_e32 v254, v96, v254
	v_max_f32_e32 v97, v29, v250
	v_min_f32_e32 v250, v29, v250
	v_max_f32_e32 v116, v103, v252
	v_min_f32_e32 v252, v103, v252
	v_max_f32_e32 v106, v61, v63
	v_min_f32_e32 v63, v61, v63
	v_max_f32_e32 v18, v100, v98
	v_min_f32_e32 v98, v100, v98
	v_max_f32_e32 v114, v99, v116
	v_min_f32_e32 v116, v99, v116
	v_max_f32_e32 v16, v2, v1
	v_min_f32_e32 v1, v2, v1
	v_max_f32_e32 v17, v108, v254
	v_min_f32_e32 v254, v108, v254
	v_max_f32_e32 v127, v97, v121
	v_min_f32_e32 v121, v97, v121
	v_max_f32_e32 v125, v250, v112
	v_min_f32_e32 v112, v250, v112
	v_max_f32_e32 v20, v106, v252
	v_min_f32_e32 v252, v106, v252
	v_max_f32_e32 v113, v18, v16
	v_min_f32_e32 v16, v18, v16
	v_max_f32_e32 v34, v98, v1
	v_min_f32_e32 v1, v98, v1
	v_max_f32_e32 v122, v17, v127
	v_min_f32_e32 v127, v17, v127
	v_max_f32_e32 v36, v254, v121
	v_min_f32_e32 v121, v254, v121
	v_max_f32_e32 v32, v125, v20
	v_min_f32_e32 v20, v125, v20
	v_max_f32_e32 v33, v112, v252
	v_min_f32_e32 v252, v112, v252
	v_max_f32_e32 v35, v34, v16
	v_min_f32_e32 v16, v34, v16
	v_max_f32_e32 v117, v114, v1
	v_min_f32_e32 v1, v114, v1
	v_max_f32_e32 v48, v32, v116
	v_min_f32_e32 v116, v32, v116
	v_max_f32_e32 v49, v33, v20
	v_min_f32_e32 v20, v33, v20
	v_max_f32_e32 v50, v117, v122
	v_min_f32_e32 v122, v117, v122
	v_max_f32_e32 v51, v1, v127
	v_min_f32_e32 v127, v1, v127
	v_max_f32_e32 v52, v36, v48
	v_min_f32_e32 v48, v36, v48
	v_max_f32_e32 v53, v121, v116
	v_min_f32_e32 v116, v121, v116
	v_max_f32_e32 v55, v50, v16
	v_min_f32_e32 v16, v50, v16
	v_max_f32_e32 v57, v122, v51
	v_min_f32_e32 v51, v122, v51
	v_max_f32_e32 v40, v52, v127
	v_min_f32_e32 v127, v52, v127
	v_max_f32_e32 v42, v48, v53
	v_min_f32_e32 v53, v48, v53
	v_max_f32_e32 v43, v49, v116
	v_min_f32_e32 v116, v49, v116
	v_max_f32_e32 v149, v51, v40
	v_min_f32_e32 v40, v51, v40
	v_max_f32_e32 v54, v127, v42
	v_min_f32_e32 v42, v127, v42
	s_waitcnt vmcnt(0)
	v_pk_mul_f32 v[160:161], v[160:161], v[176:177]
	v_pk_mul_f32 v[162:163], v[162:163], v[178:179]
	v_pk_mul_f32 v[164:165], v[164:165], v[180:181]
	v_pk_mul_f32 v[166:167], v[166:167], v[182:183]
	v_pk_mul_f32 v[168:169], v[168:169], v[184:185]
	v_pk_mul_f32 v[170:171], v[170:171], v[186:187]
	v_pk_mul_f32 v[172:173], v[172:173], v[188:189]
	v_pk_mul_f32 v[174:175], v[174:175], v[190:191]
	v_max3_f32 v192, |v160|, |v161|, |v162|
	v_max3_f32 v192, |v163|, |v164|, v192
	v_max3_f32 v192, |v165|, |v166|, v192
	v_max3_f32 v192, |v167|, |v168|, v192
	v_max3_f32 v192, |v169|, |v170|, v192
	v_max3_f32 v192, |v171|, |v172|, v192
	v_max3_f32 v192, |v173|, |v174|, v192
	v_max_f32_e64 v192, |v175|, v192
	s_nop 1
	v_mov_b32_dpp v193, v192 quad_perm:[1,0,3,2] row_mask:0xf bank_mask:0xf bound_ctrl:1
	v_max_f32_e32 v192, v192, v193
	s_nop 1
	v_mov_b32_dpp v193, v192 quad_perm:[2,3,0,1] row_mask:0xf bank_mask:0xf bound_ctrl:1
	v_max_f32_e32 v192, v192, v193
	s_nop 1
	v_mov_b32_dpp v193, v192 row_half_mirror row_mask:0xf bank_mask:0xf bound_ctrl:1
	v_max_f32_e32 v192, v192, v193
	s_nop 1
	v_mov_b32_dpp v193, v192 row_mirror row_mask:0xf bank_mask:0xf bound_ctrl:1
	v_max_f32_e32 v192, v192, v193
	v_mov_b32_e32 v193, v192
	s_nop 1
	v_permlane16_swap_b32_e32 v192, v193
	s_nop 1
	v_max_f32_e32 v192, v192, v193
	v_mov_b32_e32 v193, v192
	s_nop 1
	v_permlane32_swap_b32_e32 v192, v193
	s_nop 1
	v_max_f32_e32 v192, v192, v193
	v_max_f32_e32 v192, 0xda24260, v192
	v_mul_f32_e32 v194, 0x3e2aaaab, v192
	global_store_dword v214, v194, s[12:13]
	v_div_scale_f32 v195, s[26:27], v194, v194, 1.0
	v_rcp_f32_e32 v196, v195
	v_div_scale_f32 v204, vcc, 1.0, v194, 1.0
	v_fma_f32 v205, -v195, v196, 1.0
	v_fmac_f32_e32 v196, v205, v196
	v_mul_f32_e32 v205, v204, v196
	v_fma_f32 v206, -v195, v205, v204
	v_fmac_f32_e32 v205, v206, v196
	v_fma_f32 v195, -v195, v205, v204
	s_nop 0
	v_div_fmas_f32 v195, v195, v196, v205
	v_div_fixup_f32 v207, v195, v194, 1.0
	v_mul_f32_e32 v160, v207, v160
	v_mul_f32_e32 v161, v207, v161
	v_mul_f32_e32 v162, v207, v162
	v_mul_f32_e32 v163, v207, v163
	v_mul_f32_e32 v164, v207, v164
	v_mul_f32_e32 v165, v207, v165
	v_mul_f32_e32 v166, v207, v166
	v_mul_f32_e32 v167, v207, v167
	v_mul_f32_e32 v168, v207, v168
	v_mul_f32_e32 v169, v207, v169
	v_mul_f32_e32 v170, v207, v170
	v_mul_f32_e32 v171, v207, v171
	v_mul_f32_e32 v172, v207, v172
	v_mul_f32_e32 v173, v207, v173
	v_mul_f32_e32 v174, v207, v174
	v_mul_f32_e32 v175, v207, v175
	v_mov_b32_e32 v208, 0
	v_mov_b32_e32 v209, 0
	v_mov_b32_e32 v210, 0
	v_mov_b32_e32 v193, 0
	v_cvt_scalef32_pk_fp4_f32 v208, v160, v161, 1.0
	v_cvt_scalef32_pk_fp4_f32 v209, v164, v165, 1.0
	v_cvt_scalef32_pk_fp4_f32 v210, v168, v169, 1.0
	v_cvt_scalef32_pk_fp4_f32 v193, v172, v173, 1.0
	v_cvt_scalef32_pk_fp4_f32 v208, v162, v163, 1.0 op_sel:[0,0,1,0]
	v_cvt_scalef32_pk_fp4_f32 v209, v166, v167, 1.0 op_sel:[0,0,1,0]
	v_cvt_scalef32_pk_fp4_f32 v210, v170, v171, 1.0 op_sel:[0,0,1,0]
	v_cvt_scalef32_pk_fp4_f32 v193, v174, v175, 1.0 op_sel:[0,0,1,0]
	global_store_short v213, v208, s[10:11] nt
	s_add_u32 s14, s10, 0x200000
	s_addc_u32 s15, s11, 0
	global_store_short v213, v209, s[14:15] nt
	s_add_u32 s14, s10, 0x400000
	s_addc_u32 s15, s11, 0
	global_store_short v213, v210, s[14:15] nt
	s_add_u32 s14, s10, 0x600000
	s_addc_u32 s15, s11, 0
	global_store_short v213, v193, s[14:15] nt
	s_add_u32 s10, s10, 0x20000
	s_addc_u32 s11, s11, 0
	s_add_u32 s12, s12, 0x2000
	s_addc_u32 s13, s13, 0
	global_load_dwordx4 v[160:163], v212, s[8:9] offset:0 nt
	global_load_dwordx4 v[164:167], v212, s[8:9] offset:1024 nt
	global_load_dwordx4 v[168:171], v212, s[8:9] offset:2048 nt
	global_load_dwordx4 v[172:175], v212, s[8:9] offset:3072 nt
	s_add_u32 s8, s8, 0x800000
	s_addc_u32 s9, s9, 0
	v_max_f32_e32 v105, v105, v31
	v_max_f32_e32 v120, v120, v110
	v_max_f32_e32 v126, v126, v123
	v_max_f32_e32 v7, v7, v118
	v_max_f32_e32 v115, v115, v11
	v_max_f32_e32 v9, v9, v21
	v_max_f32_e32 v147, v147, v10
	v_max_f32_e32 v144, v144, v22
	v_max_f32_e32 v6, v6, v8
	v_max_f32_e32 v145, v145, v249
	v_max_f32_e32 v5, v5, v25
	v_max_f32_e32 v146, v146, v124
	v_max_f32_e32 v111, v111, v23
	v_max_f32_e32 v119, v119, v3
	v_max_f32_e32 v104, v104, v102
	v_max_f32_e32 v15, v15, v151
	v_max_f32_e32 v56, v105, v6
	v_min_f32_e32 v6, v105, v6
	v_max_f32_e32 v58, v120, v145
	v_min_f32_e32 v145, v120, v145
	v_max_f32_e32 v59, v126, v5
	v_min_f32_e32 v5, v126, v5
	v_max_f32_e32 v148, v7, v146
	v_min_f32_e32 v146, v7, v146
	v_max_f32_e32 v46, v115, v111
	v_min_f32_e32 v111, v115, v111
	v_max_f32_e32 v30, v9, v119
	v_min_f32_e32 v119, v9, v119
	v_max_f32_e32 v28, v147, v104
	v_min_f32_e32 v104, v147, v104
	v_max_f32_e32 v12, v144, v15
	v_min_f32_e32 v15, v144, v15
	v_max_f32_e32 v251, v56, v46
	v_min_f32_e32 v46, v56, v46
	v_max_f32_e32 v60, v58, v30
	v_min_f32_e32 v30, v58, v30
	v_max_f32_e32 v62, v59, v28
	v_min_f32_e32 v28, v59, v28
	v_max_f32_e32 v13, v148, v12
	v_min_f32_e32 v12, v148, v12
	v_max_f32_e32 v44, v6, v111
	v_min_f32_e32 v111, v6, v111
	v_max_f32_e32 v45, v145, v119
	v_min_f32_e32 v119, v145, v119
	v_max_f32_e32 v14, v5, v104
	v_min_f32_e32 v104, v5, v104
	v_max_f32_e32 v96, v146, v15
	v_min_f32_e32 v15, v146, v15
	v_max_f32_e32 v29, v251, v62
	v_min_f32_e32 v62, v251, v62
	v_max_f32_e32 v103, v60, v13
	v_min_f32_e32 v13, v60, v13
	v_max_f32_e32 v61, v46, v28
	v_min_f32_e32 v28, v46, v28
	v_max_f32_e32 v100, v30, v12
	v_min_f32_e32 v12, v30, v12
	v_max_f32_e32 v99, v44, v14
	v_min_f32_e32 v14, v44, v14
	v_max_f32_e32 v2, v45, v96
	v_min_f32_e32 v96, v45, v96
	v_max_f32_e32 v108, v111, v104
	v_min_f32_e32 v104, v111, v104
	v_max_f32_e32 v97, v119, v15
	v_min_f32_e32 v15, v119, v15
	v_max_f32_e32 v250, v29, v103
	v_min_f32_e32 v103, v29, v103
	v_max_f32_e32 v106, v62, v13
	v_min_f32_e32 v13, v62, v13
	v_max_f32_e32 v18, v61, v100
	v_min_f32_e32 v100, v61, v100
	v_max_f32_e32 v98, v28, v12
	v_min_f32_e32 v12, v28, v12
	v_max_f32_e32 v17, v99, v2
	v_min_f32_e32 v2, v99, v2
	v_max_f32_e32 v254, v14, v96
	v_min_f32_e32 v96, v14, v96
	v_max_f32_e32 v125, v108, v97
	v_min_f32_e32 v97, v108, v97
	v_max_f32_e32 v112, v104, v15
	v_min_f32_e32 v15, v104, v15
	v_max_f32_e32 v150, v150, v63
	v_max_f32_e32 v107, v107, v252
	v_max_f32_e32 v19, v19, v20
	v_max_f32_e32 v39, v39, v116
	v_max_f32_e32 v0, v0, v43
	v_max_f32_e32 v41, v41, v53
	v_max_f32_e32 v255, v255, v42
	v_max_f32_e32 v24, v24, v54
	v_max_f32_e32 v38, v38, v40
	v_max_f32_e32 v26, v26, v149
	v_max_f32_e32 v37, v37, v57
	v_max_f32_e32 v27, v27, v16
	v_max_f32_e32 v109, v109, v55
	v_max_f32_e32 v4, v4, v35
	v_max_f32_e32 v101, v101, v113
	v_max_f32_e32 v47, v47, v253
	v_max_f32_e32 v34, v150, v38
	v_min_f32_e32 v38, v150, v38
	v_max_f32_e32 v114, v107, v26
	v_min_f32_e32 v26, v107, v26
	v_max_f32_e32 v32, v19, v37
	v_min_f32_e32 v37, v19, v37
	v_max_f32_e32 v33, v39, v27
	v_min_f32_e32 v27, v39, v27
	v_max_f32_e32 v117, v0, v109
	v_min_f32_e32 v109, v0, v109
	v_max_f32_e32 v1, v41, v4
	v_min_f32_e32 v4, v41, v4
	v_max_f32_e32 v36, v255, v101
	v_min_f32_e32 v101, v255, v101
	v_max_f32_e32 v121, v24, v47
	v_min_f32_e32 v47, v24, v47
	v_max_f32_e32 v50, v34, v117
	v_min_f32_e32 v117, v34, v117
	v_max_f32_e32 v122, v114, v1
	v_min_f32_e32 v1, v114, v1
	v_max_f32_e32 v52, v32, v36
	v_min_f32_e32 v36, v32, v36
	v_max_f32_e32 v48, v33, v121
	v_min_f32_e32 v121, v33, v121
	v_max_f32_e32 v49, v38, v109
	v_min_f32_e32 v109, v38, v109
	v_max_f32_e32 v51, v26, v4
	v_min_f32_e32 v4, v26, v4
	v_max_f32_e32 v127, v37, v101
	v_min_f32_e32 v101, v37, v101
	v_max_f32_e32 v151, v27, v47
	v_min_f32_e32 v47, v27, v47
	v_max_f32_e32 v102, v50, v52
	v_min_f32_e32 v52, v50, v52
	v_max_f32_e32 v3, v122, v48
	v_min_f32_e32 v48, v122, v48
	v_max_f32_e32 v23, v117, v36
	v_min_f32_e32 v36, v117, v36
	v_max_f32_e32 v124, v1, v121
	v_min_f32_e32 v121, v1, v121
	v_max_f32_e32 v25, v49, v127
	v_min_f32_e32 v127, v49, v127
	v_max_f32_e32 v249, v51, v151
	v_min_f32_e32 v151, v51, v151
	v_max_f32_e32 v8, v109, v101
	v_min_f32_e32 v101, v109, v101
	v_max_f32_e32 v22, v4, v47
	v_min_f32_e32 v47, v4, v47
	v_max_f32_e32 v10, v102, v3
	v_min_f32_e32 v3, v102, v3
	v_max_f32_e32 v21, v52, v48
	v_min_f32_e32 v48, v52, v48
	v_max_f32_e32 v11, v23, v124
	v_min_f32_e32 v124, v23, v124
	v_max_f32_e32 v118, v36, v121
	v_min_f32_e32 v121, v36, v121
	v_max_f32_e32 v123, v25, v249
	v_min_f32_e32 v249, v25, v249
	v_max_f32_e32 v110, v127, v151
	v_min_f32_e32 v151, v127, v151
	v_max_f32_e32 v31, v8, v22
	v_min_f32_e32 v22, v8, v22
	v_max_f32_e32 v105, v101, v47
	v_min_f32_e32 v47, v101, v47
	v_max_f32_e32 v250, v250, v47
	v_max_f32_e32 v103, v103, v105
	v_max_f32_e32 v106, v106, v22
	v_max_f32_e32 v13, v13, v31
	v_max_f32_e32 v18, v18, v151
	v_max_f32_e32 v100, v100, v110
	v_max_f32_e32 v98, v98, v249
	v_max_f32_e32 v12, v12, v123
	v_max_f32_e32 v17, v17, v121
	v_max_f32_e32 v2, v2, v118
	v_max_f32_e32 v254, v254, v124
	v_max_f32_e32 v96, v96, v11
	v_max_f32_e32 v125, v125, v48
	v_max_f32_e32 v97, v97, v21
	v_max_f32_e32 v112, v112, v3
	v_max_f32_e32 v15, v15, v10
	v_max_f32_e32 v120, v250, v17
	v_min_f32_e32 v17, v250, v17
	v_max_f32_e32 v126, v103, v2
	v_min_f32_e32 v2, v103, v2
	v_max_f32_e32 v7, v106, v254
	v_min_f32_e32 v254, v106, v254
	v_max_f32_e32 v115, v13, v96
	v_min_f32_e32 v96, v13, v96
	v_max_f32_e32 v9, v18, v125
	v_min_f32_e32 v125, v18, v125
	v_max_f32_e32 v147, v100, v97
	v_min_f32_e32 v97, v100, v97
	v_max_f32_e32 v144, v98, v112
	v_min_f32_e32 v112, v98, v112
	v_max_f32_e32 v56, v12, v15
	v_min_f32_e32 v15, v12, v15
	v_max_f32_e32 v58, v120, v9
	v_min_f32_e32 v9, v120, v9
	v_max_f32_e32 v59, v126, v147
	v_min_f32_e32 v147, v126, v147
	v_max_f32_e32 v148, v7, v144
	v_min_f32_e32 v144, v7, v144
	v_max_f32_e32 v6, v115, v56
	v_min_f32_e32 v56, v115, v56
	v_max_f32_e32 v145, v17, v125
	v_min_f32_e32 v125, v17, v125
	v_max_f32_e32 v5, v2, v97
	v_min_f32_e32 v97, v2, v97
	v_max_f32_e32 v146, v254, v112
	v_min_f32_e32 v112, v254, v112
	v_max_f32_e32 v251, v96, v15
	v_min_f32_e32 v15, v96, v15
	v_max_f32_e32 v60, v58, v148
	v_min_f32_e32 v148, v58, v148
	v_max_f32_e32 v46, v59, v6
	v_min_f32_e32 v6, v59, v6
	v_max_f32_e32 v30, v9, v144
	v_min_f32_e32 v144, v9, v144
	v_max_f32_e32 v44, v147, v56
	v_min_f32_e32 v56, v147, v56
	v_max_f32_e32 v45, v145, v146
	v_min_f32_e32 v146, v145, v146
	v_max_f32_e32 v111, v5, v251
	v_min_f32_e32 v251, v5, v251
	v_max_f32_e32 v119, v125, v112
	v_min_f32_e32 v112, v125, v112
	v_max_f32_e32 v29, v97, v15
	v_min_f32_e32 v15, v97, v15
	v_max_f32_e32 v62, v60, v46
	v_min_f32_e32 v46, v60, v46
	v_max_f32_e32 v61, v148, v6
	v_min_f32_e32 v6, v148, v6
	v_max_f32_e32 v28, v30, v44
	v_min_f32_e32 v44, v30, v44
	v_max_f32_e32 v99, v144, v56
	v_min_f32_e32 v56, v144, v56
	v_max_f32_e32 v14, v45, v111
	v_min_f32_e32 v111, v45, v111
	v_max_f32_e32 v108, v146, v251
	v_min_f32_e32 v251, v146, v251
	v_max_f32_e32 v104, v119, v29
	v_min_f32_e32 v29, v119, v29
	v_max_f32_e32 v253, v112, v15
	v_min_f32_e32 v15, v112, v15
	v_mov_b32_e32 v113, v62
	v_mov_b32_e32 v35, v46
	v_mov_b32_e32 v55, v61
	v_mov_b32_e32 v16, v6
	v_mov_b32_e32 v57, v28
	v_mov_b32_e32 v149, v44
	v_mov_b32_e32 v40, v99
	v_mov_b32_e32 v54, v56
	v_mov_b32_e32 v42, v14
	v_mov_b32_e32 v53, v111
	v_mov_b32_e32 v43, v108
	v_mov_b32_e32 v116, v251
	v_mov_b32_e32 v20, v104
	v_mov_b32_e32 v252, v29
	v_mov_b32_e32 v63, v253
	v_mov_b32_e32 v150, v15
	s_nop 1
	v_permlane32_swap_b32_e32 v62, v113
	v_permlane32_swap_b32_e32 v46, v35
	v_permlane32_swap_b32_e32 v61, v55
	v_permlane32_swap_b32_e32 v6, v16
	v_permlane32_swap_b32_e32 v28, v57
	v_permlane32_swap_b32_e32 v44, v149
	v_permlane32_swap_b32_e32 v99, v40
	v_permlane32_swap_b32_e32 v56, v54
	v_permlane32_swap_b32_e32 v14, v42
	v_permlane32_swap_b32_e32 v111, v53
	v_permlane32_swap_b32_e32 v108, v43
	v_permlane32_swap_b32_e32 v251, v116
	v_permlane32_swap_b32_e32 v104, v20
	v_permlane32_swap_b32_e32 v29, v252
	v_permlane32_swap_b32_e32 v253, v63
	v_permlane32_swap_b32_e32 v15, v150
	s_nop 1
	v_max_f32_e32 v62, v62, v150
	v_max_f32_e32 v46, v46, v63
	v_max_f32_e32 v61, v61, v252
	v_max_f32_e32 v6, v6, v20
	v_max_f32_e32 v28, v28, v116
	v_max_f32_e32 v44, v44, v43
	v_max_f32_e32 v99, v99, v53
	v_max_f32_e32 v56, v56, v42
	v_max_f32_e32 v14, v14, v54
	v_max_f32_e32 v111, v111, v40
	v_max_f32_e32 v108, v108, v149
	v_max_f32_e32 v251, v251, v57
	v_max_f32_e32 v104, v104, v16
	v_max_f32_e32 v29, v29, v55
	v_max_f32_e32 v253, v253, v35
	v_max_f32_e32 v15, v15, v113
	v_max_f32_e32 v107, v62, v14
	v_min_f32_e32 v14, v62, v14
	v_max_f32_e32 v19, v46, v111
	v_min_f32_e32 v111, v46, v111
	v_max_f32_e32 v39, v61, v108
	v_min_f32_e32 v108, v61, v108
	v_max_f32_e32 v0, v6, v251
	v_min_f32_e32 v251, v6, v251
	v_max_f32_e32 v41, v28, v104
	v_min_f32_e32 v104, v28, v104
	v_max_f32_e32 v255, v44, v29
	v_min_f32_e32 v29, v44, v29
	v_max_f32_e32 v24, v99, v253
	v_min_f32_e32 v253, v99, v253
	v_max_f32_e32 v34, v56, v15
	v_min_f32_e32 v15, v56, v15
	v_max_f32_e32 v114, v107, v41
	v_min_f32_e32 v41, v107, v41
	v_max_f32_e32 v32, v19, v255
	v_min_f32_e32 v255, v19, v255
	v_max_f32_e32 v33, v39, v24
	v_min_f32_e32 v24, v39, v24
	v_max_f32_e32 v38, v0, v34
	v_min_f32_e32 v34, v0, v34
	v_max_f32_e32 v26, v14, v104
	v_min_f32_e32 v104, v14, v104
	v_max_f32_e32 v37, v111, v29
	v_min_f32_e32 v29, v111, v29
	v_max_f32_e32 v27, v108, v253
	v_min_f32_e32 v253, v108, v253
	v_max_f32_e32 v50, v251, v15
	v_min_f32_e32 v15, v251, v15
	v_max_f32_e32 v122, v114, v33
	v_min_f32_e32 v33, v114, v33
	v_max_f32_e32 v117, v32, v38
	v_min_f32_e32 v38, v32, v38
	v_max_f32_e32 v1, v41, v24
	v_min_f32_e32 v24, v41, v24
	v_max_f32_e32 v49, v255, v34
	v_min_f32_e32 v34, v255, v34
	v_max_f32_e32 v51, v26, v27
	v_min_f32_e32 v27, v26, v27
	v_max_f32_e32 v109, v37, v50
	v_min_f32_e32 v50, v37, v50
	v_max_f32_e32 v4, v104, v253
	v_min_f32_e32 v253, v104, v253
	v_max_f32_e32 v102, v29, v15
	v_min_f32_e32 v15, v29, v15
	v_max_f32_e32 v128, v122, v117
	v_min_f32_e32 v129, v122, v117
	v_max_f32_e32 v130, v33, v38
	v_min_f32_e32 v131, v33, v38
	v_max_f32_e32 v132, v1, v49
	v_min_f32_e32 v133, v1, v49
	v_max_f32_e32 v134, v24, v34
	v_min_f32_e32 v135, v24, v34
	v_max_f32_e32 v136, v51, v109
	v_min_f32_e32 v137, v51, v109
	v_max_f32_e32 v138, v27, v50
	v_min_f32_e32 v139, v27, v50
	v_max_f32_e32 v140, v4, v102
	v_min_f32_e32 v141, v4, v102
	v_max_f32_e32 v142, v253, v15
	v_min_f32_e32 v143, v253, v15
	s_waitcnt vmcnt(0)
	v_pk_mul_f32 v[160:161], v[160:161], v[176:177]
	v_pk_mul_f32 v[162:163], v[162:163], v[178:179]
	v_pk_mul_f32 v[164:165], v[164:165], v[180:181]
	v_pk_mul_f32 v[166:167], v[166:167], v[182:183]
	v_pk_mul_f32 v[168:169], v[168:169], v[184:185]
	v_pk_mul_f32 v[170:171], v[170:171], v[186:187]
	v_pk_mul_f32 v[172:173], v[172:173], v[188:189]
	v_pk_mul_f32 v[174:175], v[174:175], v[190:191]
	v_max3_f32 v192, |v160|, |v161|, |v162|
	v_max3_f32 v192, |v163|, |v164|, v192
	v_max3_f32 v192, |v165|, |v166|, v192
	v_max3_f32 v192, |v167|, |v168|, v192
	v_max3_f32 v192, |v169|, |v170|, v192
	v_max3_f32 v192, |v171|, |v172|, v192
	v_max3_f32 v192, |v173|, |v174|, v192
	v_max_f32_e64 v192, |v175|, v192
	s_nop 1
	v_mov_b32_dpp v193, v192 quad_perm:[1,0,3,2] row_mask:0xf bank_mask:0xf bound_ctrl:1
	v_max_f32_e32 v192, v192, v193
	s_nop 1
	v_mov_b32_dpp v193, v192 quad_perm:[2,3,0,1] row_mask:0xf bank_mask:0xf bound_ctrl:1
	v_max_f32_e32 v192, v192, v193
	s_nop 1
	v_mov_b32_dpp v193, v192 row_half_mirror row_mask:0xf bank_mask:0xf bound_ctrl:1
	v_max_f32_e32 v192, v192, v193
	s_nop 1
	v_mov_b32_dpp v193, v192 row_mirror row_mask:0xf bank_mask:0xf bound_ctrl:1
	v_max_f32_e32 v192, v192, v193
	v_mov_b32_e32 v193, v192
	s_nop 1
	v_permlane16_swap_b32_e32 v192, v193
	s_nop 1
	v_max_f32_e32 v192, v192, v193
	v_mov_b32_e32 v193, v192
	s_nop 1
	v_permlane32_swap_b32_e32 v192, v193
	s_nop 1
	v_max_f32_e32 v192, v192, v193
	v_max_f32_e32 v192, 0xda24260, v192
	v_mul_f32_e32 v194, 0x3e2aaaab, v192
	global_store_dword v214, v194, s[12:13]
	v_div_scale_f32 v195, s[26:27], v194, v194, 1.0
	v_rcp_f32_e32 v196, v195
	v_div_scale_f32 v204, vcc, 1.0, v194, 1.0
	v_fma_f32 v205, -v195, v196, 1.0
	v_fmac_f32_e32 v196, v205, v196
	v_mul_f32_e32 v205, v204, v196
	v_fma_f32 v206, -v195, v205, v204
	v_fmac_f32_e32 v205, v206, v196
	v_fma_f32 v195, -v195, v205, v204
	s_nop 0
	v_div_fmas_f32 v195, v195, v196, v205
	v_div_fixup_f32 v207, v195, v194, 1.0
	v_mul_f32_e32 v160, v207, v160
	v_mul_f32_e32 v161, v207, v161
	v_mul_f32_e32 v162, v207, v162
	v_mul_f32_e32 v163, v207, v163
	v_mul_f32_e32 v164, v207, v164
	v_mul_f32_e32 v165, v207, v165
	v_mul_f32_e32 v166, v207, v166
	v_mul_f32_e32 v167, v207, v167
	v_mul_f32_e32 v168, v207, v168
	v_mul_f32_e32 v169, v207, v169
	v_mul_f32_e32 v170, v207, v170
	v_mul_f32_e32 v171, v207, v171
	v_mul_f32_e32 v172, v207, v172
	v_mul_f32_e32 v173, v207, v173
	v_mul_f32_e32 v174, v207, v174
	v_mul_f32_e32 v175, v207, v175
	v_mov_b32_e32 v208, 0
	v_mov_b32_e32 v209, 0
	v_mov_b32_e32 v210, 0
	v_mov_b32_e32 v193, 0
	v_cvt_scalef32_pk_fp4_f32 v208, v160, v161, 1.0
	v_cvt_scalef32_pk_fp4_f32 v209, v164, v165, 1.0
	v_cvt_scalef32_pk_fp4_f32 v210, v168, v169, 1.0
	v_cvt_scalef32_pk_fp4_f32 v193, v172, v173, 1.0
	v_cvt_scalef32_pk_fp4_f32 v208, v162, v163, 1.0 op_sel:[0,0,1,0]
	v_cvt_scalef32_pk_fp4_f32 v209, v166, v167, 1.0 op_sel:[0,0,1,0]
	v_cvt_scalef32_pk_fp4_f32 v210, v170, v171, 1.0 op_sel:[0,0,1,0]
	v_cvt_scalef32_pk_fp4_f32 v193, v174, v175, 1.0 op_sel:[0,0,1,0]
	global_store_short v213, v208, s[10:11] nt
	s_add_u32 s14, s10, 0x200000
	s_addc_u32 s15, s11, 0
	global_store_short v213, v209, s[14:15] nt
	s_add_u32 s14, s10, 0x400000
	s_addc_u32 s15, s11, 0
	global_store_short v213, v210, s[14:15] nt
	s_add_u32 s14, s10, 0x600000
	s_addc_u32 s15, s11, 0
	global_store_short v213, v193, s[14:15] nt
	s_add_u32 s10, s10, 0x20000
	s_addc_u32 s11, s11, 0
	s_add_u32 s12, s12, 0x2000
	s_addc_u32 s13, s13, 0
	global_load_dwordx4 v[160:163], v212, s[8:9] offset:0 nt
	global_load_dwordx4 v[164:167], v212, s[8:9] offset:1024 nt
	global_load_dwordx4 v[168:171], v212, s[8:9] offset:2048 nt
	global_load_dwordx4 v[172:175], v212, s[8:9] offset:3072 nt
	s_add_u32 s8, s8, 0x800000
	s_addc_u32 s9, s9, 0
	ds_write_b8 v240, v128 offset:0
	ds_write_b8 v240, v129 offset:1
	ds_write_b8 v240, v130 offset:2
	ds_write_b8 v240, v131 offset:3
	ds_write_b8 v240, v132 offset:4
	ds_write_b8 v240, v133 offset:5
	ds_write_b8 v240, v134 offset:6
	ds_write_b8 v240, v135 offset:7
	ds_write_b8 v240, v136 offset:8
	ds_write_b8 v240, v137 offset:9
	ds_write_b8 v240, v138 offset:10
	ds_write_b8 v240, v139 offset:11
	ds_write_b8 v240, v140 offset:12
	ds_write_b8 v240, v141 offset:13
	ds_write_b8 v240, v142 offset:14
	ds_write_b8 v240, v143 offset:15
	ds_read_b128 v[96:99], v231 offset:32768
	ds_read_b128 v[100:103], v232 offset:32768
	ds_read_b128 v[104:107], v233 offset:32768
	ds_read_b128 v[108:111], v234 offset:32768
	ds_read_b128 v[112:115], v235 offset:32768
	ds_read_b128 v[116:119], v236 offset:32768
	ds_read_b128 v[120:123], v237 offset:32768
	ds_read_b128 v[124:127], v238 offset:32768
	s_waitcnt vmcnt(0)
	s_waitcnt lgkmcnt(4)
	v_mfma_f32_32x32x16_bf16 v[0:15], v[96:99], v[64:67], 0
	v_mfma_f32_32x32x16_bf16 v[0:15], v[100:103], v[68:71], v[0:15]
	v_mfma_f32_32x32x16_bf16 v[0:15], v[104:107], v[72:75], v[0:15]
	v_mfma_f32_32x32x16_bf16 v[0:15], v[108:111], v[76:79], v[0:15]
	ds_read_b128 v[96:99], v231 offset:40960
	ds_read_b128 v[100:103], v232 offset:40960
	ds_read_b128 v[104:107], v233 offset:40960
	ds_read_b128 v[108:111], v234 offset:40960
	s_waitcnt lgkmcnt(4)
	v_mfma_f32_32x32x16_bf16 v[0:15], v[112:115], v[80:83], v[0:15]
	v_mfma_f32_32x32x16_bf16 v[0:15], v[116:119], v[84:87], v[0:15]
	v_mfma_f32_32x32x16_bf16 v[0:15], v[120:123], v[88:91], v[0:15]
	v_mfma_f32_32x32x16_bf16 v[0:15], v[124:127], v[92:95], v[0:15]
	ds_read_b128 v[112:115], v235 offset:40960
	ds_read_b128 v[116:119], v236 offset:40960
	ds_read_b128 v[120:123], v237 offset:40960
	ds_read_b128 v[124:127], v238 offset:40960
	s_waitcnt lgkmcnt(4)
	v_mfma_f32_32x32x16_bf16 v[16:31], v[96:99], v[64:67], 0
	v_mfma_f32_32x32x16_bf16 v[16:31], v[100:103], v[68:71], v[16:31]
	v_mfma_f32_32x32x16_bf16 v[16:31], v[104:107], v[72:75], v[16:31]
	v_mfma_f32_32x32x16_bf16 v[16:31], v[108:111], v[76:79], v[16:31]
	ds_read_b128 v[96:99], v231 offset:49152
	ds_read_b128 v[100:103], v232 offset:49152
	ds_read_b128 v[104:107], v233 offset:49152
	ds_read_b128 v[108:111], v234 offset:49152
	s_waitcnt lgkmcnt(4)
	v_mfma_f32_32x32x16_bf16 v[16:31], v[112:115], v[80:83], v[16:31]
	v_mfma_f32_32x32x16_bf16 v[16:31], v[116:119], v[84:87], v[16:31]
	v_mfma_f32_32x32x16_bf16 v[16:31], v[120:123], v[88:91], v[16:31]
	v_mfma_f32_32x32x16_bf16 v[16:31], v[124:127], v[92:95], v[16:31]
	ds_read_b128 v[112:115], v235 offset:49152
	ds_read_b128 v[116:119], v236 offset:49152
	ds_read_b128 v[120:123], v237 offset:49152
	ds_read_b128 v[124:127], v238 offset:49152
	s_waitcnt lgkmcnt(4)
	v_mfma_f32_32x32x16_bf16 v[32:47], v[96:99], v[64:67], 0
	v_mfma_f32_32x32x16_bf16 v[32:47], v[100:103], v[68:71], v[32:47]
	v_mfma_f32_32x32x16_bf16 v[32:47], v[104:107], v[72:75], v[32:47]
	v_mfma_f32_32x32x16_bf16 v[32:47], v[108:111], v[76:79], v[32:47]
	ds_read_b128 v[96:99], v231 offset:57344
	ds_read_b128 v[100:103], v232 offset:57344
	ds_read_b128 v[104:107], v233 offset:57344
	ds_read_b128 v[108:111], v234 offset:57344
	s_waitcnt lgkmcnt(4)
	v_mfma_f32_32x32x16_bf16 v[32:47], v[112:115], v[80:83], v[32:47]
	v_mfma_f32_32x32x16_bf16 v[32:47], v[116:119], v[84:87], v[32:47]
	v_mfma_f32_32x32x16_bf16 v[32:47], v[120:123], v[88:91], v[32:47]
	v_mfma_f32_32x32x16_bf16 v[32:47], v[124:127], v[92:95], v[32:47]
	ds_read_b128 v[112:115], v235 offset:57344
	ds_read_b128 v[116:119], v236 offset:57344
	ds_read_b128 v[120:123], v237 offset:57344
	ds_read_b128 v[124:127], v238 offset:57344
	s_waitcnt lgkmcnt(4)
	v_mfma_f32_32x32x16_bf16 v[48:63], v[96:99], v[64:67], 0
	v_mfma_f32_32x32x16_bf16 v[48:63], v[100:103], v[68:71], v[48:63]
	v_mfma_f32_32x32x16_bf16 v[48:63], v[104:107], v[72:75], v[48:63]
	v_mfma_f32_32x32x16_bf16 v[48:63], v[108:111], v[76:79], v[48:63]
	s_waitcnt lgkmcnt(0)
	v_mfma_f32_32x32x16_bf16 v[48:63], v[112:115], v[80:83], v[48:63]
	v_mfma_f32_32x32x16_bf16 v[48:63], v[116:119], v[84:87], v[48:63]
	v_mfma_f32_32x32x16_bf16 v[48:63], v[120:123], v[88:91], v[48:63]
	v_mfma_f32_32x32x16_bf16 v[48:63], v[124:127], v[92:95], v[48:63]
	s_nop 11
	v_and_or_b32 v0, v0, s6, v211
	v_or_b32_e32 v0, 0x7b, v0
	v_and_or_b32 v1, v1, s6, v211
	v_or_b32_e32 v1, 0x7a, v1
	v_and_or_b32 v2, v2, s6, v211
	v_or_b32_e32 v2, 0x79, v2
	v_and_or_b32 v3, v3, s6, v211
	v_or_b32_e32 v3, 0x78, v3
	v_and_or_b32 v4, v4, s6, v211
	v_or_b32_e32 v4, 0x73, v4
	v_and_or_b32 v5, v5, s6, v211
	v_or_b32_e32 v5, 0x72, v5
	v_and_or_b32 v6, v6, s6, v211
	v_or_b32_e32 v6, 0x71, v6
	v_and_or_b32 v7, v7, s6, v211
	v_or_b32_e32 v7, 0x70, v7
	v_and_or_b32 v8, v8, s6, v211
	v_or_b32_e32 v8, 0x6b, v8
	v_and_or_b32 v9, v9, s6, v211
	v_or_b32_e32 v9, 0x6a, v9
	v_and_or_b32 v10, v10, s6, v211
	v_or_b32_e32 v10, 0x69, v10
	v_and_or_b32 v11, v11, s6, v211
	v_or_b32_e32 v11, 0x68, v11
	v_and_or_b32 v12, v12, s6, v211
	v_or_b32_e32 v12, 0x63, v12
	v_and_or_b32 v13, v13, s6, v211
	v_or_b32_e32 v13, 0x62, v13
	v_and_or_b32 v14, v14, s6, v211
	v_or_b32_e32 v14, 0x61, v14
	v_and_or_b32 v15, v15, s6, v211
	v_or_b32_e32 v15, 0x60, v15
	v_and_or_b32 v16, v16, s6, v211
	v_or_b32_e32 v16, 0x5b, v16
	v_and_or_b32 v17, v17, s6, v211
	v_or_b32_e32 v17, 0x5a, v17
	v_and_or_b32 v18, v18, s6, v211
	v_or_b32_e32 v18, 0x59, v18
	v_and_or_b32 v19, v19, s6, v211
	v_or_b32_e32 v19, 0x58, v19
	v_and_or_b32 v20, v20, s6, v211
	v_or_b32_e32 v20, 0x53, v20
	v_and_or_b32 v21, v21, s6, v211
	v_or_b32_e32 v21, 0x52, v21
	v_and_or_b32 v22, v22, s6, v211
	v_or_b32_e32 v22, 0x51, v22
	v_and_or_b32 v23, v23, s6, v211
	v_or_b32_e32 v23, 0x50, v23
	v_and_or_b32 v24, v24, s6, v211
	v_or_b32_e32 v24, 0x4b, v24
	v_and_or_b32 v25, v25, s6, v211
	v_or_b32_e32 v25, 0x4a, v25
	v_and_or_b32 v26, v26, s6, v211
	v_or_b32_e32 v26, 0x49, v26
	v_and_or_b32 v27, v27, s6, v211
	v_or_b32_e32 v27, 0x48, v27
	v_and_or_b32 v28, v28, s6, v211
	v_or_b32_e32 v28, 0x43, v28
	v_and_or_b32 v29, v29, s6, v211
	v_or_b32_e32 v29, 0x42, v29
	v_and_or_b32 v30, v30, s6, v211
	v_or_b32_e32 v30, 0x41, v30
	v_and_or_b32 v31, v31, s6, v211
	v_or_b32_e32 v31, 64, v31
	v_and_or_b32 v32, v32, s6, v211
	v_or_b32_e32 v32, 59, v32
	v_and_or_b32 v33, v33, s6, v211
	v_or_b32_e32 v33, 58, v33
	v_and_or_b32 v34, v34, s6, v211
	v_or_b32_e32 v34, 57, v34
	v_and_or_b32 v35, v35, s6, v211
	v_or_b32_e32 v35, 56, v35
	v_and_or_b32 v36, v36, s6, v211
	v_or_b32_e32 v36, 51, v36
	v_and_or_b32 v37, v37, s6, v211
	v_or_b32_e32 v37, 50, v37
	v_and_or_b32 v38, v38, s6, v211
	v_or_b32_e32 v38, 49, v38
	v_and_or_b32 v39, v39, s6, v211
	v_or_b32_e32 v39, 48, v39
	v_and_or_b32 v40, v40, s6, v211
	v_or_b32_e32 v40, 43, v40
	v_and_or_b32 v41, v41, s6, v211
	v_or_b32_e32 v41, 42, v41
	v_and_or_b32 v42, v42, s6, v211
	v_or_b32_e32 v42, 41, v42
	v_and_or_b32 v43, v43, s6, v211
	v_or_b32_e32 v43, 40, v43
	v_and_or_b32 v44, v44, s6, v211
	v_or_b32_e32 v44, 35, v44
	v_and_or_b32 v45, v45, s6, v211
	v_or_b32_e32 v45, 34, v45
	v_and_or_b32 v46, v46, s6, v211
	v_or_b32_e32 v46, 33, v46
	v_and_or_b32 v47, v47, s6, v211
	v_or_b32_e32 v47, 32, v47
	v_and_or_b32 v48, v48, s6, v211
	v_or_b32_e32 v48, 27, v48
	v_and_or_b32 v49, v49, s6, v211
	v_or_b32_e32 v49, 26, v49
	v_and_or_b32 v50, v50, s6, v211
	v_or_b32_e32 v50, 25, v50
	v_and_or_b32 v51, v51, s6, v211
	v_or_b32_e32 v51, 24, v51
	v_and_or_b32 v52, v52, s6, v211
	v_or_b32_e32 v52, 19, v52
	v_and_or_b32 v53, v53, s6, v211
	v_or_b32_e32 v53, 18, v53
	v_and_or_b32 v54, v54, s6, v211
	v_or_b32_e32 v54, 17, v54
	v_and_or_b32 v55, v55, s6, v211
	v_or_b32_e32 v55, 16, v55
	v_and_or_b32 v56, v56, s6, v211
	v_or_b32_e32 v56, 11, v56
	v_and_or_b32 v57, v57, s6, v211
	v_or_b32_e32 v57, 10, v57
	v_and_or_b32 v58, v58, s6, v211
	v_or_b32_e32 v58, 9, v58
	v_and_or_b32 v59, v59, s6, v211
	v_or_b32_e32 v59, 8, v59
	v_and_or_b32 v60, v60, s6, v211
	v_or_b32_e32 v60, 3, v60
	v_and_or_b32 v61, v61, s6, v211
	v_or_b32_e32 v61, 2, v61
	v_and_or_b32 v62, v62, s6, v211
	v_or_b32_e32 v62, 1, v62
	v_and_or_b32 v63, v63, s6, v211
	v_or_b32_e32 v63, 0, v63
	v_max_f32_e32 v144, v0, v13
	v_min_f32_e32 v13, v0, v13
	v_max_f32_e32 v145, v1, v12
	v_min_f32_e32 v12, v1, v12
	v_max_f32_e32 v146, v2, v15
	v_min_f32_e32 v15, v2, v15
	v_max_f32_e32 v147, v3, v14
	v_min_f32_e32 v14, v3, v14
	v_max_f32_e32 v148, v4, v8
	v_min_f32_e32 v8, v4, v8
	v_max_f32_e32 v149, v5, v6
	v_min_f32_e32 v6, v5, v6
	v_max_f32_e32 v150, v7, v11
	v_min_f32_e32 v11, v7, v11
	v_max_f32_e32 v151, v9, v10
	v_min_f32_e32 v10, v9, v10
	v_max_f32_e32 v249, v144, v149
	v_min_f32_e32 v149, v144, v149
	v_max_f32_e32 v250, v145, v150
	v_min_f32_e32 v150, v145, v150
	v_max_f32_e32 v251, v146, v151
	v_min_f32_e32 v151, v146, v151
	v_max_f32_e32 v252, v147, v148
	v_min_f32_e32 v148, v147, v148
	v_max_f32_e32 v253, v6, v13
	v_min_f32_e32 v13, v6, v13
	v_max_f32_e32 v254, v8, v14
	v_min_f32_e32 v14, v8, v14
	v_max_f32_e32 v255, v10, v15
	v_min_f32_e32 v15, v10, v15
	v_max_f32_e32 v96, v11, v12
	v_min_f32_e32 v12, v11, v12
	v_max_f32_e32 v97, v249, v250
	v_min_f32_e32 v250, v249, v250
	v_max_f32_e32 v98, v251, v252
	v_min_f32_e32 v252, v251, v252
	v_max_f32_e32 v99, v148, v149
	v_min_f32_e32 v149, v148, v149
	v_max_f32_e32 v100, v253, v254
	v_min_f32_e32 v254, v253, v254
	v_max_f32_e32 v101, v150, v151
	v_min_f32_e32 v151, v150, v151
	v_max_f32_e32 v102, v255, v96
	v_min_f32_e32 v96, v255, v96
	v_max_f32_e32 v103, v12, v13
	v_min_f32_e32 v13, v12, v13
	v_max_f32_e32 v104, v14, v15
	v_min_f32_e32 v15, v14, v15
	v_max_f32_e32 v105, v97, v98
	v_min_f32_e32 v98, v97, v98
	v_max_f32_e32 v106, v250, v252
	v_min_f32_e32 v252, v250, v252
	v_max_f32_e32 v107, v99, v102
	v_min_f32_e32 v102, v99, v102
	v_max_f32_e32 v108, v149, v96
	v_min_f32_e32 v96, v149, v96
	v_max_f32_e32 v109, v100, v101
	v_min_f32_e32 v101, v100, v101
	v_max_f32_e32 v110, v254, v151
	v_min_f32_e32 v151, v254, v151
	v_max_f32_e32 v111, v103, v104
	v_min_f32_e32 v104, v103, v104
	v_max_f32_e32 v112, v13, v15
	v_min_f32_e32 v15, v13, v15
	v_max_f32_e32 v113, v106, v98
	v_min_f32_e32 v98, v106, v98
	v_max_f32_e32 v114, v252, v111
	v_min_f32_e32 v111, v252, v111
	v_max_f32_e32 v115, v107, v109
	v_min_f32_e32 v109, v107, v109
	v_max_f32_e32 v116, v108, v101
	v_min_f32_e32 v101, v108, v101
	v_max_f32_e32 v117, v110, v102
	v_min_f32_e32 v102, v110, v102
	v_max_f32_e32 v118, v151, v96
	v_min_f32_e32 v96, v151, v96
	v_max_f32_e32 v119, v112, v104
	v_min_f32_e32 v104, v112, v104
	v_max_f32_e32 v120, v113, v115
	v_min_f32_e32 v115, v113, v115
	v_max_f32_e32 v121, v98, v109
	v_min_f32_e32 v109, v98, v109
	v_max_f32_e32 v122, v116, v117
	v_min_f32_e32 v117, v116, v117
	v_max_f32_e32 v123, v101, v102
	v_min_f32_e32 v102, v101, v102
	v_max_f32_e32 v124, v118, v119
	v_min_f32_e32 v119, v118, v119
	v_max_f32_e32 v125, v96, v104
	v_min_f32_e32 v104, v96, v104
	v_max_f32_e32 v126, v121, v115
	v_min_f32_e32 v115, v121, v115
	v_max_f32_e32 v127, v114, v109
	v_min_f32_e32 v109, v114, v109
	v_max_f32_e32 v64, v124, v111
	v_min_f32_e32 v111, v124, v111
	v_max_f32_e32 v65, v125, v119
	v_min_f32_e32 v119, v125, v119
	v_max_f32_e32 v66, v127, v122
	v_min_f32_e32 v122, v127, v122
	v_max_f32_e32 v67, v109, v117
	v_min_f32_e32 v117, v109, v117
	v_max_f32_e32 v68, v123, v64
	v_min_f32_e32 v64, v123, v64
	v_max_f32_e32 v69, v102, v111
	v_min_f32_e32 v111, v102, v111
	v_max_f32_e32 v70, v66, v115
	v_min_f32_e32 v115, v66, v115
	v_max_f32_e32 v71, v122, v67
	v_min_f32_e32 v67, v122, v67
	v_max_f32_e32 v72, v68, v117
	v_min_f32_e32 v117, v68, v117
	v_max_f32_e32 v73, v64, v69
	v_min_f32_e32 v69, v64, v69
	v_max_f32_e32 v74, v65, v111
	v_min_f32_e32 v111, v65, v111
	v_max_f32_e32 v75, v67, v72
	v_min_f32_e32 v72, v67, v72
	v_max_f32_e32 v76, v117, v73
	v_min_f32_e32 v73, v117, v73
	v_max_f32_e32 v77, v16, v29
	v_min_f32_e32 v29, v16, v29
	v_max_f32_e32 v78, v17, v28
	v_min_f32_e32 v28, v17, v28
	v_max_f32_e32 v79, v18, v31
	v_min_f32_e32 v31, v18, v31
	v_max_f32_e32 v80, v19, v30
	v_min_f32_e32 v30, v19, v30
	v_max_f32_e32 v81, v20, v24
	v_min_f32_e32 v24, v20, v24
	v_max_f32_e32 v82, v21, v22
	v_min_f32_e32 v22, v21, v22
	v_max_f32_e32 v83, v23, v27
	v_min_f32_e32 v27, v23, v27
	v_max_f32_e32 v84, v25, v26
	v_min_f32_e32 v26, v25, v26
	v_max_f32_e32 v85, v77, v82
	v_min_f32_e32 v82, v77, v82
	v_max_f32_e32 v86, v78, v83
	v_min_f32_e32 v83, v78, v83
	v_max_f32_e32 v87, v79, v84
	v_min_f32_e32 v84, v79, v84
	v_max_f32_e32 v88, v80, v81
	v_min_f32_e32 v81, v80, v81
	v_max_f32_e32 v89, v22, v29
	v_min_f32_e32 v29, v22, v29
	v_max_f32_e32 v90, v24, v30
	v_min_f32_e32 v30, v24, v30
	v_max_f32_e32 v91, v26, v31
	v_min_f32_e32 v31, v26, v31
	v_max_f32_e32 v92, v27, v28
	v_min_f32_e32 v28, v27, v28
	v_max_f32_e32 v93, v85, v86
	v_min_f32_e32 v86, v85, v86
	v_max_f32_e32 v94, v87, v88
	v_min_f32_e32 v88, v87, v88
	v_max_f32_e32 v95, v81, v82
	v_min_f32_e32 v82, v81, v82
	v_max_f32_e32 v0, v89, v90
	v_min_f32_e32 v90, v89, v90
	v_max_f32_e32 v1, v83, v84
	v_min_f32_e32 v84, v83, v84
	v_max_f32_e32 v2, v91, v92
	v_min_f32_e32 v92, v91, v92
	v_max_f32_e32 v3, v28, v29
	v_min_f32_e32 v29, v28, v29
	v_max_f32_e32 v4, v30, v31
	v_min_f32_e32 v31, v30, v31
	v_max_f32_e32 v5, v93, v94
	v_min_f32_e32 v94, v93, v94
	v_max_f32_e32 v7, v86, v88
	v_min_f32_e32 v88, v86, v88
	v_max_f32_e32 v9, v95, v2
	v_min_f32_e32 v2, v95, v2
	v_max_f32_e32 v144, v82, v92
	v_min_f32_e32 v92, v82, v92
	v_max_f32_e32 v145, v0, v1
	v_min_f32_e32 v1, v0, v1
	v_max_f32_e32 v146, v90, v84
	v_min_f32_e32 v84, v90, v84
	v_max_f32_e32 v147, v3, v4
	v_min_f32_e32 v4, v3, v4
	v_max_f32_e32 v6, v29, v31
	v_min_f32_e32 v31, v29, v31
	v_max_f32_e32 v8, v7, v94
	v_min_f32_e32 v94, v7, v94
	v_max_f32_e32 v10, v88, v147
	v_min_f32_e32 v147, v88, v147
	v_max_f32_e32 v11, v9, v145
	v_min_f32_e32 v145, v9, v145
	v_max_f32_e32 v249, v144, v1
	v_min_f32_e32 v1, v144, v1
	v_max_f32_e32 v251, v146, v2
	v_min_f32_e32 v2, v146, v2
	v_max_f32_e32 v148, v84, v92
	v_min_f32_e32 v92, v84, v92
	v_max_f32_e32 v253, v6, v4
	v_min_f32_e32 v4, v6, v4
	v_max_f32_e32 v150, v8, v11
	v_min_f32_e32 v11, v8, v11
	v_max_f32_e32 v255, v94, v145
	v_min_f32_e32 v145, v94, v145
	v_max_f32_e32 v12, v249, v251
	v_min_f32_e32 v251, v249, v251
	v_max_f32_e32 v14, v1, v2
	v_min_f32_e32 v2, v1, v2
	v_max_f32_e32 v97, v148, v253
	v_min_f32_e32 v253, v148, v253
	v_max_f32_e32 v250, v92, v4
	v_min_f32_e32 v4, v92, v4
	v_max_f32_e32 v99, v255, v11
	v_min_f32_e32 v11, v255, v11
	v_max_f32_e32 v149, v10, v145
	v_min_f32_e32 v145, v10, v145
	v_max_f32_e32 v100, v97, v147
	v_min_f32_e32 v147, v97, v147
	v_max_f32_e32 v254, v250, v253
	v_min_f32_e32 v253, v250, v253
	v_max_f32_e32 v103, v149, v12
	v_min_f32_e32 v12, v149, v12
	v_max_f32_e32 v13, v145, v251
	v_min_f32_e32 v251, v145, v251
	v_max_f32_e32 v106, v14, v100
	v_min_f32_e32 v100, v14, v100
	v_max_f32_e32 v252, v2, v147
	v_min_f32_e32 v147, v2, v147
	v_max_f32_e32 v107, v103, v11
	v_min_f32_e32 v11, v103, v11
	v_max_f32_e32 v108, v12, v13
	v_min_f32_e32 v13, v12, v13
	v_max_f32_e32 v110, v106, v251
	v_min_f32_e32 v251, v106, v251
	v_max_f32_e32 v151, v100, v252
	v_min_f32_e32 v252, v100, v252
	v_max_f32_e32 v112, v254, v147
	v_min_f32_e32 v147, v254, v147
	v_max_f32_e32 v113, v13, v110
	v_min_f32_e32 v110, v13, v110
	v_max_f32_e32 v98, v251, v151
	v_min_f32_e32 v151, v251, v151
	s_waitcnt vmcnt(0)
	v_pk_mul_f32 v[160:161], v[160:161], v[176:177]
	v_pk_mul_f32 v[162:163], v[162:163], v[178:179]
	v_pk_mul_f32 v[164:165], v[164:165], v[180:181]
	v_pk_mul_f32 v[166:167], v[166:167], v[182:183]
	v_pk_mul_f32 v[168:169], v[168:169], v[184:185]
	v_pk_mul_f32 v[170:171], v[170:171], v[186:187]
	v_pk_mul_f32 v[172:173], v[172:173], v[188:189]
	v_pk_mul_f32 v[174:175], v[174:175], v[190:191]
	v_max3_f32 v192, |v160|, |v161|, |v162|
	v_max3_f32 v192, |v163|, |v164|, v192
	v_max3_f32 v192, |v165|, |v166|, v192
	v_max3_f32 v192, |v167|, |v168|, v192
	v_max3_f32 v192, |v169|, |v170|, v192
	v_max3_f32 v192, |v171|, |v172|, v192
	v_max3_f32 v192, |v173|, |v174|, v192
	v_max_f32_e64 v192, |v175|, v192
	s_nop 1
	v_mov_b32_dpp v193, v192 quad_perm:[1,0,3,2] row_mask:0xf bank_mask:0xf bound_ctrl:1
	v_max_f32_e32 v192, v192, v193
	s_nop 1
	v_mov_b32_dpp v193, v192 quad_perm:[2,3,0,1] row_mask:0xf bank_mask:0xf bound_ctrl:1
	v_max_f32_e32 v192, v192, v193
	s_nop 1
	v_mov_b32_dpp v193, v192 row_half_mirror row_mask:0xf bank_mask:0xf bound_ctrl:1
	v_max_f32_e32 v192, v192, v193
	s_nop 1
	v_mov_b32_dpp v193, v192 row_mirror row_mask:0xf bank_mask:0xf bound_ctrl:1
	v_max_f32_e32 v192, v192, v193
	v_mov_b32_e32 v193, v192
	s_nop 1
	v_permlane16_swap_b32_e32 v192, v193
	s_nop 1
	v_max_f32_e32 v192, v192, v193
	v_mov_b32_e32 v193, v192
	s_nop 1
	v_permlane32_swap_b32_e32 v192, v193
	s_nop 1
	v_max_f32_e32 v192, v192, v193
	v_max_f32_e32 v192, 0xda24260, v192
	v_mul_f32_e32 v194, 0x3e2aaaab, v192
	global_store_dword v214, v194, s[12:13]
	v_div_scale_f32 v195, s[26:27], v194, v194, 1.0
	v_rcp_f32_e32 v196, v195
	v_div_scale_f32 v204, vcc, 1.0, v194, 1.0
	v_fma_f32 v205, -v195, v196, 1.0
	v_fmac_f32_e32 v196, v205, v196
	v_mul_f32_e32 v205, v204, v196
	v_fma_f32 v206, -v195, v205, v204
	v_fmac_f32_e32 v205, v206, v196
	v_fma_f32 v195, -v195, v205, v204
	s_nop 0
	v_div_fmas_f32 v195, v195, v196, v205
	v_div_fixup_f32 v207, v195, v194, 1.0
	v_mul_f32_e32 v160, v207, v160
	v_mul_f32_e32 v161, v207, v161
	v_mul_f32_e32 v162, v207, v162
	v_mul_f32_e32 v163, v207, v163
	v_mul_f32_e32 v164, v207, v164
	v_mul_f32_e32 v165, v207, v165
	v_mul_f32_e32 v166, v207, v166
	v_mul_f32_e32 v167, v207, v167
	v_mul_f32_e32 v168, v207, v168
	v_mul_f32_e32 v169, v207, v169
	v_mul_f32_e32 v170, v207, v170
	v_mul_f32_e32 v171, v207, v171
	v_mul_f32_e32 v172, v207, v172
	v_mul_f32_e32 v173, v207, v173
	v_mul_f32_e32 v174, v207, v174
	v_mul_f32_e32 v175, v207, v175
	v_mov_b32_e32 v208, 0
	v_mov_b32_e32 v209, 0
	v_mov_b32_e32 v210, 0
	v_mov_b32_e32 v193, 0
	v_cvt_scalef32_pk_fp4_f32 v208, v160, v161, 1.0
	v_cvt_scalef32_pk_fp4_f32 v209, v164, v165, 1.0
	v_cvt_scalef32_pk_fp4_f32 v210, v168, v169, 1.0
	v_cvt_scalef32_pk_fp4_f32 v193, v172, v173, 1.0
	v_cvt_scalef32_pk_fp4_f32 v208, v162, v163, 1.0 op_sel:[0,0,1,0]
	v_cvt_scalef32_pk_fp4_f32 v209, v166, v167, 1.0 op_sel:[0,0,1,0]
	v_cvt_scalef32_pk_fp4_f32 v210, v170, v171, 1.0 op_sel:[0,0,1,0]
	v_cvt_scalef32_pk_fp4_f32 v193, v174, v175, 1.0 op_sel:[0,0,1,0]
	global_store_short v213, v208, s[10:11] nt
	s_add_u32 s14, s10, 0x200000
	s_addc_u32 s15, s11, 0
	global_store_short v213, v209, s[14:15] nt
	s_add_u32 s14, s10, 0x400000
	s_addc_u32 s15, s11, 0
	global_store_short v213, v210, s[14:15] nt
	s_add_u32 s14, s10, 0x600000
	s_addc_u32 s15, s11, 0
	global_store_short v213, v193, s[14:15] nt
	s_add_u32 s10, s10, 0x20000
	s_addc_u32 s11, s11, 0
	s_add_u32 s12, s12, 0x2000
	s_addc_u32 s13, s13, 0
	global_load_dwordx4 v[160:163], v212, s[8:9] offset:0 nt
	global_load_dwordx4 v[164:167], v212, s[8:9] offset:1024 nt
	global_load_dwordx4 v[168:171], v212, s[8:9] offset:2048 nt
	global_load_dwordx4 v[172:175], v212, s[8:9] offset:3072 nt
	s_add_u32 s8, s8, 0x800000
	s_addc_u32 s9, s9, 0
	v_max_f32_e32 v116, v32, v45
	v_min_f32_e32 v45, v32, v45
	v_max_f32_e32 v101, v33, v44
	v_min_f32_e32 v44, v33, v44
	v_max_f32_e32 v118, v34, v47
	v_min_f32_e32 v47, v34, v47
	v_max_f32_e32 v96, v35, v46
	v_min_f32_e32 v46, v35, v46
	v_max_f32_e32 v121, v36, v40
	v_min_f32_e32 v40, v36, v40
	v_max_f32_e32 v114, v37, v38
	v_min_f32_e32 v38, v37, v38
	v_max_f32_e32 v124, v39, v43
	v_min_f32_e32 v43, v39, v43
	v_max_f32_e32 v125, v41, v42
	v_min_f32_e32 v42, v41, v42
	v_max_f32_e32 v127, v116, v114
	v_min_f32_e32 v114, v116, v114
	v_max_f32_e32 v109, v101, v124
	v_min_f32_e32 v124, v101, v124
	v_max_f32_e32 v123, v118, v125
	v_min_f32_e32 v125, v118, v125
	v_max_f32_e32 v102, v96, v121
	v_min_f32_e32 v121, v96, v121
	v_max_f32_e32 v66, v38, v45
	v_min_f32_e32 v45, v38, v45
	v_max_f32_e32 v122, v40, v46
	v_min_f32_e32 v46, v40, v46
	v_max_f32_e32 v68, v42, v47
	v_min_f32_e32 v47, v42, v47
	v_max_f32_e32 v64, v43, v44
	v_min_f32_e32 v44, v43, v44
	v_max_f32_e32 v65, v127, v109
	v_min_f32_e32 v109, v127, v109
	v_max_f32_e32 v67, v123, v102
	v_min_f32_e32 v102, v123, v102
	v_max_f32_e32 v117, v121, v114
	v_min_f32_e32 v114, v121, v114
	v_max_f32_e32 v16, v66, v122
	v_min_f32_e32 v122, v66, v122
	v_max_f32_e32 v17, v124, v125
	v_min_f32_e32 v125, v124, v125
	v_max_f32_e32 v18, v68, v64
	v_min_f32_e32 v64, v68, v64
	v_max_f32_e32 v19, v44, v45
	v_min_f32_e32 v45, v44, v45
	v_max_f32_e32 v20, v46, v47
	v_min_f32_e32 v47, v46, v47
	v_max_f32_e32 v21, v65, v67
	v_min_f32_e32 v67, v65, v67
	v_max_f32_e32 v23, v109, v102
	v_min_f32_e32 v102, v109, v102
	v_max_f32_e32 v25, v117, v18
	v_min_f32_e32 v18, v117, v18
	v_max_f32_e32 v77, v114, v64
	v_min_f32_e32 v64, v114, v64
	v_max_f32_e32 v78, v16, v17
	v_min_f32_e32 v17, v16, v17
	v_max_f32_e32 v79, v122, v125
	v_min_f32_e32 v125, v122, v125
	v_max_f32_e32 v80, v19, v20
	v_min_f32_e32 v20, v19, v20
	v_max_f32_e32 v22, v45, v47
	v_min_f32_e32 v47, v45, v47
	v_max_f32_e32 v24, v23, v67
	v_min_f32_e32 v67, v23, v67
	v_max_f32_e32 v26, v102, v80
	v_min_f32_e32 v80, v102, v80
	v_max_f32_e32 v27, v25, v78
	v_min_f32_e32 v78, v25, v78
	v_max_f32_e32 v85, v77, v17
	v_min_f32_e32 v17, v77, v17
	v_max_f32_e32 v87, v79, v18
	v_min_f32_e32 v18, v79, v18
	v_max_f32_e32 v81, v125, v64
	v_min_f32_e32 v64, v125, v64
	v_max_f32_e32 v89, v22, v20
	v_min_f32_e32 v20, v22, v20
	v_max_f32_e32 v83, v24, v27
	v_min_f32_e32 v27, v24, v27
	v_max_f32_e32 v91, v67, v78
	v_min_f32_e32 v78, v67, v78
	v_max_f32_e32 v28, v85, v87
	v_min_f32_e32 v87, v85, v87
	v_max_f32_e32 v30, v17, v18
	v_min_f32_e32 v18, v17, v18
	v_max_f32_e32 v93, v81, v89
	v_min_f32_e32 v89, v81, v89
	v_max_f32_e32 v86, v64, v20
	v_min_f32_e32 v20, v64, v20
	v_max_f32_e32 v95, v91, v27
	v_min_f32_e32 v27, v91, v27
	v_max_f32_e32 v82, v26, v78
	v_min_f32_e32 v78, v26, v78
	v_max_f32_e32 v0, v93, v80
	v_min_f32_e32 v80, v93, v80
	v_max_f32_e32 v90, v86, v89
	v_min_f32_e32 v89, v86, v89
	v_max_f32_e32 v3, v82, v28
	v_min_f32_e32 v28, v82, v28
	v_max_f32_e32 v29, v78, v87
	v_min_f32_e32 v87, v78, v87
	v_max_f32_e32 v7, v30, v0
	v_min_f32_e32 v0, v30, v0
	v_max_f32_e32 v88, v18, v80
	v_min_f32_e32 v80, v18, v80
	v_max_f32_e32 v9, v3, v27
	v_min_f32_e32 v27, v3, v27
	v_max_f32_e32 v144, v28, v29
	v_min_f32_e32 v29, v28, v29
	v_max_f32_e32 v146, v7, v87
	v_min_f32_e32 v87, v7, v87
	v_max_f32_e32 v84, v0, v88
	v_min_f32_e32 v88, v0, v88
	v_max_f32_e32 v6, v90, v80
	v_min_f32_e32 v80, v90, v80
	v_max_f32_e32 v8, v29, v146
	v_min_f32_e32 v146, v29, v146
	v_max_f32_e32 v94, v87, v84
	v_min_f32_e32 v84, v87, v84
	v_max_f32_e32 v249, v48, v61
	v_min_f32_e32 v61, v48, v61
	v_max_f32_e32 v1, v49, v60
	v_min_f32_e32 v60, v49, v60
	v_max_f32_e32 v148, v50, v63
	v_min_f32_e32 v63, v50, v63
	v_max_f32_e32 v92, v51, v62
	v_min_f32_e32 v62, v51, v62
	v_max_f32_e32 v255, v52, v56
	v_min_f32_e32 v56, v52, v56
	v_max_f32_e32 v10, v53, v54
	v_min_f32_e32 v54, v53, v54
	v_max_f32_e32 v97, v55, v59
	v_min_f32_e32 v59, v55, v59
	v_max_f32_e32 v250, v57, v58
	v_min_f32_e32 v58, v57, v58
	v_max_f32_e32 v149, v249, v10
	v_min_f32_e32 v10, v249, v10
	v_max_f32_e32 v145, v1, v97
	v_min_f32_e32 v97, v1, v97
	v_max_f32_e32 v14, v148, v250
	v_min_f32_e32 v250, v148, v250
	v_max_f32_e32 v2, v92, v255
	v_min_f32_e32 v255, v92, v255
	v_max_f32_e32 v103, v54, v61
	v_min_f32_e32 v61, v54, v61
	v_max_f32_e32 v12, v56, v62
	v_min_f32_e32 v62, v56, v62
	v_max_f32_e32 v106, v58, v63
	v_min_f32_e32 v63, v58, v63
	v_max_f32_e32 v100, v59, v60
	v_min_f32_e32 v60, v59, v60
	v_max_f32_e32 v254, v149, v145
	v_min_f32_e32 v145, v149, v145
	v_max_f32_e32 v13, v14, v2
	v_min_f32_e32 v2, v14, v2
	v_max_f32_e32 v251, v255, v10
	v_min_f32_e32 v10, v255, v10
	v_max_f32_e32 v32, v103, v12
	v_min_f32_e32 v12, v103, v12
	v_max_f32_e32 v33, v97, v250
	v_min_f32_e32 v250, v97, v250
	v_max_f32_e32 v34, v106, v100
	v_min_f32_e32 v100, v106, v100
	v_max_f32_e32 v35, v60, v61
	v_min_f32_e32 v61, v60, v61
	v_max_f32_e32 v36, v62, v63
	v_min_f32_e32 v63, v62, v63
	v_max_f32_e32 v37, v254, v13
	v_min_f32_e32 v13, v254, v13
	v_max_f32_e32 v39, v145, v2
	v_min_f32_e32 v2, v145, v2
	v_max_f32_e32 v41, v251, v34
	v_min_f32_e32 v34, v251, v34
	v_max_f32_e32 v116, v10, v100
	v_min_f32_e32 v100, v10, v100
	v_max_f32_e32 v101, v32, v33
	v_min_f32_e32 v33, v32, v33
	v_max_f32_e32 v118, v12, v250
	v_min_f32_e32 v250, v12, v250
	v_max_f32_e32 v96, v35, v36
	v_min_f32_e32 v36, v35, v36
	v_max_f32_e32 v38, v61, v63
	v_min_f32_e32 v63, v61, v63
	v_max_f32_e32 v40, v39, v13
	v_min_f32_e32 v13, v39, v13
	v_max_f32_e32 v42, v2, v96
	v_min_f32_e32 v96, v2, v96
	v_max_f32_e32 v43, v41, v101
	v_min_f32_e32 v101, v41, v101
	v_max_f32_e32 v127, v116, v33
	v_min_f32_e32 v33, v116, v33
	v_max_f32_e32 v123, v118, v34
	v_min_f32_e32 v34, v118, v34
	v_max_f32_e32 v121, v250, v100
	v_min_f32_e32 v100, v250, v100
	v_max_f32_e32 v66, v38, v36
	v_min_f32_e32 v36, v38, v36
	v_max_f32_e32 v124, v40, v43
	v_min_f32_e32 v43, v40, v43
	v_max_f32_e32 v68, v13, v101
	v_min_f32_e32 v101, v13, v101
	v_max_f32_e32 v44, v127, v123
	v_min_f32_e32 v123, v127, v123
	v_max_f32_e32 v46, v33, v34
	v_min_f32_e32 v34, v33, v34
	v_max_f32_e32 v65, v121, v66
	v_min_f32_e32 v66, v121, v66
	v_max_f32_e32 v109, v100, v36
	v_min_f32_e32 v36, v100, v36
	v_max_f32_e32 v117, v68, v43
	v_min_f32_e32 v43, v68, v43
	v_max_f32_e32 v114, v42, v101
	v_min_f32_e32 v101, v42, v101
	v_max_f32_e32 v16, v65, v96
	v_min_f32_e32 v96, v65, v96
	v_max_f32_e32 v122, v109, v66
	v_min_f32_e32 v66, v109, v66
	v_max_f32_e32 v19, v114, v44
	v_min_f32_e32 v44, v114, v44
	v_max_f32_e32 v45, v101, v123
	v_min_f32_e32 v123, v101, v123
	v_max_f32_e32 v23, v46, v16
	v_min_f32_e32 v16, v46, v16
	v_max_f32_e32 v102, v34, v96
	v_min_f32_e32 v96, v34, v96
	v_max_f32_e32 v25, v19, v43
	v_min_f32_e32 v43, v19, v43
	v_max_f32_e32 v77, v44, v45
	v_min_f32_e32 v45, v44, v45
	v_max_f32_e32 v79, v23, v123
	v_min_f32_e32 v123, v23, v123
	v_max_f32_e32 v125, v16, v102
	v_min_f32_e32 v102, v16, v102
	v_max_f32_e32 v22, v122, v96
	v_min_f32_e32 v96, v122, v96
	v_max_f32_e32 v24, v45, v79
	v_min_f32_e32 v79, v45, v79
	v_max_f32_e32 v67, v123, v125
	v_min_f32_e32 v125, v123, v125
	s_waitcnt vmcnt(0)
	v_pk_mul_f32 v[160:161], v[160:161], v[176:177]
	v_pk_mul_f32 v[162:163], v[162:163], v[178:179]
	v_pk_mul_f32 v[164:165], v[164:165], v[180:181]
	v_pk_mul_f32 v[166:167], v[166:167], v[182:183]
	v_pk_mul_f32 v[168:169], v[168:169], v[184:185]
	v_pk_mul_f32 v[170:171], v[170:171], v[186:187]
	v_pk_mul_f32 v[172:173], v[172:173], v[188:189]
	v_pk_mul_f32 v[174:175], v[174:175], v[190:191]
	v_max3_f32 v192, |v160|, |v161|, |v162|
	v_max3_f32 v192, |v163|, |v164|, v192
	v_max3_f32 v192, |v165|, |v166|, v192
	v_max3_f32 v192, |v167|, |v168|, v192
	v_max3_f32 v192, |v169|, |v170|, v192
	v_max3_f32 v192, |v171|, |v172|, v192
	v_max3_f32 v192, |v173|, |v174|, v192
	v_max_f32_e64 v192, |v175|, v192
	s_nop 1
	v_mov_b32_dpp v193, v192 quad_perm:[1,0,3,2] row_mask:0xf bank_mask:0xf bound_ctrl:1
	v_max_f32_e32 v192, v192, v193
	s_nop 1
	v_mov_b32_dpp v193, v192 quad_perm:[2,3,0,1] row_mask:0xf bank_mask:0xf bound_ctrl:1
	v_max_f32_e32 v192, v192, v193
	s_nop 1
	v_mov_b32_dpp v193, v192 row_half_mirror row_mask:0xf bank_mask:0xf bound_ctrl:1
	v_max_f32_e32 v192, v192, v193
	s_nop 1
	v_mov_b32_dpp v193, v192 row_mirror row_mask:0xf bank_mask:0xf bound_ctrl:1
	v_max_f32_e32 v192, v192, v193
	v_mov_b32_e32 v193, v192
	s_nop 1
	v_permlane16_swap_b32_e32 v192, v193
	s_nop 1
	v_max_f32_e32 v192, v192, v193
	v_mov_b32_e32 v193, v192
	s_nop 1
	v_permlane32_swap_b32_e32 v192, v193
	s_nop 1
	v_max_f32_e32 v192, v192, v193
	v_max_f32_e32 v192, 0xda24260, v192
	v_mul_f32_e32 v194, 0x3e2aaaab, v192
	global_store_dword v214, v194, s[12:13]
	v_div_scale_f32 v195, s[26:27], v194, v194, 1.0
	v_rcp_f32_e32 v196, v195
	v_div_scale_f32 v204, vcc, 1.0, v194, 1.0
	v_fma_f32 v205, -v195, v196, 1.0
	v_fmac_f32_e32 v196, v205, v196
	v_mul_f32_e32 v205, v204, v196
	v_fma_f32 v206, -v195, v205, v204
	v_fmac_f32_e32 v205, v206, v196
	v_fma_f32 v195, -v195, v205, v204
	s_nop 0
	v_div_fmas_f32 v195, v195, v196, v205
	v_div_fixup_f32 v207, v195, v194, 1.0
	v_mul_f32_e32 v160, v207, v160
	v_mul_f32_e32 v161, v207, v161
	v_mul_f32_e32 v162, v207, v162
	v_mul_f32_e32 v163, v207, v163
	v_mul_f32_e32 v164, v207, v164
	v_mul_f32_e32 v165, v207, v165
	v_mul_f32_e32 v166, v207, v166
	v_mul_f32_e32 v167, v207, v167
	v_mul_f32_e32 v168, v207, v168
	v_mul_f32_e32 v169, v207, v169
	v_mul_f32_e32 v170, v207, v170
	v_mul_f32_e32 v171, v207, v171
	v_mul_f32_e32 v172, v207, v172
	v_mul_f32_e32 v173, v207, v173
	v_mul_f32_e32 v174, v207, v174
	v_mul_f32_e32 v175, v207, v175
	v_mov_b32_e32 v208, 0
	v_mov_b32_e32 v209, 0
	v_mov_b32_e32 v210, 0
	v_mov_b32_e32 v193, 0
	v_cvt_scalef32_pk_fp4_f32 v208, v160, v161, 1.0
	v_cvt_scalef32_pk_fp4_f32 v209, v164, v165, 1.0
	v_cvt_scalef32_pk_fp4_f32 v210, v168, v169, 1.0
	v_cvt_scalef32_pk_fp4_f32 v193, v172, v173, 1.0
	v_cvt_scalef32_pk_fp4_f32 v208, v162, v163, 1.0 op_sel:[0,0,1,0]
	v_cvt_scalef32_pk_fp4_f32 v209, v166, v167, 1.0 op_sel:[0,0,1,0]
	v_cvt_scalef32_pk_fp4_f32 v210, v170, v171, 1.0 op_sel:[0,0,1,0]
	v_cvt_scalef32_pk_fp4_f32 v193, v174, v175, 1.0 op_sel:[0,0,1,0]
	global_store_short v213, v208, s[10:11] nt
	s_add_u32 s14, s10, 0x200000
	s_addc_u32 s15, s11, 0
	global_store_short v213, v209, s[14:15] nt
	s_add_u32 s14, s10, 0x400000
	s_addc_u32 s15, s11, 0
	global_store_short v213, v210, s[14:15] nt
	s_add_u32 s14, s10, 0x600000
	s_addc_u32 s15, s11, 0
	global_store_short v213, v193, s[14:15] nt
	s_add_u32 s10, s10, 0x20000
	s_addc_u32 s11, s11, 0
	s_add_u32 s12, s12, 0x2000
	s_addc_u32 s13, s13, 0
	global_load_dwordx4 v[160:163], v212, s[8:9] offset:0 nt
	global_load_dwordx4 v[164:167], v212, s[8:9] offset:1024 nt
	global_load_dwordx4 v[168:171], v212, s[8:9] offset:2048 nt
	global_load_dwordx4 v[172:175], v212, s[8:9] offset:3072 nt
	s_add_u32 s8, s8, 0x800000
	s_addc_u32 s9, s9, 0
	v_max_f32_e32 v105, v105, v31
	v_max_f32_e32 v120, v120, v4
	v_max_f32_e32 v126, v126, v253
	v_max_f32_e32 v70, v70, v147
	v_max_f32_e32 v115, v115, v112
	v_max_f32_e32 v71, v71, v252
	v_max_f32_e32 v75, v75, v151
	v_max_f32_e32 v72, v72, v98
	v_max_f32_e32 v76, v76, v110
	v_max_f32_e32 v73, v73, v113
	v_max_f32_e32 v69, v69, v108
	v_max_f32_e32 v74, v74, v11
	v_max_f32_e32 v111, v111, v107
	v_max_f32_e32 v119, v119, v99
	v_max_f32_e32 v104, v104, v150
	v_max_f32_e32 v15, v15, v5
	v_max_f32_e32 v85, v105, v76
	v_min_f32_e32 v76, v105, v76
	v_max_f32_e32 v17, v120, v73
	v_min_f32_e32 v73, v120, v73
	v_max_f32_e32 v81, v126, v69
	v_min_f32_e32 v69, v126, v69
	v_max_f32_e32 v64, v70, v74
	v_min_f32_e32 v74, v70, v74
	v_max_f32_e32 v91, v115, v111
	v_min_f32_e32 v111, v115, v111
	v_max_f32_e32 v26, v71, v119
	v_min_f32_e32 v119, v71, v119
	v_max_f32_e32 v93, v75, v104
	v_min_f32_e32 v104, v75, v104
	v_max_f32_e32 v86, v72, v15
	v_min_f32_e32 v15, v72, v15
	v_max_f32_e32 v82, v85, v91
	v_min_f32_e32 v91, v85, v91
	v_max_f32_e32 v78, v17, v26
	v_min_f32_e32 v26, v17, v26
	v_max_f32_e32 v30, v81, v93
	v_min_f32_e32 v93, v81, v93
	v_max_f32_e32 v18, v64, v86
	v_min_f32_e32 v86, v64, v86
	v_max_f32_e32 v3, v76, v111
	v_min_f32_e32 v111, v76, v111
	v_max_f32_e32 v28, v73, v119
	v_min_f32_e32 v119, v73, v119
	v_max_f32_e32 v7, v69, v104
	v_min_f32_e32 v104, v69, v104
	v_max_f32_e32 v0, v74, v15
	v_min_f32_e32 v15, v74, v15
	v_max_f32_e32 v90, v82, v30
	v_min_f32_e32 v30, v82, v30
	v_max_f32_e32 v29, v78, v18
	v_min_f32_e32 v18, v78, v18
	v_max_f32_e32 v87, v91, v93
	v_min_f32_e32 v93, v91, v93
	v_max_f32_e32 v48, v26, v86
	v_min_f32_e32 v86, v26, v86
	v_max_f32_e32 v49, v3, v7
	v_min_f32_e32 v7, v3, v7
	v_max_f32_e32 v50, v28, v0
	v_min_f32_e32 v0, v28, v0
	v_max_f32_e32 v51, v111, v104
	v_min_f32_e32 v104, v111, v104
	v_max_f32_e32 v52, v119, v15
	v_min_f32_e32 v15, v119, v15
	v_max_f32_e32 v53, v90, v29
	v_min_f32_e32 v29, v90, v29
	v_max_f32_e32 v55, v30, v18
	v_min_f32_e32 v18, v30, v18
	v_max_f32_e32 v57, v87, v48
	v_min_f32_e32 v48, v87, v48
	v_max_f32_e32 v249, v93, v86
	v_min_f32_e32 v86, v93, v86
	v_max_f32_e32 v1, v49, v50
	v_min_f32_e32 v50, v49, v50
	v_max_f32_e32 v148, v7, v0
	v_min_f32_e32 v0, v7, v0
	v_max_f32_e32 v92, v51, v52
	v_min_f32_e32 v52, v51, v52
	v_max_f32_e32 v54, v104, v15
	v_min_f32_e32 v15, v104, v15
	v_max_f32_e32 v21, v21, v63
	v_max_f32_e32 v83, v83, v36
	v_max_f32_e32 v95, v95, v66
	v_max_f32_e32 v9, v9, v96
	v_max_f32_e32 v27, v27, v22
	v_max_f32_e32 v144, v144, v102
	v_max_f32_e32 v8, v8, v125
	v_max_f32_e32 v146, v146, v67
	v_max_f32_e32 v94, v94, v79
	v_max_f32_e32 v84, v84, v24
	v_max_f32_e32 v88, v88, v77
	v_max_f32_e32 v6, v6, v43
	v_max_f32_e32 v80, v80, v25
	v_max_f32_e32 v89, v89, v117
	v_max_f32_e32 v20, v20, v124
	v_max_f32_e32 v47, v47, v37
	v_max_f32_e32 v56, v21, v94
	v_min_f32_e32 v94, v21, v94
	v_max_f32_e32 v58, v83, v84
	v_min_f32_e32 v84, v83, v84
	v_max_f32_e32 v59, v95, v88
	v_min_f32_e32 v88, v95, v88
	v_max_f32_e32 v149, v9, v6
	v_min_f32_e32 v6, v9, v6
	v_max_f32_e32 v14, v27, v80
	v_min_f32_e32 v80, v27, v80
	v_max_f32_e32 v255, v144, v89
	v_min_f32_e32 v89, v144, v89
	v_max_f32_e32 v103, v8, v20
	v_min_f32_e32 v20, v8, v20
	v_max_f32_e32 v97, v146, v47
	v_min_f32_e32 v47, v146, v47
	v_max_f32_e32 v106, v56, v14
	v_min_f32_e32 v14, v56, v14
	v_max_f32_e32 v60, v58, v255
	v_min_f32_e32 v255, v58, v255
	v_max_f32_e32 v62, v59, v103
	v_min_f32_e32 v103, v59, v103
	v_max_f32_e32 v254, v149, v97
	v_min_f32_e32 v97, v149, v97
	v_max_f32_e32 v145, v94, v80
	v_min_f32_e32 v80, v94, v80
	v_max_f32_e32 v251, v84, v89
	v_min_f32_e32 v89, v84, v89
	v_max_f32_e32 v10, v88, v20
	v_min_f32_e32 v20, v88, v20
	v_max_f32_e32 v32, v6, v47
	v_min_f32_e32 v47, v6, v47
	v_max_f32_e32 v12, v106, v62
	v_min_f32_e32 v62, v106, v62
	v_max_f32_e32 v35, v60, v254
	v_min_f32_e32 v254, v60, v254
	v_max_f32_e32 v61, v14, v103
	v_min_f32_e32 v103, v14, v103
	v_max_f32_e32 v39, v255, v97
	v_min_f32_e32 v97, v255, v97
	v_max_f32_e32 v2, v145, v10
	v_min_f32_e32 v10, v145, v10
	v_max_f32_e32 v41, v251, v32
	v_min_f32_e32 v32, v251, v32
	v_max_f32_e32 v116, v80, v20
	v_min_f32_e32 v20, v80, v20
	v_max_f32_e32 v118, v89, v47
	v_min_f32_e32 v47, v89, v47
	v_max_f32_e32 v250, v12, v35
	v_min_f32_e32 v35, v12, v35
	v_max_f32_e32 v38, v62, v254
	v_min_f32_e32 v254, v62, v254
	v_max_f32_e32 v40, v61, v39
	v_min_f32_e32 v39, v61, v39
	v_max_f32_e32 v13, v103, v97
	v_min_f32_e32 v97, v103, v97
	v_max_f32_e32 v127, v2, v41
	v_min_f32_e32 v41, v2, v41
	v_max_f32_e32 v33, v10, v32
	v_min_f32_e32 v32, v10, v32
	v_max_f32_e32 v121, v116, v118
	v_min_f32_e32 v118, v116, v118
	v_max_f32_e32 v100, v20, v47
	v_min_f32_e32 v47, v20, v47
	v_max_f32_e32 v53, v53, v47
	v_max_f32_e32 v29, v29, v100
	v_max_f32_e32 v55, v55, v118
	v_max_f32_e32 v18, v18, v121
	v_max_f32_e32 v57, v57, v32
	v_max_f32_e32 v48, v48, v33
	v_max_f32_e32 v249, v249, v41
	v_max_f32_e32 v86, v86, v127
	v_max_f32_e32 v1, v1, v97
	v_max_f32_e32 v50, v50, v13
	v_max_f32_e32 v148, v148, v39
	v_max_f32_e32 v0, v0, v40
	v_max_f32_e32 v92, v92, v254
	v_max_f32_e32 v52, v52, v38
	v_max_f32_e32 v54, v54, v35
	v_max_f32_e32 v15, v15, v250
	v_max_f32_e32 v68, v53, v1
	v_min_f32_e32 v1, v53, v1
	v_max_f32_e32 v42, v29, v50
	v_min_f32_e32 v50, v29, v50
	v_max_f32_e32 v65, v55, v148
	v_min_f32_e32 v148, v55, v148
	v_max_f32_e32 v109, v18, v0
	v_min_f32_e32 v0, v18, v0
	v_max_f32_e32 v114, v57, v92
	v_min_f32_e32 v92, v57, v92
	v_max_f32_e32 v101, v48, v52
	v_min_f32_e32 v52, v48, v52
	v_max_f32_e32 v46, v249, v54
	v_min_f32_e32 v54, v249, v54
	v_max_f32_e32 v34, v86, v15
	v_min_f32_e32 v15, v86, v15
	v_max_f32_e32 v19, v68, v114
	v_min_f32_e32 v114, v68, v114
	v_max_f32_e32 v44, v42, v101
	v_min_f32_e32 v101, v42, v101
	v_max_f32_e32 v23, v65, v46
	v_min_f32_e32 v46, v65, v46
	v_max_f32_e32 v16, v109, v34
	v_min_f32_e32 v34, v109, v34
	v_max_f32_e32 v122, v1, v92
	v_min_f32_e32 v92, v1, v92
	v_max_f32_e32 v45, v50, v52
	v_min_f32_e32 v52, v50, v52
	v_max_f32_e32 v123, v148, v54
	v_min_f32_e32 v54, v148, v54
	v_max_f32_e32 v5, v0, v15
	v_min_f32_e32 v15, v0, v15
	v_max_f32_e32 v150, v19, v23
	v_min_f32_e32 v23, v19, v23
	v_max_f32_e32 v99, v44, v16
	v_min_f32_e32 v16, v44, v16
	v_max_f32_e32 v107, v114, v46
	v_min_f32_e32 v46, v114, v46
	v_max_f32_e32 v11, v101, v34
	v_min_f32_e32 v34, v101, v34
	v_max_f32_e32 v108, v122, v123
	v_min_f32_e32 v123, v122, v123
	v_max_f32_e32 v113, v45, v5
	v_min_f32_e32 v5, v45, v5
	v_max_f32_e32 v110, v92, v54
	v_min_f32_e32 v54, v92, v54
	v_max_f32_e32 v98, v52, v15
	v_min_f32_e32 v15, v52, v15
	v_max_f32_e32 v151, v150, v99
	v_min_f32_e32 v99, v150, v99
	v_max_f32_e32 v252, v23, v16
	v_min_f32_e32 v16, v23, v16
	v_max_f32_e32 v112, v107, v11
	v_min_f32_e32 v11, v107, v11
	v_max_f32_e32 v147, v46, v34
	v_min_f32_e32 v34, v46, v34
	v_max_f32_e32 v253, v108, v113
	v_min_f32_e32 v113, v108, v113
	v_max_f32_e32 v4, v123, v5
	v_min_f32_e32 v5, v123, v5
	v_max_f32_e32 v31, v110, v98
	v_min_f32_e32 v98, v110, v98
	v_max_f32_e32 v105, v54, v15
	v_min_f32_e32 v15, v54, v15
	v_mov_b32_e32 v120, v151
	v_mov_b32_e32 v126, v99
	v_mov_b32_e32 v70, v252
	v_mov_b32_e32 v115, v16
	v_mov_b32_e32 v71, v112
	v_mov_b32_e32 v75, v11
	v_mov_b32_e32 v72, v147
	v_mov_b32_e32 v85, v34
	v_mov_b32_e32 v17, v253
	v_mov_b32_e32 v81, v113
	v_mov_b32_e32 v64, v4
	v_mov_b32_e32 v76, v5
	v_mov_b32_e32 v73, v31
	v_mov_b32_e32 v69, v98
	v_mov_b32_e32 v74, v105
	v_mov_b32_e32 v82, v15
	s_nop 1
	v_permlane32_swap_b32_e32 v151, v120
	v_permlane32_swap_b32_e32 v99, v126
	v_permlane32_swap_b32_e32 v252, v70
	v_permlane32_swap_b32_e32 v16, v115
	v_permlane32_swap_b32_e32 v112, v71
	v_permlane32_swap_b32_e32 v11, v75
	v_permlane32_swap_b32_e32 v147, v72
	v_permlane32_swap_b32_e32 v34, v85
	v_permlane32_swap_b32_e32 v253, v17
	v_permlane32_swap_b32_e32 v113, v81
	v_permlane32_swap_b32_e32 v4, v64
	v_permlane32_swap_b32_e32 v5, v76
	v_permlane32_swap_b32_e32 v31, v73
	v_permlane32_swap_b32_e32 v98, v69
	v_permlane32_swap_b32_e32 v105, v74
	v_permlane32_swap_b32_e32 v15, v82
	s_nop 1
	v_max_f32_e32 v151, v151, v82
	v_max_f32_e32 v99, v99, v74
	v_max_f32_e32 v252, v252, v69
	v_max_f32_e32 v16, v16, v73
	v_max_f32_e32 v112, v112, v76
	v_max_f32_e32 v11, v11, v64
	v_max_f32_e32 v147, v147, v81
	v_max_f32_e32 v34, v34, v17
	v_max_f32_e32 v253, v253, v85
	v_max_f32_e32 v113, v113, v72
	v_max_f32_e32 v4, v4, v75
	v_max_f32_e32 v5, v5, v71
	v_max_f32_e32 v31, v31, v115
	v_max_f32_e32 v98, v98, v70
	v_max_f32_e32 v105, v105, v126
	v_max_f32_e32 v15, v15, v120
	v_max_f32_e32 v78, v151, v253
	v_min_f32_e32 v253, v151, v253
	v_max_f32_e32 v91, v99, v113
	v_min_f32_e32 v113, v99, v113
	v_max_f32_e32 v26, v252, v4
	v_min_f32_e32 v4, v252, v4
	v_max_f32_e32 v3, v16, v5
	v_min_f32_e32 v5, v16, v5
	v_max_f32_e32 v28, v112, v31
	v_min_f32_e32 v31, v112, v31
	v_max_f32_e32 v111, v11, v98
	v_min_f32_e32 v98, v11, v98
	v_max_f32_e32 v119, v147, v105
	v_min_f32_e32 v105, v147, v105
	v_max_f32_e32 v90, v34, v15
	v_min_f32_e32 v15, v34, v15
	v_max_f32_e32 v30, v78, v28
	v_min_f32_e32 v28, v78, v28
	v_max_f32_e32 v87, v91, v111
	v_min_f32_e32 v111, v91, v111
	v_max_f32_e32 v93, v26, v119
	v_min_f32_e32 v119, v26, v119
	v_max_f32_e32 v49, v3, v90
	v_min_f32_e32 v90, v3, v90
	v_max_f32_e32 v7, v253, v31
	v_min_f32_e32 v31, v253, v31
	v_max_f32_e32 v51, v113, v98
	v_min_f32_e32 v98, v113, v98
	v_max_f32_e32 v104, v4, v105
	v_min_f32_e32 v105, v4, v105
	v_max_f32_e32 v37, v5, v15
	v_min_f32_e32 v15, v5, v15
	v_max_f32_e32 v124, v30, v93
	v_min_f32_e32 v93, v30, v93
	v_max_f32_e32 v117, v87, v49
	v_min_f32_e32 v49, v87, v49
	v_max_f32_e32 v25, v28, v119
	v_min_f32_e32 v119, v28, v119
	v_max_f32_e32 v43, v111, v90
	v_min_f32_e32 v90, v111, v90
	v_max_f32_e32 v77, v7, v104
	v_min_f32_e32 v104, v7, v104
	v_max_f32_e32 v24, v51, v37
	v_min_f32_e32 v37, v51, v37
	v_max_f32_e32 v79, v31, v105
	v_min_f32_e32 v105, v31, v105
	v_max_f32_e32 v67, v98, v15
	v_min_f32_e32 v15, v98, v15
	v_max_f32_e32 v125, v124, v117
	v_min_f32_e32 v117, v124, v117
	v_max_f32_e32 v102, v93, v49
	v_min_f32_e32 v49, v93, v49
	v_max_f32_e32 v22, v25, v43
	v_min_f32_e32 v43, v25, v43
	v_max_f32_e32 v96, v119, v90
	v_min_f32_e32 v90, v119, v90
	v_max_f32_e32 v66, v77, v24
	v_min_f32_e32 v24, v77, v24
	v_max_f32_e32 v36, v104, v37
	v_min_f32_e32 v37, v104, v37
	v_max_f32_e32 v63, v79, v67
	v_min_f32_e32 v67, v79, v67
	v_max_f32_e32 v21, v105, v15
	v_min_f32_e32 v15, v105, v15
	s_waitcnt vmcnt(0)
	v_pk_mul_f32 v[160:161], v[160:161], v[176:177]
	v_pk_mul_f32 v[162:163], v[162:163], v[178:179]
	v_pk_mul_f32 v[164:165], v[164:165], v[180:181]
	v_pk_mul_f32 v[166:167], v[166:167], v[182:183]
	v_pk_mul_f32 v[168:169], v[168:169], v[184:185]
	v_pk_mul_f32 v[170:171], v[170:171], v[186:187]
	v_pk_mul_f32 v[172:173], v[172:173], v[188:189]
	v_pk_mul_f32 v[174:175], v[174:175], v[190:191]
	v_max3_f32 v192, |v160|, |v161|, |v162|
	v_max3_f32 v192, |v163|, |v164|, v192
	v_max3_f32 v192, |v165|, |v166|, v192
	v_max3_f32 v192, |v167|, |v168|, v192
	v_max3_f32 v192, |v169|, |v170|, v192
	v_max3_f32 v192, |v171|, |v172|, v192
	v_max3_f32 v192, |v173|, |v174|, v192
	v_max_f32_e64 v192, |v175|, v192
	s_nop 1
	v_mov_b32_dpp v193, v192 quad_perm:[1,0,3,2] row_mask:0xf bank_mask:0xf bound_ctrl:1
	v_max_f32_e32 v192, v192, v193
	s_nop 1
	v_mov_b32_dpp v193, v192 quad_perm:[2,3,0,1] row_mask:0xf bank_mask:0xf bound_ctrl:1
	v_max_f32_e32 v192, v192, v193
	s_nop 1
	v_mov_b32_dpp v193, v192 row_half_mirror row_mask:0xf bank_mask:0xf bound_ctrl:1
	v_max_f32_e32 v192, v192, v193
	s_nop 1
	v_mov_b32_dpp v193, v192 row_mirror row_mask:0xf bank_mask:0xf bound_ctrl:1
	v_max_f32_e32 v192, v192, v193
	v_mov_b32_e32 v193, v192
	s_nop 1
	v_permlane16_swap_b32_e32 v192, v193
	s_nop 1
	v_max_f32_e32 v192, v192, v193
	v_mov_b32_e32 v193, v192
	s_nop 1
	v_permlane32_swap_b32_e32 v192, v193
	s_nop 1
	v_max_f32_e32 v192, v192, v193
	v_max_f32_e32 v192, 0xda24260, v192
	v_mul_f32_e32 v194, 0x3e2aaaab, v192
	global_store_dword v214, v194, s[12:13]
	v_div_scale_f32 v195, s[26:27], v194, v194, 1.0
	v_rcp_f32_e32 v196, v195
	v_div_scale_f32 v204, vcc, 1.0, v194, 1.0
	v_fma_f32 v205, -v195, v196, 1.0
	v_fmac_f32_e32 v196, v205, v196
	v_mul_f32_e32 v205, v204, v196
	v_fma_f32 v206, -v195, v205, v204
	v_fmac_f32_e32 v205, v206, v196
	v_fma_f32 v195, -v195, v205, v204
	s_nop 0
	v_div_fmas_f32 v195, v195, v196, v205
	v_div_fixup_f32 v207, v195, v194, 1.0
	v_mul_f32_e32 v160, v207, v160
	v_mul_f32_e32 v161, v207, v161
	v_mul_f32_e32 v162, v207, v162
	v_mul_f32_e32 v163, v207, v163
	v_mul_f32_e32 v164, v207, v164
	v_mul_f32_e32 v165, v207, v165
	v_mul_f32_e32 v166, v207, v166
	v_mul_f32_e32 v167, v207, v167
	v_mul_f32_e32 v168, v207, v168
	v_mul_f32_e32 v169, v207, v169
	v_mul_f32_e32 v170, v207, v170
	v_mul_f32_e32 v171, v207, v171
	v_mul_f32_e32 v172, v207, v172
	v_mul_f32_e32 v173, v207, v173
	v_mul_f32_e32 v174, v207, v174
	v_mul_f32_e32 v175, v207, v175
	v_mov_b32_e32 v208, 0
	v_mov_b32_e32 v209, 0
	v_mov_b32_e32 v210, 0
	v_mov_b32_e32 v193, 0
	v_cvt_scalef32_pk_fp4_f32 v208, v160, v161, 1.0
	v_cvt_scalef32_pk_fp4_f32 v209, v164, v165, 1.0
	v_cvt_scalef32_pk_fp4_f32 v210, v168, v169, 1.0
	v_cvt_scalef32_pk_fp4_f32 v193, v172, v173, 1.0
	v_cvt_scalef32_pk_fp4_f32 v208, v162, v163, 1.0 op_sel:[0,0,1,0]
	v_cvt_scalef32_pk_fp4_f32 v209, v166, v167, 1.0 op_sel:[0,0,1,0]
	v_cvt_scalef32_pk_fp4_f32 v210, v170, v171, 1.0 op_sel:[0,0,1,0]
	v_cvt_scalef32_pk_fp4_f32 v193, v174, v175, 1.0 op_sel:[0,0,1,0]
	global_store_short v213, v208, s[10:11] nt
	s_add_u32 s14, s10, 0x200000
	s_addc_u32 s15, s11, 0
	global_store_short v213, v209, s[14:15] nt
	s_add_u32 s14, s10, 0x400000
	s_addc_u32 s15, s11, 0
	global_store_short v213, v210, s[14:15] nt
	s_add_u32 s14, s10, 0x600000
	s_addc_u32 s15, s11, 0
	global_store_short v213, v193, s[14:15] nt
	s_add_u32 s10, s10, 0x20000
	s_addc_u32 s11, s11, 0
	s_add_u32 s12, s12, 0x2000
	s_addc_u32 s13, s13, 0
	global_load_dwordx4 v[160:163], v212, s[8:9] offset:0 nt
	global_load_dwordx4 v[164:167], v212, s[8:9] offset:1024 nt
	global_load_dwordx4 v[168:171], v212, s[8:9] offset:2048 nt
	global_load_dwordx4 v[172:175], v212, s[8:9] offset:3072 nt
	s_add_u32 s8, s8, 0x800000
	s_addc_u32 s9, s9, 0
	ds_write_b8 v240, v125 offset:512
	ds_write_b8 v240, v117 offset:513
	ds_write_b8 v240, v102 offset:514
	ds_write_b8 v240, v49 offset:515
	ds_write_b8 v240, v22 offset:516
	ds_write_b8 v240, v43 offset:517
	ds_write_b8 v240, v96 offset:518
	ds_write_b8 v240, v90 offset:519
	ds_write_b8 v240, v66 offset:520
	ds_write_b8 v240, v24 offset:521
	ds_write_b8 v240, v36 offset:522
	ds_write_b8 v240, v37 offset:523
	ds_write_b8 v240, v63 offset:524
	ds_write_b8 v240, v67 offset:525
	ds_write_b8 v240, v21 offset:526
	ds_write_b8 v240, v15 offset:527
	v_cndmask_b32_e64 v0, v128, v125, s[4:5]
	v_cndmask_b32_e64 v17, v125, v128, s[4:5]
	v_cndmask_b32_e64 v1, v129, v117, s[4:5]
	v_cndmask_b32_e64 v18, v117, v129, s[4:5]
	v_cndmask_b32_e64 v2, v130, v102, s[4:5]
	v_cndmask_b32_e64 v19, v102, v130, s[4:5]
	v_cndmask_b32_e64 v3, v131, v49, s[4:5]
	v_cndmask_b32_e64 v20, v49, v131, s[4:5]
	v_cndmask_b32_e64 v4, v132, v22, s[4:5]
	v_cndmask_b32_e64 v23, v22, v132, s[4:5]
	v_cndmask_b32_e64 v5, v133, v43, s[4:5]
	v_cndmask_b32_e64 v25, v43, v133, s[4:5]
	v_cndmask_b32_e64 v6, v134, v96, s[4:5]
	v_cndmask_b32_e64 v26, v96, v134, s[4:5]
	v_cndmask_b32_e64 v7, v135, v90, s[4:5]
	v_cndmask_b32_e64 v27, v90, v135, s[4:5]
	v_cndmask_b32_e64 v8, v136, v66, s[4:5]
	v_cndmask_b32_e64 v28, v66, v136, s[4:5]
	v_cndmask_b32_e64 v9, v137, v24, s[4:5]
	v_cndmask_b32_e64 v29, v24, v137, s[4:5]
	v_cndmask_b32_e64 v10, v138, v36, s[4:5]
	v_cndmask_b32_e64 v30, v36, v138, s[4:5]
	v_cndmask_b32_e64 v11, v139, v37, s[4:5]
	v_cndmask_b32_e64 v31, v37, v139, s[4:5]
	v_cndmask_b32_e64 v12, v140, v63, s[4:5]
	v_cndmask_b32_e64 v32, v63, v140, s[4:5]
	v_cndmask_b32_e64 v13, v141, v67, s[4:5]
	v_cndmask_b32_e64 v33, v67, v141, s[4:5]
	v_cndmask_b32_e64 v14, v142, v21, s[4:5]
	v_cndmask_b32_e64 v34, v21, v142, s[4:5]
	v_cndmask_b32_e64 v16, v143, v15, s[4:5]
	v_cndmask_b32_e64 v35, v15, v143, s[4:5]
	v_and_b32_e32 v0, s6, v0
	v_and_b32_e32 v17, s6, v17
	v_and_b32_e32 v1, s6, v1
	v_and_b32_e32 v18, s6, v18
	v_and_b32_e32 v2, s6, v2
	v_and_b32_e32 v19, s6, v19
	v_and_b32_e32 v3, s6, v3
	v_and_b32_e32 v20, s6, v20
	v_and_b32_e32 v4, s6, v4
	v_and_b32_e32 v23, s6, v23
	v_and_b32_e32 v5, s6, v5
	v_and_b32_e32 v25, s6, v25
	v_and_b32_e32 v6, s6, v6
	v_and_b32_e32 v26, s6, v26
	v_and_b32_e32 v7, s6, v7
	v_and_b32_e32 v27, s6, v27
	v_and_b32_e32 v8, s6, v8
	v_and_b32_e32 v28, s6, v28
	v_and_b32_e32 v9, s6, v9
	v_and_b32_e32 v29, s6, v29
	v_and_b32_e32 v10, s6, v10
	v_and_b32_e32 v30, s6, v30
	v_and_b32_e32 v11, s6, v11
	v_and_b32_e32 v31, s6, v31
	v_and_b32_e32 v12, s6, v12
	v_and_b32_e32 v32, s6, v32
	v_and_b32_e32 v13, s6, v13
	v_and_b32_e32 v33, s6, v33
	v_and_b32_e32 v14, s6, v14
	v_and_b32_e32 v34, s6, v34
	v_and_b32_e32 v16, s6, v16
	v_and_b32_e32 v35, s6, v35
	v_add_f32_e32 v38, v0, v18
	v_and_or_b32 v38, v38, s7, 0
	v_add_f32_e32 v39, v0, v19
	v_and_or_b32 v39, v39, s7, 2
	v_add_f32_e32 v40, v0, v20
	v_and_or_b32 v40, v40, s7, 4
	v_add_f32_e32 v41, v0, v23
	v_and_or_b32 v41, v41, s7, 6
	v_add_f32_e32 v42, v0, v25
	v_and_or_b32 v42, v42, s7, 8
	v_add_f32_e32 v44, v0, v26
	v_and_or_b32 v44, v44, s7, 10
	v_add_f32_e32 v45, v0, v27
	v_and_or_b32 v45, v45, s7, 12
	v_add_f32_e32 v46, v0, v28
	v_and_or_b32 v46, v46, s7, 14
	v_add_f32_e32 v47, v0, v29
	v_and_or_b32 v47, v47, s7, 16
	v_add_f32_e32 v48, v0, v30
	v_and_or_b32 v48, v48, s7, 18
	v_add_f32_e32 v50, v0, v31
	v_and_or_b32 v50, v50, s7, 20
	v_add_f32_e32 v51, v0, v32
	v_and_or_b32 v51, v51, s7, 22
	v_add_f32_e32 v52, v0, v33
	v_and_or_b32 v52, v52, s7, 24
	v_add_f32_e32 v53, v0, v34
	v_and_or_b32 v53, v53, s7, 26
	v_add_f32_e32 v54, v0, v35
	v_and_or_b32 v54, v54, s7, 28
	v_add_f32_e32 v55, v1, v19
	v_and_or_b32 v55, v55, s7, 30
	v_add_f32_e32 v56, v1, v20
	v_and_or_b32 v56, v56, s7, 32
	v_add_f32_e32 v57, v1, v23
	v_and_or_b32 v57, v57, s7, 34
	v_add_f32_e32 v58, v1, v25
	v_and_or_b32 v58, v58, s7, 36
	v_add_f32_e32 v59, v1, v26
	v_and_or_b32 v59, v59, s7, 38
	v_add_f32_e32 v60, v1, v27
	v_and_or_b32 v60, v60, s7, 40
	v_add_f32_e32 v61, v2, v20
	v_and_or_b32 v61, v61, s7, 42
	v_add_f32_e32 v62, v2, v23
	v_and_or_b32 v62, v62, s7, 44
	v_add_f32_e32 v64, v0, v17
	v_and_or_b32 v64, v64, s7, 46
	v_cndmask_b32_e64 v64, v64, v244, s[4:5]
	v_add_f32_e32 v65, v1, v18
	v_and_or_b32 v65, v65, s7, 48
	v_cndmask_b32_e64 v65, v65, v244, s[4:5]
	v_add_f32_e32 v68, v2, v19
	v_and_or_b32 v68, v68, s7, 50
	v_cndmask_b32_e64 v68, v68, v244, s[4:5]
	v_add_f32_e32 v69, v3, v20
	v_and_or_b32 v69, v69, s7, 52
	v_cndmask_b32_e64 v69, v69, v244, s[4:5]
	v_max_f32_e32 v70, v38, v53
	v_min_f32_e32 v53, v38, v53
	v_max_f32_e32 v71, v39, v52
	v_min_f32_e32 v52, v39, v52
	v_max_f32_e32 v72, v40, v55
	v_min_f32_e32 v55, v40, v55
	v_max_f32_e32 v73, v41, v54
	v_min_f32_e32 v54, v41, v54
	v_max_f32_e32 v74, v42, v47
	v_min_f32_e32 v47, v42, v47
	v_max_f32_e32 v75, v44, v45
	v_min_f32_e32 v45, v44, v45
	v_max_f32_e32 v76, v46, v51
	v_min_f32_e32 v51, v46, v51
	v_max_f32_e32 v77, v48, v50
	v_min_f32_e32 v50, v48, v50
	v_max_f32_e32 v78, v70, v75
	v_min_f32_e32 v75, v70, v75
	v_max_f32_e32 v79, v71, v76
	v_min_f32_e32 v76, v71, v76
	v_max_f32_e32 v80, v72, v77
	v_min_f32_e32 v77, v72, v77
	v_max_f32_e32 v81, v73, v74
	v_min_f32_e32 v74, v73, v74
	v_max_f32_e32 v82, v45, v53
	v_min_f32_e32 v53, v45, v53
	v_max_f32_e32 v83, v47, v54
	v_min_f32_e32 v54, v47, v54
	v_max_f32_e32 v84, v50, v55
	v_min_f32_e32 v55, v50, v55
	v_max_f32_e32 v85, v51, v52
	v_min_f32_e32 v52, v51, v52
	v_max_f32_e32 v86, v78, v79
	v_min_f32_e32 v79, v78, v79
	v_max_f32_e32 v87, v80, v81
	v_min_f32_e32 v81, v80, v81
	v_max_f32_e32 v88, v74, v75
	v_min_f32_e32 v75, v74, v75
	v_max_f32_e32 v89, v82, v83
	v_min_f32_e32 v83, v82, v83
	v_max_f32_e32 v91, v76, v77
	v_min_f32_e32 v77, v76, v77
	v_max_f32_e32 v92, v84, v85
	v_min_f32_e32 v85, v84, v85
	v_max_f32_e32 v93, v52, v53
	v_min_f32_e32 v53, v52, v53
	v_max_f32_e32 v94, v54, v55
	v_min_f32_e32 v55, v54, v55
	v_max_f32_e32 v95, v86, v87
	v_min_f32_e32 v87, v86, v87
	v_max_f32_e32 v97, v79, v81
	v_min_f32_e32 v81, v79, v81
	v_max_f32_e32 v98, v88, v92
	v_min_f32_e32 v92, v88, v92
	v_max_f32_e32 v99, v75, v85
	v_min_f32_e32 v85, v75, v85
	v_max_f32_e32 v100, v89, v91
	v_min_f32_e32 v91, v89, v91
	v_max_f32_e32 v101, v83, v77
	v_min_f32_e32 v77, v83, v77
	v_max_f32_e32 v103, v93, v94
	v_min_f32_e32 v94, v93, v94
	v_max_f32_e32 v104, v53, v55
	v_min_f32_e32 v55, v53, v55
	v_max_f32_e32 v105, v97, v87
	v_min_f32_e32 v87, v97, v87
	v_max_f32_e32 v106, v81, v103
	v_min_f32_e32 v103, v81, v103
	v_max_f32_e32 v107, v98, v100
	v_min_f32_e32 v100, v98, v100
	v_max_f32_e32 v108, v99, v91
	v_min_f32_e32 v91, v99, v91
	v_max_f32_e32 v109, v101, v92
	v_min_f32_e32 v92, v101, v92
	v_max_f32_e32 v110, v77, v85
	v_min_f32_e32 v85, v77, v85
	v_max_f32_e32 v111, v104, v94
	v_min_f32_e32 v94, v104, v94
	v_max_f32_e32 v112, v105, v107
	v_min_f32_e32 v107, v105, v107
	v_max_f32_e32 v113, v87, v100
	v_min_f32_e32 v100, v87, v100
	v_max_f32_e32 v114, v108, v109
	v_min_f32_e32 v109, v108, v109
	v_max_f32_e32 v115, v91, v92
	v_min_f32_e32 v92, v91, v92
	v_max_f32_e32 v116, v110, v111
	v_min_f32_e32 v111, v110, v111
	v_max_f32_e32 v118, v85, v94
	v_min_f32_e32 v94, v85, v94
	v_max_f32_e32 v119, v113, v107
	v_min_f32_e32 v107, v113, v107
	v_max_f32_e32 v120, v106, v100
	v_min_f32_e32 v100, v106, v100
	v_max_f32_e32 v121, v116, v103
	v_min_f32_e32 v103, v116, v103
	v_max_f32_e32 v122, v118, v111
	v_min_f32_e32 v111, v118, v111
	v_max_f32_e32 v123, v120, v114
	v_min_f32_e32 v114, v120, v114
	v_max_f32_e32 v124, v100, v109
	v_min_f32_e32 v109, v100, v109
	v_max_f32_e32 v126, v115, v121
	v_min_f32_e32 v121, v115, v121
	v_max_f32_e32 v127, v92, v103
	v_min_f32_e32 v103, v92, v103
	v_max_f32_e32 v144, v123, v107
	v_min_f32_e32 v107, v123, v107
	v_max_f32_e32 v145, v114, v124
	v_min_f32_e32 v124, v114, v124
	v_max_f32_e32 v146, v126, v109
	v_min_f32_e32 v109, v126, v109
	v_max_f32_e32 v147, v121, v127
	v_min_f32_e32 v127, v121, v127
	v_max_f32_e32 v148, v122, v103
	v_min_f32_e32 v103, v122, v103
	v_max_f32_e32 v149, v124, v146
	v_min_f32_e32 v146, v124, v146
	v_max_f32_e32 v150, v109, v147
	v_min_f32_e32 v147, v109, v147
	v_max_f32_e32 v151, v60, v65
	v_min_f32_e32 v65, v60, v65
	v_max_f32_e32 v249, v61, v62
	v_min_f32_e32 v62, v61, v62
	v_max_f32_e32 v250, v68, v69
	v_min_f32_e32 v69, v68, v69
	v_max_f32_e32 v251, v56, v249
	v_min_f32_e32 v249, v56, v249
	v_max_f32_e32 v252, v57, v64
	v_min_f32_e32 v64, v57, v64
	v_max_f32_e32 v253, v58, v250
	v_min_f32_e32 v250, v58, v250
	v_max_f32_e32 v254, v59, v151
	v_min_f32_e32 v151, v59, v151
	v_max_f32_e32 v255, v251, v252
	v_min_f32_e32 v252, v251, v252
	v_max_f32_e32 v128, v253, v254
	v_min_f32_e32 v254, v253, v254
	v_max_f32_e32 v129, v151, v249
	v_min_f32_e32 v249, v151, v249
	v_max_f32_e32 v130, v62, v65
	v_min_f32_e32 v65, v62, v65
	v_max_f32_e32 v131, v64, v250
	v_min_f32_e32 v250, v64, v250
	v_max_f32_e32 v132, v255, v128
	v_min_f32_e32 v128, v255, v128
	v_max_f32_e32 v133, v252, v254
	v_min_f32_e32 v254, v252, v254
	v_max_f32_e32 v134, v129, v69
	v_min_f32_e32 v69, v129, v69
	v_max_f32_e32 v135, v130, v131
	v_min_f32_e32 v131, v130, v131
	v_max_f32_e32 v136, v65, v250
	v_min_f32_e32 v250, v65, v250
	v_max_f32_e32 v137, v133, v128
	v_min_f32_e32 v128, v133, v128
	v_max_f32_e32 v138, v134, v135
	v_min_f32_e32 v135, v134, v135
	v_max_f32_e32 v139, v249, v131
	v_min_f32_e32 v131, v249, v131
	v_max_f32_e32 v140, v136, v69
	v_min_f32_e32 v69, v136, v69
	v_max_f32_e32 v141, v137, v138
	v_min_f32_e32 v138, v137, v138
	v_max_f32_e32 v142, v128, v135
	v_min_f32_e32 v135, v128, v135
	v_max_f32_e32 v143, v139, v140
	v_min_f32_e32 v140, v139, v140
	v_max_f32_e32 v125, v131, v69
	v_min_f32_e32 v69, v131, v69
	v_max_f32_e32 v117, v142, v138
	v_min_f32_e32 v138, v142, v138
	v_max_f32_e32 v102, v254, v135
	v_min_f32_e32 v135, v254, v135
	v_max_f32_e32 v49, v102, v143
	v_min_f32_e32 v143, v102, v143
	v_max_f32_e32 v22, v135, v140
	v_min_f32_e32 v140, v135, v140
	v_max_f32_e32 v43, v125, v250
	v_min_f32_e32 v250, v125, v250
	v_max_f32_e32 v96, v49, v138
	v_min_f32_e32 v138, v49, v138
	v_max_f32_e32 v90, v143, v22
	v_min_f32_e32 v22, v143, v22
	v_max_f32_e32 v66, v43, v140
	v_min_f32_e32 v140, v43, v140
	v_max_f32_e32 v24, v250, v69
	v_min_f32_e32 v69, v250, v69
	v_max_f32_e32 v36, v22, v66
	v_min_f32_e32 v66, v22, v66
	v_max_f32_e32 v37, v140, v24
	v_min_f32_e32 v24, v140, v24
	s_waitcnt vmcnt(0)
	v_pk_mul_f32 v[160:161], v[160:161], v[176:177]
	v_pk_mul_f32 v[162:163], v[162:163], v[178:179]
	v_pk_mul_f32 v[164:165], v[164:165], v[180:181]
	v_pk_mul_f32 v[166:167], v[166:167], v[182:183]
	v_pk_mul_f32 v[168:169], v[168:169], v[184:185]
	v_pk_mul_f32 v[170:171], v[170:171], v[186:187]
	v_pk_mul_f32 v[172:173], v[172:173], v[188:189]
	v_pk_mul_f32 v[174:175], v[174:175], v[190:191]
	v_max3_f32 v192, |v160|, |v161|, |v162|
	v_max3_f32 v192, |v163|, |v164|, v192
	v_max3_f32 v192, |v165|, |v166|, v192
	v_max3_f32 v192, |v167|, |v168|, v192
	v_max3_f32 v192, |v169|, |v170|, v192
	v_max3_f32 v192, |v171|, |v172|, v192
	v_max3_f32 v192, |v173|, |v174|, v192
	v_max_f32_e64 v192, |v175|, v192
	s_nop 1
	v_mov_b32_dpp v193, v192 quad_perm:[1,0,3,2] row_mask:0xf bank_mask:0xf bound_ctrl:1
	v_max_f32_e32 v192, v192, v193
	s_nop 1
	v_mov_b32_dpp v193, v192 quad_perm:[2,3,0,1] row_mask:0xf bank_mask:0xf bound_ctrl:1
	v_max_f32_e32 v192, v192, v193
	s_nop 1
	v_mov_b32_dpp v193, v192 row_half_mirror row_mask:0xf bank_mask:0xf bound_ctrl:1
	v_max_f32_e32 v192, v192, v193
	s_nop 1
	v_mov_b32_dpp v193, v192 row_mirror row_mask:0xf bank_mask:0xf bound_ctrl:1
	v_max_f32_e32 v192, v192, v193
	v_mov_b32_e32 v193, v192
	s_nop 1
	v_permlane16_swap_b32_e32 v192, v193
	s_nop 1
	v_max_f32_e32 v192, v192, v193
	v_mov_b32_e32 v193, v192
	s_nop 1
	v_permlane32_swap_b32_e32 v192, v193
	s_nop 1
	v_max_f32_e32 v192, v192, v193
	v_max_f32_e32 v192, 0xda24260, v192
	v_mul_f32_e32 v194, 0x3e2aaaab, v192
	global_store_dword v214, v194, s[12:13]
	v_div_scale_f32 v195, s[26:27], v194, v194, 1.0
	v_rcp_f32_e32 v196, v195
	v_div_scale_f32 v204, vcc, 1.0, v194, 1.0
	v_fma_f32 v205, -v195, v196, 1.0
	v_fmac_f32_e32 v196, v205, v196
	v_mul_f32_e32 v205, v204, v196
	v_fma_f32 v206, -v195, v205, v204
	v_fmac_f32_e32 v205, v206, v196
	v_fma_f32 v195, -v195, v205, v204
	s_nop 0
	v_div_fmas_f32 v195, v195, v196, v205
	v_div_fixup_f32 v207, v195, v194, 1.0
	v_mul_f32_e32 v160, v207, v160
	v_mul_f32_e32 v161, v207, v161
	v_mul_f32_e32 v162, v207, v162
	v_mul_f32_e32 v163, v207, v163
	v_mul_f32_e32 v164, v207, v164
	v_mul_f32_e32 v165, v207, v165
	v_mul_f32_e32 v166, v207, v166
	v_mul_f32_e32 v167, v207, v167
	v_mul_f32_e32 v168, v207, v168
	v_mul_f32_e32 v169, v207, v169
	v_mul_f32_e32 v170, v207, v170
	v_mul_f32_e32 v171, v207, v171
	v_mul_f32_e32 v172, v207, v172
	v_mul_f32_e32 v173, v207, v173
	v_mul_f32_e32 v174, v207, v174
	v_mul_f32_e32 v175, v207, v175
	v_mov_b32_e32 v208, 0
	v_mov_b32_e32 v209, 0
	v_mov_b32_e32 v210, 0
	v_mov_b32_e32 v193, 0
	v_cvt_scalef32_pk_fp4_f32 v208, v160, v161, 1.0
	v_cvt_scalef32_pk_fp4_f32 v209, v164, v165, 1.0
	v_cvt_scalef32_pk_fp4_f32 v210, v168, v169, 1.0
	v_cvt_scalef32_pk_fp4_f32 v193, v172, v173, 1.0
	v_cvt_scalef32_pk_fp4_f32 v208, v162, v163, 1.0 op_sel:[0,0,1,0]
	v_cvt_scalef32_pk_fp4_f32 v209, v166, v167, 1.0 op_sel:[0,0,1,0]
	v_cvt_scalef32_pk_fp4_f32 v210, v170, v171, 1.0 op_sel:[0,0,1,0]
	v_cvt_scalef32_pk_fp4_f32 v193, v174, v175, 1.0 op_sel:[0,0,1,0]
	global_store_short v213, v208, s[10:11] nt
	s_add_u32 s14, s10, 0x200000
	s_addc_u32 s15, s11, 0
	global_store_short v213, v209, s[14:15] nt
	s_add_u32 s14, s10, 0x400000
	s_addc_u32 s15, s11, 0
	global_store_short v213, v210, s[14:15] nt
	s_add_u32 s14, s10, 0x600000
	s_addc_u32 s15, s11, 0
	global_store_short v213, v193, s[14:15] nt
	s_add_u32 s10, s10, 0x20000
	s_addc_u32 s11, s11, 0
	s_add_u32 s12, s12, 0x2000
	s_addc_u32 s13, s13, 0
	global_load_dwordx4 v[160:163], v212, s[8:9] offset:0 nt
	global_load_dwordx4 v[164:167], v212, s[8:9] offset:1024 nt
	global_load_dwordx4 v[168:171], v212, s[8:9] offset:2048 nt
	global_load_dwordx4 v[172:175], v212, s[8:9] offset:3072 nt
	s_add_u32 s8, s8, 0x800000
	s_addc_u32 s9, s9, 0
	v_max_f32_e32 v145, v145, v69
	v_max_f32_e32 v149, v149, v24
	v_max_f32_e32 v146, v146, v37
	v_max_f32_e32 v150, v150, v66
	v_max_f32_e32 v147, v147, v36
	v_max_f32_e32 v127, v127, v90
	v_max_f32_e32 v148, v148, v138
	v_max_f32_e32 v103, v103, v96
	v_max_f32_e32 v111, v111, v117
	v_max_f32_e32 v94, v94, v141
	v_max_f32_e32 v55, v55, v132
	v_max_f32_e32 v63, v95, v150
	v_min_f32_e32 v150, v95, v150
	v_max_f32_e32 v67, v112, v147
	v_min_f32_e32 v147, v112, v147
	v_max_f32_e32 v21, v119, v127
	v_min_f32_e32 v127, v119, v127
	v_max_f32_e32 v15, v144, v148
	v_min_f32_e32 v148, v144, v148
	v_max_f32_e32 v0, v107, v103
	v_min_f32_e32 v103, v107, v103
	v_max_f32_e32 v1, v145, v111
	v_min_f32_e32 v111, v145, v111
	v_max_f32_e32 v2, v149, v94
	v_min_f32_e32 v94, v149, v94
	v_max_f32_e32 v3, v146, v55
	v_min_f32_e32 v55, v146, v55
	v_max_f32_e32 v4, v63, v0
	v_min_f32_e32 v0, v63, v0
	v_max_f32_e32 v5, v67, v1
	v_min_f32_e32 v1, v67, v1
	v_max_f32_e32 v6, v21, v2
	v_min_f32_e32 v2, v21, v2
	v_max_f32_e32 v7, v15, v3
	v_min_f32_e32 v3, v15, v3
	v_max_f32_e32 v8, v150, v103
	v_min_f32_e32 v103, v150, v103
	v_max_f32_e32 v9, v147, v111
	v_min_f32_e32 v111, v147, v111
	v_max_f32_e32 v10, v127, v94
	v_min_f32_e32 v94, v127, v94
	v_max_f32_e32 v11, v148, v55
	v_min_f32_e32 v55, v148, v55
	v_max_f32_e32 v12, v4, v6
	v_min_f32_e32 v6, v4, v6
	v_max_f32_e32 v13, v5, v7
	v_min_f32_e32 v7, v5, v7
	v_max_f32_e32 v14, v0, v2
	v_min_f32_e32 v2, v0, v2
	v_max_f32_e32 v16, v1, v3
	v_min_f32_e32 v3, v1, v3
	v_max_f32_e32 v17, v8, v10
	v_min_f32_e32 v10, v8, v10
	v_max_f32_e32 v18, v9, v11
	v_min_f32_e32 v11, v9, v11
	v_max_f32_e32 v19, v103, v94
	v_min_f32_e32 v94, v103, v94
	v_max_f32_e32 v20, v111, v55
	v_min_f32_e32 v55, v111, v55
	v_max_f32_e32 v23, v12, v13
	v_min_f32_e32 v13, v12, v13
	v_max_f32_e32 v25, v6, v7
	v_min_f32_e32 v7, v6, v7
	v_max_f32_e32 v26, v14, v16
	v_min_f32_e32 v16, v14, v16
	v_max_f32_e32 v27, v2, v3
	v_min_f32_e32 v3, v2, v3
	v_max_f32_e32 v28, v17, v18
	v_min_f32_e32 v18, v17, v18
	v_max_f32_e32 v29, v10, v11
	v_min_f32_e32 v11, v10, v11
	v_max_f32_e32 v30, v19, v20
	v_min_f32_e32 v20, v19, v20
	v_max_f32_e32 v31, v94, v55
	v_min_f32_e32 v55, v94, v55
	v_or_b32_e32 v23, v23, v245
	v_or_b32_e32 v13, v13, v245
	v_or_b32_e32 v25, v25, v245
	v_or_b32_e32 v7, v7, v245
	v_or_b32_e32 v26, v26, v245
	v_or_b32_e32 v16, v16, v245
	v_or_b32_e32 v27, v27, v245
	v_or_b32_e32 v3, v3, v245
	v_or_b32_e32 v28, v28, v245
	v_or_b32_e32 v18, v18, v245
	v_or_b32_e32 v29, v29, v245
	v_or_b32_e32 v11, v11, v245
	v_or_b32_e32 v30, v30, v245
	v_or_b32_e32 v20, v20, v245
	v_or_b32_e32 v31, v31, v245
	v_or_b32_e32 v55, v55, v245
	v_mov_b32_e32 v32, v23
	v_mov_b32_e32 v33, v13
	v_mov_b32_e32 v34, v25
	v_mov_b32_e32 v35, v7
	v_mov_b32_e32 v38, v26
	v_mov_b32_e32 v39, v16
	v_mov_b32_e32 v40, v27
	v_mov_b32_e32 v41, v3
	v_mov_b32_e32 v42, v28
	v_mov_b32_e32 v44, v18
	v_mov_b32_e32 v46, v29
	v_mov_b32_e32 v48, v11
	v_mov_b32_e32 v70, v30
	v_mov_b32_e32 v71, v20
	v_mov_b32_e32 v72, v31
	v_mov_b32_e32 v73, v55
	s_nop 1
	v_permlane32_swap_b32_e32 v23, v32
	v_permlane32_swap_b32_e32 v13, v33
	v_permlane32_swap_b32_e32 v25, v34
	v_permlane32_swap_b32_e32 v7, v35
	v_permlane32_swap_b32_e32 v26, v38
	v_permlane32_swap_b32_e32 v16, v39
	v_permlane32_swap_b32_e32 v27, v40
	v_permlane32_swap_b32_e32 v3, v41
	v_permlane32_swap_b32_e32 v28, v42
	v_permlane32_swap_b32_e32 v18, v44
	v_permlane32_swap_b32_e32 v29, v46
	v_permlane32_swap_b32_e32 v11, v48
	v_permlane32_swap_b32_e32 v30, v70
	v_permlane32_swap_b32_e32 v20, v71
	v_permlane32_swap_b32_e32 v31, v72
	v_permlane32_swap_b32_e32 v55, v73
	s_nop 1
	v_max_f32_e32 v23, v23, v73
	v_max_f32_e32 v13, v13, v72
	v_max_f32_e32 v25, v25, v71
	v_max_f32_e32 v7, v7, v70
	v_max_f32_e32 v26, v26, v48
	v_max_f32_e32 v16, v16, v46
	v_max_f32_e32 v27, v27, v44
	v_max_f32_e32 v3, v3, v42
	v_max_f32_e32 v28, v28, v41
	v_max_f32_e32 v18, v18, v40
	v_max_f32_e32 v29, v29, v39
	v_max_f32_e32 v11, v11, v38
	v_max_f32_e32 v30, v30, v35
	v_max_f32_e32 v20, v20, v34
	v_max_f32_e32 v31, v31, v33
	v_max_f32_e32 v55, v55, v32
	v_max_f32_e32 v45, v23, v28
	v_min_f32_e32 v28, v23, v28
	v_max_f32_e32 v47, v13, v18
	v_min_f32_e32 v18, v13, v18
	v_max_f32_e32 v50, v25, v29
	v_min_f32_e32 v29, v25, v29
	v_max_f32_e32 v51, v7, v11
	v_min_f32_e32 v11, v7, v11
	v_max_f32_e32 v78, v26, v30
	v_min_f32_e32 v30, v26, v30
	v_max_f32_e32 v80, v16, v20
	v_min_f32_e32 v20, v16, v20
	v_max_f32_e32 v74, v27, v31
	v_min_f32_e32 v31, v27, v31
	v_max_f32_e32 v82, v3, v55
	v_min_f32_e32 v55, v3, v55
	v_max_f32_e32 v76, v45, v78
	v_min_f32_e32 v78, v45, v78
	v_max_f32_e32 v84, v47, v80
	v_min_f32_e32 v80, v47, v80
	v_max_f32_e32 v52, v50, v74
	v_min_f32_e32 v74, v50, v74
	v_max_f32_e32 v54, v51, v82
	v_min_f32_e32 v82, v51, v82
	v_max_f32_e32 v86, v28, v30
	v_min_f32_e32 v30, v28, v30
	v_max_f32_e32 v79, v18, v20
	v_min_f32_e32 v20, v18, v20
	v_max_f32_e32 v88, v29, v31
	v_min_f32_e32 v31, v29, v31
	v_max_f32_e32 v75, v11, v55
	v_min_f32_e32 v55, v11, v55
	v_max_f32_e32 v89, v76, v52
	v_min_f32_e32 v52, v76, v52
	v_max_f32_e32 v83, v84, v54
	v_min_f32_e32 v54, v84, v54
	v_max_f32_e32 v93, v78, v74
	v_min_f32_e32 v74, v78, v74
	v_max_f32_e32 v53, v80, v82
	v_min_f32_e32 v82, v80, v82
	v_max_f32_e32 v97, v86, v88
	v_min_f32_e32 v88, v86, v88
	v_max_f32_e32 v81, v79, v75
	v_min_f32_e32 v75, v79, v75
	v_max_f32_e32 v98, v30, v31
	v_min_f32_e32 v31, v30, v31
	v_max_f32_e32 v99, v20, v55
	v_min_f32_e32 v55, v20, v55
	v_max_f32_e32 v101, v89, v83
	v_min_f32_e32 v83, v89, v83
	v_max_f32_e32 v77, v52, v54
	v_min_f32_e32 v54, v52, v54
	v_max_f32_e32 v104, v93, v53
	v_min_f32_e32 v53, v93, v53
	v_max_f32_e32 v105, v74, v82
	v_min_f32_e32 v82, v74, v82
	v_max_f32_e32 v87, v97, v81
	v_min_f32_e32 v81, v97, v81
	v_max_f32_e32 v108, v88, v75
	v_min_f32_e32 v75, v88, v75
	v_max_f32_e32 v91, v98, v99
	v_min_f32_e32 v99, v98, v99
	v_max_f32_e32 v110, v31, v55
	v_min_f32_e32 v55, v31, v55
	v_and_b32_e32 v85, s7, v101
	v_cndmask_b32_e64 v113, v101, v87, s[4:5]
	v_cndmask_b32_e64 v106, v83, v81, s[4:5]
	v_cndmask_b32_e64 v116, v77, v108, s[4:5]
	v_cndmask_b32_e64 v118, v54, v75, s[4:5]
	v_cndmask_b32_e64 v120, v104, v91, s[4:5]
	v_cndmask_b32_e64 v100, v53, v99, s[4:5]
	v_cndmask_b32_e64 v115, v105, v110, s[4:5]
	v_cndmask_b32_e64 v92, v82, v55, s[4:5]
	v_and_or_b32 v123, v113, 63, v246
	ds_read_u8 v123, v123
	v_and_or_b32 v114, v106, 63, v246
	ds_read_u8 v114, v114
	v_and_or_b32 v126, v116, 63, v246
	ds_read_u8 v126, v126
	v_and_or_b32 v121, v118, 63, v246
	ds_read_u8 v121, v121
	v_and_or_b32 v122, v120, 63, v246
	ds_read_u8 v122, v122
	v_and_or_b32 v124, v100, 63, v246
	ds_read_u8 v124, v124
	v_and_or_b32 v109, v115, 63, v246
	ds_read_u8 v109, v109
	v_and_or_b32 v60, v92, 63, v246
	ds_read_u8 v60, v60
	v_and_b32_e32 v113, s7, v113
	v_sub_f32_e32 v113, v113, v85
	v_mul_f32_e32 v113, 0x3fb8aa3b, v113
	v_exp_f32_e32 v113, v113
	v_and_b32_e32 v106, s7, v106
	v_sub_f32_e32 v106, v106, v85
	v_mul_f32_e32 v106, 0x3fb8aa3b, v106
	v_exp_f32_e32 v106, v106
	v_and_b32_e32 v116, s7, v116
	v_sub_f32_e32 v116, v116, v85
	v_mul_f32_e32 v116, 0x3fb8aa3b, v116
	v_exp_f32_e32 v116, v116
	v_and_b32_e32 v118, s7, v118
	v_sub_f32_e32 v118, v118, v85
	v_mul_f32_e32 v118, 0x3fb8aa3b, v118
	v_exp_f32_e32 v118, v118
	v_and_b32_e32 v120, s7, v120
	v_sub_f32_e32 v120, v120, v85
	v_mul_f32_e32 v120, 0x3fb8aa3b, v120
	v_exp_f32_e32 v120, v120
	v_and_b32_e32 v100, s7, v100
	v_sub_f32_e32 v100, v100, v85
	v_mul_f32_e32 v100, 0x3fb8aa3b, v100
	v_exp_f32_e32 v100, v100
	v_and_b32_e32 v115, s7, v115
	v_sub_f32_e32 v115, v115, v85
	v_mul_f32_e32 v115, 0x3fb8aa3b, v115
	v_exp_f32_e32 v115, v115
	v_and_b32_e32 v92, s7, v92
	v_sub_f32_e32 v92, v92, v85
	v_mul_f32_e32 v92, 0x3fb8aa3b, v92
	v_exp_f32_e32 v92, v92
	s_nop 0
	v_add_f32_e32 v85, v113, v106
	v_add_f32_e32 v85, v85, v116
	v_add_f32_e32 v85, v85, v118
	v_add_f32_e32 v85, v85, v120
	v_add_f32_e32 v85, v85, v100
	v_add_f32_e32 v85, v85, v115
	v_add_f32_e32 v85, v85, v92
	v_mov_b32_e32 v61, v85
	s_nop 1
	v_permlane32_swap_b32_e32 v85, v61
	s_nop 1
	v_add_f32_e32 v85, v85, v61
	s_waitcnt lgkmcnt(0)
	v_bfe_u32 v68, v123, 4, 4
	v_or_b32_e32 v68, v68, v240
	v_and_or_b32 v123, v123, 15, v240
	ds_read_u8 v68, v68
	ds_read_u8 v123, v123 offset:512
	v_bfe_u32 v56, v114, 4, 4
	v_or_b32_e32 v56, v56, v240
	v_and_or_b32 v114, v114, 15, v240
	ds_read_u8 v56, v56
	ds_read_u8 v114, v114 offset:512
	v_bfe_u32 v57, v126, 4, 4
	v_or_b32_e32 v57, v57, v240
	v_and_or_b32 v126, v126, 15, v240
	ds_read_u8 v57, v57
	ds_read_u8 v126, v126 offset:512
	v_bfe_u32 v58, v121, 4, 4
	v_or_b32_e32 v58, v58, v240
	v_and_or_b32 v121, v121, 15, v240
	ds_read_u8 v58, v58
	ds_read_u8 v121, v121 offset:512
	v_bfe_u32 v59, v122, 4, 4
	v_or_b32_e32 v59, v59, v240
	v_and_or_b32 v122, v122, 15, v240
	ds_read_u8 v59, v59
	ds_read_u8 v122, v122 offset:512
	v_bfe_u32 v251, v124, 4, 4
	v_or_b32_e32 v251, v251, v240
	v_and_or_b32 v124, v124, 15, v240
	ds_read_u8 v251, v251
	ds_read_u8 v124, v124 offset:512
	v_bfe_u32 v253, v109, 4, 4
	v_or_b32_e32 v253, v253, v240
	v_and_or_b32 v109, v109, 15, v240
	ds_read_u8 v253, v253
	ds_read_u8 v109, v109 offset:512
	v_bfe_u32 v151, v60, 4, 4
	v_or_b32_e32 v151, v151, v240
	v_and_or_b32 v60, v60, 15, v240
	ds_read_u8 v151, v151
	ds_read_u8 v60, v60 offset:512
	v_div_scale_f32 v134, s[26:27], v85, v85, v113
	v_rcp_f32_e32 v249, v134
	s_nop 0
	v_fma_f32 v136, -v134, v249, 1.0
	v_fmac_f32_e32 v249, v136, v249
	v_div_scale_f32 v136, vcc, v113, v85, v113
	v_mul_f32_e32 v137, v136, v249
	v_fma_f32 v62, -v134, v137, v136
	v_fmac_f32_e32 v137, v62, v249
	v_fma_f32 v136, -v134, v137, v136
	s_nop 0
	v_div_fmas_f32 v136, v136, v249, v137
	v_div_fixup_f32 v62, v136, v85, v113
	v_div_scale_f32 v134, s[26:27], v85, v85, v106
	v_rcp_f32_e32 v249, v134
	s_nop 0
	v_fma_f32 v136, -v134, v249, 1.0
	v_fmac_f32_e32 v249, v136, v249
	v_div_scale_f32 v136, vcc, v106, v85, v106
	v_mul_f32_e32 v137, v136, v249
	v_fma_f32 v64, -v134, v137, v136
	v_fmac_f32_e32 v137, v64, v249
	v_fma_f32 v136, -v134, v137, v136
	s_nop 0
	v_div_fmas_f32 v136, v136, v249, v137
	v_div_fixup_f32 v64, v136, v85, v106
	v_div_scale_f32 v134, s[26:27], v85, v85, v116
	v_rcp_f32_e32 v249, v134
	s_nop 0
	v_fma_f32 v136, -v134, v249, 1.0
	v_fmac_f32_e32 v249, v136, v249
	v_div_scale_f32 v136, vcc, v116, v85, v116
	v_mul_f32_e32 v137, v136, v249
	v_fma_f32 v255, -v134, v137, v136
	v_fmac_f32_e32 v137, v255, v249
	v_fma_f32 v136, -v134, v137, v136
	s_nop 0
	v_div_fmas_f32 v136, v136, v249, v137
	v_div_fixup_f32 v255, v136, v85, v116
	v_div_scale_f32 v134, s[26:27], v85, v85, v118
	v_rcp_f32_e32 v249, v134
	s_nop 0
	v_fma_f32 v136, -v134, v249, 1.0
	v_fmac_f32_e32 v249, v136, v249
	v_div_scale_f32 v136, vcc, v118, v85, v118
	v_mul_f32_e32 v137, v136, v249
	v_fma_f32 v252, -v134, v137, v136
	v_fmac_f32_e32 v137, v252, v249
	v_fma_f32 v136, -v134, v137, v136
	s_nop 0
	v_div_fmas_f32 v136, v136, v249, v137
	v_div_fixup_f32 v252, v136, v85, v118
	v_div_scale_f32 v134, s[26:27], v85, v85, v120
	v_rcp_f32_e32 v249, v134
	s_nop 0
	v_fma_f32 v136, -v134, v249, 1.0
	v_fmac_f32_e32 v249, v136, v249
	v_div_scale_f32 v136, vcc, v120, v85, v120
	v_mul_f32_e32 v137, v136, v249
	v_fma_f32 v129, -v134, v137, v136
	v_fmac_f32_e32 v137, v129, v249
	v_fma_f32 v136, -v134, v137, v136
	s_nop 0
	v_div_fmas_f32 v136, v136, v249, v137
	v_div_fixup_f32 v129, v136, v85, v120
	v_div_scale_f32 v134, s[26:27], v85, v85, v100
	v_rcp_f32_e32 v249, v134
	s_nop 0
	v_fma_f32 v136, -v134, v249, 1.0
	v_fmac_f32_e32 v249, v136, v249
	v_div_scale_f32 v136, vcc, v100, v85, v100
	v_mul_f32_e32 v137, v136, v249
	v_fma_f32 v130, -v134, v137, v136
	v_fmac_f32_e32 v137, v130, v249
	v_fma_f32 v136, -v134, v137, v136
	s_nop 0
	v_div_fmas_f32 v136, v136, v249, v137
	v_div_fixup_f32 v130, v136, v85, v100
	v_div_scale_f32 v134, s[26:27], v85, v85, v115
	v_rcp_f32_e32 v249, v134
	s_nop 0
	v_fma_f32 v136, -v134, v249, 1.0
	v_fmac_f32_e32 v249, v136, v249
	v_div_scale_f32 v136, vcc, v115, v85, v115
	v_mul_f32_e32 v137, v136, v249
	v_fma_f32 v65, -v134, v137, v136
	v_fmac_f32_e32 v137, v65, v249
	v_fma_f32 v136, -v134, v137, v136
	s_nop 0
	v_div_fmas_f32 v136, v136, v249, v137
	v_div_fixup_f32 v65, v136, v85, v115
	v_div_scale_f32 v134, s[26:27], v85, v85, v92
	v_rcp_f32_e32 v249, v134
	s_nop 0
	v_fma_f32 v136, -v134, v249, 1.0
	v_fmac_f32_e32 v249, v136, v249
	v_div_scale_f32 v136, vcc, v92, v85, v92
	v_mul_f32_e32 v137, v136, v249
	v_fma_f32 v133, -v134, v137, v136
	v_fmac_f32_e32 v137, v133, v249
	v_fma_f32 v136, -v134, v137, v136
	s_nop 0
	v_div_fmas_f32 v136, v136, v249, v137
	v_div_fixup_f32 v133, v136, v85, v92
	s_waitcnt lgkmcnt(0)
	v_and_b32_e32 v68, 0x7f, v68
	v_and_b32_e32 v123, 0x7f, v123
	v_lshl_or_b32 v68, v68, 7, v123
	v_xor_b32_e32 v68, 0x3fff, v68
	v_and_b32_e32 v56, 0x7f, v56
	v_and_b32_e32 v114, 0x7f, v114
	v_lshl_or_b32 v56, v56, 7, v114
	v_xor_b32_e32 v56, 0x3fff, v56
	v_and_b32_e32 v57, 0x7f, v57
	v_and_b32_e32 v126, 0x7f, v126
	v_lshl_or_b32 v57, v57, 7, v126
	v_xor_b32_e32 v57, 0x3fff, v57
	v_and_b32_e32 v58, 0x7f, v58
	v_and_b32_e32 v121, 0x7f, v121
	v_lshl_or_b32 v58, v58, 7, v121
	v_xor_b32_e32 v58, 0x3fff, v58
	v_and_b32_e32 v59, 0x7f, v59
	v_and_b32_e32 v122, 0x7f, v122
	v_lshl_or_b32 v59, v59, 7, v122
	v_xor_b32_e32 v59, 0x3fff, v59
	v_and_b32_e32 v251, 0x7f, v251
	v_and_b32_e32 v124, 0x7f, v124
	v_lshl_or_b32 v251, v251, 7, v124
	v_xor_b32_e32 v251, 0x3fff, v251
	v_and_b32_e32 v253, 0x7f, v253
	v_and_b32_e32 v109, 0x7f, v109
	v_lshl_or_b32 v253, v253, 7, v109
	v_xor_b32_e32 v253, 0x3fff, v253
	v_and_b32_e32 v151, 0x7f, v151
	v_and_b32_e32 v60, 0x7f, v60
	v_lshl_or_b32 v151, v151, 7, v60
	v_xor_b32_e32 v151, 0x3fff, v151
	s_waitcnt vmcnt(0)
	v_pk_mul_f32 v[160:161], v[160:161], v[176:177]
	v_pk_mul_f32 v[162:163], v[162:163], v[178:179]
	v_pk_mul_f32 v[164:165], v[164:165], v[180:181]
	v_pk_mul_f32 v[166:167], v[166:167], v[182:183]
	v_pk_mul_f32 v[168:169], v[168:169], v[184:185]
	v_pk_mul_f32 v[170:171], v[170:171], v[186:187]
	v_pk_mul_f32 v[172:173], v[172:173], v[188:189]
	v_pk_mul_f32 v[174:175], v[174:175], v[190:191]
	v_max3_f32 v192, |v160|, |v161|, |v162|
	v_max3_f32 v192, |v163|, |v164|, v192
	v_max3_f32 v192, |v165|, |v166|, v192
	v_max3_f32 v192, |v167|, |v168|, v192
	v_max3_f32 v192, |v169|, |v170|, v192
	v_max3_f32 v192, |v171|, |v172|, v192
	v_max3_f32 v192, |v173|, |v174|, v192
	v_max_f32_e64 v192, |v175|, v192
	s_nop 1
	v_mov_b32_dpp v193, v192 quad_perm:[1,0,3,2] row_mask:0xf bank_mask:0xf bound_ctrl:1
	v_max_f32_e32 v192, v192, v193
	s_nop 1
	v_mov_b32_dpp v193, v192 quad_perm:[2,3,0,1] row_mask:0xf bank_mask:0xf bound_ctrl:1
	v_max_f32_e32 v192, v192, v193
	s_nop 1
	v_mov_b32_dpp v193, v192 row_half_mirror row_mask:0xf bank_mask:0xf bound_ctrl:1
	v_max_f32_e32 v192, v192, v193
	s_nop 1
	v_mov_b32_dpp v193, v192 row_mirror row_mask:0xf bank_mask:0xf bound_ctrl:1
	v_max_f32_e32 v192, v192, v193
	v_mov_b32_e32 v193, v192
	s_nop 1
	v_permlane16_swap_b32_e32 v192, v193
	s_nop 1
	v_max_f32_e32 v192, v192, v193
	v_mov_b32_e32 v193, v192
	s_nop 1
	v_permlane32_swap_b32_e32 v192, v193
	s_nop 1
	v_max_f32_e32 v192, v192, v193
	v_max_f32_e32 v192, 0xda24260, v192
	v_mul_f32_e32 v194, 0x3e2aaaab, v192
	global_store_dword v214, v194, s[12:13]
	v_div_scale_f32 v195, s[26:27], v194, v194, 1.0
	v_rcp_f32_e32 v196, v195
	v_div_scale_f32 v204, vcc, 1.0, v194, 1.0
	v_fma_f32 v205, -v195, v196, 1.0
	v_fmac_f32_e32 v196, v205, v196
	v_mul_f32_e32 v205, v204, v196
	v_fma_f32 v206, -v195, v205, v204
	v_fmac_f32_e32 v205, v206, v196
	v_fma_f32 v195, -v195, v205, v204
	s_nop 0
	v_div_fmas_f32 v195, v195, v196, v205
	v_div_fixup_f32 v207, v195, v194, 1.0
	v_mul_f32_e32 v160, v207, v160
	v_mul_f32_e32 v161, v207, v161
	v_mul_f32_e32 v162, v207, v162
	v_mul_f32_e32 v163, v207, v163
	v_mul_f32_e32 v164, v207, v164
	v_mul_f32_e32 v165, v207, v165
	v_mul_f32_e32 v166, v207, v166
	v_mul_f32_e32 v167, v207, v167
	v_mul_f32_e32 v168, v207, v168
	v_mul_f32_e32 v169, v207, v169
	v_mul_f32_e32 v170, v207, v170
	v_mul_f32_e32 v171, v207, v171
	v_mul_f32_e32 v172, v207, v172
	v_mul_f32_e32 v173, v207, v173
	v_mul_f32_e32 v174, v207, v174
	v_mul_f32_e32 v175, v207, v175
	v_mov_b32_e32 v208, 0
	v_mov_b32_e32 v209, 0
	v_mov_b32_e32 v210, 0
	v_mov_b32_e32 v193, 0
	v_cvt_scalef32_pk_fp4_f32 v208, v160, v161, 1.0
	v_cvt_scalef32_pk_fp4_f32 v209, v164, v165, 1.0
	v_cvt_scalef32_pk_fp4_f32 v210, v168, v169, 1.0
	v_cvt_scalef32_pk_fp4_f32 v193, v172, v173, 1.0
	v_cvt_scalef32_pk_fp4_f32 v208, v162, v163, 1.0 op_sel:[0,0,1,0]
	v_cvt_scalef32_pk_fp4_f32 v209, v166, v167, 1.0 op_sel:[0,0,1,0]
	v_cvt_scalef32_pk_fp4_f32 v210, v170, v171, 1.0 op_sel:[0,0,1,0]
	v_cvt_scalef32_pk_fp4_f32 v193, v174, v175, 1.0 op_sel:[0,0,1,0]
	global_store_short v213, v208, s[10:11] nt
	s_add_u32 s14, s10, 0x200000
	s_addc_u32 s15, s11, 0
	global_store_short v213, v209, s[14:15] nt
	s_add_u32 s14, s10, 0x400000
	s_addc_u32 s15, s11, 0
	global_store_short v213, v210, s[14:15] nt
	s_add_u32 s14, s10, 0x600000
	s_addc_u32 s15, s11, 0
	global_store_short v213, v193, s[14:15] nt
	s_add_u32 s10, s10, 0x20000
	s_addc_u32 s11, s11, 0
	s_add_u32 s12, s12, 0x2000
	s_addc_u32 s13, s13, 0
	s_cmp_eq_u32 s22, 1
	s_cbranch_scc1 .Ltk0_noload
	global_load_dwordx4 v[160:163], v212, s[8:9] offset:0 nt
	global_load_dwordx4 v[164:167], v212, s[8:9] offset:1024 nt
	global_load_dwordx4 v[168:171], v212, s[8:9] offset:2048 nt
	global_load_dwordx4 v[172:175], v212, s[8:9] offset:3072 nt
	s_add_u32 s8, s8, 0x800000
	s_addc_u32 s9, s9, 0
.Ltk0_noload:
	v_mov_b32_e32 v0, v68
	v_mov_b32_e32 v1, v56
	v_mov_b32_e32 v2, v57
	v_mov_b32_e32 v3, v58
	global_store_dwordx4 v241, v[0:3], s[28:29] offset:0
	v_mov_b32_e32 v4, v59
	v_mov_b32_e32 v5, v251
	v_mov_b32_e32 v6, v253
	v_mov_b32_e32 v7, v151
	global_store_dwordx4 v241, v[4:7], s[28:29] offset:16
	v_mov_b32_e32 v8, v62
	v_mov_b32_e32 v9, v64
	v_mov_b32_e32 v10, v255
	v_mov_b32_e32 v11, v252
	global_store_dwordx4 v241, v[8:11], s[30:31] offset:0
	v_mov_b32_e32 v12, v129
	v_mov_b32_e32 v13, v130
	v_mov_b32_e32 v14, v65
	v_mov_b32_e32 v15, v133
	global_store_dwordx4 v241, v[12:15], s[30:31] offset:16
	s_add_i32 s24, s24, 4
	s_add_i32 s22, s22, 1
	s_cmp_lt_u32 s22, 2
	s_cbranch_scc1 .Ltk0_unit

.LBB0_966:
	s_cmp_lt_i32 s56, 15
	s_cselect_b64 s[0:1], -1, 0
	s_and_b64 s[40:41], s[0:1], s[4:5]
	s_andn2_b64 vcc, exec, s[40:41]
	s_cbranch_vccnz .LBB0_1021
	v_mbcnt_lo_u32_b32 v246, -1, 0
	v_mbcnt_hi_u32_b32 v246, -1, v246
	v_readlane_b32 s21, v248, 0
	s_andn2_b32 s26, s21, 63
	v_add_u32_e32 v242, s26, v246
	s_lshr_b32 s21, s21, 6
	s_mov_b32 s4, 0
	s_mov_b32 s5, -1
	s_mov_b32 s6, 0xffffff80
	s_mov_b32 s7, 0xffffffc0
	v_lshrrev_b32_e32 v245, 5, v246
	v_and_b32_e32 v247, 31, v246
	v_lshlrev_b32_e32 v239, 12, v247
	v_lshl_or_b32 v239, v245, 4, v239
	v_lshlrev_b32_e32 v241, 9, v247
	v_lshl_or_b32 v241, v245, 5, v241
	v_lshlrev_b32_e32 v240, 4, v247
	s_lshl_b32 s26, s21, 11
	s_add_i32 s26, s26, 0x10000
	v_add_u32_e32 v240, s26, v240
	v_and_b32_e32 v231, 15, v246
	v_xor_b32_e32 v231, v231, v245
	v_lshlrev_b32_e32 v231, 4, v231
	v_lshl_or_b32 v231, v247, 8, v231
	v_xor_b32_e32 v232, 32, v231
	v_xor_b32_e32 v233, 64, v231
	v_xor_b32_e32 v234, 0x60, v231
	v_xor_b32_e32 v235, 0x80, v231
	v_xor_b32_e32 v236, 0xa0, v231
	v_xor_b32_e32 v237, 0xc0, v231
	v_xor_b32_e32 v238, 0xe0, v231
	v_lshlrev_b32_e32 v247, 2, v245
	v_xor_b32_e32 v211, 4, v247
	v_lshrrev_b32_e32 v243, 4, v242
	v_xor_b32_e32 v247, v243, v242
	v_lshlrev_b32_e32 v242, 4, v242
	v_and_b32_e32 v247, 15, v247
	v_lshlrev_b32_e32 v247, 4, v247
	v_lshl_or_b32 v243, v243, 8, v247
	v_mov_b32_e32 v244, 0xff800000
	v_mov_b32_e32 v247, 0x14000
	v_mov_b32_e32 v128, 0x20021001
	ds_write_b32 v247, v128 offset:0
	v_mov_b32_e32 v128, 0x40043003
	ds_write_b32 v247, v128 offset:4
	v_mov_b32_e32 v128, 0x60065005
	ds_write_b32 v247, v128 offset:8
	v_mov_b32_e32 v128, 0x80087007
	ds_write_b32 v247, v128 offset:12
	v_mov_b32_e32 v128, 0xa00a9009
	ds_write_b32 v247, v128 offset:16
	v_mov_b32_e32 v128, 0xc00cb00b
	ds_write_b32 v247, v128 offset:20
	v_mov_b32_e32 v128, 0xe00ed00d
	ds_write_b32 v247, v128 offset:24
	v_mov_b32_e32 v128, 0x2112f00f
	ds_write_b32 v247, v128 offset:28
	v_mov_b32_e32 v128, 0x41143113
	ds_write_b32 v247, v128 offset:32
	v_mov_b32_e32 v128, 0x61165115
	ds_write_b32 v247, v128 offset:36
	v_mov_b32_e32 v128, 0x32237117
	ds_write_b32 v247, v128 offset:40
	v_mov_b32_e32 v128, 0x4224
	ds_write_b32 v247, v128 offset:44
	v_mov_b32_e32 v128, 0x22221111
	ds_write_b32 v247, v128 offset:48
	v_mov_b32_e32 v128, 0x3333
	ds_write_b32 v247, v128 offset:52
	v_mov_b32_e32 v128, 0
	ds_write_b32 v247, v128 offset:56
	v_mov_b32_e32 v128, 0
	ds_write_b32 v247, v128 offset:60
	s_and_b32 s25, s2, 7
	s_lshl_b32 s25, s25, 3
	s_bfe_u32 s26, s2, 0x30003
	s_add_i32 s25, s25, s26
	s_lshl_b32 s23, s25, 8
	s_lshl_b32 s26, s21, 5
	s_add_i32 s23, s23, s26
	v_lshlrev_b32_e32 v212, 4, v246
	v_lshlrev_b32_e32 v213, 1, v246
	v_mov_b32_e32 v214, 0
	s_lshl_b32 s14, s2, 3
	s_add_i32 s14, s14, s21
	s_and_b32 s15, s14, 1
	s_lshr_b32 s14, s14, 1
	v_readlane_b32 s8, v248, 12
	v_readlane_b32 s9, v248, 13
	s_lshl_b32 s26, s14, 13
	s_lshl_b32 s34, s15, 12
	s_add_i32 s26, s26, s34
	s_add_i32 s26, s26, 0x8000000
	s_add_u32 s8, s8, s26
	s_addc_u32 s9, s9, 0
	v_readlane_b32 s12, v248, 14
	v_readlane_b32 s13, v248, 15
	s_add_i32 s34, s34, 0x2000
	s_add_u32 s12, s12, s34
	s_addc_u32 s13, s13, 0
	global_load_dwordx4 v[176:179], v212, s[12:13] offset:0
	global_load_dwordx4 v[180:183], v212, s[12:13] offset:1024
	global_load_dwordx4 v[184:187], v212, s[12:13] offset:2048
	global_load_dwordx4 v[188:191], v212, s[12:13] offset:3072
	s_lshl_b32 s26, s15, 23
	s_lshl_b32 s34, s14, 7
	s_add_i32 s26, s26, s34
	s_add_i32 s26, s26, 0x10000000
	s_add_u32 s10, s54, s26
	s_addc_u32 s11, s55, 0
	s_lshl_b32 s26, s14, 3
	s_lshl_b32 s34, s15, 2
	s_add_i32 s26, s26, s34
	s_add_i32 s26, s26, 0xa0000
	s_add_u32 s12, s54, s26
	s_addc_u32 s13, s55, 0
	global_load_dwordx4 v[160:163], v212, s[8:9] offset:0 nt
	global_load_dwordx4 v[164:167], v212, s[8:9] offset:1024 nt
	global_load_dwordx4 v[168:171], v212, s[8:9] offset:2048 nt
	global_load_dwordx4 v[172:175], v212, s[8:9] offset:3072 nt
	s_add_u32 s8, s8, 0x800000
	s_addc_u32 s9, s9, 0
	v_mov_b32_e32 v246, 0x14000
	s_lshr_b32 s24, s2, 6
	s_mov_b32 s22, 0
.Ltk1_unit:
	s_lshl_b32 s26, s24, 9
	s_lshl_b32 s20, s23, 12
	s_add_i32 s26, s26, s20
	s_add_i32 s26, s26, 0x1c000000
	s_add_u32 s16, s54, s26
	s_addc_u32 s17, s55, 0
	s_lshl_b32 s26, s24, 16
	s_add_i32 s26, s26, 0x380000
	s_add_u32 s18, s54, s26
	s_addc_u32 s19, s55, 0
	s_lshl_b32 s20, s23, 9
	s_lshl_b32 s26, s24, 6
	s_add_i32 s20, s20, s26
	s_add_i32 s26, s20, 0x28000000
	s_add_u32 s28, s54, s26
	s_addc_u32 s29, s55, 0
	s_add_i32 s26, s20, 0x28800000
	s_add_u32 s30, s54, s26
	s_addc_u32 s31, s55, 0
	s_barrier
	global_load_dwordx4 v[0:3], v242, s[18:19]
	v_add_u32_e32 v247, 0x2000, v242
	global_load_dwordx4 v[4:7], v247, s[18:19]
	v_add_u32_e32 v247, 0x4000, v242
	global_load_dwordx4 v[8:11], v247, s[18:19]
	v_add_u32_e32 v247, 0x6000, v242
	global_load_dwordx4 v[12:15], v247, s[18:19]
	v_add_u32_e32 v247, 0x8000, v242
	global_load_dwordx4 v[16:19], v247, s[18:19]
	v_add_u32_e32 v247, 0xa000, v242
	global_load_dwordx4 v[20:23], v247, s[18:19]
	v_add_u32_e32 v247, 0xc000, v242
	global_load_dwordx4 v[24:27], v247, s[18:19]
	v_add_u32_e32 v247, 0xe000, v242
	global_load_dwordx4 v[28:31], v247, s[18:19]
	global_load_dwordx4 v[64:67], v239, s[16:17] offset:0
	global_load_dwordx4 v[68:71], v239, s[16:17] offset:32
	global_load_dwordx4 v[72:75], v239, s[16:17] offset:64
	global_load_dwordx4 v[76:79], v239, s[16:17] offset:96
	global_load_dwordx4 v[80:83], v239, s[16:17] offset:128
	global_load_dwordx4 v[84:87], v239, s[16:17] offset:160
	global_load_dwordx4 v[88:91], v239, s[16:17] offset:192
	global_load_dwordx4 v[92:95], v239, s[16:17] offset:224
	s_waitcnt vmcnt(15)
	ds_write_b128 v243, v[0:3] offset:0
	s_waitcnt vmcnt(14)
	ds_write_b128 v243, v[4:7] offset:8192
	s_waitcnt vmcnt(13)
	ds_write_b128 v243, v[8:11] offset:16384
	s_waitcnt vmcnt(12)
	ds_write_b128 v243, v[12:15] offset:24576
	s_waitcnt vmcnt(11)
	ds_write_b128 v243, v[16:19] offset:32768
	s_waitcnt vmcnt(10)
	ds_write_b128 v243, v[20:23] offset:40960
	s_waitcnt vmcnt(9)
	ds_write_b128 v243, v[24:27] offset:49152
	s_waitcnt vmcnt(8)
	ds_write_b128 v243, v[28:31] offset:57344
	s_waitcnt lgkmcnt(0)
	s_barrier
	ds_read_b128 v[96:99], v231 offset:0
	ds_read_b128 v[100:103], v232 offset:0
	ds_read_b128 v[104:107], v233 offset:0
	ds_read_b128 v[108:111], v234 offset:0
	ds_read_b128 v[112:115], v235 offset:0
	ds_read_b128 v[116:119], v236 offset:0
	ds_read_b128 v[120:123], v237 offset:0
	ds_read_b128 v[124:127], v238 offset:0
	s_waitcnt vmcnt(0)
	s_waitcnt lgkmcnt(4)
	v_mfma_f32_32x32x16_bf16 v[0:15], v[96:99], v[64:67], 0
	v_mfma_f32_32x32x16_bf16 v[0:15], v[100:103], v[68:71], v[0:15]
	v_mfma_f32_32x32x16_bf16 v[0:15], v[104:107], v[72:75], v[0:15]
	v_mfma_f32_32x32x16_bf16 v[0:15], v[108:111], v[76:79], v[0:15]
	ds_read_b128 v[96:99], v231 offset:8192
	ds_read_b128 v[100:103], v232 offset:8192
	ds_read_b128 v[104:107], v233 offset:8192
	ds_read_b128 v[108:111], v234 offset:8192
	s_waitcnt lgkmcnt(4)
	v_mfma_f32_32x32x16_bf16 v[0:15], v[112:115], v[80:83], v[0:15]
	v_mfma_f32_32x32x16_bf16 v[0:15], v[116:119], v[84:87], v[0:15]
	v_mfma_f32_32x32x16_bf16 v[0:15], v[120:123], v[88:91], v[0:15]
	v_mfma_f32_32x32x16_bf16 v[0:15], v[124:127], v[92:95], v[0:15]
	ds_read_b128 v[112:115], v235 offset:8192
	ds_read_b128 v[116:119], v236 offset:8192
	ds_read_b128 v[120:123], v237 offset:8192
	ds_read_b128 v[124:127], v238 offset:8192
	s_waitcnt lgkmcnt(4)
	v_mfma_f32_32x32x16_bf16 v[16:31], v[96:99], v[64:67], 0
	v_mfma_f32_32x32x16_bf16 v[16:31], v[100:103], v[68:71], v[16:31]
	v_mfma_f32_32x32x16_bf16 v[16:31], v[104:107], v[72:75], v[16:31]
	v_mfma_f32_32x32x16_bf16 v[16:31], v[108:111], v[76:79], v[16:31]
	ds_read_b128 v[96:99], v231 offset:16384
	ds_read_b128 v[100:103], v232 offset:16384
	ds_read_b128 v[104:107], v233 offset:16384
	ds_read_b128 v[108:111], v234 offset:16384
	s_waitcnt lgkmcnt(4)
	v_mfma_f32_32x32x16_bf16 v[16:31], v[112:115], v[80:83], v[16:31]
	v_mfma_f32_32x32x16_bf16 v[16:31], v[116:119], v[84:87], v[16:31]
	v_mfma_f32_32x32x16_bf16 v[16:31], v[120:123], v[88:91], v[16:31]
	v_mfma_f32_32x32x16_bf16 v[16:31], v[124:127], v[92:95], v[16:31]
	ds_read_b128 v[112:115], v235 offset:16384
	ds_read_b128 v[116:119], v236 offset:16384
	ds_read_b128 v[120:123], v237 offset:16384
	ds_read_b128 v[124:127], v238 offset:16384
	s_waitcnt lgkmcnt(4)
	v_mfma_f32_32x32x16_bf16 v[32:47], v[96:99], v[64:67], 0
	v_mfma_f32_32x32x16_bf16 v[32:47], v[100:103], v[68:71], v[32:47]
	v_mfma_f32_32x32x16_bf16 v[32:47], v[104:107], v[72:75], v[32:47]
	v_mfma_f32_32x32x16_bf16 v[32:47], v[108:111], v[76:79], v[32:47]
	ds_read_b128 v[96:99], v231 offset:24576
	ds_read_b128 v[100:103], v232 offset:24576
	ds_read_b128 v[104:107], v233 offset:24576
	ds_read_b128 v[108:111], v234 offset:24576
	s_waitcnt lgkmcnt(4)
	v_mfma_f32_32x32x16_bf16 v[32:47], v[112:115], v[80:83], v[32:47]
	v_mfma_f32_32x32x16_bf16 v[32:47], v[116:119], v[84:87], v[32:47]
	v_mfma_f32_32x32x16_bf16 v[32:47], v[120:123], v[88:91], v[32:47]
	v_mfma_f32_32x32x16_bf16 v[32:47], v[124:127], v[92:95], v[32:47]
	ds_read_b128 v[112:115], v235 offset:24576
	ds_read_b128 v[116:119], v236 offset:24576
	ds_read_b128 v[120:123], v237 offset:24576
	ds_read_b128 v[124:127], v238 offset:24576
	s_waitcnt lgkmcnt(4)
	v_mfma_f32_32x32x16_bf16 v[48:63], v[96:99], v[64:67], 0
	v_mfma_f32_32x32x16_bf16 v[48:63], v[100:103], v[68:71], v[48:63]
	v_mfma_f32_32x32x16_bf16 v[48:63], v[104:107], v[72:75], v[48:63]
	v_mfma_f32_32x32x16_bf16 v[48:63], v[108:111], v[76:79], v[48:63]
	s_waitcnt lgkmcnt(0)
	v_mfma_f32_32x32x16_bf16 v[48:63], v[112:115], v[80:83], v[48:63]
	v_mfma_f32_32x32x16_bf16 v[48:63], v[116:119], v[84:87], v[48:63]
	v_mfma_f32_32x32x16_bf16 v[48:63], v[120:123], v[88:91], v[48:63]
	v_mfma_f32_32x32x16_bf16 v[48:63], v[124:127], v[92:95], v[48:63]
	global_load_dwordx4 v[64:67], v239, s[16:17] offset:256
	global_load_dwordx4 v[68:71], v239, s[16:17] offset:288
	global_load_dwordx4 v[72:75], v239, s[16:17] offset:320
	global_load_dwordx4 v[76:79], v239, s[16:17] offset:352
	global_load_dwordx4 v[80:83], v239, s[16:17] offset:384
	global_load_dwordx4 v[84:87], v239, s[16:17] offset:416
	global_load_dwordx4 v[88:91], v239, s[16:17] offset:448
	global_load_dwordx4 v[92:95], v239, s[16:17] offset:480
	s_nop 11
	v_and_or_b32 v0, v0, s6, v211
	v_or_b32_e32 v0, 0x7b, v0
	v_and_or_b32 v1, v1, s6, v211
	v_or_b32_e32 v1, 0x7a, v1
	v_and_or_b32 v2, v2, s6, v211
	v_or_b32_e32 v2, 0x79, v2
	v_and_or_b32 v3, v3, s6, v211
	v_or_b32_e32 v3, 0x78, v3
	v_and_or_b32 v4, v4, s6, v211
	v_or_b32_e32 v4, 0x73, v4
	v_and_or_b32 v5, v5, s6, v211
	v_or_b32_e32 v5, 0x72, v5
	v_and_or_b32 v6, v6, s6, v211
	v_or_b32_e32 v6, 0x71, v6
	v_and_or_b32 v7, v7, s6, v211
	v_or_b32_e32 v7, 0x70, v7
	v_and_or_b32 v8, v8, s6, v211
	v_or_b32_e32 v8, 0x6b, v8
	v_and_or_b32 v9, v9, s6, v211
	v_or_b32_e32 v9, 0x6a, v9
	v_and_or_b32 v10, v10, s6, v211
	v_or_b32_e32 v10, 0x69, v10
	v_and_or_b32 v11, v11, s6, v211
	v_or_b32_e32 v11, 0x68, v11
	v_and_or_b32 v12, v12, s6, v211
	v_or_b32_e32 v12, 0x63, v12
	v_and_or_b32 v13, v13, s6, v211
	v_or_b32_e32 v13, 0x62, v13
	v_and_or_b32 v14, v14, s6, v211
	v_or_b32_e32 v14, 0x61, v14
	v_and_or_b32 v15, v15, s6, v211
	v_or_b32_e32 v15, 0x60, v15
	v_and_or_b32 v16, v16, s6, v211
	v_or_b32_e32 v16, 0x5b, v16
	v_and_or_b32 v17, v17, s6, v211
	v_or_b32_e32 v17, 0x5a, v17
	v_and_or_b32 v18, v18, s6, v211
	v_or_b32_e32 v18, 0x59, v18
	v_and_or_b32 v19, v19, s6, v211
	v_or_b32_e32 v19, 0x58, v19
	v_and_or_b32 v20, v20, s6, v211
	v_or_b32_e32 v20, 0x53, v20
	v_and_or_b32 v21, v21, s6, v211
	v_or_b32_e32 v21, 0x52, v21
	v_and_or_b32 v22, v22, s6, v211
	v_or_b32_e32 v22, 0x51, v22
	v_and_or_b32 v23, v23, s6, v211
	v_or_b32_e32 v23, 0x50, v23
	v_and_or_b32 v24, v24, s6, v211
	v_or_b32_e32 v24, 0x4b, v24
	v_and_or_b32 v25, v25, s6, v211
	v_or_b32_e32 v25, 0x4a, v25
	v_and_or_b32 v26, v26, s6, v211
	v_or_b32_e32 v26, 0x49, v26
	v_and_or_b32 v27, v27, s6, v211
	v_or_b32_e32 v27, 0x48, v27
	v_and_or_b32 v28, v28, s6, v211
	v_or_b32_e32 v28, 0x43, v28
	v_and_or_b32 v29, v29, s6, v211
	v_or_b32_e32 v29, 0x42, v29
	v_and_or_b32 v30, v30, s6, v211
	v_or_b32_e32 v30, 0x41, v30
	v_and_or_b32 v31, v31, s6, v211
	v_or_b32_e32 v31, 64, v31
	v_and_or_b32 v32, v32, s6, v211
	v_or_b32_e32 v32, 59, v32
	v_and_or_b32 v33, v33, s6, v211
	v_or_b32_e32 v33, 58, v33
	v_and_or_b32 v34, v34, s6, v211
	v_or_b32_e32 v34, 57, v34
	v_and_or_b32 v35, v35, s6, v211
	v_or_b32_e32 v35, 56, v35
	v_and_or_b32 v36, v36, s6, v211
	v_or_b32_e32 v36, 51, v36
	v_and_or_b32 v37, v37, s6, v211
	v_or_b32_e32 v37, 50, v37
	v_and_or_b32 v38, v38, s6, v211
	v_or_b32_e32 v38, 49, v38
	v_and_or_b32 v39, v39, s6, v211
	v_or_b32_e32 v39, 48, v39
	v_and_or_b32 v40, v40, s6, v211
	v_or_b32_e32 v40, 43, v40
	v_and_or_b32 v41, v41, s6, v211
	v_or_b32_e32 v41, 42, v41
	v_and_or_b32 v42, v42, s6, v211
	v_or_b32_e32 v42, 41, v42
	v_and_or_b32 v43, v43, s6, v211
	v_or_b32_e32 v43, 40, v43
	v_and_or_b32 v44, v44, s6, v211
	v_or_b32_e32 v44, 35, v44
	v_and_or_b32 v45, v45, s6, v211
	v_or_b32_e32 v45, 34, v45
	v_and_or_b32 v46, v46, s6, v211
	v_or_b32_e32 v46, 33, v46
	v_and_or_b32 v47, v47, s6, v211
	v_or_b32_e32 v47, 32, v47
	v_and_or_b32 v48, v48, s6, v211
	v_or_b32_e32 v48, 27, v48
	v_and_or_b32 v49, v49, s6, v211
	v_or_b32_e32 v49, 26, v49
	v_and_or_b32 v50, v50, s6, v211
	v_or_b32_e32 v50, 25, v50
	v_and_or_b32 v51, v51, s6, v211
	v_or_b32_e32 v51, 24, v51
	v_and_or_b32 v52, v52, s6, v211
	v_or_b32_e32 v52, 19, v52
	v_and_or_b32 v53, v53, s6, v211
	v_or_b32_e32 v53, 18, v53
	v_and_or_b32 v54, v54, s6, v211
	v_or_b32_e32 v54, 17, v54
	v_and_or_b32 v55, v55, s6, v211
	v_or_b32_e32 v55, 16, v55
	v_and_or_b32 v56, v56, s6, v211
	v_or_b32_e32 v56, 11, v56
	v_and_or_b32 v57, v57, s6, v211
	v_or_b32_e32 v57, 10, v57
	v_and_or_b32 v58, v58, s6, v211
	v_or_b32_e32 v58, 9, v58
	v_and_or_b32 v59, v59, s6, v211
	v_or_b32_e32 v59, 8, v59
	v_and_or_b32 v60, v60, s6, v211
	v_or_b32_e32 v60, 3, v60
	v_and_or_b32 v61, v61, s6, v211
	v_or_b32_e32 v61, 2, v61
	v_and_or_b32 v62, v62, s6, v211
	v_or_b32_e32 v62, 1, v62
	v_and_or_b32 v63, v63, s6, v211
	v_or_b32_e32 v63, 0, v63
	v_max_f32_e32 v144, v0, v13
	v_min_f32_e32 v13, v0, v13
	v_max_f32_e32 v145, v1, v12
	v_min_f32_e32 v12, v1, v12
	v_max_f32_e32 v146, v2, v15
	v_min_f32_e32 v15, v2, v15
	v_max_f32_e32 v147, v3, v14
	v_min_f32_e32 v14, v3, v14
	v_max_f32_e32 v148, v4, v8
	v_min_f32_e32 v8, v4, v8
	v_max_f32_e32 v149, v5, v6
	v_min_f32_e32 v6, v5, v6
	v_max_f32_e32 v150, v7, v11
	v_min_f32_e32 v11, v7, v11
	v_max_f32_e32 v151, v9, v10
	v_min_f32_e32 v10, v9, v10
	v_max_f32_e32 v249, v144, v149
	v_min_f32_e32 v149, v144, v149
	v_max_f32_e32 v250, v145, v150
	v_min_f32_e32 v150, v145, v150
	v_max_f32_e32 v251, v146, v151
	v_min_f32_e32 v151, v146, v151
	v_max_f32_e32 v252, v147, v148
	v_min_f32_e32 v148, v147, v148
	v_max_f32_e32 v253, v6, v13
	v_min_f32_e32 v13, v6, v13
	v_max_f32_e32 v254, v8, v14
	v_min_f32_e32 v14, v8, v14
	v_max_f32_e32 v255, v10, v15
	v_min_f32_e32 v15, v10, v15
	v_max_f32_e32 v96, v11, v12
	v_min_f32_e32 v12, v11, v12
	v_max_f32_e32 v97, v249, v250
	v_min_f32_e32 v250, v249, v250
	v_max_f32_e32 v98, v251, v252
	v_min_f32_e32 v252, v251, v252
	v_max_f32_e32 v99, v148, v149
	v_min_f32_e32 v149, v148, v149
	v_max_f32_e32 v100, v253, v254
	v_min_f32_e32 v254, v253, v254
	v_max_f32_e32 v101, v150, v151
	v_min_f32_e32 v151, v150, v151
	v_max_f32_e32 v102, v255, v96
	v_min_f32_e32 v96, v255, v96
	v_max_f32_e32 v103, v12, v13
	v_min_f32_e32 v13, v12, v13
	v_max_f32_e32 v104, v14, v15
	v_min_f32_e32 v15, v14, v15
	v_max_f32_e32 v105, v97, v98
	v_min_f32_e32 v98, v97, v98
	v_max_f32_e32 v106, v250, v252
	v_min_f32_e32 v252, v250, v252
	v_max_f32_e32 v107, v99, v102
	v_min_f32_e32 v102, v99, v102
	v_max_f32_e32 v108, v149, v96
	v_min_f32_e32 v96, v149, v96
	v_max_f32_e32 v109, v100, v101
	v_min_f32_e32 v101, v100, v101
	v_max_f32_e32 v110, v254, v151
	v_min_f32_e32 v151, v254, v151
	v_max_f32_e32 v111, v103, v104
	v_min_f32_e32 v104, v103, v104
	v_max_f32_e32 v112, v13, v15
	v_min_f32_e32 v15, v13, v15
	v_max_f32_e32 v113, v106, v98
	v_min_f32_e32 v98, v106, v98
	v_max_f32_e32 v114, v252, v111
	v_min_f32_e32 v111, v252, v111
	v_max_f32_e32 v115, v107, v109
	v_min_f32_e32 v109, v107, v109
	v_max_f32_e32 v116, v108, v101
	v_min_f32_e32 v101, v108, v101
	v_max_f32_e32 v117, v110, v102
	v_min_f32_e32 v102, v110, v102
	v_max_f32_e32 v118, v151, v96
	v_min_f32_e32 v96, v151, v96
	v_max_f32_e32 v119, v112, v104
	v_min_f32_e32 v104, v112, v104
	v_max_f32_e32 v120, v113, v115
	v_min_f32_e32 v115, v113, v115
	v_max_f32_e32 v121, v98, v109
	v_min_f32_e32 v109, v98, v109
	v_max_f32_e32 v122, v116, v117
	v_min_f32_e32 v117, v116, v117
	v_max_f32_e32 v123, v101, v102
	v_min_f32_e32 v102, v101, v102
	v_max_f32_e32 v124, v118, v119
	v_min_f32_e32 v119, v118, v119
	v_max_f32_e32 v125, v96, v104
	v_min_f32_e32 v104, v96, v104
	v_max_f32_e32 v126, v121, v115
	v_min_f32_e32 v115, v121, v115
	v_max_f32_e32 v127, v114, v109
	v_min_f32_e32 v109, v114, v109
	v_max_f32_e32 v0, v124, v111
	v_min_f32_e32 v111, v124, v111
	v_max_f32_e32 v1, v125, v119
	v_min_f32_e32 v119, v125, v119
	v_max_f32_e32 v2, v127, v122
	v_min_f32_e32 v122, v127, v122
	v_max_f32_e32 v3, v109, v117
	v_min_f32_e32 v117, v109, v117
	v_max_f32_e32 v4, v123, v0
	v_min_f32_e32 v0, v123, v0
	v_max_f32_e32 v5, v102, v111
	v_min_f32_e32 v111, v102, v111
	v_max_f32_e32 v7, v2, v115
	v_min_f32_e32 v115, v2, v115
	v_max_f32_e32 v9, v122, v3
	v_min_f32_e32 v3, v122, v3
	v_max_f32_e32 v144, v4, v117
	v_min_f32_e32 v117, v4, v117
	v_max_f32_e32 v145, v0, v5
	v_min_f32_e32 v5, v0, v5
	v_max_f32_e32 v146, v1, v111
	v_min_f32_e32 v111, v1, v111
	v_max_f32_e32 v147, v3, v144
	v_min_f32_e32 v144, v3, v144
	v_max_f32_e32 v6, v117, v145
	v_min_f32_e32 v145, v117, v145
	v_max_f32_e32 v8, v16, v29
	v_min_f32_e32 v29, v16, v29
	v_max_f32_e32 v10, v17, v28
	v_min_f32_e32 v28, v17, v28
	v_max_f32_e32 v11, v18, v31
	v_min_f32_e32 v31, v18, v31
	v_max_f32_e32 v249, v19, v30
	v_min_f32_e32 v30, v19, v30
	v_max_f32_e32 v251, v20, v24
	v_min_f32_e32 v24, v20, v24
	v_max_f32_e32 v148, v21, v22
	v_min_f32_e32 v22, v21, v22
	v_max_f32_e32 v253, v23, v27
	v_min_f32_e32 v27, v23, v27
	v_max_f32_e32 v150, v25, v26
	v_min_f32_e32 v26, v25, v26
	v_max_f32_e32 v255, v8, v148
	v_min_f32_e32 v148, v8, v148
	v_max_f32_e32 v12, v10, v253
	v_min_f32_e32 v253, v10, v253
	v_max_f32_e32 v14, v11, v150
	v_min_f32_e32 v150, v11, v150
	v_max_f32_e32 v97, v249, v251
	v_min_f32_e32 v251, v249, v251
	v_max_f32_e32 v250, v22, v29
	v_min_f32_e32 v29, v22, v29
	v_max_f32_e32 v99, v24, v30
	v_min_f32_e32 v30, v24, v30
	v_max_f32_e32 v149, v26, v31
	v_min_f32_e32 v31, v26, v31
	v_max_f32_e32 v100, v27, v28
	v_min_f32_e32 v28, v27, v28
	v_max_f32_e32 v254, v255, v12
	v_min_f32_e32 v12, v255, v12
	v_max_f32_e32 v103, v14, v97
	v_min_f32_e32 v97, v14, v97
	v_max_f32_e32 v13, v251, v148
	v_min_f32_e32 v148, v251, v148
	v_max_f32_e32 v106, v250, v99
	v_min_f32_e32 v99, v250, v99
	v_max_f32_e32 v252, v253, v150
	v_min_f32_e32 v150, v253, v150
	v_max_f32_e32 v107, v149, v100
	v_min_f32_e32 v100, v149, v100
	v_max_f32_e32 v108, v28, v29
	v_min_f32_e32 v29, v28, v29
	v_max_f32_e32 v110, v30, v31
	v_min_f32_e32 v31, v30, v31
	v_max_f32_e32 v151, v254, v103
	v_min_f32_e32 v103, v254, v103
	v_max_f32_e32 v112, v12, v97
	v_min_f32_e32 v97, v12, v97
	v_max_f32_e32 v113, v13, v107
	v_min_f32_e32 v107, v13, v107
	v_max_f32_e32 v98, v148, v100
	v_min_f32_e32 v100, v148, v100
	v_max_f32_e32 v116, v106, v252
	v_min_f32_e32 v252, v106, v252
	v_max_f32_e32 v101, v99, v150
	v_min_f32_e32 v150, v99, v150
	v_max_f32_e32 v118, v108, v110
	v_min_f32_e32 v110, v108, v110
	v_max_f32_e32 v96, v29, v31
	v_min_f32_e32 v31, v29, v31
	v_max_f32_e32 v121, v112, v103
	v_min_f32_e32 v103, v112, v103
	v_max_f32_e32 v114, v97, v118
	v_min_f32_e32 v118, v97, v118
	v_max_f32_e32 v124, v113, v116
	v_min_f32_e32 v116, v113, v116
	v_max_f32_e32 v125, v98, v252
	v_min_f32_e32 v252, v98, v252
	v_max_f32_e32 v127, v101, v107
	v_min_f32_e32 v107, v101, v107
	v_max_f32_e32 v109, v150, v100
	v_min_f32_e32 v100, v150, v100
	v_max_f32_e32 v123, v96, v110
	v_min_f32_e32 v110, v96, v110
	v_max_f32_e32 v102, v121, v124
	v_min_f32_e32 v124, v121, v124
	v_max_f32_e32 v2, v103, v116
	v_min_f32_e32 v116, v103, v116
	v_max_f32_e32 v122, v125, v127
	v_min_f32_e32 v127, v125, v127
	v_max_f32_e32 v4, v252, v107
	v_min_f32_e32 v107, v252, v107
	v_max_f32_e32 v0, v109, v123
	v_min_f32_e32 v123, v109, v123
	v_max_f32_e32 v1, v100, v110
	v_min_f32_e32 v110, v100, v110
	v_max_f32_e32 v3, v2, v124
	v_min_f32_e32 v124, v2, v124
	v_max_f32_e32 v117, v114, v116
	v_min_f32_e32 v116, v114, v116
	v_max_f32_e32 v16, v0, v118
	v_min_f32_e32 v118, v0, v118
	v_max_f32_e32 v17, v1, v123
	v_min_f32_e32 v123, v1, v123
	v_max_f32_e32 v18, v117, v122
	v_min_f32_e32 v122, v117, v122
	v_max_f32_e32 v19, v116, v127
	v_min_f32_e32 v127, v116, v127
	v_max_f32_e32 v20, v4, v16
	v_min_f32_e32 v16, v4, v16
	v_max_f32_e32 v21, v107, v118
	v_min_f32_e32 v118, v107, v118
	v_max_f32_e32 v23, v18, v124
	v_min_f32_e32 v124, v18, v124
	v_max_f32_e32 v25, v122, v19
	v_min_f32_e32 v19, v122, v19
	v_max_f32_e32 v8, v20, v127
	v_min_f32_e32 v127, v20, v127
	v_max_f32_e32 v10, v16, v21
	v_min_f32_e32 v21, v16, v21
	v_max_f32_e32 v11, v17, v118
	v_min_f32_e32 v118, v17, v118
	v_max_f32_e32 v249, v19, v8
	v_min_f32_e32 v8, v19, v8
	v_max_f32_e32 v22, v127, v10
	v_min_f32_e32 v10, v127, v10
	s_waitcnt vmcnt(24)
	v_pk_mul_f32 v[160:161], v[160:161], v[176:177]
	v_pk_mul_f32 v[162:163], v[162:163], v[178:179]
	v_pk_mul_f32 v[164:165], v[164:165], v[180:181]
	v_pk_mul_f32 v[166:167], v[166:167], v[182:183]
	v_pk_mul_f32 v[168:169], v[168:169], v[184:185]
	v_pk_mul_f32 v[170:171], v[170:171], v[186:187]
	v_pk_mul_f32 v[172:173], v[172:173], v[188:189]
	v_pk_mul_f32 v[174:175], v[174:175], v[190:191]
	v_max3_f32 v192, |v160|, |v161|, |v162|
	v_max3_f32 v192, |v163|, |v164|, v192
	v_max3_f32 v192, |v165|, |v166|, v192
	v_max3_f32 v192, |v167|, |v168|, v192
	v_max3_f32 v192, |v169|, |v170|, v192
	v_max3_f32 v192, |v171|, |v172|, v192
	v_max3_f32 v192, |v173|, |v174|, v192
	v_max_f32_e64 v192, |v175|, v192
	s_nop 1
	v_mov_b32_dpp v193, v192 quad_perm:[1,0,3,2] row_mask:0xf bank_mask:0xf bound_ctrl:1
	v_max_f32_e32 v192, v192, v193
	s_nop 1
	v_mov_b32_dpp v193, v192 quad_perm:[2,3,0,1] row_mask:0xf bank_mask:0xf bound_ctrl:1
	v_max_f32_e32 v192, v192, v193
	s_nop 1
	v_mov_b32_dpp v193, v192 row_half_mirror row_mask:0xf bank_mask:0xf bound_ctrl:1
	v_max_f32_e32 v192, v192, v193
	s_nop 1
	v_mov_b32_dpp v193, v192 row_mirror row_mask:0xf bank_mask:0xf bound_ctrl:1
	v_max_f32_e32 v192, v192, v193
	v_mov_b32_e32 v193, v192
	s_nop 1
	v_permlane16_swap_b32_e32 v192, v193
	s_nop 1
	v_max_f32_e32 v192, v192, v193
	v_mov_b32_e32 v193, v192
	s_nop 1
	v_permlane32_swap_b32_e32 v192, v193
	s_nop 1
	v_max_f32_e32 v192, v192, v193
	v_max_f32_e32 v192, 0xda24260, v192
	v_mul_f32_e32 v194, 0x3e2aaaab, v192
	global_store_dword v214, v194, s[12:13]
	v_div_scale_f32 v195, s[26:27], v194, v194, 1.0
	v_rcp_f32_e32 v196, v195
	v_div_scale_f32 v204, vcc, 1.0, v194, 1.0
	v_fma_f32 v205, -v195, v196, 1.0
	v_fmac_f32_e32 v196, v205, v196
	v_mul_f32_e32 v205, v204, v196
	v_fma_f32 v206, -v195, v205, v204
	v_fmac_f32_e32 v205, v206, v196
	v_fma_f32 v195, -v195, v205, v204
	s_nop 0
	v_div_fmas_f32 v195, v195, v196, v205
	v_div_fixup_f32 v207, v195, v194, 1.0
	v_mul_f32_e32 v160, v207, v160
	v_mul_f32_e32 v161, v207, v161
	v_mul_f32_e32 v162, v207, v162
	v_mul_f32_e32 v163, v207, v163
	v_mul_f32_e32 v164, v207, v164
	v_mul_f32_e32 v165, v207, v165
	v_mul_f32_e32 v166, v207, v166
	v_mul_f32_e32 v167, v207, v167
	v_mul_f32_e32 v168, v207, v168
	v_mul_f32_e32 v169, v207, v169
	v_mul_f32_e32 v170, v207, v170
	v_mul_f32_e32 v171, v207, v171
	v_mul_f32_e32 v172, v207, v172
	v_mul_f32_e32 v173, v207, v173
	v_mul_f32_e32 v174, v207, v174
	v_mul_f32_e32 v175, v207, v175
	v_mov_b32_e32 v208, 0
	v_mov_b32_e32 v209, 0
	v_mov_b32_e32 v210, 0
	v_mov_b32_e32 v193, 0
	v_cvt_scalef32_pk_fp4_f32 v208, v160, v161, 1.0
	v_cvt_scalef32_pk_fp4_f32 v209, v164, v165, 1.0
	v_cvt_scalef32_pk_fp4_f32 v210, v168, v169, 1.0
	v_cvt_scalef32_pk_fp4_f32 v193, v172, v173, 1.0
	v_cvt_scalef32_pk_fp4_f32 v208, v162, v163, 1.0 op_sel:[0,0,1,0]
	v_cvt_scalef32_pk_fp4_f32 v209, v166, v167, 1.0 op_sel:[0,0,1,0]
	v_cvt_scalef32_pk_fp4_f32 v210, v170, v171, 1.0 op_sel:[0,0,1,0]
	v_cvt_scalef32_pk_fp4_f32 v193, v174, v175, 1.0 op_sel:[0,0,1,0]
	global_store_short v213, v208, s[10:11] nt
	s_add_u32 s14, s10, 0x200000
	s_addc_u32 s15, s11, 0
	global_store_short v213, v209, s[14:15] nt
	s_add_u32 s14, s10, 0x400000
	s_addc_u32 s15, s11, 0
	global_store_short v213, v210, s[14:15] nt
	s_add_u32 s14, s10, 0x600000
	s_addc_u32 s15, s11, 0
	global_store_short v213, v193, s[14:15] nt
	s_add_u32 s10, s10, 0x20000
	s_addc_u32 s11, s11, 0
	s_add_u32 s12, s12, 0x2000
	s_addc_u32 s13, s13, 0
	global_load_dwordx4 v[160:163], v212, s[8:9] offset:0 nt
	global_load_dwordx4 v[164:167], v212, s[8:9] offset:1024 nt
	global_load_dwordx4 v[168:171], v212, s[8:9] offset:2048 nt
	global_load_dwordx4 v[172:175], v212, s[8:9] offset:3072 nt
	s_add_u32 s8, s8, 0x800000
	s_addc_u32 s9, s9, 0
	v_max_f32_e32 v24, v32, v45
	v_min_f32_e32 v45, v32, v45
	v_max_f32_e32 v26, v33, v44
	v_min_f32_e32 v44, v33, v44
	v_max_f32_e32 v27, v34, v47
	v_min_f32_e32 v47, v34, v47
	v_max_f32_e32 v255, v35, v46
	v_min_f32_e32 v46, v35, v46
	v_max_f32_e32 v14, v36, v40
	v_min_f32_e32 v40, v36, v40
	v_max_f32_e32 v251, v37, v38
	v_min_f32_e32 v38, v37, v38
	v_max_f32_e32 v250, v39, v43
	v_min_f32_e32 v43, v39, v43
	v_max_f32_e32 v253, v41, v42
	v_min_f32_e32 v42, v41, v42
	v_max_f32_e32 v149, v24, v251
	v_min_f32_e32 v251, v24, v251
	v_max_f32_e32 v28, v26, v250
	v_min_f32_e32 v250, v26, v250
	v_max_f32_e32 v30, v27, v253
	v_min_f32_e32 v253, v27, v253
	v_max_f32_e32 v254, v255, v14
	v_min_f32_e32 v14, v255, v14
	v_max_f32_e32 v12, v38, v45
	v_min_f32_e32 v45, v38, v45
	v_max_f32_e32 v13, v40, v46
	v_min_f32_e32 v46, v40, v46
	v_max_f32_e32 v148, v42, v47
	v_min_f32_e32 v47, v42, v47
	v_max_f32_e32 v106, v43, v44
	v_min_f32_e32 v44, v43, v44
	v_max_f32_e32 v99, v149, v28
	v_min_f32_e32 v28, v149, v28
	v_max_f32_e32 v108, v30, v254
	v_min_f32_e32 v254, v30, v254
	v_max_f32_e32 v29, v14, v251
	v_min_f32_e32 v251, v14, v251
	v_max_f32_e32 v112, v12, v13
	v_min_f32_e32 v13, v12, v13
	v_max_f32_e32 v97, v250, v253
	v_min_f32_e32 v253, v250, v253
	v_max_f32_e32 v113, v148, v106
	v_min_f32_e32 v106, v148, v106
	v_max_f32_e32 v98, v44, v45
	v_min_f32_e32 v45, v44, v45
	v_max_f32_e32 v101, v46, v47
	v_min_f32_e32 v47, v46, v47
	v_max_f32_e32 v150, v99, v108
	v_min_f32_e32 v108, v99, v108
	v_max_f32_e32 v96, v28, v254
	v_min_f32_e32 v254, v28, v254
	v_max_f32_e32 v121, v29, v113
	v_min_f32_e32 v113, v29, v113
	v_max_f32_e32 v103, v251, v106
	v_min_f32_e32 v106, v251, v106
	v_max_f32_e32 v125, v112, v97
	v_min_f32_e32 v97, v112, v97
	v_max_f32_e32 v252, v13, v253
	v_min_f32_e32 v253, v13, v253
	v_max_f32_e32 v109, v98, v101
	v_min_f32_e32 v101, v98, v101
	v_max_f32_e32 v100, v45, v47
	v_min_f32_e32 v47, v45, v47
	v_max_f32_e32 v2, v96, v108
	v_min_f32_e32 v108, v96, v108
	v_max_f32_e32 v114, v254, v109
	v_min_f32_e32 v109, v254, v109
	v_max_f32_e32 v0, v121, v125
	v_min_f32_e32 v125, v121, v125
	v_max_f32_e32 v1, v103, v97
	v_min_f32_e32 v97, v103, v97
	v_max_f32_e32 v117, v252, v113
	v_min_f32_e32 v113, v252, v113
	v_max_f32_e32 v116, v253, v106
	v_min_f32_e32 v106, v253, v106
	v_max_f32_e32 v4, v100, v101
	v_min_f32_e32 v101, v100, v101
	v_max_f32_e32 v107, v2, v0
	v_min_f32_e32 v0, v2, v0
	v_max_f32_e32 v18, v108, v125
	v_min_f32_e32 v125, v108, v125
	v_max_f32_e32 v122, v1, v117
	v_min_f32_e32 v117, v1, v117
	v_max_f32_e32 v20, v97, v113
	v_min_f32_e32 v113, v97, v113
	v_max_f32_e32 v16, v116, v4
	v_min_f32_e32 v4, v116, v4
	v_max_f32_e32 v17, v106, v101
	v_min_f32_e32 v101, v106, v101
	v_max_f32_e32 v19, v18, v0
	v_min_f32_e32 v0, v18, v0
	v_max_f32_e32 v127, v114, v125
	v_min_f32_e32 v125, v114, v125
	v_max_f32_e32 v32, v16, v109
	v_min_f32_e32 v109, v16, v109
	v_max_f32_e32 v33, v17, v4
	v_min_f32_e32 v4, v17, v4
	v_max_f32_e32 v34, v127, v122
	v_min_f32_e32 v122, v127, v122
	v_max_f32_e32 v35, v125, v117
	v_min_f32_e32 v117, v125, v117
	v_max_f32_e32 v36, v20, v32
	v_min_f32_e32 v32, v20, v32
	v_max_f32_e32 v37, v113, v109
	v_min_f32_e32 v109, v113, v109
	v_max_f32_e32 v39, v34, v0
	v_min_f32_e32 v0, v34, v0
	v_max_f32_e32 v41, v122, v35
	v_min_f32_e32 v35, v122, v35
	v_max_f32_e32 v24, v36, v117
	v_min_f32_e32 v117, v36, v117
	v_max_f32_e32 v26, v32, v37
	v_min_f32_e32 v37, v32, v37
	v_max_f32_e32 v27, v33, v109
	v_min_f32_e32 v109, v33, v109
	v_max_f32_e32 v255, v35, v24
	v_min_f32_e32 v24, v35, v24
	v_max_f32_e32 v38, v117, v26
	v_min_f32_e32 v26, v117, v26
	v_max_f32_e32 v40, v48, v61
	v_min_f32_e32 v61, v48, v61
	v_max_f32_e32 v42, v49, v60
	v_min_f32_e32 v60, v49, v60
	v_max_f32_e32 v43, v50, v63
	v_min_f32_e32 v63, v50, v63
	v_max_f32_e32 v149, v51, v62
	v_min_f32_e32 v62, v51, v62
	v_max_f32_e32 v30, v52, v56
	v_min_f32_e32 v56, v52, v56
	v_max_f32_e32 v14, v53, v54
	v_min_f32_e32 v54, v53, v54
	v_max_f32_e32 v12, v55, v59
	v_min_f32_e32 v59, v55, v59
	v_max_f32_e32 v250, v57, v58
	v_min_f32_e32 v58, v57, v58
	v_max_f32_e32 v148, v40, v14
	v_min_f32_e32 v14, v40, v14
	v_max_f32_e32 v44, v42, v12
	v_min_f32_e32 v12, v42, v12
	v_max_f32_e32 v46, v43, v250
	v_min_f32_e32 v250, v43, v250
	v_max_f32_e32 v99, v149, v30
	v_min_f32_e32 v30, v149, v30
	v_max_f32_e32 v28, v54, v61
	v_min_f32_e32 v61, v54, v61
	v_max_f32_e32 v29, v56, v62
	v_min_f32_e32 v62, v56, v62
	v_max_f32_e32 v251, v58, v63
	v_min_f32_e32 v63, v58, v63
	v_max_f32_e32 v112, v59, v60
	v_min_f32_e32 v60, v59, v60
	v_max_f32_e32 v13, v148, v44
	v_min_f32_e32 v44, v148, v44
	v_max_f32_e32 v98, v46, v99
	v_min_f32_e32 v99, v46, v99
	v_max_f32_e32 v45, v30, v14
	v_min_f32_e32 v14, v30, v14
	v_max_f32_e32 v96, v28, v29
	v_min_f32_e32 v29, v28, v29
	v_max_f32_e32 v254, v12, v250
	v_min_f32_e32 v250, v12, v250
	v_max_f32_e32 v121, v251, v112
	v_min_f32_e32 v112, v251, v112
	v_max_f32_e32 v103, v60, v61
	v_min_f32_e32 v61, v60, v61
	v_max_f32_e32 v252, v62, v63
	v_min_f32_e32 v63, v62, v63
	v_max_f32_e32 v253, v13, v98
	v_min_f32_e32 v98, v13, v98
	v_max_f32_e32 v100, v44, v99
	v_min_f32_e32 v99, v44, v99
	v_max_f32_e32 v2, v45, v121
	v_min_f32_e32 v121, v45, v121
	v_max_f32_e32 v108, v14, v112
	v_min_f32_e32 v112, v14, v112
	v_max_f32_e32 v1, v96, v254
	v_min_f32_e32 v254, v96, v254
	v_max_f32_e32 v97, v29, v250
	v_min_f32_e32 v250, v29, v250
	v_max_f32_e32 v116, v103, v252
	v_min_f32_e32 v252, v103, v252
	v_max_f32_e32 v106, v61, v63
	v_min_f32_e32 v63, v61, v63
	v_max_f32_e32 v18, v100, v98
	v_min_f32_e32 v98, v100, v98
	v_max_f32_e32 v114, v99, v116
	v_min_f32_e32 v116, v99, v116
	v_max_f32_e32 v16, v2, v1
	v_min_f32_e32 v1, v2, v1
	v_max_f32_e32 v17, v108, v254
	v_min_f32_e32 v254, v108, v254
	v_max_f32_e32 v127, v97, v121
	v_min_f32_e32 v121, v97, v121
	v_max_f32_e32 v125, v250, v112
	v_min_f32_e32 v112, v250, v112
	v_max_f32_e32 v20, v106, v252
	v_min_f32_e32 v252, v106, v252
	v_max_f32_e32 v113, v18, v16
	v_min_f32_e32 v16, v18, v16
	v_max_f32_e32 v34, v98, v1
	v_min_f32_e32 v1, v98, v1
	v_max_f32_e32 v122, v17, v127
	v_min_f32_e32 v127, v17, v127
	v_max_f32_e32 v36, v254, v121
	v_min_f32_e32 v121, v254, v121
	v_max_f32_e32 v32, v125, v20
	v_min_f32_e32 v20, v125, v20
	v_max_f32_e32 v33, v112, v252
	v_min_f32_e32 v252, v112, v252
	v_max_f32_e32 v35, v34, v16
	v_min_f32_e32 v16, v34, v16
	v_max_f32_e32 v117, v114, v1
	v_min_f32_e32 v1, v114, v1
	v_max_f32_e32 v48, v32, v116
	v_min_f32_e32 v116, v32, v116
	v_max_f32_e32 v49, v33, v20
	v_min_f32_e32 v20, v33, v20
	v_max_f32_e32 v50, v117, v122
	v_min_f32_e32 v122, v117, v122
	v_max_f32_e32 v51, v1, v127
	v_min_f32_e32 v127, v1, v127
	v_max_f32_e32 v52, v36, v48
	v_min_f32_e32 v48, v36, v48
	v_max_f32_e32 v53, v121, v116
	v_min_f32_e32 v116, v121, v116
	v_max_f32_e32 v55, v50, v16
	v_min_f32_e32 v16, v50, v16
	v_max_f32_e32 v57, v122, v51
	v_min_f32_e32 v51, v122, v51
	v_max_f32_e32 v40, v52, v127
	v_min_f32_e32 v127, v52, v127
	v_max_f32_e32 v42, v48, v53
	v_min_f32_e32 v53, v48, v53
	v_max_f32_e32 v43, v49, v116
	v_min_f32_e32 v116, v49, v116
	v_max_f32_e32 v149, v51, v40
	v_min_f32_e32 v40, v51, v40
	v_max_f32_e32 v54, v127, v42
	v_min_f32_e32 v42, v127, v42
	s_waitcnt vmcnt(0)
	v_pk_mul_f32 v[160:161], v[160:161], v[176:177]
	v_pk_mul_f32 v[162:163], v[162:163], v[178:179]
	v_pk_mul_f32 v[164:165], v[164:165], v[180:181]
	v_pk_mul_f32 v[166:167], v[166:167], v[182:183]
	v_pk_mul_f32 v[168:169], v[168:169], v[184:185]
	v_pk_mul_f32 v[170:171], v[170:171], v[186:187]
	v_pk_mul_f32 v[172:173], v[172:173], v[188:189]
	v_pk_mul_f32 v[174:175], v[174:175], v[190:191]
	v_max3_f32 v192, |v160|, |v161|, |v162|
	v_max3_f32 v192, |v163|, |v164|, v192
	v_max3_f32 v192, |v165|, |v166|, v192
	v_max3_f32 v192, |v167|, |v168|, v192
	v_max3_f32 v192, |v169|, |v170|, v192
	v_max3_f32 v192, |v171|, |v172|, v192
	v_max3_f32 v192, |v173|, |v174|, v192
	v_max_f32_e64 v192, |v175|, v192
	s_nop 1
	v_mov_b32_dpp v193, v192 quad_perm:[1,0,3,2] row_mask:0xf bank_mask:0xf bound_ctrl:1
	v_max_f32_e32 v192, v192, v193
	s_nop 1
	v_mov_b32_dpp v193, v192 quad_perm:[2,3,0,1] row_mask:0xf bank_mask:0xf bound_ctrl:1
	v_max_f32_e32 v192, v192, v193
	s_nop 1
	v_mov_b32_dpp v193, v192 row_half_mirror row_mask:0xf bank_mask:0xf bound_ctrl:1
	v_max_f32_e32 v192, v192, v193
	s_nop 1
	v_mov_b32_dpp v193, v192 row_mirror row_mask:0xf bank_mask:0xf bound_ctrl:1
	v_max_f32_e32 v192, v192, v193
	v_mov_b32_e32 v193, v192
	s_nop 1
	v_permlane16_swap_b32_e32 v192, v193
	s_nop 1
	v_max_f32_e32 v192, v192, v193
	v_mov_b32_e32 v193, v192
	s_nop 1
	v_permlane32_swap_b32_e32 v192, v193
	s_nop 1
	v_max_f32_e32 v192, v192, v193
	v_max_f32_e32 v192, 0xda24260, v192
	v_mul_f32_e32 v194, 0x3e2aaaab, v192
	global_store_dword v214, v194, s[12:13]
	v_div_scale_f32 v195, s[26:27], v194, v194, 1.0
	v_rcp_f32_e32 v196, v195
	v_div_scale_f32 v204, vcc, 1.0, v194, 1.0
	v_fma_f32 v205, -v195, v196, 1.0
	v_fmac_f32_e32 v196, v205, v196
	v_mul_f32_e32 v205, v204, v196
	v_fma_f32 v206, -v195, v205, v204
	v_fmac_f32_e32 v205, v206, v196
	v_fma_f32 v195, -v195, v205, v204
	s_nop 0
	v_div_fmas_f32 v195, v195, v196, v205
	v_div_fixup_f32 v207, v195, v194, 1.0
	v_mul_f32_e32 v160, v207, v160
	v_mul_f32_e32 v161, v207, v161
	v_mul_f32_e32 v162, v207, v162
	v_mul_f32_e32 v163, v207, v163
	v_mul_f32_e32 v164, v207, v164
	v_mul_f32_e32 v165, v207, v165
	v_mul_f32_e32 v166, v207, v166
	v_mul_f32_e32 v167, v207, v167
	v_mul_f32_e32 v168, v207, v168
	v_mul_f32_e32 v169, v207, v169
	v_mul_f32_e32 v170, v207, v170
	v_mul_f32_e32 v171, v207, v171
	v_mul_f32_e32 v172, v207, v172
	v_mul_f32_e32 v173, v207, v173
	v_mul_f32_e32 v174, v207, v174
	v_mul_f32_e32 v175, v207, v175
	v_mov_b32_e32 v208, 0
	v_mov_b32_e32 v209, 0
	v_mov_b32_e32 v210, 0
	v_mov_b32_e32 v193, 0
	v_cvt_scalef32_pk_fp4_f32 v208, v160, v161, 1.0
	v_cvt_scalef32_pk_fp4_f32 v209, v164, v165, 1.0
	v_cvt_scalef32_pk_fp4_f32 v210, v168, v169, 1.0
	v_cvt_scalef32_pk_fp4_f32 v193, v172, v173, 1.0
	v_cvt_scalef32_pk_fp4_f32 v208, v162, v163, 1.0 op_sel:[0,0,1,0]
	v_cvt_scalef32_pk_fp4_f32 v209, v166, v167, 1.0 op_sel:[0,0,1,0]
	v_cvt_scalef32_pk_fp4_f32 v210, v170, v171, 1.0 op_sel:[0,0,1,0]
	v_cvt_scalef32_pk_fp4_f32 v193, v174, v175, 1.0 op_sel:[0,0,1,0]
	global_store_short v213, v208, s[10:11] nt
	s_add_u32 s14, s10, 0x200000
	s_addc_u32 s15, s11, 0
	global_store_short v213, v209, s[14:15] nt
	s_add_u32 s14, s10, 0x400000
	s_addc_u32 s15, s11, 0
	global_store_short v213, v210, s[14:15] nt
	s_add_u32 s14, s10, 0x600000
	s_addc_u32 s15, s11, 0
	global_store_short v213, v193, s[14:15] nt
	s_add_u32 s10, s10, 0x20000
	s_addc_u32 s11, s11, 0
	s_add_u32 s12, s12, 0x2000
	s_addc_u32 s13, s13, 0
	global_load_dwordx4 v[160:163], v212, s[8:9] offset:0 nt
	global_load_dwordx4 v[164:167], v212, s[8:9] offset:1024 nt
	global_load_dwordx4 v[168:171], v212, s[8:9] offset:2048 nt
	global_load_dwordx4 v[172:175], v212, s[8:9] offset:3072 nt
	s_add_u32 s8, s8, 0x800000
	s_addc_u32 s9, s9, 0
	v_max_f32_e32 v105, v105, v31
	v_max_f32_e32 v120, v120, v110
	v_max_f32_e32 v126, v126, v123
	v_max_f32_e32 v7, v7, v118
	v_max_f32_e32 v115, v115, v11
	v_max_f32_e32 v9, v9, v21
	v_max_f32_e32 v147, v147, v10
	v_max_f32_e32 v144, v144, v22
	v_max_f32_e32 v6, v6, v8
	v_max_f32_e32 v145, v145, v249
	v_max_f32_e32 v5, v5, v25
	v_max_f32_e32 v146, v146, v124
	v_max_f32_e32 v111, v111, v23
	v_max_f32_e32 v119, v119, v3
	v_max_f32_e32 v104, v104, v102
	v_max_f32_e32 v15, v15, v151
	v_max_f32_e32 v56, v105, v6
	v_min_f32_e32 v6, v105, v6
	v_max_f32_e32 v58, v120, v145
	v_min_f32_e32 v145, v120, v145
	v_max_f32_e32 v59, v126, v5
	v_min_f32_e32 v5, v126, v5
	v_max_f32_e32 v148, v7, v146
	v_min_f32_e32 v146, v7, v146
	v_max_f32_e32 v46, v115, v111
	v_min_f32_e32 v111, v115, v111
	v_max_f32_e32 v30, v9, v119
	v_min_f32_e32 v119, v9, v119
	v_max_f32_e32 v28, v147, v104
	v_min_f32_e32 v104, v147, v104
	v_max_f32_e32 v12, v144, v15
	v_min_f32_e32 v15, v144, v15
	v_max_f32_e32 v251, v56, v46
	v_min_f32_e32 v46, v56, v46
	v_max_f32_e32 v60, v58, v30
	v_min_f32_e32 v30, v58, v30
	v_max_f32_e32 v62, v59, v28
	v_min_f32_e32 v28, v59, v28
	v_max_f32_e32 v13, v148, v12
	v_min_f32_e32 v12, v148, v12
	v_max_f32_e32 v44, v6, v111
	v_min_f32_e32 v111, v6, v111
	v_max_f32_e32 v45, v145, v119
	v_min_f32_e32 v119, v145, v119
	v_max_f32_e32 v14, v5, v104
	v_min_f32_e32 v104, v5, v104
	v_max_f32_e32 v96, v146, v15
	v_min_f32_e32 v15, v146, v15
	v_max_f32_e32 v29, v251, v62
	v_min_f32_e32 v62, v251, v62
	v_max_f32_e32 v103, v60, v13
	v_min_f32_e32 v13, v60, v13
	v_max_f32_e32 v61, v46, v28
	v_min_f32_e32 v28, v46, v28
	v_max_f32_e32 v100, v30, v12
	v_min_f32_e32 v12, v30, v12
	v_max_f32_e32 v99, v44, v14
	v_min_f32_e32 v14, v44, v14
	v_max_f32_e32 v2, v45, v96
	v_min_f32_e32 v96, v45, v96
	v_max_f32_e32 v108, v111, v104
	v_min_f32_e32 v104, v111, v104
	v_max_f32_e32 v97, v119, v15
	v_min_f32_e32 v15, v119, v15
	v_max_f32_e32 v250, v29, v103
	v_min_f32_e32 v103, v29, v103
	v_max_f32_e32 v106, v62, v13
	v_min_f32_e32 v13, v62, v13
	v_max_f32_e32 v18, v61, v100
	v_min_f32_e32 v100, v61, v100
	v_max_f32_e32 v98, v28, v12
	v_min_f32_e32 v12, v28, v12
	v_max_f32_e32 v17, v99, v2
	v_min_f32_e32 v2, v99, v2
	v_max_f32_e32 v254, v14, v96
	v_min_f32_e32 v96, v14, v96
	v_max_f32_e32 v125, v108, v97
	v_min_f32_e32 v97, v108, v97
	v_max_f32_e32 v112, v104, v15
	v_min_f32_e32 v15, v104, v15
	v_max_f32_e32 v150, v150, v63
	v_max_f32_e32 v107, v107, v252
	v_max_f32_e32 v19, v19, v20
	v_max_f32_e32 v39, v39, v116
	v_max_f32_e32 v0, v0, v43
	v_max_f32_e32 v41, v41, v53
	v_max_f32_e32 v255, v255, v42
	v_max_f32_e32 v24, v24, v54
	v_max_f32_e32 v38, v38, v40
	v_max_f32_e32 v26, v26, v149
	v_max_f32_e32 v37, v37, v57
	v_max_f32_e32 v27, v27, v16
	v_max_f32_e32 v109, v109, v55
	v_max_f32_e32 v4, v4, v35
	v_max_f32_e32 v101, v101, v113
	v_max_f32_e32 v47, v47, v253
	v_max_f32_e32 v34, v150, v38
	v_min_f32_e32 v38, v150, v38
	v_max_f32_e32 v114, v107, v26
	v_min_f32_e32 v26, v107, v26
	v_max_f32_e32 v32, v19, v37
	v_min_f32_e32 v37, v19, v37
	v_max_f32_e32 v33, v39, v27
	v_min_f32_e32 v27, v39, v27
	v_max_f32_e32 v117, v0, v109
	v_min_f32_e32 v109, v0, v109
	v_max_f32_e32 v1, v41, v4
	v_min_f32_e32 v4, v41, v4
	v_max_f32_e32 v36, v255, v101
	v_min_f32_e32 v101, v255, v101
	v_max_f32_e32 v121, v24, v47
	v_min_f32_e32 v47, v24, v47
	v_max_f32_e32 v50, v34, v117
	v_min_f32_e32 v117, v34, v117
	v_max_f32_e32 v122, v114, v1
	v_min_f32_e32 v1, v114, v1
	v_max_f32_e32 v52, v32, v36
	v_min_f32_e32 v36, v32, v36
	v_max_f32_e32 v48, v33, v121
	v_min_f32_e32 v121, v33, v121
	v_max_f32_e32 v49, v38, v109
	v_min_f32_e32 v109, v38, v109
	v_max_f32_e32 v51, v26, v4
	v_min_f32_e32 v4, v26, v4
	v_max_f32_e32 v127, v37, v101
	v_min_f32_e32 v101, v37, v101
	v_max_f32_e32 v151, v27, v47
	v_min_f32_e32 v47, v27, v47
	v_max_f32_e32 v102, v50, v52
	v_min_f32_e32 v52, v50, v52
	v_max_f32_e32 v3, v122, v48
	v_min_f32_e32 v48, v122, v48
	v_max_f32_e32 v23, v117, v36
	v_min_f32_e32 v36, v117, v36
	v_max_f32_e32 v124, v1, v121
	v_min_f32_e32 v121, v1, v121
	v_max_f32_e32 v25, v49, v127
	v_min_f32_e32 v127, v49, v127
	v_max_f32_e32 v249, v51, v151
	v_min_f32_e32 v151, v51, v151
	v_max_f32_e32 v8, v109, v101
	v_min_f32_e32 v101, v109, v101
	v_max_f32_e32 v22, v4, v47
	v_min_f32_e32 v47, v4, v47
	v_max_f32_e32 v10, v102, v3
	v_min_f32_e32 v3, v102, v3
	v_max_f32_e32 v21, v52, v48
	v_min_f32_e32 v48, v52, v48
	v_max_f32_e32 v11, v23, v124
	v_min_f32_e32 v124, v23, v124
	v_max_f32_e32 v118, v36, v121
	v_min_f32_e32 v121, v36, v121
	v_max_f32_e32 v123, v25, v249
	v_min_f32_e32 v249, v25, v249
	v_max_f32_e32 v110, v127, v151
	v_min_f32_e32 v151, v127, v151
	v_max_f32_e32 v31, v8, v22
	v_min_f32_e32 v22, v8, v22
	v_max_f32_e32 v105, v101, v47
	v_min_f32_e32 v47, v101, v47
	v_max_f32_e32 v250, v250, v47
	v_max_f32_e32 v103, v103, v105
	v_max_f32_e32 v106, v106, v22
	v_max_f32_e32 v13, v13, v31
	v_max_f32_e32 v18, v18, v151
	v_max_f32_e32 v100, v100, v110
	v_max_f32_e32 v98, v98, v249
	v_max_f32_e32 v12, v12, v123
	v_max_f32_e32 v17, v17, v121
	v_max_f32_e32 v2, v2, v118
	v_max_f32_e32 v254, v254, v124
	v_max_f32_e32 v96, v96, v11
	v_max_f32_e32 v125, v125, v48
	v_max_f32_e32 v97, v97, v21
	v_max_f32_e32 v112, v112, v3
	v_max_f32_e32 v15, v15, v10
	v_max_f32_e32 v120, v250, v17
	v_min_f32_e32 v17, v250, v17
	v_max_f32_e32 v126, v103, v2
	v_min_f32_e32 v2, v103, v2
	v_max_f32_e32 v7, v106, v254
	v_min_f32_e32 v254, v106, v254
	v_max_f32_e32 v115, v13, v96
	v_min_f32_e32 v96, v13, v96
	v_max_f32_e32 v9, v18, v125
	v_min_f32_e32 v125, v18, v125
	v_max_f32_e32 v147, v100, v97
	v_min_f32_e32 v97, v100, v97
	v_max_f32_e32 v144, v98, v112
	v_min_f32_e32 v112, v98, v112
	v_max_f32_e32 v56, v12, v15
	v_min_f32_e32 v15, v12, v15
	v_max_f32_e32 v58, v120, v9
	v_min_f32_e32 v9, v120, v9
	v_max_f32_e32 v59, v126, v147
	v_min_f32_e32 v147, v126, v147
	v_max_f32_e32 v148, v7, v144
	v_min_f32_e32 v144, v7, v144
	v_max_f32_e32 v6, v115, v56
	v_min_f32_e32 v56, v115, v56
	v_max_f32_e32 v145, v17, v125
	v_min_f32_e32 v125, v17, v125
	v_max_f32_e32 v5, v2, v97
	v_min_f32_e32 v97, v2, v97
	v_max_f32_e32 v146, v254, v112
	v_min_f32_e32 v112, v254, v112
	v_max_f32_e32 v251, v96, v15
	v_min_f32_e32 v15, v96, v15
	v_max_f32_e32 v60, v58, v148
	v_min_f32_e32 v148, v58, v148
	v_max_f32_e32 v46, v59, v6
	v_min_f32_e32 v6, v59, v6
	v_max_f32_e32 v30, v9, v144
	v_min_f32_e32 v144, v9, v144
	v_max_f32_e32 v44, v147, v56
	v_min_f32_e32 v56, v147, v56
	v_max_f32_e32 v45, v145, v146
	v_min_f32_e32 v146, v145, v146
	v_max_f32_e32 v111, v5, v251
	v_min_f32_e32 v251, v5, v251
	v_max_f32_e32 v119, v125, v112
	v_min_f32_e32 v112, v125, v112
	v_max_f32_e32 v29, v97, v15
	v_min_f32_e32 v15, v97, v15
	v_max_f32_e32 v62, v60, v46
	v_min_f32_e32 v46, v60, v46
	v_max_f32_e32 v61, v148, v6
	v_min_f32_e32 v6, v148, v6
	v_max_f32_e32 v28, v30, v44
	v_min_f32_e32 v44, v30, v44
	v_max_f32_e32 v99, v144, v56
	v_min_f32_e32 v56, v144, v56
	v_max_f32_e32 v14, v45, v111
	v_min_f32_e32 v111, v45, v111
	v_max_f32_e32 v108, v146, v251
	v_min_f32_e32 v251, v146, v251
	v_max_f32_e32 v104, v119, v29
	v_min_f32_e32 v29, v119, v29
	v_max_f32_e32 v253, v112, v15
	v_min_f32_e32 v15, v112, v15
	v_mov_b32_e32 v113, v62
	v_mov_b32_e32 v35, v46
	v_mov_b32_e32 v55, v61
	v_mov_b32_e32 v16, v6
	v_mov_b32_e32 v57, v28
	v_mov_b32_e32 v149, v44
	v_mov_b32_e32 v40, v99
	v_mov_b32_e32 v54, v56
	v_mov_b32_e32 v42, v14
	v_mov_b32_e32 v53, v111
	v_mov_b32_e32 v43, v108
	v_mov_b32_e32 v116, v251
	v_mov_b32_e32 v20, v104
	v_mov_b32_e32 v252, v29
	v_mov_b32_e32 v63, v253
	v_mov_b32_e32 v150, v15
	s_nop 1
	v_permlane32_swap_b32_e32 v62, v113
	v_permlane32_swap_b32_e32 v46, v35
	v_permlane32_swap_b32_e32 v61, v55
	v_permlane32_swap_b32_e32 v6, v16
	v_permlane32_swap_b32_e32 v28, v57
	v_permlane32_swap_b32_e32 v44, v149
	v_permlane32_swap_b32_e32 v99, v40
	v_permlane32_swap_b32_e32 v56, v54
	v_permlane32_swap_b32_e32 v14, v42
	v_permlane32_swap_b32_e32 v111, v53
	v_permlane32_swap_b32_e32 v108, v43
	v_permlane32_swap_b32_e32 v251, v116
	v_permlane32_swap_b32_e32 v104, v20
	v_permlane32_swap_b32_e32 v29, v252
	v_permlane32_swap_b32_e32 v253, v63
	v_permlane32_swap_b32_e32 v15, v150
	s_nop 1
	v_max_f32_e32 v62, v62, v150
	v_max_f32_e32 v46, v46, v63
	v_max_f32_e32 v61, v61, v252
	v_max_f32_e32 v6, v6, v20
	v_max_f32_e32 v28, v28, v116
	v_max_f32_e32 v44, v44, v43
	v_max_f32_e32 v99, v99, v53
	v_max_f32_e32 v56, v56, v42
	v_max_f32_e32 v14, v14, v54
	v_max_f32_e32 v111, v111, v40
	v_max_f32_e32 v108, v108, v149
	v_max_f32_e32 v251, v251, v57
	v_max_f32_e32 v104, v104, v16
	v_max_f32_e32 v29, v29, v55
	v_max_f32_e32 v253, v253, v35
	v_max_f32_e32 v15, v15, v113
	v_max_f32_e32 v107, v62, v14
	v_min_f32_e32 v14, v62, v14
	v_max_f32_e32 v19, v46, v111
	v_min_f32_e32 v111, v46, v111
	v_max_f32_e32 v39, v61, v108
	v_min_f32_e32 v108, v61, v108
	v_max_f32_e32 v0, v6, v251
	v_min_f32_e32 v251, v6, v251
	v_max_f32_e32 v41, v28, v104
	v_min_f32_e32 v104, v28, v104
	v_max_f32_e32 v255, v44, v29
	v_min_f32_e32 v29, v44, v29
	v_max_f32_e32 v24, v99, v253
	v_min_f32_e32 v253, v99, v253
	v_max_f32_e32 v34, v56, v15
	v_min_f32_e32 v15, v56, v15
	v_max_f32_e32 v114, v107, v41
	v_min_f32_e32 v41, v107, v41
	v_max_f32_e32 v32, v19, v255
	v_min_f32_e32 v255, v19, v255
	v_max_f32_e32 v33, v39, v24
	v_min_f32_e32 v24, v39, v24
	v_max_f32_e32 v38, v0, v34
	v_min_f32_e32 v34, v0, v34
	v_max_f32_e32 v26, v14, v104
	v_min_f32_e32 v104, v14, v104
	v_max_f32_e32 v37, v111, v29
	v_min_f32_e32 v29, v111, v29
	v_max_f32_e32 v27, v108, v253
	v_min_f32_e32 v253, v108, v253
	v_max_f32_e32 v50, v251, v15
	v_min_f32_e32 v15, v251, v15
	v_max_f32_e32 v122, v114, v33
	v_min_f32_e32 v33, v114, v33
	v_max_f32_e32 v117, v32, v38
	v_min_f32_e32 v38, v32, v38
	v_max_f32_e32 v1, v41, v24
	v_min_f32_e32 v24, v41, v24
	v_max_f32_e32 v49, v255, v34
	v_min_f32_e32 v34, v255, v34
	v_max_f32_e32 v51, v26, v27
	v_min_f32_e32 v27, v26, v27
	v_max_f32_e32 v109, v37, v50
	v_min_f32_e32 v50, v37, v50
	v_max_f32_e32 v4, v104, v253
	v_min_f32_e32 v253, v104, v253
	v_max_f32_e32 v102, v29, v15
	v_min_f32_e32 v15, v29, v15
	v_max_f32_e32 v128, v122, v117
	v_min_f32_e32 v129, v122, v117
	v_max_f32_e32 v130, v33, v38
	v_min_f32_e32 v131, v33, v38
	v_max_f32_e32 v132, v1, v49
	v_min_f32_e32 v133, v1, v49
	v_max_f32_e32 v134, v24, v34
	v_min_f32_e32 v135, v24, v34
	v_max_f32_e32 v136, v51, v109
	v_min_f32_e32 v137, v51, v109
	v_max_f32_e32 v138, v27, v50
	v_min_f32_e32 v139, v27, v50
	v_max_f32_e32 v140, v4, v102
	v_min_f32_e32 v141, v4, v102
	v_max_f32_e32 v142, v253, v15
	v_min_f32_e32 v143, v253, v15
	s_waitcnt vmcnt(0)
	v_pk_mul_f32 v[160:161], v[160:161], v[176:177]
	v_pk_mul_f32 v[162:163], v[162:163], v[178:179]
	v_pk_mul_f32 v[164:165], v[164:165], v[180:181]
	v_pk_mul_f32 v[166:167], v[166:167], v[182:183]
	v_pk_mul_f32 v[168:169], v[168:169], v[184:185]
	v_pk_mul_f32 v[170:171], v[170:171], v[186:187]
	v_pk_mul_f32 v[172:173], v[172:173], v[188:189]
	v_pk_mul_f32 v[174:175], v[174:175], v[190:191]
	v_max3_f32 v192, |v160|, |v161|, |v162|
	v_max3_f32 v192, |v163|, |v164|, v192
	v_max3_f32 v192, |v165|, |v166|, v192
	v_max3_f32 v192, |v167|, |v168|, v192
	v_max3_f32 v192, |v169|, |v170|, v192
	v_max3_f32 v192, |v171|, |v172|, v192
	v_max3_f32 v192, |v173|, |v174|, v192
	v_max_f32_e64 v192, |v175|, v192
	s_nop 1
	v_mov_b32_dpp v193, v192 quad_perm:[1,0,3,2] row_mask:0xf bank_mask:0xf bound_ctrl:1
	v_max_f32_e32 v192, v192, v193
	s_nop 1
	v_mov_b32_dpp v193, v192 quad_perm:[2,3,0,1] row_mask:0xf bank_mask:0xf bound_ctrl:1
	v_max_f32_e32 v192, v192, v193
	s_nop 1
	v_mov_b32_dpp v193, v192 row_half_mirror row_mask:0xf bank_mask:0xf bound_ctrl:1
	v_max_f32_e32 v192, v192, v193
	s_nop 1
	v_mov_b32_dpp v193, v192 row_mirror row_mask:0xf bank_mask:0xf bound_ctrl:1
	v_max_f32_e32 v192, v192, v193
	v_mov_b32_e32 v193, v192
	s_nop 1
	v_permlane16_swap_b32_e32 v192, v193
	s_nop 1
	v_max_f32_e32 v192, v192, v193
	v_mov_b32_e32 v193, v192
	s_nop 1
	v_permlane32_swap_b32_e32 v192, v193
	s_nop 1
	v_max_f32_e32 v192, v192, v193
	v_max_f32_e32 v192, 0xda24260, v192
	v_mul_f32_e32 v194, 0x3e2aaaab, v192
	global_store_dword v214, v194, s[12:13]
	v_div_scale_f32 v195, s[26:27], v194, v194, 1.0
	v_rcp_f32_e32 v196, v195
	v_div_scale_f32 v204, vcc, 1.0, v194, 1.0
	v_fma_f32 v205, -v195, v196, 1.0
	v_fmac_f32_e32 v196, v205, v196
	v_mul_f32_e32 v205, v204, v196
	v_fma_f32 v206, -v195, v205, v204
	v_fmac_f32_e32 v205, v206, v196
	v_fma_f32 v195, -v195, v205, v204
	s_nop 0
	v_div_fmas_f32 v195, v195, v196, v205
	v_div_fixup_f32 v207, v195, v194, 1.0
	v_mul_f32_e32 v160, v207, v160
	v_mul_f32_e32 v161, v207, v161
	v_mul_f32_e32 v162, v207, v162
	v_mul_f32_e32 v163, v207, v163
	v_mul_f32_e32 v164, v207, v164
	v_mul_f32_e32 v165, v207, v165
	v_mul_f32_e32 v166, v207, v166
	v_mul_f32_e32 v167, v207, v167
	v_mul_f32_e32 v168, v207, v168
	v_mul_f32_e32 v169, v207, v169
	v_mul_f32_e32 v170, v207, v170
	v_mul_f32_e32 v171, v207, v171
	v_mul_f32_e32 v172, v207, v172
	v_mul_f32_e32 v173, v207, v173
	v_mul_f32_e32 v174, v207, v174
	v_mul_f32_e32 v175, v207, v175
	v_mov_b32_e32 v208, 0
	v_mov_b32_e32 v209, 0
	v_mov_b32_e32 v210, 0
	v_mov_b32_e32 v193, 0
	v_cvt_scalef32_pk_fp4_f32 v208, v160, v161, 1.0
	v_cvt_scalef32_pk_fp4_f32 v209, v164, v165, 1.0
	v_cvt_scalef32_pk_fp4_f32 v210, v168, v169, 1.0
	v_cvt_scalef32_pk_fp4_f32 v193, v172, v173, 1.0
	v_cvt_scalef32_pk_fp4_f32 v208, v162, v163, 1.0 op_sel:[0,0,1,0]
	v_cvt_scalef32_pk_fp4_f32 v209, v166, v167, 1.0 op_sel:[0,0,1,0]
	v_cvt_scalef32_pk_fp4_f32 v210, v170, v171, 1.0 op_sel:[0,0,1,0]
	v_cvt_scalef32_pk_fp4_f32 v193, v174, v175, 1.0 op_sel:[0,0,1,0]
	global_store_short v213, v208, s[10:11] nt
	s_add_u32 s14, s10, 0x200000
	s_addc_u32 s15, s11, 0
	global_store_short v213, v209, s[14:15] nt
	s_add_u32 s14, s10, 0x400000
	s_addc_u32 s15, s11, 0
	global_store_short v213, v210, s[14:15] nt
	s_add_u32 s14, s10, 0x600000
	s_addc_u32 s15, s11, 0
	global_store_short v213, v193, s[14:15] nt
	s_add_u32 s10, s10, 0x20000
	s_addc_u32 s11, s11, 0
	s_add_u32 s12, s12, 0x2000
	s_addc_u32 s13, s13, 0
	global_load_dwordx4 v[160:163], v212, s[8:9] offset:0 nt
	global_load_dwordx4 v[164:167], v212, s[8:9] offset:1024 nt
	global_load_dwordx4 v[168:171], v212, s[8:9] offset:2048 nt
	global_load_dwordx4 v[172:175], v212, s[8:9] offset:3072 nt
	s_add_u32 s8, s8, 0x800000
	s_addc_u32 s9, s9, 0
	ds_write_b8 v240, v128 offset:0
	ds_write_b8 v240, v129 offset:1
	ds_write_b8 v240, v130 offset:2
	ds_write_b8 v240, v131 offset:3
	ds_write_b8 v240, v132 offset:4
	ds_write_b8 v240, v133 offset:5
	ds_write_b8 v240, v134 offset:6
	ds_write_b8 v240, v135 offset:7
	ds_write_b8 v240, v136 offset:8
	ds_write_b8 v240, v137 offset:9
	ds_write_b8 v240, v138 offset:10
	ds_write_b8 v240, v139 offset:11
	ds_write_b8 v240, v140 offset:12
	ds_write_b8 v240, v141 offset:13
	ds_write_b8 v240, v142 offset:14
	ds_write_b8 v240, v143 offset:15
	ds_read_b128 v[96:99], v231 offset:32768
	ds_read_b128 v[100:103], v232 offset:32768
	ds_read_b128 v[104:107], v233 offset:32768
	ds_read_b128 v[108:111], v234 offset:32768
	ds_read_b128 v[112:115], v235 offset:32768
	ds_read_b128 v[116:119], v236 offset:32768
	ds_read_b128 v[120:123], v237 offset:32768
	ds_read_b128 v[124:127], v238 offset:32768
	s_waitcnt vmcnt(0)
	s_waitcnt lgkmcnt(4)
	v_mfma_f32_32x32x16_bf16 v[0:15], v[96:99], v[64:67], 0
	v_mfma_f32_32x32x16_bf16 v[0:15], v[100:103], v[68:71], v[0:15]
	v_mfma_f32_32x32x16_bf16 v[0:15], v[104:107], v[72:75], v[0:15]
	v_mfma_f32_32x32x16_bf16 v[0:15], v[108:111], v[76:79], v[0:15]
	ds_read_b128 v[96:99], v231 offset:40960
	ds_read_b128 v[100:103], v232 offset:40960
	ds_read_b128 v[104:107], v233 offset:40960
	ds_read_b128 v[108:111], v234 offset:40960
	s_waitcnt lgkmcnt(4)
	v_mfma_f32_32x32x16_bf16 v[0:15], v[112:115], v[80:83], v[0:15]
	v_mfma_f32_32x32x16_bf16 v[0:15], v[116:119], v[84:87], v[0:15]
	v_mfma_f32_32x32x16_bf16 v[0:15], v[120:123], v[88:91], v[0:15]
	v_mfma_f32_32x32x16_bf16 v[0:15], v[124:127], v[92:95], v[0:15]
	ds_read_b128 v[112:115], v235 offset:40960
	ds_read_b128 v[116:119], v236 offset:40960
	ds_read_b128 v[120:123], v237 offset:40960
	ds_read_b128 v[124:127], v238 offset:40960
	s_waitcnt lgkmcnt(4)
	v_mfma_f32_32x32x16_bf16 v[16:31], v[96:99], v[64:67], 0
	v_mfma_f32_32x32x16_bf16 v[16:31], v[100:103], v[68:71], v[16:31]
	v_mfma_f32_32x32x16_bf16 v[16:31], v[104:107], v[72:75], v[16:31]
	v_mfma_f32_32x32x16_bf16 v[16:31], v[108:111], v[76:79], v[16:31]
	ds_read_b128 v[96:99], v231 offset:49152
	ds_read_b128 v[100:103], v232 offset:49152
	ds_read_b128 v[104:107], v233 offset:49152
	ds_read_b128 v[108:111], v234 offset:49152
	s_waitcnt lgkmcnt(4)
	v_mfma_f32_32x32x16_bf16 v[16:31], v[112:115], v[80:83], v[16:31]
	v_mfma_f32_32x32x16_bf16 v[16:31], v[116:119], v[84:87], v[16:31]
	v_mfma_f32_32x32x16_bf16 v[16:31], v[120:123], v[88:91], v[16:31]
	v_mfma_f32_32x32x16_bf16 v[16:31], v[124:127], v[92:95], v[16:31]
	ds_read_b128 v[112:115], v235 offset:49152
	ds_read_b128 v[116:119], v236 offset:49152
	ds_read_b128 v[120:123], v237 offset:49152
	ds_read_b128 v[124:127], v238 offset:49152
	s_waitcnt lgkmcnt(4)
	v_mfma_f32_32x32x16_bf16 v[32:47], v[96:99], v[64:67], 0
	v_mfma_f32_32x32x16_bf16 v[32:47], v[100:103], v[68:71], v[32:47]
	v_mfma_f32_32x32x16_bf16 v[32:47], v[104:107], v[72:75], v[32:47]
	v_mfma_f32_32x32x16_bf16 v[32:47], v[108:111], v[76:79], v[32:47]
	ds_read_b128 v[96:99], v231 offset:57344
	ds_read_b128 v[100:103], v232 offset:57344
	ds_read_b128 v[104:107], v233 offset:57344
	ds_read_b128 v[108:111], v234 offset:57344
	s_waitcnt lgkmcnt(4)
	v_mfma_f32_32x32x16_bf16 v[32:47], v[112:115], v[80:83], v[32:47]
	v_mfma_f32_32x32x16_bf16 v[32:47], v[116:119], v[84:87], v[32:47]
	v_mfma_f32_32x32x16_bf16 v[32:47], v[120:123], v[88:91], v[32:47]
	v_mfma_f32_32x32x16_bf16 v[32:47], v[124:127], v[92:95], v[32:47]
	ds_read_b128 v[112:115], v235 offset:57344
	ds_read_b128 v[116:119], v236 offset:57344
	ds_read_b128 v[120:123], v237 offset:57344
	ds_read_b128 v[124:127], v238 offset:57344
	s_waitcnt lgkmcnt(4)
	v_mfma_f32_32x32x16_bf16 v[48:63], v[96:99], v[64:67], 0
	v_mfma_f32_32x32x16_bf16 v[48:63], v[100:103], v[68:71], v[48:63]
	v_mfma_f32_32x32x16_bf16 v[48:63], v[104:107], v[72:75], v[48:63]
	v_mfma_f32_32x32x16_bf16 v[48:63], v[108:111], v[76:79], v[48:63]
	s_waitcnt lgkmcnt(0)
	v_mfma_f32_32x32x16_bf16 v[48:63], v[112:115], v[80:83], v[48:63]
	v_mfma_f32_32x32x16_bf16 v[48:63], v[116:119], v[84:87], v[48:63]
	v_mfma_f32_32x32x16_bf16 v[48:63], v[120:123], v[88:91], v[48:63]
	v_mfma_f32_32x32x16_bf16 v[48:63], v[124:127], v[92:95], v[48:63]
	s_nop 11
	v_and_or_b32 v0, v0, s6, v211
	v_or_b32_e32 v0, 0x7b, v0
	v_and_or_b32 v1, v1, s6, v211
	v_or_b32_e32 v1, 0x7a, v1
	v_and_or_b32 v2, v2, s6, v211
	v_or_b32_e32 v2, 0x79, v2
	v_and_or_b32 v3, v3, s6, v211
	v_or_b32_e32 v3, 0x78, v3
	v_and_or_b32 v4, v4, s6, v211
	v_or_b32_e32 v4, 0x73, v4
	v_and_or_b32 v5, v5, s6, v211
	v_or_b32_e32 v5, 0x72, v5
	v_and_or_b32 v6, v6, s6, v211
	v_or_b32_e32 v6, 0x71, v6
	v_and_or_b32 v7, v7, s6, v211
	v_or_b32_e32 v7, 0x70, v7
	v_and_or_b32 v8, v8, s6, v211
	v_or_b32_e32 v8, 0x6b, v8
	v_and_or_b32 v9, v9, s6, v211
	v_or_b32_e32 v9, 0x6a, v9
	v_and_or_b32 v10, v10, s6, v211
	v_or_b32_e32 v10, 0x69, v10
	v_and_or_b32 v11, v11, s6, v211
	v_or_b32_e32 v11, 0x68, v11
	v_and_or_b32 v12, v12, s6, v211
	v_or_b32_e32 v12, 0x63, v12
	v_and_or_b32 v13, v13, s6, v211
	v_or_b32_e32 v13, 0x62, v13
	v_and_or_b32 v14, v14, s6, v211
	v_or_b32_e32 v14, 0x61, v14
	v_and_or_b32 v15, v15, s6, v211
	v_or_b32_e32 v15, 0x60, v15
	v_and_or_b32 v16, v16, s6, v211
	v_or_b32_e32 v16, 0x5b, v16
	v_and_or_b32 v17, v17, s6, v211
	v_or_b32_e32 v17, 0x5a, v17
	v_and_or_b32 v18, v18, s6, v211
	v_or_b32_e32 v18, 0x59, v18
	v_and_or_b32 v19, v19, s6, v211
	v_or_b32_e32 v19, 0x58, v19
	v_and_or_b32 v20, v20, s6, v211
	v_or_b32_e32 v20, 0x53, v20
	v_and_or_b32 v21, v21, s6, v211
	v_or_b32_e32 v21, 0x52, v21
	v_and_or_b32 v22, v22, s6, v211
	v_or_b32_e32 v22, 0x51, v22
	v_and_or_b32 v23, v23, s6, v211
	v_or_b32_e32 v23, 0x50, v23
	v_and_or_b32 v24, v24, s6, v211
	v_or_b32_e32 v24, 0x4b, v24
	v_and_or_b32 v25, v25, s6, v211
	v_or_b32_e32 v25, 0x4a, v25
	v_and_or_b32 v26, v26, s6, v211
	v_or_b32_e32 v26, 0x49, v26
	v_and_or_b32 v27, v27, s6, v211
	v_or_b32_e32 v27, 0x48, v27
	v_and_or_b32 v28, v28, s6, v211
	v_or_b32_e32 v28, 0x43, v28
	v_and_or_b32 v29, v29, s6, v211
	v_or_b32_e32 v29, 0x42, v29
	v_and_or_b32 v30, v30, s6, v211
	v_or_b32_e32 v30, 0x41, v30
	v_and_or_b32 v31, v31, s6, v211
	v_or_b32_e32 v31, 64, v31
	v_and_or_b32 v32, v32, s6, v211
	v_or_b32_e32 v32, 59, v32
	v_and_or_b32 v33, v33, s6, v211
	v_or_b32_e32 v33, 58, v33
	v_and_or_b32 v34, v34, s6, v211
	v_or_b32_e32 v34, 57, v34
	v_and_or_b32 v35, v35, s6, v211
	v_or_b32_e32 v35, 56, v35
	v_and_or_b32 v36, v36, s6, v211
	v_or_b32_e32 v36, 51, v36
	v_and_or_b32 v37, v37, s6, v211
	v_or_b32_e32 v37, 50, v37
	v_and_or_b32 v38, v38, s6, v211
	v_or_b32_e32 v38, 49, v38
	v_and_or_b32 v39, v39, s6, v211
	v_or_b32_e32 v39, 48, v39
	v_and_or_b32 v40, v40, s6, v211
	v_or_b32_e32 v40, 43, v40
	v_and_or_b32 v41, v41, s6, v211
	v_or_b32_e32 v41, 42, v41
	v_and_or_b32 v42, v42, s6, v211
	v_or_b32_e32 v42, 41, v42
	v_and_or_b32 v43, v43, s6, v211
	v_or_b32_e32 v43, 40, v43
	v_and_or_b32 v44, v44, s6, v211
	v_or_b32_e32 v44, 35, v44
	v_and_or_b32 v45, v45, s6, v211
	v_or_b32_e32 v45, 34, v45
	v_and_or_b32 v46, v46, s6, v211
	v_or_b32_e32 v46, 33, v46
	v_and_or_b32 v47, v47, s6, v211
	v_or_b32_e32 v47, 32, v47
	v_and_or_b32 v48, v48, s6, v211
	v_or_b32_e32 v48, 27, v48
	v_and_or_b32 v49, v49, s6, v211
	v_or_b32_e32 v49, 26, v49
	v_and_or_b32 v50, v50, s6, v211
	v_or_b32_e32 v50, 25, v50
	v_and_or_b32 v51, v51, s6, v211
	v_or_b32_e32 v51, 24, v51
	v_and_or_b32 v52, v52, s6, v211
	v_or_b32_e32 v52, 19, v52
	v_and_or_b32 v53, v53, s6, v211
	v_or_b32_e32 v53, 18, v53
	v_and_or_b32 v54, v54, s6, v211
	v_or_b32_e32 v54, 17, v54
	v_and_or_b32 v55, v55, s6, v211
	v_or_b32_e32 v55, 16, v55
	v_and_or_b32 v56, v56, s6, v211
	v_or_b32_e32 v56, 11, v56
	v_and_or_b32 v57, v57, s6, v211
	v_or_b32_e32 v57, 10, v57
	v_and_or_b32 v58, v58, s6, v211
	v_or_b32_e32 v58, 9, v58
	v_and_or_b32 v59, v59, s6, v211
	v_or_b32_e32 v59, 8, v59
	v_and_or_b32 v60, v60, s6, v211
	v_or_b32_e32 v60, 3, v60
	v_and_or_b32 v61, v61, s6, v211
	v_or_b32_e32 v61, 2, v61
	v_and_or_b32 v62, v62, s6, v211
	v_or_b32_e32 v62, 1, v62
	v_and_or_b32 v63, v63, s6, v211
	v_or_b32_e32 v63, 0, v63
	v_max_f32_e32 v144, v0, v13
	v_min_f32_e32 v13, v0, v13
	v_max_f32_e32 v145, v1, v12
	v_min_f32_e32 v12, v1, v12
	v_max_f32_e32 v146, v2, v15
	v_min_f32_e32 v15, v2, v15
	v_max_f32_e32 v147, v3, v14
	v_min_f32_e32 v14, v3, v14
	v_max_f32_e32 v148, v4, v8
	v_min_f32_e32 v8, v4, v8
	v_max_f32_e32 v149, v5, v6
	v_min_f32_e32 v6, v5, v6
	v_max_f32_e32 v150, v7, v11
	v_min_f32_e32 v11, v7, v11
	v_max_f32_e32 v151, v9, v10
	v_min_f32_e32 v10, v9, v10
	v_max_f32_e32 v249, v144, v149
	v_min_f32_e32 v149, v144, v149
	v_max_f32_e32 v250, v145, v150
	v_min_f32_e32 v150, v145, v150
	v_max_f32_e32 v251, v146, v151
	v_min_f32_e32 v151, v146, v151
	v_max_f32_e32 v252, v147, v148
	v_min_f32_e32 v148, v147, v148
	v_max_f32_e32 v253, v6, v13
	v_min_f32_e32 v13, v6, v13
	v_max_f32_e32 v254, v8, v14
	v_min_f32_e32 v14, v8, v14
	v_max_f32_e32 v255, v10, v15
	v_min_f32_e32 v15, v10, v15
	v_max_f32_e32 v96, v11, v12
	v_min_f32_e32 v12, v11, v12
	v_max_f32_e32 v97, v249, v250
	v_min_f32_e32 v250, v249, v250
	v_max_f32_e32 v98, v251, v252
	v_min_f32_e32 v252, v251, v252
	v_max_f32_e32 v99, v148, v149
	v_min_f32_e32 v149, v148, v149
	v_max_f32_e32 v100, v253, v254
	v_min_f32_e32 v254, v253, v254
	v_max_f32_e32 v101, v150, v151
	v_min_f32_e32 v151, v150, v151
	v_max_f32_e32 v102, v255, v96
	v_min_f32_e32 v96, v255, v96
	v_max_f32_e32 v103, v12, v13
	v_min_f32_e32 v13, v12, v13
	v_max_f32_e32 v104, v14, v15
	v_min_f32_e32 v15, v14, v15
	v_max_f32_e32 v105, v97, v98
	v_min_f32_e32 v98, v97, v98
	v_max_f32_e32 v106, v250, v252
	v_min_f32_e32 v252, v250, v252
	v_max_f32_e32 v107, v99, v102
	v_min_f32_e32 v102, v99, v102
	v_max_f32_e32 v108, v149, v96
	v_min_f32_e32 v96, v149, v96
	v_max_f32_e32 v109, v100, v101
	v_min_f32_e32 v101, v100, v101
	v_max_f32_e32 v110, v254, v151
	v_min_f32_e32 v151, v254, v151
	v_max_f32_e32 v111, v103, v104
	v_min_f32_e32 v104, v103, v104
	v_max_f32_e32 v112, v13, v15
	v_min_f32_e32 v15, v13, v15
	v_max_f32_e32 v113, v106, v98
	v_min_f32_e32 v98, v106, v98
	v_max_f32_e32 v114, v252, v111
	v_min_f32_e32 v111, v252, v111
	v_max_f32_e32 v115, v107, v109
	v_min_f32_e32 v109, v107, v109
	v_max_f32_e32 v116, v108, v101
	v_min_f32_e32 v101, v108, v101
	v_max_f32_e32 v117, v110, v102
	v_min_f32_e32 v102, v110, v102
	v_max_f32_e32 v118, v151, v96
	v_min_f32_e32 v96, v151, v96
	v_max_f32_e32 v119, v112, v104
	v_min_f32_e32 v104, v112, v104
	v_max_f32_e32 v120, v113, v115
	v_min_f32_e32 v115, v113, v115
	v_max_f32_e32 v121, v98, v109
	v_min_f32_e32 v109, v98, v109
	v_max_f32_e32 v122, v116, v117
	v_min_f32_e32 v117, v116, v117
	v_max_f32_e32 v123, v101, v102
	v_min_f32_e32 v102, v101, v102
	v_max_f32_e32 v124, v118, v119
	v_min_f32_e32 v119, v118, v119
	v_max_f32_e32 v125, v96, v104
	v_min_f32_e32 v104, v96, v104
	v_max_f32_e32 v126, v121, v115
	v_min_f32_e32 v115, v121, v115
	v_max_f32_e32 v127, v114, v109
	v_min_f32_e32 v109, v114, v109
	v_max_f32_e32 v64, v124, v111
	v_min_f32_e32 v111, v124, v111
	v_max_f32_e32 v65, v125, v119
	v_min_f32_e32 v119, v125, v119
	v_max_f32_e32 v66, v127, v122
	v_min_f32_e32 v122, v127, v122
	v_max_f32_e32 v67, v109, v117
	v_min_f32_e32 v117, v109, v117
	v_max_f32_e32 v68, v123, v64
	v_min_f32_e32 v64, v123, v64
	v_max_f32_e32 v69, v102, v111
	v_min_f32_e32 v111, v102, v111
	v_max_f32_e32 v70, v66, v115
	v_min_f32_e32 v115, v66, v115
	v_max_f32_e32 v71, v122, v67
	v_min_f32_e32 v67, v122, v67
	v_max_f32_e32 v72, v68, v117
	v_min_f32_e32 v117, v68, v117
	v_max_f32_e32 v73, v64, v69
	v_min_f32_e32 v69, v64, v69
	v_max_f32_e32 v74, v65, v111
	v_min_f32_e32 v111, v65, v111
	v_max_f32_e32 v75, v67, v72
	v_min_f32_e32 v72, v67, v72
	v_max_f32_e32 v76, v117, v73
	v_min_f32_e32 v73, v117, v73
	v_max_f32_e32 v77, v16, v29
	v_min_f32_e32 v29, v16, v29
	v_max_f32_e32 v78, v17, v28
	v_min_f32_e32 v28, v17, v28
	v_max_f32_e32 v79, v18, v31
	v_min_f32_e32 v31, v18, v31
	v_max_f32_e32 v80, v19, v30
	v_min_f32_e32 v30, v19, v30
	v_max_f32_e32 v81, v20, v24
	v_min_f32_e32 v24, v20, v24
	v_max_f32_e32 v82, v21, v22
	v_min_f32_e32 v22, v21, v22
	v_max_f32_e32 v83, v23, v27
	v_min_f32_e32 v27, v23, v27
	v_max_f32_e32 v84, v25, v26
	v_min_f32_e32 v26, v25, v26
	v_max_f32_e32 v85, v77, v82
	v_min_f32_e32 v82, v77, v82
	v_max_f32_e32 v86, v78, v83
	v_min_f32_e32 v83, v78, v83
	v_max_f32_e32 v87, v79, v84
	v_min_f32_e32 v84, v79, v84
	v_max_f32_e32 v88, v80, v81
	v_min_f32_e32 v81, v80, v81
	v_max_f32_e32 v89, v22, v29
	v_min_f32_e32 v29, v22, v29
	v_max_f32_e32 v90, v24, v30
	v_min_f32_e32 v30, v24, v30
	v_max_f32_e32 v91, v26, v31
	v_min_f32_e32 v31, v26, v31
	v_max_f32_e32 v92, v27, v28
	v_min_f32_e32 v28, v27, v28
	v_max_f32_e32 v93, v85, v86
	v_min_f32_e32 v86, v85, v86
	v_max_f32_e32 v94, v87, v88
	v_min_f32_e32 v88, v87, v88
	v_max_f32_e32 v95, v81, v82
	v_min_f32_e32 v82, v81, v82
	v_max_f32_e32 v0, v89, v90
	v_min_f32_e32 v90, v89, v90
	v_max_f32_e32 v1, v83, v84
	v_min_f32_e32 v84, v83, v84
	v_max_f32_e32 v2, v91, v92
	v_min_f32_e32 v92, v91, v92
	v_max_f32_e32 v3, v28, v29
	v_min_f32_e32 v29, v28, v29
	v_max_f32_e32 v4, v30, v31
	v_min_f32_e32 v31, v30, v31
	v_max_f32_e32 v5, v93, v94
	v_min_f32_e32 v94, v93, v94
	v_max_f32_e32 v7, v86, v88
	v_min_f32_e32 v88, v86, v88
	v_max_f32_e32 v9, v95, v2
	v_min_f32_e32 v2, v95, v2
	v_max_f32_e32 v144, v82, v92
	v_min_f32_e32 v92, v82, v92
	v_max_f32_e32 v145, v0, v1
	v_min_f32_e32 v1, v0, v1
	v_max_f32_e32 v146, v90, v84
	v_min_f32_e32 v84, v90, v84
	v_max_f32_e32 v147, v3, v4
	v_min_f32_e32 v4, v3, v4
	v_max_f32_e32 v6, v29, v31
	v_min_f32_e32 v31, v29, v31
	v_max_f32_e32 v8, v7, v94
	v_min_f32_e32 v94, v7, v94
	v_max_f32_e32 v10, v88, v147
	v_min_f32_e32 v147, v88, v147
	v_max_f32_e32 v11, v9, v145
	v_min_f32_e32 v145, v9, v145
	v_max_f32_e32 v249, v144, v1
	v_min_f32_e32 v1, v144, v1
	v_max_f32_e32 v251, v146, v2
	v_min_f32_e32 v2, v146, v2
	v_max_f32_e32 v148, v84, v92
	v_min_f32_e32 v92, v84, v92
	v_max_f32_e32 v253, v6, v4
	v_min_f32_e32 v4, v6, v4
	v_max_f32_e32 v150, v8, v11
	v_min_f32_e32 v11, v8, v11
	v_max_f32_e32 v255, v94, v145
	v_min_f32_e32 v145, v94, v145
	v_max_f32_e32 v12, v249, v251
	v_min_f32_e32 v251, v249, v251
	v_max_f32_e32 v14, v1, v2
	v_min_f32_e32 v2, v1, v2
	v_max_f32_e32 v97, v148, v253
	v_min_f32_e32 v253, v148, v253
	v_max_f32_e32 v250, v92, v4
	v_min_f32_e32 v4, v92, v4
	v_max_f32_e32 v99, v255, v11
	v_min_f32_e32 v11, v255, v11
	v_max_f32_e32 v149, v10, v145
	v_min_f32_e32 v145, v10, v145
	v_max_f32_e32 v100, v97, v147
	v_min_f32_e32 v147, v97, v147
	v_max_f32_e32 v254, v250, v253
	v_min_f32_e32 v253, v250, v253
	v_max_f32_e32 v103, v149, v12
	v_min_f32_e32 v12, v149, v12
	v_max_f32_e32 v13, v145, v251
	v_min_f32_e32 v251, v145, v251
	v_max_f32_e32 v106, v14, v100
	v_min_f32_e32 v100, v14, v100
	v_max_f32_e32 v252, v2, v147
	v_min_f32_e32 v147, v2, v147
	v_max_f32_e32 v107, v103, v11
	v_min_f32_e32 v11, v103, v11
	v_max_f32_e32 v108, v12, v13
	v_min_f32_e32 v13, v12, v13
	v_max_f32_e32 v110, v106, v251
	v_min_f32_e32 v251, v106, v251
	v_max_f32_e32 v151, v100, v252
	v_min_f32_e32 v252, v100, v252
	v_max_f32_e32 v112, v254, v147
	v_min_f32_e32 v147, v254, v147
	v_max_f32_e32 v113, v13, v110
	v_min_f32_e32 v110, v13, v110
	v_max_f32_e32 v98, v251, v151
	v_min_f32_e32 v151, v251, v151
	s_waitcnt vmcnt(0)
	v_pk_mul_f32 v[160:161], v[160:161], v[176:177]
	v_pk_mul_f32 v[162:163], v[162:163], v[178:179]
	v_pk_mul_f32 v[164:165], v[164:165], v[180:181]
	v_pk_mul_f32 v[166:167], v[166:167], v[182:183]
	v_pk_mul_f32 v[168:169], v[168:169], v[184:185]
	v_pk_mul_f32 v[170:171], v[170:171], v[186:187]
	v_pk_mul_f32 v[172:173], v[172:173], v[188:189]
	v_pk_mul_f32 v[174:175], v[174:175], v[190:191]
	v_max3_f32 v192, |v160|, |v161|, |v162|
	v_max3_f32 v192, |v163|, |v164|, v192
	v_max3_f32 v192, |v165|, |v166|, v192
	v_max3_f32 v192, |v167|, |v168|, v192
	v_max3_f32 v192, |v169|, |v170|, v192
	v_max3_f32 v192, |v171|, |v172|, v192
	v_max3_f32 v192, |v173|, |v174|, v192
	v_max_f32_e64 v192, |v175|, v192
	s_nop 1
	v_mov_b32_dpp v193, v192 quad_perm:[1,0,3,2] row_mask:0xf bank_mask:0xf bound_ctrl:1
	v_max_f32_e32 v192, v192, v193
	s_nop 1
	v_mov_b32_dpp v193, v192 quad_perm:[2,3,0,1] row_mask:0xf bank_mask:0xf bound_ctrl:1
	v_max_f32_e32 v192, v192, v193
	s_nop 1
	v_mov_b32_dpp v193, v192 row_half_mirror row_mask:0xf bank_mask:0xf bound_ctrl:1
	v_max_f32_e32 v192, v192, v193
	s_nop 1
	v_mov_b32_dpp v193, v192 row_mirror row_mask:0xf bank_mask:0xf bound_ctrl:1
	v_max_f32_e32 v192, v192, v193
	v_mov_b32_e32 v193, v192
	s_nop 1
	v_permlane16_swap_b32_e32 v192, v193
	s_nop 1
	v_max_f32_e32 v192, v192, v193
	v_mov_b32_e32 v193, v192
	s_nop 1
	v_permlane32_swap_b32_e32 v192, v193
	s_nop 1
	v_max_f32_e32 v192, v192, v193
	v_max_f32_e32 v192, 0xda24260, v192
	v_mul_f32_e32 v194, 0x3e2aaaab, v192
	global_store_dword v214, v194, s[12:13]
	v_div_scale_f32 v195, s[26:27], v194, v194, 1.0
	v_rcp_f32_e32 v196, v195
	v_div_scale_f32 v204, vcc, 1.0, v194, 1.0
	v_fma_f32 v205, -v195, v196, 1.0
	v_fmac_f32_e32 v196, v205, v196
	v_mul_f32_e32 v205, v204, v196
	v_fma_f32 v206, -v195, v205, v204
	v_fmac_f32_e32 v205, v206, v196
	v_fma_f32 v195, -v195, v205, v204
	s_nop 0
	v_div_fmas_f32 v195, v195, v196, v205
	v_div_fixup_f32 v207, v195, v194, 1.0
	v_mul_f32_e32 v160, v207, v160
	v_mul_f32_e32 v161, v207, v161
	v_mul_f32_e32 v162, v207, v162
	v_mul_f32_e32 v163, v207, v163
	v_mul_f32_e32 v164, v207, v164
	v_mul_f32_e32 v165, v207, v165
	v_mul_f32_e32 v166, v207, v166
	v_mul_f32_e32 v167, v207, v167
	v_mul_f32_e32 v168, v207, v168
	v_mul_f32_e32 v169, v207, v169
	v_mul_f32_e32 v170, v207, v170
	v_mul_f32_e32 v171, v207, v171
	v_mul_f32_e32 v172, v207, v172
	v_mul_f32_e32 v173, v207, v173
	v_mul_f32_e32 v174, v207, v174
	v_mul_f32_e32 v175, v207, v175
	v_mov_b32_e32 v208, 0
	v_mov_b32_e32 v209, 0
	v_mov_b32_e32 v210, 0
	v_mov_b32_e32 v193, 0
	v_cvt_scalef32_pk_fp4_f32 v208, v160, v161, 1.0
	v_cvt_scalef32_pk_fp4_f32 v209, v164, v165, 1.0
	v_cvt_scalef32_pk_fp4_f32 v210, v168, v169, 1.0
	v_cvt_scalef32_pk_fp4_f32 v193, v172, v173, 1.0
	v_cvt_scalef32_pk_fp4_f32 v208, v162, v163, 1.0 op_sel:[0,0,1,0]
	v_cvt_scalef32_pk_fp4_f32 v209, v166, v167, 1.0 op_sel:[0,0,1,0]
	v_cvt_scalef32_pk_fp4_f32 v210, v170, v171, 1.0 op_sel:[0,0,1,0]
	v_cvt_scalef32_pk_fp4_f32 v193, v174, v175, 1.0 op_sel:[0,0,1,0]
	global_store_short v213, v208, s[10:11] nt
	s_add_u32 s14, s10, 0x200000
	s_addc_u32 s15, s11, 0
	global_store_short v213, v209, s[14:15] nt
	s_add_u32 s14, s10, 0x400000
	s_addc_u32 s15, s11, 0
	global_store_short v213, v210, s[14:15] nt
	s_add_u32 s14, s10, 0x600000
	s_addc_u32 s15, s11, 0
	global_store_short v213, v193, s[14:15] nt
	s_add_u32 s10, s10, 0x20000
	s_addc_u32 s11, s11, 0
	s_add_u32 s12, s12, 0x2000
	s_addc_u32 s13, s13, 0
	global_load_dwordx4 v[160:163], v212, s[8:9] offset:0 nt
	global_load_dwordx4 v[164:167], v212, s[8:9] offset:1024 nt
	global_load_dwordx4 v[168:171], v212, s[8:9] offset:2048 nt
	global_load_dwordx4 v[172:175], v212, s[8:9] offset:3072 nt
	s_add_u32 s8, s8, 0x800000
	s_addc_u32 s9, s9, 0
	v_max_f32_e32 v116, v32, v45
	v_min_f32_e32 v45, v32, v45
	v_max_f32_e32 v101, v33, v44
	v_min_f32_e32 v44, v33, v44
	v_max_f32_e32 v118, v34, v47
	v_min_f32_e32 v47, v34, v47
	v_max_f32_e32 v96, v35, v46
	v_min_f32_e32 v46, v35, v46
	v_max_f32_e32 v121, v36, v40
	v_min_f32_e32 v40, v36, v40
	v_max_f32_e32 v114, v37, v38
	v_min_f32_e32 v38, v37, v38
	v_max_f32_e32 v124, v39, v43
	v_min_f32_e32 v43, v39, v43
	v_max_f32_e32 v125, v41, v42
	v_min_f32_e32 v42, v41, v42
	v_max_f32_e32 v127, v116, v114
	v_min_f32_e32 v114, v116, v114
	v_max_f32_e32 v109, v101, v124
	v_min_f32_e32 v124, v101, v124
	v_max_f32_e32 v123, v118, v125
	v_min_f32_e32 v125, v118, v125
	v_max_f32_e32 v102, v96, v121
	v_min_f32_e32 v121, v96, v121
	v_max_f32_e32 v66, v38, v45
	v_min_f32_e32 v45, v38, v45
	v_max_f32_e32 v122, v40, v46
	v_min_f32_e32 v46, v40, v46
	v_max_f32_e32 v68, v42, v47
	v_min_f32_e32 v47, v42, v47
	v_max_f32_e32 v64, v43, v44
	v_min_f32_e32 v44, v43, v44
	v_max_f32_e32 v65, v127, v109
	v_min_f32_e32 v109, v127, v109
	v_max_f32_e32 v67, v123, v102
	v_min_f32_e32 v102, v123, v102
	v_max_f32_e32 v117, v121, v114
	v_min_f32_e32 v114, v121, v114
	v_max_f32_e32 v16, v66, v122
	v_min_f32_e32 v122, v66, v122
	v_max_f32_e32 v17, v124, v125
	v_min_f32_e32 v125, v124, v125
	v_max_f32_e32 v18, v68, v64
	v_min_f32_e32 v64, v68, v64
	v_max_f32_e32 v19, v44, v45
	v_min_f32_e32 v45, v44, v45
	v_max_f32_e32 v20, v46, v47
	v_min_f32_e32 v47, v46, v47
	v_max_f32_e32 v21, v65, v67
	v_min_f32_e32 v67, v65, v67
	v_max_f32_e32 v23, v109, v102
	v_min_f32_e32 v102, v109, v102
	v_max_f32_e32 v25, v117, v18
	v_min_f32_e32 v18, v117, v18
	v_max_f32_e32 v77, v114, v64
	v_min_f32_e32 v64, v114, v64
	v_max_f32_e32 v78, v16, v17
	v_min_f32_e32 v17, v16, v17
	v_max_f32_e32 v79, v122, v125
	v_min_f32_e32 v125, v122, v125
	v_max_f32_e32 v80, v19, v20
	v_min_f32_e32 v20, v19, v20
	v_max_f32_e32 v22, v45, v47
	v_min_f32_e32 v47, v45, v47
	v_max_f32_e32 v24, v23, v67
	v_min_f32_e32 v67, v23, v67
	v_max_f32_e32 v26, v102, v80
	v_min_f32_e32 v80, v102, v80
	v_max_f32_e32 v27, v25, v78
	v_min_f32_e32 v78, v25, v78
	v_max_f32_e32 v85, v77, v17
	v_min_f32_e32 v17, v77, v17
	v_max_f32_e32 v87, v79, v18
	v_min_f32_e32 v18, v79, v18
	v_max_f32_e32 v81, v125, v64
	v_min_f32_e32 v64, v125, v64
	v_max_f32_e32 v89, v22, v20
	v_min_f32_e32 v20, v22, v20
	v_max_f32_e32 v83, v24, v27
	v_min_f32_e32 v27, v24, v27
	v_max_f32_e32 v91, v67, v78
	v_min_f32_e32 v78, v67, v78
	v_max_f32_e32 v28, v85, v87
	v_min_f32_e32 v87, v85, v87
	v_max_f32_e32 v30, v17, v18
	v_min_f32_e32 v18, v17, v18
	v_max_f32_e32 v93, v81, v89
	v_min_f32_e32 v89, v81, v89
	v_max_f32_e32 v86, v64, v20
	v_min_f32_e32 v20, v64, v20
	v_max_f32_e32 v95, v91, v27
	v_min_f32_e32 v27, v91, v27
	v_max_f32_e32 v82, v26, v78
	v_min_f32_e32 v78, v26, v78
	v_max_f32_e32 v0, v93, v80
	v_min_f32_e32 v80, v93, v80
	v_max_f32_e32 v90, v86, v89
	v_min_f32_e32 v89, v86, v89
	v_max_f32_e32 v3, v82, v28
	v_min_f32_e32 v28, v82, v28
	v_max_f32_e32 v29, v78, v87
	v_min_f32_e32 v87, v78, v87
	v_max_f32_e32 v7, v30, v0
	v_min_f32_e32 v0, v30, v0
	v_max_f32_e32 v88, v18, v80
	v_min_f32_e32 v80, v18, v80
	v_max_f32_e32 v9, v3, v27
	v_min_f32_e32 v27, v3, v27
	v_max_f32_e32 v144, v28, v29
	v_min_f32_e32 v29, v28, v29
	v_max_f32_e32 v146, v7, v87
	v_min_f32_e32 v87, v7, v87
	v_max_f32_e32 v84, v0, v88
	v_min_f32_e32 v88, v0, v88
	v_max_f32_e32 v6, v90, v80
	v_min_f32_e32 v80, v90, v80
	v_max_f32_e32 v8, v29, v146
	v_min_f32_e32 v146, v29, v146
	v_max_f32_e32 v94, v87, v84
	v_min_f32_e32 v84, v87, v84
	v_max_f32_e32 v249, v48, v61
	v_min_f32_e32 v61, v48, v61
	v_max_f32_e32 v1, v49, v60
	v_min_f32_e32 v60, v49, v60
	v_max_f32_e32 v148, v50, v63
	v_min_f32_e32 v63, v50, v63
	v_max_f32_e32 v92, v51, v62
	v_min_f32_e32 v62, v51, v62
	v_max_f32_e32 v255, v52, v56
	v_min_f32_e32 v56, v52, v56
	v_max_f32_e32 v10, v53, v54
	v_min_f32_e32 v54, v53, v54
	v_max_f32_e32 v97, v55, v59
	v_min_f32_e32 v59, v55, v59
	v_max_f32_e32 v250, v57, v58
	v_min_f32_e32 v58, v57, v58
	v_max_f32_e32 v149, v249, v10
	v_min_f32_e32 v10, v249, v10
	v_max_f32_e32 v145, v1, v97
	v_min_f32_e32 v97, v1, v97
	v_max_f32_e32 v14, v148, v250
	v_min_f32_e32 v250, v148, v250
	v_max_f32_e32 v2, v92, v255
	v_min_f32_e32 v255, v92, v255
	v_max_f32_e32 v103, v54, v61
	v_min_f32_e32 v61, v54, v61
	v_max_f32_e32 v12, v56, v62
	v_min_f32_e32 v62, v56, v62
	v_max_f32_e32 v106, v58, v63
	v_min_f32_e32 v63, v58, v63
	v_max_f32_e32 v100, v59, v60
	v_min_f32_e32 v60, v59, v60
	v_max_f32_e32 v254, v149, v145
	v_min_f32_e32 v145, v149, v145
	v_max_f32_e32 v13, v14, v2
	v_min_f32_e32 v2, v14, v2
	v_max_f32_e32 v251, v255, v10
	v_min_f32_e32 v10, v255, v10
	v_max_f32_e32 v32, v103, v12
	v_min_f32_e32 v12, v103, v12
	v_max_f32_e32 v33, v97, v250
	v_min_f32_e32 v250, v97, v250
	v_max_f32_e32 v34, v106, v100
	v_min_f32_e32 v100, v106, v100
	v_max_f32_e32 v35, v60, v61
	v_min_f32_e32 v61, v60, v61
	v_max_f32_e32 v36, v62, v63
	v_min_f32_e32 v63, v62, v63
	v_max_f32_e32 v37, v254, v13
	v_min_f32_e32 v13, v254, v13
	v_max_f32_e32 v39, v145, v2
	v_min_f32_e32 v2, v145, v2
	v_max_f32_e32 v41, v251, v34
	v_min_f32_e32 v34, v251, v34
	v_max_f32_e32 v116, v10, v100
	v_min_f32_e32 v100, v10, v100
	v_max_f32_e32 v101, v32, v33
	v_min_f32_e32 v33, v32, v33
	v_max_f32_e32 v118, v12, v250
	v_min_f32_e32 v250, v12, v250
	v_max_f32_e32 v96, v35, v36
	v_min_f32_e32 v36, v35, v36
	v_max_f32_e32 v38, v61, v63
	v_min_f32_e32 v63, v61, v63
	v_max_f32_e32 v40, v39, v13
	v_min_f32_e32 v13, v39, v13
	v_max_f32_e32 v42, v2, v96
	v_min_f32_e32 v96, v2, v96
	v_max_f32_e32 v43, v41, v101
	v_min_f32_e32 v101, v41, v101
	v_max_f32_e32 v127, v116, v33
	v_min_f32_e32 v33, v116, v33
	v_max_f32_e32 v123, v118, v34
	v_min_f32_e32 v34, v118, v34
	v_max_f32_e32 v121, v250, v100
	v_min_f32_e32 v100, v250, v100
	v_max_f32_e32 v66, v38, v36
	v_min_f32_e32 v36, v38, v36
	v_max_f32_e32 v124, v40, v43
	v_min_f32_e32 v43, v40, v43
	v_max_f32_e32 v68, v13, v101
	v_min_f32_e32 v101, v13, v101
	v_max_f32_e32 v44, v127, v123
	v_min_f32_e32 v123, v127, v123
	v_max_f32_e32 v46, v33, v34
	v_min_f32_e32 v34, v33, v34
	v_max_f32_e32 v65, v121, v66
	v_min_f32_e32 v66, v121, v66
	v_max_f32_e32 v109, v100, v36
	v_min_f32_e32 v36, v100, v36
	v_max_f32_e32 v117, v68, v43
	v_min_f32_e32 v43, v68, v43
	v_max_f32_e32 v114, v42, v101
	v_min_f32_e32 v101, v42, v101
	v_max_f32_e32 v16, v65, v96
	v_min_f32_e32 v96, v65, v96
	v_max_f32_e32 v122, v109, v66
	v_min_f32_e32 v66, v109, v66
	v_max_f32_e32 v19, v114, v44
	v_min_f32_e32 v44, v114, v44
	v_max_f32_e32 v45, v101, v123
	v_min_f32_e32 v123, v101, v123
	v_max_f32_e32 v23, v46, v16
	v_min_f32_e32 v16, v46, v16
	v_max_f32_e32 v102, v34, v96
	v_min_f32_e32 v96, v34, v96
	v_max_f32_e32 v25, v19, v43
	v_min_f32_e32 v43, v19, v43
	v_max_f32_e32 v77, v44, v45
	v_min_f32_e32 v45, v44, v45
	v_max_f32_e32 v79, v23, v123
	v_min_f32_e32 v123, v23, v123
	v_max_f32_e32 v125, v16, v102
	v_min_f32_e32 v102, v16, v102
	v_max_f32_e32 v22, v122, v96
	v_min_f32_e32 v96, v122, v96
	v_max_f32_e32 v24, v45, v79
	v_min_f32_e32 v79, v45, v79
	v_max_f32_e32 v67, v123, v125
	v_min_f32_e32 v125, v123, v125
	s_waitcnt vmcnt(0)
	v_pk_mul_f32 v[160:161], v[160:161], v[176:177]
	v_pk_mul_f32 v[162:163], v[162:163], v[178:179]
	v_pk_mul_f32 v[164:165], v[164:165], v[180:181]
	v_pk_mul_f32 v[166:167], v[166:167], v[182:183]
	v_pk_mul_f32 v[168:169], v[168:169], v[184:185]
	v_pk_mul_f32 v[170:171], v[170:171], v[186:187]
	v_pk_mul_f32 v[172:173], v[172:173], v[188:189]
	v_pk_mul_f32 v[174:175], v[174:175], v[190:191]
	v_max3_f32 v192, |v160|, |v161|, |v162|
	v_max3_f32 v192, |v163|, |v164|, v192
	v_max3_f32 v192, |v165|, |v166|, v192
	v_max3_f32 v192, |v167|, |v168|, v192
	v_max3_f32 v192, |v169|, |v170|, v192
	v_max3_f32 v192, |v171|, |v172|, v192
	v_max3_f32 v192, |v173|, |v174|, v192
	v_max_f32_e64 v192, |v175|, v192
	s_nop 1
	v_mov_b32_dpp v193, v192 quad_perm:[1,0,3,2] row_mask:0xf bank_mask:0xf bound_ctrl:1
	v_max_f32_e32 v192, v192, v193
	s_nop 1
	v_mov_b32_dpp v193, v192 quad_perm:[2,3,0,1] row_mask:0xf bank_mask:0xf bound_ctrl:1
	v_max_f32_e32 v192, v192, v193
	s_nop 1
	v_mov_b32_dpp v193, v192 row_half_mirror row_mask:0xf bank_mask:0xf bound_ctrl:1
	v_max_f32_e32 v192, v192, v193
	s_nop 1
	v_mov_b32_dpp v193, v192 row_mirror row_mask:0xf bank_mask:0xf bound_ctrl:1
	v_max_f32_e32 v192, v192, v193
	v_mov_b32_e32 v193, v192
	s_nop 1
	v_permlane16_swap_b32_e32 v192, v193
	s_nop 1
	v_max_f32_e32 v192, v192, v193
	v_mov_b32_e32 v193, v192
	s_nop 1
	v_permlane32_swap_b32_e32 v192, v193
	s_nop 1
	v_max_f32_e32 v192, v192, v193
	v_max_f32_e32 v192, 0xda24260, v192
	v_mul_f32_e32 v194, 0x3e2aaaab, v192
	global_store_dword v214, v194, s[12:13]
	v_div_scale_f32 v195, s[26:27], v194, v194, 1.0
	v_rcp_f32_e32 v196, v195
	v_div_scale_f32 v204, vcc, 1.0, v194, 1.0
	v_fma_f32 v205, -v195, v196, 1.0
	v_fmac_f32_e32 v196, v205, v196
	v_mul_f32_e32 v205, v204, v196
	v_fma_f32 v206, -v195, v205, v204
	v_fmac_f32_e32 v205, v206, v196
	v_fma_f32 v195, -v195, v205, v204
	s_nop 0
	v_div_fmas_f32 v195, v195, v196, v205
	v_div_fixup_f32 v207, v195, v194, 1.0
	v_mul_f32_e32 v160, v207, v160
	v_mul_f32_e32 v161, v207, v161
	v_mul_f32_e32 v162, v207, v162
	v_mul_f32_e32 v163, v207, v163
	v_mul_f32_e32 v164, v207, v164
	v_mul_f32_e32 v165, v207, v165
	v_mul_f32_e32 v166, v207, v166
	v_mul_f32_e32 v167, v207, v167
	v_mul_f32_e32 v168, v207, v168
	v_mul_f32_e32 v169, v207, v169
	v_mul_f32_e32 v170, v207, v170
	v_mul_f32_e32 v171, v207, v171
	v_mul_f32_e32 v172, v207, v172
	v_mul_f32_e32 v173, v207, v173
	v_mul_f32_e32 v174, v207, v174
	v_mul_f32_e32 v175, v207, v175
	v_mov_b32_e32 v208, 0
	v_mov_b32_e32 v209, 0
	v_mov_b32_e32 v210, 0
	v_mov_b32_e32 v193, 0
	v_cvt_scalef32_pk_fp4_f32 v208, v160, v161, 1.0
	v_cvt_scalef32_pk_fp4_f32 v209, v164, v165, 1.0
	v_cvt_scalef32_pk_fp4_f32 v210, v168, v169, 1.0
	v_cvt_scalef32_pk_fp4_f32 v193, v172, v173, 1.0
	v_cvt_scalef32_pk_fp4_f32 v208, v162, v163, 1.0 op_sel:[0,0,1,0]
	v_cvt_scalef32_pk_fp4_f32 v209, v166, v167, 1.0 op_sel:[0,0,1,0]
	v_cvt_scalef32_pk_fp4_f32 v210, v170, v171, 1.0 op_sel:[0,0,1,0]
	v_cvt_scalef32_pk_fp4_f32 v193, v174, v175, 1.0 op_sel:[0,0,1,0]
	global_store_short v213, v208, s[10:11] nt
	s_add_u32 s14, s10, 0x200000
	s_addc_u32 s15, s11, 0
	global_store_short v213, v209, s[14:15] nt
	s_add_u32 s14, s10, 0x400000
	s_addc_u32 s15, s11, 0
	global_store_short v213, v210, s[14:15] nt
	s_add_u32 s14, s10, 0x600000
	s_addc_u32 s15, s11, 0
	global_store_short v213, v193, s[14:15] nt
	s_add_u32 s10, s10, 0x20000
	s_addc_u32 s11, s11, 0
	s_add_u32 s12, s12, 0x2000
	s_addc_u32 s13, s13, 0
	global_load_dwordx4 v[160:163], v212, s[8:9] offset:0 nt
	global_load_dwordx4 v[164:167], v212, s[8:9] offset:1024 nt
	global_load_dwordx4 v[168:171], v212, s[8:9] offset:2048 nt
	global_load_dwordx4 v[172:175], v212, s[8:9] offset:3072 nt
	s_add_u32 s8, s8, 0x800000
	s_addc_u32 s9, s9, 0
	v_max_f32_e32 v105, v105, v31
	v_max_f32_e32 v120, v120, v4
	v_max_f32_e32 v126, v126, v253
	v_max_f32_e32 v70, v70, v147
	v_max_f32_e32 v115, v115, v112
	v_max_f32_e32 v71, v71, v252
	v_max_f32_e32 v75, v75, v151
	v_max_f32_e32 v72, v72, v98
	v_max_f32_e32 v76, v76, v110
	v_max_f32_e32 v73, v73, v113
	v_max_f32_e32 v69, v69, v108
	v_max_f32_e32 v74, v74, v11
	v_max_f32_e32 v111, v111, v107
	v_max_f32_e32 v119, v119, v99
	v_max_f32_e32 v104, v104, v150
	v_max_f32_e32 v15, v15, v5
	v_max_f32_e32 v85, v105, v76
	v_min_f32_e32 v76, v105, v76
	v_max_f32_e32 v17, v120, v73
	v_min_f32_e32 v73, v120, v73
	v_max_f32_e32 v81, v126, v69
	v_min_f32_e32 v69, v126, v69
	v_max_f32_e32 v64, v70, v74
	v_min_f32_e32 v74, v70, v74
	v_max_f32_e32 v91, v115, v111
	v_min_f32_e32 v111, v115, v111
	v_max_f32_e32 v26, v71, v119
	v_min_f32_e32 v119, v71, v119
	v_max_f32_e32 v93, v75, v104
	v_min_f32_e32 v104, v75, v104
	v_max_f32_e32 v86, v72, v15
	v_min_f32_e32 v15, v72, v15
	v_max_f32_e32 v82, v85, v91
	v_min_f32_e32 v91, v85, v91
	v_max_f32_e32 v78, v17, v26
	v_min_f32_e32 v26, v17, v26
	v_max_f32_e32 v30, v81, v93
	v_min_f32_e32 v93, v81, v93
	v_max_f32_e32 v18, v64, v86
	v_min_f32_e32 v86, v64, v86
	v_max_f32_e32 v3, v76, v111
	v_min_f32_e32 v111, v76, v111
	v_max_f32_e32 v28, v73, v119
	v_min_f32_e32 v119, v73, v119
	v_max_f32_e32 v7, v69, v104
	v_min_f32_e32 v104, v69, v104
	v_max_f32_e32 v0, v74, v15
	v_min_f32_e32 v15, v74, v15
	v_max_f32_e32 v90, v82, v30
	v_min_f32_e32 v30, v82, v30
	v_max_f32_e32 v29, v78, v18
	v_min_f32_e32 v18, v78, v18
	v_max_f32_e32 v87, v91, v93
	v_min_f32_e32 v93, v91, v93
	v_max_f32_e32 v48, v26, v86
	v_min_f32_e32 v86, v26, v86
	v_max_f32_e32 v49, v3, v7
	v_min_f32_e32 v7, v3, v7
	v_max_f32_e32 v50, v28, v0
	v_min_f32_e32 v0, v28, v0
	v_max_f32_e32 v51, v111, v104
	v_min_f32_e32 v104, v111, v104
	v_max_f32_e32 v52, v119, v15
	v_min_f32_e32 v15, v119, v15
	v_max_f32_e32 v53, v90, v29
	v_min_f32_e32 v29, v90, v29
	v_max_f32_e32 v55, v30, v18
	v_min_f32_e32 v18, v30, v18
	v_max_f32_e32 v57, v87, v48
	v_min_f32_e32 v48, v87, v48
	v_max_f32_e32 v249, v93, v86
	v_min_f32_e32 v86, v93, v86
	v_max_f32_e32 v1, v49, v50
	v_min_f32_e32 v50, v49, v50
	v_max_f32_e32 v148, v7, v0
	v_min_f32_e32 v0, v7, v0
	v_max_f32_e32 v92, v51, v52
	v_min_f32_e32 v52, v51, v52
	v_max_f32_e32 v54, v104, v15
	v_min_f32_e32 v15, v104, v15
	v_max_f32_e32 v21, v21, v63
	v_max_f32_e32 v83, v83, v36
	v_max_f32_e32 v95, v95, v66
	v_max_f32_e32 v9, v9, v96
	v_max_f32_e32 v27, v27, v22
	v_max_f32_e32 v144, v144, v102
	v_max_f32_e32 v8, v8, v125
	v_max_f32_e32 v146, v146, v67
	v_max_f32_e32 v94, v94, v79
	v_max_f32_e32 v84, v84, v24
	v_max_f32_e32 v88, v88, v77
	v_max_f32_e32 v6, v6, v43
	v_max_f32_e32 v80, v80, v25
	v_max_f32_e32 v89, v89, v117
	v_max_f32_e32 v20, v20, v124
	v_max_f32_e32 v47, v47, v37
	v_max_f32_e32 v56, v21, v94
	v_min_f32_e32 v94, v21, v94
	v_max_f32_e32 v58, v83, v84
	v_min_f32_e32 v84, v83, v84
	v_max_f32_e32 v59, v95, v88
	v_min_f32_e32 v88, v95, v88
	v_max_f32_e32 v149, v9, v6
	v_min_f32_e32 v6, v9, v6
	v_max_f32_e32 v14, v27, v80
	v_min_f32_e32 v80, v27, v80
	v_max_f32_e32 v255, v144, v89
	v_min_f32_e32 v89, v144, v89
	v_max_f32_e32 v103, v8, v20
	v_min_f32_e32 v20, v8, v20
	v_max_f32_e32 v97, v146, v47
	v_min_f32_e32 v47, v146, v47
	v_max_f32_e32 v106, v56, v14
	v_min_f32_e32 v14, v56, v14
	v_max_f32_e32 v60, v58, v255
	v_min_f32_e32 v255, v58, v255
	v_max_f32_e32 v62, v59, v103
	v_min_f32_e32 v103, v59, v103
	v_max_f32_e32 v254, v149, v97
	v_min_f32_e32 v97, v149, v97
	v_max_f32_e32 v145, v94, v80
	v_min_f32_e32 v80, v94, v80
	v_max_f32_e32 v251, v84, v89
	v_min_f32_e32 v89, v84, v89
	v_max_f32_e32 v10, v88, v20
	v_min_f32_e32 v20, v88, v20
	v_max_f32_e32 v32, v6, v47
	v_min_f32_e32 v47, v6, v47
	v_max_f32_e32 v12, v106, v62
	v_min_f32_e32 v62, v106, v62
	v_max_f32_e32 v35, v60, v254
	v_min_f32_e32 v254, v60, v254
	v_max_f32_e32 v61, v14, v103
	v_min_f32_e32 v103, v14, v103
	v_max_f32_e32 v39, v255, v97
	v_min_f32_e32 v97, v255, v97
	v_max_f32_e32 v2, v145, v10
	v_min_f32_e32 v10, v145, v10
	v_max_f32_e32 v41, v251, v32
	v_min_f32_e32 v32, v251, v32
	v_max_f32_e32 v116, v80, v20
	v_min_f32_e32 v20, v80, v20
	v_max_f32_e32 v118, v89, v47
	v_min_f32_e32 v47, v89, v47
	v_max_f32_e32 v250, v12, v35
	v_min_f32_e32 v35, v12, v35
	v_max_f32_e32 v38, v62, v254
	v_min_f32_e32 v254, v62, v254
	v_max_f32_e32 v40, v61, v39
	v_min_f32_e32 v39, v61, v39
	v_max_f32_e32 v13, v103, v97
	v_min_f32_e32 v97, v103, v97
	v_max_f32_e32 v127, v2, v41
	v_min_f32_e32 v41, v2, v41
	v_max_f32_e32 v33, v10, v32
	v_min_f32_e32 v32, v10, v32
	v_max_f32_e32 v121, v116, v118
	v_min_f32_e32 v118, v116, v118
	v_max_f32_e32 v100, v20, v47
	v_min_f32_e32 v47, v20, v47
	v_max_f32_e32 v53, v53, v47
	v_max_f32_e32 v29, v29, v100
	v_max_f32_e32 v55, v55, v118
	v_max_f32_e32 v18, v18, v121
	v_max_f32_e32 v57, v57, v32
	v_max_f32_e32 v48, v48, v33
	v_max_f32_e32 v249, v249, v41
	v_max_f32_e32 v86, v86, v127
	v_max_f32_e32 v1, v1, v97
	v_max_f32_e32 v50, v50, v13
	v_max_f32_e32 v148, v148, v39
	v_max_f32_e32 v0, v0, v40
	v_max_f32_e32 v92, v92, v254
	v_max_f32_e32 v52, v52, v38
	v_max_f32_e32 v54, v54, v35
	v_max_f32_e32 v15, v15, v250
	v_max_f32_e32 v68, v53, v1
	v_min_f32_e32 v1, v53, v1
	v_max_f32_e32 v42, v29, v50
	v_min_f32_e32 v50, v29, v50
	v_max_f32_e32 v65, v55, v148
	v_min_f32_e32 v148, v55, v148
	v_max_f32_e32 v109, v18, v0
	v_min_f32_e32 v0, v18, v0
	v_max_f32_e32 v114, v57, v92
	v_min_f32_e32 v92, v57, v92
	v_max_f32_e32 v101, v48, v52
	v_min_f32_e32 v52, v48, v52
	v_max_f32_e32 v46, v249, v54
	v_min_f32_e32 v54, v249, v54
	v_max_f32_e32 v34, v86, v15
	v_min_f32_e32 v15, v86, v15
	v_max_f32_e32 v19, v68, v114
	v_min_f32_e32 v114, v68, v114
	v_max_f32_e32 v44, v42, v101
	v_min_f32_e32 v101, v42, v101
	v_max_f32_e32 v23, v65, v46
	v_min_f32_e32 v46, v65, v46
	v_max_f32_e32 v16, v109, v34
	v_min_f32_e32 v34, v109, v34
	v_max_f32_e32 v122, v1, v92
	v_min_f32_e32 v92, v1, v92
	v_max_f32_e32 v45, v50, v52
	v_min_f32_e32 v52, v50, v52
	v_max_f32_e32 v123, v148, v54
	v_min_f32_e32 v54, v148, v54
	v_max_f32_e32 v5, v0, v15
	v_min_f32_e32 v15, v0, v15
	v_max_f32_e32 v150, v19, v23
	v_min_f32_e32 v23, v19, v23
	v_max_f32_e32 v99, v44, v16
	v_min_f32_e32 v16, v44, v16
	v_max_f32_e32 v107, v114, v46
	v_min_f32_e32 v46, v114, v46
	v_max_f32_e32 v11, v101, v34
	v_min_f32_e32 v34, v101, v34
	v_max_f32_e32 v108, v122, v123
	v_min_f32_e32 v123, v122, v123
	v_max_f32_e32 v113, v45, v5
	v_min_f32_e32 v5, v45, v5
	v_max_f32_e32 v110, v92, v54
	v_min_f32_e32 v54, v92, v54
	v_max_f32_e32 v98, v52, v15
	v_min_f32_e32 v15, v52, v15
	v_max_f32_e32 v151, v150, v99
	v_min_f32_e32 v99, v150, v99
	v_max_f32_e32 v252, v23, v16
	v_min_f32_e32 v16, v23, v16
	v_max_f32_e32 v112, v107, v11
	v_min_f32_e32 v11, v107, v11
	v_max_f32_e32 v147, v46, v34
	v_min_f32_e32 v34, v46, v34
	v_max_f32_e32 v253, v108, v113
	v_min_f32_e32 v113, v108, v113
	v_max_f32_e32 v4, v123, v5
	v_min_f32_e32 v5, v123, v5
	v_max_f32_e32 v31, v110, v98
	v_min_f32_e32 v98, v110, v98
	v_max_f32_e32 v105, v54, v15
	v_min_f32_e32 v15, v54, v15
	v_mov_b32_e32 v120, v151
	v_mov_b32_e32 v126, v99
	v_mov_b32_e32 v70, v252
	v_mov_b32_e32 v115, v16
	v_mov_b32_e32 v71, v112
	v_mov_b32_e32 v75, v11
	v_mov_b32_e32 v72, v147
	v_mov_b32_e32 v85, v34
	v_mov_b32_e32 v17, v253
	v_mov_b32_e32 v81, v113
	v_mov_b32_e32 v64, v4
	v_mov_b32_e32 v76, v5
	v_mov_b32_e32 v73, v31
	v_mov_b32_e32 v69, v98
	v_mov_b32_e32 v74, v105
	v_mov_b32_e32 v82, v15
	s_nop 1
	v_permlane32_swap_b32_e32 v151, v120
	v_permlane32_swap_b32_e32 v99, v126
	v_permlane32_swap_b32_e32 v252, v70
	v_permlane32_swap_b32_e32 v16, v115
	v_permlane32_swap_b32_e32 v112, v71
	v_permlane32_swap_b32_e32 v11, v75
	v_permlane32_swap_b32_e32 v147, v72
	v_permlane32_swap_b32_e32 v34, v85
	v_permlane32_swap_b32_e32 v253, v17
	v_permlane32_swap_b32_e32 v113, v81
	v_permlane32_swap_b32_e32 v4, v64
	v_permlane32_swap_b32_e32 v5, v76
	v_permlane32_swap_b32_e32 v31, v73
	v_permlane32_swap_b32_e32 v98, v69
	v_permlane32_swap_b32_e32 v105, v74
	v_permlane32_swap_b32_e32 v15, v82
	s_nop 1
	v_max_f32_e32 v151, v151, v82
	v_max_f32_e32 v99, v99, v74
	v_max_f32_e32 v252, v252, v69
	v_max_f32_e32 v16, v16, v73
	v_max_f32_e32 v112, v112, v76
	v_max_f32_e32 v11, v11, v64
	v_max_f32_e32 v147, v147, v81
	v_max_f32_e32 v34, v34, v17
	v_max_f32_e32 v253, v253, v85
	v_max_f32_e32 v113, v113, v72
	v_max_f32_e32 v4, v4, v75
	v_max_f32_e32 v5, v5, v71
	v_max_f32_e32 v31, v31, v115
	v_max_f32_e32 v98, v98, v70
	v_max_f32_e32 v105, v105, v126
	v_max_f32_e32 v15, v15, v120
	v_max_f32_e32 v78, v151, v253
	v_min_f32_e32 v253, v151, v253
	v_max_f32_e32 v91, v99, v113
	v_min_f32_e32 v113, v99, v113
	v_max_f32_e32 v26, v252, v4
	v_min_f32_e32 v4, v252, v4
	v_max_f32_e32 v3, v16, v5
	v_min_f32_e32 v5, v16, v5
	v_max_f32_e32 v28, v112, v31
	v_min_f32_e32 v31, v112, v31
	v_max_f32_e32 v111, v11, v98
	v_min_f32_e32 v98, v11, v98
	v_max_f32_e32 v119, v147, v105
	v_min_f32_e32 v105, v147, v105
	v_max_f32_e32 v90, v34, v15
	v_min_f32_e32 v15, v34, v15
	v_max_f32_e32 v30, v78, v28
	v_min_f32_e32 v28, v78, v28
	v_max_f32_e32 v87, v91, v111
	v_min_f32_e32 v111, v91, v111
	v_max_f32_e32 v93, v26, v119
	v_min_f32_e32 v119, v26, v119
	v_max_f32_e32 v49, v3, v90
	v_min_f32_e32 v90, v3, v90
	v_max_f32_e32 v7, v253, v31
	v_min_f32_e32 v31, v253, v31
	v_max_f32_e32 v51, v113, v98
	v_min_f32_e32 v98, v113, v98
	v_max_f32_e32 v104, v4, v105
	v_min_f32_e32 v105, v4, v105
	v_max_f32_e32 v37, v5, v15
	v_min_f32_e32 v15, v5, v15
	v_max_f32_e32 v124, v30, v93
	v_min_f32_e32 v93, v30, v93
	v_max_f32_e32 v117, v87, v49
	v_min_f32_e32 v49, v87, v49
	v_max_f32_e32 v25, v28, v119
	v_min_f32_e32 v119, v28, v119
	v_max_f32_e32 v43, v111, v90
	v_min_f32_e32 v90, v111, v90
	v_max_f32_e32 v77, v7, v104
	v_min_f32_e32 v104, v7, v104
	v_max_f32_e32 v24, v51, v37
	v_min_f32_e32 v37, v51, v37
	v_max_f32_e32 v79, v31, v105
	v_min_f32_e32 v105, v31, v105
	v_max_f32_e32 v67, v98, v15
	v_min_f32_e32 v15, v98, v15
	v_max_f32_e32 v125, v124, v117
	v_min_f32_e32 v117, v124, v117
	v_max_f32_e32 v102, v93, v49
	v_min_f32_e32 v49, v93, v49
	v_max_f32_e32 v22, v25, v43
	v_min_f32_e32 v43, v25, v43
	v_max_f32_e32 v96, v119, v90
	v_min_f32_e32 v90, v119, v90
	v_max_f32_e32 v66, v77, v24
	v_min_f32_e32 v24, v77, v24
	v_max_f32_e32 v36, v104, v37
	v_min_f32_e32 v37, v104, v37
	v_max_f32_e32 v63, v79, v67
	v_min_f32_e32 v67, v79, v67
	v_max_f32_e32 v21, v105, v15
	v_min_f32_e32 v15, v105, v15
	s_waitcnt vmcnt(0)
	v_pk_mul_f32 v[160:161], v[160:161], v[176:177]
	v_pk_mul_f32 v[162:163], v[162:163], v[178:179]
	v_pk_mul_f32 v[164:165], v[164:165], v[180:181]
	v_pk_mul_f32 v[166:167], v[166:167], v[182:183]
	v_pk_mul_f32 v[168:169], v[168:169], v[184:185]
	v_pk_mul_f32 v[170:171], v[170:171], v[186:187]
	v_pk_mul_f32 v[172:173], v[172:173], v[188:189]
	v_pk_mul_f32 v[174:175], v[174:175], v[190:191]
	v_max3_f32 v192, |v160|, |v161|, |v162|
	v_max3_f32 v192, |v163|, |v164|, v192
	v_max3_f32 v192, |v165|, |v166|, v192
	v_max3_f32 v192, |v167|, |v168|, v192
	v_max3_f32 v192, |v169|, |v170|, v192
	v_max3_f32 v192, |v171|, |v172|, v192
	v_max3_f32 v192, |v173|, |v174|, v192
	v_max_f32_e64 v192, |v175|, v192
	s_nop 1
	v_mov_b32_dpp v193, v192 quad_perm:[1,0,3,2] row_mask:0xf bank_mask:0xf bound_ctrl:1
	v_max_f32_e32 v192, v192, v193
	s_nop 1
	v_mov_b32_dpp v193, v192 quad_perm:[2,3,0,1] row_mask:0xf bank_mask:0xf bound_ctrl:1
	v_max_f32_e32 v192, v192, v193
	s_nop 1
	v_mov_b32_dpp v193, v192 row_half_mirror row_mask:0xf bank_mask:0xf bound_ctrl:1
	v_max_f32_e32 v192, v192, v193
	s_nop 1
	v_mov_b32_dpp v193, v192 row_mirror row_mask:0xf bank_mask:0xf bound_ctrl:1
	v_max_f32_e32 v192, v192, v193
	v_mov_b32_e32 v193, v192
	s_nop 1
	v_permlane16_swap_b32_e32 v192, v193
	s_nop 1
	v_max_f32_e32 v192, v192, v193
	v_mov_b32_e32 v193, v192
	s_nop 1
	v_permlane32_swap_b32_e32 v192, v193
	s_nop 1
	v_max_f32_e32 v192, v192, v193
	v_max_f32_e32 v192, 0xda24260, v192
	v_mul_f32_e32 v194, 0x3e2aaaab, v192
	global_store_dword v214, v194, s[12:13]
	v_div_scale_f32 v195, s[26:27], v194, v194, 1.0
	v_rcp_f32_e32 v196, v195
	v_div_scale_f32 v204, vcc, 1.0, v194, 1.0
	v_fma_f32 v205, -v195, v196, 1.0
	v_fmac_f32_e32 v196, v205, v196
	v_mul_f32_e32 v205, v204, v196
	v_fma_f32 v206, -v195, v205, v204
	v_fmac_f32_e32 v205, v206, v196
	v_fma_f32 v195, -v195, v205, v204
	s_nop 0
	v_div_fmas_f32 v195, v195, v196, v205
	v_div_fixup_f32 v207, v195, v194, 1.0
	v_mul_f32_e32 v160, v207, v160
	v_mul_f32_e32 v161, v207, v161
	v_mul_f32_e32 v162, v207, v162
	v_mul_f32_e32 v163, v207, v163
	v_mul_f32_e32 v164, v207, v164
	v_mul_f32_e32 v165, v207, v165
	v_mul_f32_e32 v166, v207, v166
	v_mul_f32_e32 v167, v207, v167
	v_mul_f32_e32 v168, v207, v168
	v_mul_f32_e32 v169, v207, v169
	v_mul_f32_e32 v170, v207, v170
	v_mul_f32_e32 v171, v207, v171
	v_mul_f32_e32 v172, v207, v172
	v_mul_f32_e32 v173, v207, v173
	v_mul_f32_e32 v174, v207, v174
	v_mul_f32_e32 v175, v207, v175
	v_mov_b32_e32 v208, 0
	v_mov_b32_e32 v209, 0
	v_mov_b32_e32 v210, 0
	v_mov_b32_e32 v193, 0
	v_cvt_scalef32_pk_fp4_f32 v208, v160, v161, 1.0
	v_cvt_scalef32_pk_fp4_f32 v209, v164, v165, 1.0
	v_cvt_scalef32_pk_fp4_f32 v210, v168, v169, 1.0
	v_cvt_scalef32_pk_fp4_f32 v193, v172, v173, 1.0
	v_cvt_scalef32_pk_fp4_f32 v208, v162, v163, 1.0 op_sel:[0,0,1,0]
	v_cvt_scalef32_pk_fp4_f32 v209, v166, v167, 1.0 op_sel:[0,0,1,0]
	v_cvt_scalef32_pk_fp4_f32 v210, v170, v171, 1.0 op_sel:[0,0,1,0]
	v_cvt_scalef32_pk_fp4_f32 v193, v174, v175, 1.0 op_sel:[0,0,1,0]
	global_store_short v213, v208, s[10:11] nt
	s_add_u32 s14, s10, 0x200000
	s_addc_u32 s15, s11, 0
	global_store_short v213, v209, s[14:15] nt
	s_add_u32 s14, s10, 0x400000
	s_addc_u32 s15, s11, 0
	global_store_short v213, v210, s[14:15] nt
	s_add_u32 s14, s10, 0x600000
	s_addc_u32 s15, s11, 0
	global_store_short v213, v193, s[14:15] nt
	s_add_u32 s10, s10, 0x20000
	s_addc_u32 s11, s11, 0
	s_add_u32 s12, s12, 0x2000
	s_addc_u32 s13, s13, 0
	global_load_dwordx4 v[160:163], v212, s[8:9] offset:0 nt
	global_load_dwordx4 v[164:167], v212, s[8:9] offset:1024 nt
	global_load_dwordx4 v[168:171], v212, s[8:9] offset:2048 nt
	global_load_dwordx4 v[172:175], v212, s[8:9] offset:3072 nt
	s_add_u32 s8, s8, 0x800000
	s_addc_u32 s9, s9, 0
	ds_write_b8 v240, v125 offset:512
	ds_write_b8 v240, v117 offset:513
	ds_write_b8 v240, v102 offset:514
	ds_write_b8 v240, v49 offset:515
	ds_write_b8 v240, v22 offset:516
	ds_write_b8 v240, v43 offset:517
	ds_write_b8 v240, v96 offset:518
	ds_write_b8 v240, v90 offset:519
	ds_write_b8 v240, v66 offset:520
	ds_write_b8 v240, v24 offset:521
	ds_write_b8 v240, v36 offset:522
	ds_write_b8 v240, v37 offset:523
	ds_write_b8 v240, v63 offset:524
	ds_write_b8 v240, v67 offset:525
	ds_write_b8 v240, v21 offset:526
	ds_write_b8 v240, v15 offset:527
	v_cndmask_b32_e64 v0, v128, v125, s[4:5]
	v_cndmask_b32_e64 v17, v125, v128, s[4:5]
	v_cndmask_b32_e64 v1, v129, v117, s[4:5]
	v_cndmask_b32_e64 v18, v117, v129, s[4:5]
	v_cndmask_b32_e64 v2, v130, v102, s[4:5]
	v_cndmask_b32_e64 v19, v102, v130, s[4:5]
	v_cndmask_b32_e64 v3, v131, v49, s[4:5]
	v_cndmask_b32_e64 v20, v49, v131, s[4:5]
	v_cndmask_b32_e64 v4, v132, v22, s[4:5]
	v_cndmask_b32_e64 v23, v22, v132, s[4:5]
	v_cndmask_b32_e64 v5, v133, v43, s[4:5]
	v_cndmask_b32_e64 v25, v43, v133, s[4:5]
	v_cndmask_b32_e64 v6, v134, v96, s[4:5]
	v_cndmask_b32_e64 v26, v96, v134, s[4:5]
	v_cndmask_b32_e64 v7, v135, v90, s[4:5]
	v_cndmask_b32_e64 v27, v90, v135, s[4:5]
	v_cndmask_b32_e64 v8, v136, v66, s[4:5]
	v_cndmask_b32_e64 v28, v66, v136, s[4:5]
	v_cndmask_b32_e64 v9, v137, v24, s[4:5]
	v_cndmask_b32_e64 v29, v24, v137, s[4:5]
	v_cndmask_b32_e64 v10, v138, v36, s[4:5]
	v_cndmask_b32_e64 v30, v36, v138, s[4:5]
	v_cndmask_b32_e64 v11, v139, v37, s[4:5]
	v_cndmask_b32_e64 v31, v37, v139, s[4:5]
	v_cndmask_b32_e64 v12, v140, v63, s[4:5]
	v_cndmask_b32_e64 v32, v63, v140, s[4:5]
	v_cndmask_b32_e64 v13, v141, v67, s[4:5]
	v_cndmask_b32_e64 v33, v67, v141, s[4:5]
	v_cndmask_b32_e64 v14, v142, v21, s[4:5]
	v_cndmask_b32_e64 v34, v21, v142, s[4:5]
	v_cndmask_b32_e64 v16, v143, v15, s[4:5]
	v_cndmask_b32_e64 v35, v15, v143, s[4:5]
	v_and_b32_e32 v0, s6, v0
	v_and_b32_e32 v17, s6, v17
	v_and_b32_e32 v1, s6, v1
	v_and_b32_e32 v18, s6, v18
	v_and_b32_e32 v2, s6, v2
	v_and_b32_e32 v19, s6, v19
	v_and_b32_e32 v3, s6, v3
	v_and_b32_e32 v20, s6, v20
	v_and_b32_e32 v4, s6, v4
	v_and_b32_e32 v23, s6, v23
	v_and_b32_e32 v5, s6, v5
	v_and_b32_e32 v25, s6, v25
	v_and_b32_e32 v6, s6, v6
	v_and_b32_e32 v26, s6, v26
	v_and_b32_e32 v7, s6, v7
	v_and_b32_e32 v27, s6, v27
	v_and_b32_e32 v8, s6, v8
	v_and_b32_e32 v28, s6, v28
	v_and_b32_e32 v9, s6, v9
	v_and_b32_e32 v29, s6, v29
	v_and_b32_e32 v10, s6, v10
	v_and_b32_e32 v30, s6, v30
	v_and_b32_e32 v11, s6, v11
	v_and_b32_e32 v31, s6, v31
	v_and_b32_e32 v12, s6, v12
	v_and_b32_e32 v32, s6, v32
	v_and_b32_e32 v13, s6, v13
	v_and_b32_e32 v33, s6, v33
	v_and_b32_e32 v14, s6, v14
	v_and_b32_e32 v34, s6, v34
	v_and_b32_e32 v16, s6, v16
	v_and_b32_e32 v35, s6, v35
	v_add_f32_e32 v38, v0, v18
	v_and_or_b32 v38, v38, s7, 0
	v_add_f32_e32 v39, v0, v19
	v_and_or_b32 v39, v39, s7, 2
	v_add_f32_e32 v40, v0, v20
	v_and_or_b32 v40, v40, s7, 4
	v_add_f32_e32 v41, v0, v23
	v_and_or_b32 v41, v41, s7, 6
	v_add_f32_e32 v42, v0, v25
	v_and_or_b32 v42, v42, s7, 8
	v_add_f32_e32 v44, v0, v26
	v_and_or_b32 v44, v44, s7, 10
	v_add_f32_e32 v45, v0, v27
	v_and_or_b32 v45, v45, s7, 12
	v_add_f32_e32 v46, v0, v28
	v_and_or_b32 v46, v46, s7, 14
	v_add_f32_e32 v47, v0, v29
	v_and_or_b32 v47, v47, s7, 16
	v_add_f32_e32 v48, v0, v30
	v_and_or_b32 v48, v48, s7, 18
	v_add_f32_e32 v50, v0, v31
	v_and_or_b32 v50, v50, s7, 20
	v_add_f32_e32 v51, v0, v32
	v_and_or_b32 v51, v51, s7, 22
	v_add_f32_e32 v52, v0, v33
	v_and_or_b32 v52, v52, s7, 24
	v_add_f32_e32 v53, v0, v34
	v_and_or_b32 v53, v53, s7, 26
	v_add_f32_e32 v54, v0, v35
	v_and_or_b32 v54, v54, s7, 28
	v_add_f32_e32 v55, v1, v19
	v_and_or_b32 v55, v55, s7, 30
	v_add_f32_e32 v56, v1, v20
	v_and_or_b32 v56, v56, s7, 32
	v_add_f32_e32 v57, v1, v23
	v_and_or_b32 v57, v57, s7, 34
	v_add_f32_e32 v58, v1, v25
	v_and_or_b32 v58, v58, s7, 36
	v_add_f32_e32 v59, v1, v26
	v_and_or_b32 v59, v59, s7, 38
	v_add_f32_e32 v60, v1, v27
	v_and_or_b32 v60, v60, s7, 40
	v_add_f32_e32 v61, v2, v20
	v_and_or_b32 v61, v61, s7, 42
	v_add_f32_e32 v62, v2, v23
	v_and_or_b32 v62, v62, s7, 44
	v_add_f32_e32 v64, v0, v17
	v_and_or_b32 v64, v64, s7, 46
	v_cndmask_b32_e64 v64, v64, v244, s[4:5]
	v_add_f32_e32 v65, v1, v18
	v_and_or_b32 v65, v65, s7, 48
	v_cndmask_b32_e64 v65, v65, v244, s[4:5]
	v_add_f32_e32 v68, v2, v19
	v_and_or_b32 v68, v68, s7, 50
	v_cndmask_b32_e64 v68, v68, v244, s[4:5]
	v_add_f32_e32 v69, v3, v20
	v_and_or_b32 v69, v69, s7, 52
	v_cndmask_b32_e64 v69, v69, v244, s[4:5]
	v_max_f32_e32 v70, v38, v53
	v_min_f32_e32 v53, v38, v53
	v_max_f32_e32 v71, v39, v52
	v_min_f32_e32 v52, v39, v52
	v_max_f32_e32 v72, v40, v55
	v_min_f32_e32 v55, v40, v55
	v_max_f32_e32 v73, v41, v54
	v_min_f32_e32 v54, v41, v54
	v_max_f32_e32 v74, v42, v47
	v_min_f32_e32 v47, v42, v47
	v_max_f32_e32 v75, v44, v45
	v_min_f32_e32 v45, v44, v45
	v_max_f32_e32 v76, v46, v51
	v_min_f32_e32 v51, v46, v51
	v_max_f32_e32 v77, v48, v50
	v_min_f32_e32 v50, v48, v50
	v_max_f32_e32 v78, v70, v75
	v_min_f32_e32 v75, v70, v75
	v_max_f32_e32 v79, v71, v76
	v_min_f32_e32 v76, v71, v76
	v_max_f32_e32 v80, v72, v77
	v_min_f32_e32 v77, v72, v77
	v_max_f32_e32 v81, v73, v74
	v_min_f32_e32 v74, v73, v74
	v_max_f32_e32 v82, v45, v53
	v_min_f32_e32 v53, v45, v53
	v_max_f32_e32 v83, v47, v54
	v_min_f32_e32 v54, v47, v54
	v_max_f32_e32 v84, v50, v55
	v_min_f32_e32 v55, v50, v55
	v_max_f32_e32 v85, v51, v52
	v_min_f32_e32 v52, v51, v52
	v_max_f32_e32 v86, v78, v79
	v_min_f32_e32 v79, v78, v79
	v_max_f32_e32 v87, v80, v81
	v_min_f32_e32 v81, v80, v81
	v_max_f32_e32 v88, v74, v75
	v_min_f32_e32 v75, v74, v75
	v_max_f32_e32 v89, v82, v83
	v_min_f32_e32 v83, v82, v83
	v_max_f32_e32 v91, v76, v77
	v_min_f32_e32 v77, v76, v77
	v_max_f32_e32 v92, v84, v85
	v_min_f32_e32 v85, v84, v85
	v_max_f32_e32 v93, v52, v53
	v_min_f32_e32 v53, v52, v53
	v_max_f32_e32 v94, v54, v55
	v_min_f32_e32 v55, v54, v55
	v_max_f32_e32 v95, v86, v87
	v_min_f32_e32 v87, v86, v87
	v_max_f32_e32 v97, v79, v81
	v_min_f32_e32 v81, v79, v81
	v_max_f32_e32 v98, v88, v92
	v_min_f32_e32 v92, v88, v92
	v_max_f32_e32 v99, v75, v85
	v_min_f32_e32 v85, v75, v85
	v_max_f32_e32 v100, v89, v91
	v_min_f32_e32 v91, v89, v91
	v_max_f32_e32 v101, v83, v77
	v_min_f32_e32 v77, v83, v77
	v_max_f32_e32 v103, v93, v94
	v_min_f32_e32 v94, v93, v94
	v_max_f32_e32 v104, v53, v55
	v_min_f32_e32 v55, v53, v55
	v_max_f32_e32 v105, v97, v87
	v_min_f32_e32 v87, v97, v87
	v_max_f32_e32 v106, v81, v103
	v_min_f32_e32 v103, v81, v103
	v_max_f32_e32 v107, v98, v100
	v_min_f32_e32 v100, v98, v100
	v_max_f32_e32 v108, v99, v91
	v_min_f32_e32 v91, v99, v91
	v_max_f32_e32 v109, v101, v92
	v_min_f32_e32 v92, v101, v92
	v_max_f32_e32 v110, v77, v85
	v_min_f32_e32 v85, v77, v85
	v_max_f32_e32 v111, v104, v94
	v_min_f32_e32 v94, v104, v94
	v_max_f32_e32 v112, v105, v107
	v_min_f32_e32 v107, v105, v107
	v_max_f32_e32 v113, v87, v100
	v_min_f32_e32 v100, v87, v100
	v_max_f32_e32 v114, v108, v109
	v_min_f32_e32 v109, v108, v109
	v_max_f32_e32 v115, v91, v92
	v_min_f32_e32 v92, v91, v92
	v_max_f32_e32 v116, v110, v111
	v_min_f32_e32 v111, v110, v111
	v_max_f32_e32 v118, v85, v94
	v_min_f32_e32 v94, v85, v94
	v_max_f32_e32 v119, v113, v107
	v_min_f32_e32 v107, v113, v107
	v_max_f32_e32 v120, v106, v100
	v_min_f32_e32 v100, v106, v100
	v_max_f32_e32 v121, v116, v103
	v_min_f32_e32 v103, v116, v103
	v_max_f32_e32 v122, v118, v111
	v_min_f32_e32 v111, v118, v111
	v_max_f32_e32 v123, v120, v114
	v_min_f32_e32 v114, v120, v114
	v_max_f32_e32 v124, v100, v109
	v_min_f32_e32 v109, v100, v109
	v_max_f32_e32 v126, v115, v121
	v_min_f32_e32 v121, v115, v121
	v_max_f32_e32 v127, v92, v103
	v_min_f32_e32 v103, v92, v103
	v_max_f32_e32 v144, v123, v107
	v_min_f32_e32 v107, v123, v107
	v_max_f32_e32 v145, v114, v124
	v_min_f32_e32 v124, v114, v124
	v_max_f32_e32 v146, v126, v109
	v_min_f32_e32 v109, v126, v109
	v_max_f32_e32 v147, v121, v127
	v_min_f32_e32 v127, v121, v127
	v_max_f32_e32 v148, v122, v103
	v_min_f32_e32 v103, v122, v103
	v_max_f32_e32 v149, v124, v146
	v_min_f32_e32 v146, v124, v146
	v_max_f32_e32 v150, v109, v147
	v_min_f32_e32 v147, v109, v147
	v_max_f32_e32 v151, v60, v65
	v_min_f32_e32 v65, v60, v65
	v_max_f32_e32 v249, v61, v62
	v_min_f32_e32 v62, v61, v62
	v_max_f32_e32 v250, v68, v69
	v_min_f32_e32 v69, v68, v69
	v_max_f32_e32 v251, v56, v249
	v_min_f32_e32 v249, v56, v249
	v_max_f32_e32 v252, v57, v64
	v_min_f32_e32 v64, v57, v64
	v_max_f32_e32 v253, v58, v250
	v_min_f32_e32 v250, v58, v250
	v_max_f32_e32 v254, v59, v151
	v_min_f32_e32 v151, v59, v151
	v_max_f32_e32 v255, v251, v252
	v_min_f32_e32 v252, v251, v252
	v_max_f32_e32 v128, v253, v254
	v_min_f32_e32 v254, v253, v254
	v_max_f32_e32 v129, v151, v249
	v_min_f32_e32 v249, v151, v249
	v_max_f32_e32 v130, v62, v65
	v_min_f32_e32 v65, v62, v65
	v_max_f32_e32 v131, v64, v250
	v_min_f32_e32 v250, v64, v250
	v_max_f32_e32 v132, v255, v128
	v_min_f32_e32 v128, v255, v128
	v_max_f32_e32 v133, v252, v254
	v_min_f32_e32 v254, v252, v254
	v_max_f32_e32 v134, v129, v69
	v_min_f32_e32 v69, v129, v69
	v_max_f32_e32 v135, v130, v131
	v_min_f32_e32 v131, v130, v131
	v_max_f32_e32 v136, v65, v250
	v_min_f32_e32 v250, v65, v250
	v_max_f32_e32 v137, v133, v128
	v_min_f32_e32 v128, v133, v128
	v_max_f32_e32 v138, v134, v135
	v_min_f32_e32 v135, v134, v135
	v_max_f32_e32 v139, v249, v131
	v_min_f32_e32 v131, v249, v131
	v_max_f32_e32 v140, v136, v69
	v_min_f32_e32 v69, v136, v69
	v_max_f32_e32 v141, v137, v138
	v_min_f32_e32 v138, v137, v138
	v_max_f32_e32 v142, v128, v135
	v_min_f32_e32 v135, v128, v135
	v_max_f32_e32 v143, v139, v140
	v_min_f32_e32 v140, v139, v140
	v_max_f32_e32 v125, v131, v69
	v_min_f32_e32 v69, v131, v69
	v_max_f32_e32 v117, v142, v138
	v_min_f32_e32 v138, v142, v138
	v_max_f32_e32 v102, v254, v135
	v_min_f32_e32 v135, v254, v135
	v_max_f32_e32 v49, v102, v143
	v_min_f32_e32 v143, v102, v143
	v_max_f32_e32 v22, v135, v140
	v_min_f32_e32 v140, v135, v140
	v_max_f32_e32 v43, v125, v250
	v_min_f32_e32 v250, v125, v250
	v_max_f32_e32 v96, v49, v138
	v_min_f32_e32 v138, v49, v138
	v_max_f32_e32 v90, v143, v22
	v_min_f32_e32 v22, v143, v22
	v_max_f32_e32 v66, v43, v140
	v_min_f32_e32 v140, v43, v140
	v_max_f32_e32 v24, v250, v69
	v_min_f32_e32 v69, v250, v69
	v_max_f32_e32 v36, v22, v66
	v_min_f32_e32 v66, v22, v66
	v_max_f32_e32 v37, v140, v24
	v_min_f32_e32 v24, v140, v24
	s_waitcnt vmcnt(0)
	v_pk_mul_f32 v[160:161], v[160:161], v[176:177]
	v_pk_mul_f32 v[162:163], v[162:163], v[178:179]
	v_pk_mul_f32 v[164:165], v[164:165], v[180:181]
	v_pk_mul_f32 v[166:167], v[166:167], v[182:183]
	v_pk_mul_f32 v[168:169], v[168:169], v[184:185]
	v_pk_mul_f32 v[170:171], v[170:171], v[186:187]
	v_pk_mul_f32 v[172:173], v[172:173], v[188:189]
	v_pk_mul_f32 v[174:175], v[174:175], v[190:191]
	v_max3_f32 v192, |v160|, |v161|, |v162|
	v_max3_f32 v192, |v163|, |v164|, v192
	v_max3_f32 v192, |v165|, |v166|, v192
	v_max3_f32 v192, |v167|, |v168|, v192
	v_max3_f32 v192, |v169|, |v170|, v192
	v_max3_f32 v192, |v171|, |v172|, v192
	v_max3_f32 v192, |v173|, |v174|, v192
	v_max_f32_e64 v192, |v175|, v192
	s_nop 1
	v_mov_b32_dpp v193, v192 quad_perm:[1,0,3,2] row_mask:0xf bank_mask:0xf bound_ctrl:1
	v_max_f32_e32 v192, v192, v193
	s_nop 1
	v_mov_b32_dpp v193, v192 quad_perm:[2,3,0,1] row_mask:0xf bank_mask:0xf bound_ctrl:1
	v_max_f32_e32 v192, v192, v193
	s_nop 1
	v_mov_b32_dpp v193, v192 row_half_mirror row_mask:0xf bank_mask:0xf bound_ctrl:1
	v_max_f32_e32 v192, v192, v193
	s_nop 1
	v_mov_b32_dpp v193, v192 row_mirror row_mask:0xf bank_mask:0xf bound_ctrl:1
	v_max_f32_e32 v192, v192, v193
	v_mov_b32_e32 v193, v192
	s_nop 1
	v_permlane16_swap_b32_e32 v192, v193
	s_nop 1
	v_max_f32_e32 v192, v192, v193
	v_mov_b32_e32 v193, v192
	s_nop 1
	v_permlane32_swap_b32_e32 v192, v193
	s_nop 1
	v_max_f32_e32 v192, v192, v193
	v_max_f32_e32 v192, 0xda24260, v192
	v_mul_f32_e32 v194, 0x3e2aaaab, v192
	global_store_dword v214, v194, s[12:13]
	v_div_scale_f32 v195, s[26:27], v194, v194, 1.0
	v_rcp_f32_e32 v196, v195
	v_div_scale_f32 v204, vcc, 1.0, v194, 1.0
	v_fma_f32 v205, -v195, v196, 1.0
	v_fmac_f32_e32 v196, v205, v196
	v_mul_f32_e32 v205, v204, v196
	v_fma_f32 v206, -v195, v205, v204
	v_fmac_f32_e32 v205, v206, v196
	v_fma_f32 v195, -v195, v205, v204
	s_nop 0
	v_div_fmas_f32 v195, v195, v196, v205
	v_div_fixup_f32 v207, v195, v194, 1.0
	v_mul_f32_e32 v160, v207, v160
	v_mul_f32_e32 v161, v207, v161
	v_mul_f32_e32 v162, v207, v162
	v_mul_f32_e32 v163, v207, v163
	v_mul_f32_e32 v164, v207, v164
	v_mul_f32_e32 v165, v207, v165
	v_mul_f32_e32 v166, v207, v166
	v_mul_f32_e32 v167, v207, v167
	v_mul_f32_e32 v168, v207, v168
	v_mul_f32_e32 v169, v207, v169
	v_mul_f32_e32 v170, v207, v170
	v_mul_f32_e32 v171, v207, v171
	v_mul_f32_e32 v172, v207, v172
	v_mul_f32_e32 v173, v207, v173
	v_mul_f32_e32 v174, v207, v174
	v_mul_f32_e32 v175, v207, v175
	v_mov_b32_e32 v208, 0
	v_mov_b32_e32 v209, 0
	v_mov_b32_e32 v210, 0
	v_mov_b32_e32 v193, 0
	v_cvt_scalef32_pk_fp4_f32 v208, v160, v161, 1.0
	v_cvt_scalef32_pk_fp4_f32 v209, v164, v165, 1.0
	v_cvt_scalef32_pk_fp4_f32 v210, v168, v169, 1.0
	v_cvt_scalef32_pk_fp4_f32 v193, v172, v173, 1.0
	v_cvt_scalef32_pk_fp4_f32 v208, v162, v163, 1.0 op_sel:[0,0,1,0]
	v_cvt_scalef32_pk_fp4_f32 v209, v166, v167, 1.0 op_sel:[0,0,1,0]
	v_cvt_scalef32_pk_fp4_f32 v210, v170, v171, 1.0 op_sel:[0,0,1,0]
	v_cvt_scalef32_pk_fp4_f32 v193, v174, v175, 1.0 op_sel:[0,0,1,0]
	global_store_short v213, v208, s[10:11] nt
	s_add_u32 s14, s10, 0x200000
	s_addc_u32 s15, s11, 0
	global_store_short v213, v209, s[14:15] nt
	s_add_u32 s14, s10, 0x400000
	s_addc_u32 s15, s11, 0
	global_store_short v213, v210, s[14:15] nt
	s_add_u32 s14, s10, 0x600000
	s_addc_u32 s15, s11, 0
	global_store_short v213, v193, s[14:15] nt
	s_add_u32 s10, s10, 0x20000
	s_addc_u32 s11, s11, 0
	s_add_u32 s12, s12, 0x2000
	s_addc_u32 s13, s13, 0
	global_load_dwordx4 v[160:163], v212, s[8:9] offset:0 nt
	global_load_dwordx4 v[164:167], v212, s[8:9] offset:1024 nt
	global_load_dwordx4 v[168:171], v212, s[8:9] offset:2048 nt
	global_load_dwordx4 v[172:175], v212, s[8:9] offset:3072 nt
	s_add_u32 s8, s8, 0x800000
	s_addc_u32 s9, s9, 0
	v_max_f32_e32 v145, v145, v69
	v_max_f32_e32 v149, v149, v24
	v_max_f32_e32 v146, v146, v37
	v_max_f32_e32 v150, v150, v66
	v_max_f32_e32 v147, v147, v36
	v_max_f32_e32 v127, v127, v90
	v_max_f32_e32 v148, v148, v138
	v_max_f32_e32 v103, v103, v96
	v_max_f32_e32 v111, v111, v117
	v_max_f32_e32 v94, v94, v141
	v_max_f32_e32 v55, v55, v132
	v_max_f32_e32 v63, v95, v150
	v_min_f32_e32 v150, v95, v150
	v_max_f32_e32 v67, v112, v147
	v_min_f32_e32 v147, v112, v147
	v_max_f32_e32 v21, v119, v127
	v_min_f32_e32 v127, v119, v127
	v_max_f32_e32 v15, v144, v148
	v_min_f32_e32 v148, v144, v148
	v_max_f32_e32 v0, v107, v103
	v_min_f32_e32 v103, v107, v103
	v_max_f32_e32 v1, v145, v111
	v_min_f32_e32 v111, v145, v111
	v_max_f32_e32 v2, v149, v94
	v_min_f32_e32 v94, v149, v94
	v_max_f32_e32 v3, v146, v55
	v_min_f32_e32 v55, v146, v55
	v_max_f32_e32 v4, v63, v0
	v_min_f32_e32 v0, v63, v0
	v_max_f32_e32 v5, v67, v1
	v_min_f32_e32 v1, v67, v1
	v_max_f32_e32 v6, v21, v2
	v_min_f32_e32 v2, v21, v2
	v_max_f32_e32 v7, v15, v3
	v_min_f32_e32 v3, v15, v3
	v_max_f32_e32 v8, v150, v103
	v_min_f32_e32 v103, v150, v103
	v_max_f32_e32 v9, v147, v111
	v_min_f32_e32 v111, v147, v111
	v_max_f32_e32 v10, v127, v94
	v_min_f32_e32 v94, v127, v94
	v_max_f32_e32 v11, v148, v55
	v_min_f32_e32 v55, v148, v55
	v_max_f32_e32 v12, v4, v6
	v_min_f32_e32 v6, v4, v6
	v_max_f32_e32 v13, v5, v7
	v_min_f32_e32 v7, v5, v7
	v_max_f32_e32 v14, v0, v2
	v_min_f32_e32 v2, v0, v2
	v_max_f32_e32 v16, v1, v3
	v_min_f32_e32 v3, v1, v3
	v_max_f32_e32 v17, v8, v10
	v_min_f32_e32 v10, v8, v10
	v_max_f32_e32 v18, v9, v11
	v_min_f32_e32 v11, v9, v11
	v_max_f32_e32 v19, v103, v94
	v_min_f32_e32 v94, v103, v94
	v_max_f32_e32 v20, v111, v55
	v_min_f32_e32 v55, v111, v55
	v_max_f32_e32 v23, v12, v13
	v_min_f32_e32 v13, v12, v13
	v_max_f32_e32 v25, v6, v7
	v_min_f32_e32 v7, v6, v7
	v_max_f32_e32 v26, v14, v16
	v_min_f32_e32 v16, v14, v16
	v_max_f32_e32 v27, v2, v3
	v_min_f32_e32 v3, v2, v3
	v_max_f32_e32 v28, v17, v18
	v_min_f32_e32 v18, v17, v18
	v_max_f32_e32 v29, v10, v11
	v_min_f32_e32 v11, v10, v11
	v_max_f32_e32 v30, v19, v20
	v_min_f32_e32 v20, v19, v20
	v_max_f32_e32 v31, v94, v55
	v_min_f32_e32 v55, v94, v55
	v_or_b32_e32 v23, v23, v245
	v_or_b32_e32 v13, v13, v245
	v_or_b32_e32 v25, v25, v245
	v_or_b32_e32 v7, v7, v245
	v_or_b32_e32 v26, v26, v245
	v_or_b32_e32 v16, v16, v245
	v_or_b32_e32 v27, v27, v245
	v_or_b32_e32 v3, v3, v245
	v_or_b32_e32 v28, v28, v245
	v_or_b32_e32 v18, v18, v245
	v_or_b32_e32 v29, v29, v245
	v_or_b32_e32 v11, v11, v245
	v_or_b32_e32 v30, v30, v245
	v_or_b32_e32 v20, v20, v245
	v_or_b32_e32 v31, v31, v245
	v_or_b32_e32 v55, v55, v245
	v_mov_b32_e32 v32, v23
	v_mov_b32_e32 v33, v13
	v_mov_b32_e32 v34, v25
	v_mov_b32_e32 v35, v7
	v_mov_b32_e32 v38, v26
	v_mov_b32_e32 v39, v16
	v_mov_b32_e32 v40, v27
	v_mov_b32_e32 v41, v3
	v_mov_b32_e32 v42, v28
	v_mov_b32_e32 v44, v18
	v_mov_b32_e32 v46, v29
	v_mov_b32_e32 v48, v11
	v_mov_b32_e32 v70, v30
	v_mov_b32_e32 v71, v20
	v_mov_b32_e32 v72, v31
	v_mov_b32_e32 v73, v55
	s_nop 1
	v_permlane32_swap_b32_e32 v23, v32
	v_permlane32_swap_b32_e32 v13, v33
	v_permlane32_swap_b32_e32 v25, v34
	v_permlane32_swap_b32_e32 v7, v35
	v_permlane32_swap_b32_e32 v26, v38
	v_permlane32_swap_b32_e32 v16, v39
	v_permlane32_swap_b32_e32 v27, v40
	v_permlane32_swap_b32_e32 v3, v41
	v_permlane32_swap_b32_e32 v28, v42
	v_permlane32_swap_b32_e32 v18, v44
	v_permlane32_swap_b32_e32 v29, v46
	v_permlane32_swap_b32_e32 v11, v48
	v_permlane32_swap_b32_e32 v30, v70
	v_permlane32_swap_b32_e32 v20, v71
	v_permlane32_swap_b32_e32 v31, v72
	v_permlane32_swap_b32_e32 v55, v73
	s_nop 1
	v_max_f32_e32 v23, v23, v73
	v_max_f32_e32 v13, v13, v72
	v_max_f32_e32 v25, v25, v71
	v_max_f32_e32 v7, v7, v70
	v_max_f32_e32 v26, v26, v48
	v_max_f32_e32 v16, v16, v46
	v_max_f32_e32 v27, v27, v44
	v_max_f32_e32 v3, v3, v42
	v_max_f32_e32 v28, v28, v41
	v_max_f32_e32 v18, v18, v40
	v_max_f32_e32 v29, v29, v39
	v_max_f32_e32 v11, v11, v38
	v_max_f32_e32 v30, v30, v35
	v_max_f32_e32 v20, v20, v34
	v_max_f32_e32 v31, v31, v33
	v_max_f32_e32 v55, v55, v32
	v_max_f32_e32 v45, v23, v28
	v_min_f32_e32 v28, v23, v28
	v_max_f32_e32 v47, v13, v18
	v_min_f32_e32 v18, v13, v18
	v_max_f32_e32 v50, v25, v29
	v_min_f32_e32 v29, v25, v29
	v_max_f32_e32 v51, v7, v11
	v_min_f32_e32 v11, v7, v11
	v_max_f32_e32 v78, v26, v30
	v_min_f32_e32 v30, v26, v30
	v_max_f32_e32 v80, v16, v20
	v_min_f32_e32 v20, v16, v20
	v_max_f32_e32 v74, v27, v31
	v_min_f32_e32 v31, v27, v31
	v_max_f32_e32 v82, v3, v55
	v_min_f32_e32 v55, v3, v55
	v_max_f32_e32 v76, v45, v78
	v_min_f32_e32 v78, v45, v78
	v_max_f32_e32 v84, v47, v80
	v_min_f32_e32 v80, v47, v80
	v_max_f32_e32 v52, v50, v74
	v_min_f32_e32 v74, v50, v74
	v_max_f32_e32 v54, v51, v82
	v_min_f32_e32 v82, v51, v82
	v_max_f32_e32 v86, v28, v30
	v_min_f32_e32 v30, v28, v30
	v_max_f32_e32 v79, v18, v20
	v_min_f32_e32 v20, v18, v20
	v_max_f32_e32 v88, v29, v31
	v_min_f32_e32 v31, v29, v31
	v_max_f32_e32 v75, v11, v55
	v_min_f32_e32 v55, v11, v55
	v_max_f32_e32 v89, v76, v52
	v_min_f32_e32 v52, v76, v52
	v_max_f32_e32 v83, v84, v54
	v_min_f32_e32 v54, v84, v54
	v_max_f32_e32 v93, v78, v74
	v_min_f32_e32 v74, v78, v74
	v_max_f32_e32 v53, v80, v82
	v_min_f32_e32 v82, v80, v82
	v_max_f32_e32 v97, v86, v88
	v_min_f32_e32 v88, v86, v88
	v_max_f32_e32 v81, v79, v75
	v_min_f32_e32 v75, v79, v75
	v_max_f32_e32 v98, v30, v31
	v_min_f32_e32 v31, v30, v31
	v_max_f32_e32 v99, v20, v55
	v_min_f32_e32 v55, v20, v55
	v_max_f32_e32 v101, v89, v83
	v_min_f32_e32 v83, v89, v83
	v_max_f32_e32 v77, v52, v54
	v_min_f32_e32 v54, v52, v54
	v_max_f32_e32 v104, v93, v53
	v_min_f32_e32 v53, v93, v53
	v_max_f32_e32 v105, v74, v82
	v_min_f32_e32 v82, v74, v82
	v_max_f32_e32 v87, v97, v81
	v_min_f32_e32 v81, v97, v81
	v_max_f32_e32 v108, v88, v75
	v_min_f32_e32 v75, v88, v75
	v_max_f32_e32 v91, v98, v99
	v_min_f32_e32 v99, v98, v99
	v_max_f32_e32 v110, v31, v55
	v_min_f32_e32 v55, v31, v55
	v_and_b32_e32 v85, s7, v101
	v_cndmask_b32_e64 v113, v101, v87, s[4:5]
	v_cndmask_b32_e64 v106, v83, v81, s[4:5]
	v_cndmask_b32_e64 v116, v77, v108, s[4:5]
	v_cndmask_b32_e64 v118, v54, v75, s[4:5]
	v_cndmask_b32_e64 v120, v104, v91, s[4:5]
	v_cndmask_b32_e64 v100, v53, v99, s[4:5]
	v_cndmask_b32_e64 v115, v105, v110, s[4:5]
	v_cndmask_b32_e64 v92, v82, v55, s[4:5]
	v_and_or_b32 v123, v113, 63, v246
	ds_read_u8 v123, v123
	v_and_or_b32 v114, v106, 63, v246
	ds_read_u8 v114, v114
	v_and_or_b32 v126, v116, 63, v246
	ds_read_u8 v126, v126
	v_and_or_b32 v121, v118, 63, v246
	ds_read_u8 v121, v121
	v_and_or_b32 v122, v120, 63, v246
	ds_read_u8 v122, v122
	v_and_or_b32 v124, v100, 63, v246
	ds_read_u8 v124, v124
	v_and_or_b32 v109, v115, 63, v246
	ds_read_u8 v109, v109
	v_and_or_b32 v60, v92, 63, v246
	ds_read_u8 v60, v60
	v_and_b32_e32 v113, s7, v113
	v_sub_f32_e32 v113, v113, v85
	v_mul_f32_e32 v113, 0x3fb8aa3b, v113
	v_exp_f32_e32 v113, v113
	v_and_b32_e32 v106, s7, v106
	v_sub_f32_e32 v106, v106, v85
	v_mul_f32_e32 v106, 0x3fb8aa3b, v106
	v_exp_f32_e32 v106, v106
	v_and_b32_e32 v116, s7, v116
	v_sub_f32_e32 v116, v116, v85
	v_mul_f32_e32 v116, 0x3fb8aa3b, v116
	v_exp_f32_e32 v116, v116
	v_and_b32_e32 v118, s7, v118
	v_sub_f32_e32 v118, v118, v85
	v_mul_f32_e32 v118, 0x3fb8aa3b, v118
	v_exp_f32_e32 v118, v118
	v_and_b32_e32 v120, s7, v120
	v_sub_f32_e32 v120, v120, v85
	v_mul_f32_e32 v120, 0x3fb8aa3b, v120
	v_exp_f32_e32 v120, v120
	v_and_b32_e32 v100, s7, v100
	v_sub_f32_e32 v100, v100, v85
	v_mul_f32_e32 v100, 0x3fb8aa3b, v100
	v_exp_f32_e32 v100, v100
	v_and_b32_e32 v115, s7, v115
	v_sub_f32_e32 v115, v115, v85
	v_mul_f32_e32 v115, 0x3fb8aa3b, v115
	v_exp_f32_e32 v115, v115
	v_and_b32_e32 v92, s7, v92
	v_sub_f32_e32 v92, v92, v85
	v_mul_f32_e32 v92, 0x3fb8aa3b, v92
	v_exp_f32_e32 v92, v92
	s_nop 0
	v_add_f32_e32 v85, v113, v106
	v_add_f32_e32 v85, v85, v116
	v_add_f32_e32 v85, v85, v118
	v_add_f32_e32 v85, v85, v120
	v_add_f32_e32 v85, v85, v100
	v_add_f32_e32 v85, v85, v115
	v_add_f32_e32 v85, v85, v92
	v_mov_b32_e32 v61, v85
	s_nop 1
	v_permlane32_swap_b32_e32 v85, v61
	s_nop 1
	v_add_f32_e32 v85, v85, v61
	s_waitcnt lgkmcnt(0)
	v_bfe_u32 v68, v123, 4, 4
	v_or_b32_e32 v68, v68, v240
	v_and_or_b32 v123, v123, 15, v240
	ds_read_u8 v68, v68
	ds_read_u8 v123, v123 offset:512
	v_bfe_u32 v56, v114, 4, 4
	v_or_b32_e32 v56, v56, v240
	v_and_or_b32 v114, v114, 15, v240
	ds_read_u8 v56, v56
	ds_read_u8 v114, v114 offset:512
	v_bfe_u32 v57, v126, 4, 4
	v_or_b32_e32 v57, v57, v240
	v_and_or_b32 v126, v126, 15, v240
	ds_read_u8 v57, v57
	ds_read_u8 v126, v126 offset:512
	v_bfe_u32 v58, v121, 4, 4
	v_or_b32_e32 v58, v58, v240
	v_and_or_b32 v121, v121, 15, v240
	ds_read_u8 v58, v58
	ds_read_u8 v121, v121 offset:512
	v_bfe_u32 v59, v122, 4, 4
	v_or_b32_e32 v59, v59, v240
	v_and_or_b32 v122, v122, 15, v240
	ds_read_u8 v59, v59
	ds_read_u8 v122, v122 offset:512
	v_bfe_u32 v251, v124, 4, 4
	v_or_b32_e32 v251, v251, v240
	v_and_or_b32 v124, v124, 15, v240
	ds_read_u8 v251, v251
	ds_read_u8 v124, v124 offset:512
	v_bfe_u32 v253, v109, 4, 4
	v_or_b32_e32 v253, v253, v240
	v_and_or_b32 v109, v109, 15, v240
	ds_read_u8 v253, v253
	ds_read_u8 v109, v109 offset:512
	v_bfe_u32 v151, v60, 4, 4
	v_or_b32_e32 v151, v151, v240
	v_and_or_b32 v60, v60, 15, v240
	ds_read_u8 v151, v151
	ds_read_u8 v60, v60 offset:512
	v_div_scale_f32 v134, s[26:27], v85, v85, v113
	v_rcp_f32_e32 v249, v134
	s_nop 0
	v_fma_f32 v136, -v134, v249, 1.0
	v_fmac_f32_e32 v249, v136, v249
	v_div_scale_f32 v136, vcc, v113, v85, v113
	v_mul_f32_e32 v137, v136, v249
	v_fma_f32 v62, -v134, v137, v136
	v_fmac_f32_e32 v137, v62, v249
	v_fma_f32 v136, -v134, v137, v136
	s_nop 0
	v_div_fmas_f32 v136, v136, v249, v137
	v_div_fixup_f32 v62, v136, v85, v113
	v_div_scale_f32 v134, s[26:27], v85, v85, v106
	v_rcp_f32_e32 v249, v134
	s_nop 0
	v_fma_f32 v136, -v134, v249, 1.0
	v_fmac_f32_e32 v249, v136, v249
	v_div_scale_f32 v136, vcc, v106, v85, v106
	v_mul_f32_e32 v137, v136, v249
	v_fma_f32 v64, -v134, v137, v136
	v_fmac_f32_e32 v137, v64, v249
	v_fma_f32 v136, -v134, v137, v136
	s_nop 0
	v_div_fmas_f32 v136, v136, v249, v137
	v_div_fixup_f32 v64, v136, v85, v106
	v_div_scale_f32 v134, s[26:27], v85, v85, v116
	v_rcp_f32_e32 v249, v134
	s_nop 0
	v_fma_f32 v136, -v134, v249, 1.0
	v_fmac_f32_e32 v249, v136, v249
	v_div_scale_f32 v136, vcc, v116, v85, v116
	v_mul_f32_e32 v137, v136, v249
	v_fma_f32 v255, -v134, v137, v136
	v_fmac_f32_e32 v137, v255, v249
	v_fma_f32 v136, -v134, v137, v136
	s_nop 0
	v_div_fmas_f32 v136, v136, v249, v137
	v_div_fixup_f32 v255, v136, v85, v116
	v_div_scale_f32 v134, s[26:27], v85, v85, v118
	v_rcp_f32_e32 v249, v134
	s_nop 0
	v_fma_f32 v136, -v134, v249, 1.0
	v_fmac_f32_e32 v249, v136, v249
	v_div_scale_f32 v136, vcc, v118, v85, v118
	v_mul_f32_e32 v137, v136, v249
	v_fma_f32 v252, -v134, v137, v136
	v_fmac_f32_e32 v137, v252, v249
	v_fma_f32 v136, -v134, v137, v136
	s_nop 0
	v_div_fmas_f32 v136, v136, v249, v137
	v_div_fixup_f32 v252, v136, v85, v118
	v_div_scale_f32 v134, s[26:27], v85, v85, v120
	v_rcp_f32_e32 v249, v134
	s_nop 0
	v_fma_f32 v136, -v134, v249, 1.0
	v_fmac_f32_e32 v249, v136, v249
	v_div_scale_f32 v136, vcc, v120, v85, v120
	v_mul_f32_e32 v137, v136, v249
	v_fma_f32 v129, -v134, v137, v136
	v_fmac_f32_e32 v137, v129, v249
	v_fma_f32 v136, -v134, v137, v136
	s_nop 0
	v_div_fmas_f32 v136, v136, v249, v137
	v_div_fixup_f32 v129, v136, v85, v120
	v_div_scale_f32 v134, s[26:27], v85, v85, v100
	v_rcp_f32_e32 v249, v134
	s_nop 0
	v_fma_f32 v136, -v134, v249, 1.0
	v_fmac_f32_e32 v249, v136, v249
	v_div_scale_f32 v136, vcc, v100, v85, v100
	v_mul_f32_e32 v137, v136, v249
	v_fma_f32 v130, -v134, v137, v136
	v_fmac_f32_e32 v137, v130, v249
	v_fma_f32 v136, -v134, v137, v136
	s_nop 0
	v_div_fmas_f32 v136, v136, v249, v137
	v_div_fixup_f32 v130, v136, v85, v100
	v_div_scale_f32 v134, s[26:27], v85, v85, v115
	v_rcp_f32_e32 v249, v134
	s_nop 0
	v_fma_f32 v136, -v134, v249, 1.0
	v_fmac_f32_e32 v249, v136, v249
	v_div_scale_f32 v136, vcc, v115, v85, v115
	v_mul_f32_e32 v137, v136, v249
	v_fma_f32 v65, -v134, v137, v136
	v_fmac_f32_e32 v137, v65, v249
	v_fma_f32 v136, -v134, v137, v136
	s_nop 0
	v_div_fmas_f32 v136, v136, v249, v137
	v_div_fixup_f32 v65, v136, v85, v115
	v_div_scale_f32 v134, s[26:27], v85, v85, v92
	v_rcp_f32_e32 v249, v134
	s_nop 0
	v_fma_f32 v136, -v134, v249, 1.0
	v_fmac_f32_e32 v249, v136, v249
	v_div_scale_f32 v136, vcc, v92, v85, v92
	v_mul_f32_e32 v137, v136, v249
	v_fma_f32 v133, -v134, v137, v136
	v_fmac_f32_e32 v137, v133, v249
	v_fma_f32 v136, -v134, v137, v136
	s_nop 0
	v_div_fmas_f32 v136, v136, v249, v137
	v_div_fixup_f32 v133, v136, v85, v92
	s_waitcnt lgkmcnt(0)
	v_and_b32_e32 v68, 0x7f, v68
	v_and_b32_e32 v123, 0x7f, v123
	v_lshl_or_b32 v68, v68, 7, v123
	v_xor_b32_e32 v68, 0x3fff, v68
	v_and_b32_e32 v56, 0x7f, v56
	v_and_b32_e32 v114, 0x7f, v114
	v_lshl_or_b32 v56, v56, 7, v114
	v_xor_b32_e32 v56, 0x3fff, v56
	v_and_b32_e32 v57, 0x7f, v57
	v_and_b32_e32 v126, 0x7f, v126
	v_lshl_or_b32 v57, v57, 7, v126
	v_xor_b32_e32 v57, 0x3fff, v57
	v_and_b32_e32 v58, 0x7f, v58
	v_and_b32_e32 v121, 0x7f, v121
	v_lshl_or_b32 v58, v58, 7, v121
	v_xor_b32_e32 v58, 0x3fff, v58
	v_and_b32_e32 v59, 0x7f, v59
	v_and_b32_e32 v122, 0x7f, v122
	v_lshl_or_b32 v59, v59, 7, v122
	v_xor_b32_e32 v59, 0x3fff, v59
	v_and_b32_e32 v251, 0x7f, v251
	v_and_b32_e32 v124, 0x7f, v124
	v_lshl_or_b32 v251, v251, 7, v124
	v_xor_b32_e32 v251, 0x3fff, v251
	v_and_b32_e32 v253, 0x7f, v253
	v_and_b32_e32 v109, 0x7f, v109
	v_lshl_or_b32 v253, v253, 7, v109
	v_xor_b32_e32 v253, 0x3fff, v253
	v_and_b32_e32 v151, 0x7f, v151
	v_and_b32_e32 v60, 0x7f, v60
	v_lshl_or_b32 v151, v151, 7, v60
	v_xor_b32_e32 v151, 0x3fff, v151
	s_waitcnt vmcnt(0)
	v_pk_mul_f32 v[160:161], v[160:161], v[176:177]
	v_pk_mul_f32 v[162:163], v[162:163], v[178:179]
	v_pk_mul_f32 v[164:165], v[164:165], v[180:181]
	v_pk_mul_f32 v[166:167], v[166:167], v[182:183]
	v_pk_mul_f32 v[168:169], v[168:169], v[184:185]
	v_pk_mul_f32 v[170:171], v[170:171], v[186:187]
	v_pk_mul_f32 v[172:173], v[172:173], v[188:189]
	v_pk_mul_f32 v[174:175], v[174:175], v[190:191]
	v_max3_f32 v192, |v160|, |v161|, |v162|
	v_max3_f32 v192, |v163|, |v164|, v192
	v_max3_f32 v192, |v165|, |v166|, v192
	v_max3_f32 v192, |v167|, |v168|, v192
	v_max3_f32 v192, |v169|, |v170|, v192
	v_max3_f32 v192, |v171|, |v172|, v192
	v_max3_f32 v192, |v173|, |v174|, v192
	v_max_f32_e64 v192, |v175|, v192
	s_nop 1
	v_mov_b32_dpp v193, v192 quad_perm:[1,0,3,2] row_mask:0xf bank_mask:0xf bound_ctrl:1
	v_max_f32_e32 v192, v192, v193
	s_nop 1
	v_mov_b32_dpp v193, v192 quad_perm:[2,3,0,1] row_mask:0xf bank_mask:0xf bound_ctrl:1
	v_max_f32_e32 v192, v192, v193
	s_nop 1
	v_mov_b32_dpp v193, v192 row_half_mirror row_mask:0xf bank_mask:0xf bound_ctrl:1
	v_max_f32_e32 v192, v192, v193
	s_nop 1
	v_mov_b32_dpp v193, v192 row_mirror row_mask:0xf bank_mask:0xf bound_ctrl:1
	v_max_f32_e32 v192, v192, v193
	v_mov_b32_e32 v193, v192
	s_nop 1
	v_permlane16_swap_b32_e32 v192, v193
	s_nop 1
	v_max_f32_e32 v192, v192, v193
	v_mov_b32_e32 v193, v192
	s_nop 1
	v_permlane32_swap_b32_e32 v192, v193
	s_nop 1
	v_max_f32_e32 v192, v192, v193
	v_max_f32_e32 v192, 0xda24260, v192
	v_mul_f32_e32 v194, 0x3e2aaaab, v192
	global_store_dword v214, v194, s[12:13]
	v_div_scale_f32 v195, s[26:27], v194, v194, 1.0
	v_rcp_f32_e32 v196, v195
	v_div_scale_f32 v204, vcc, 1.0, v194, 1.0
	v_fma_f32 v205, -v195, v196, 1.0
	v_fmac_f32_e32 v196, v205, v196
	v_mul_f32_e32 v205, v204, v196
	v_fma_f32 v206, -v195, v205, v204
	v_fmac_f32_e32 v205, v206, v196
	v_fma_f32 v195, -v195, v205, v204
	s_nop 0
	v_div_fmas_f32 v195, v195, v196, v205
	v_div_fixup_f32 v207, v195, v194, 1.0
	v_mul_f32_e32 v160, v207, v160
	v_mul_f32_e32 v161, v207, v161
	v_mul_f32_e32 v162, v207, v162
	v_mul_f32_e32 v163, v207, v163
	v_mul_f32_e32 v164, v207, v164
	v_mul_f32_e32 v165, v207, v165
	v_mul_f32_e32 v166, v207, v166
	v_mul_f32_e32 v167, v207, v167
	v_mul_f32_e32 v168, v207, v168
	v_mul_f32_e32 v169, v207, v169
	v_mul_f32_e32 v170, v207, v170
	v_mul_f32_e32 v171, v207, v171
	v_mul_f32_e32 v172, v207, v172
	v_mul_f32_e32 v173, v207, v173
	v_mul_f32_e32 v174, v207, v174
	v_mul_f32_e32 v175, v207, v175
	v_mov_b32_e32 v208, 0
	v_mov_b32_e32 v209, 0
	v_mov_b32_e32 v210, 0
	v_mov_b32_e32 v193, 0
	v_cvt_scalef32_pk_fp4_f32 v208, v160, v161, 1.0
	v_cvt_scalef32_pk_fp4_f32 v209, v164, v165, 1.0
	v_cvt_scalef32_pk_fp4_f32 v210, v168, v169, 1.0
	v_cvt_scalef32_pk_fp4_f32 v193, v172, v173, 1.0
	v_cvt_scalef32_pk_fp4_f32 v208, v162, v163, 1.0 op_sel:[0,0,1,0]
	v_cvt_scalef32_pk_fp4_f32 v209, v166, v167, 1.0 op_sel:[0,0,1,0]
	v_cvt_scalef32_pk_fp4_f32 v210, v170, v171, 1.0 op_sel:[0,0,1,0]
	v_cvt_scalef32_pk_fp4_f32 v193, v174, v175, 1.0 op_sel:[0,0,1,0]
	global_store_short v213, v208, s[10:11] nt
	s_add_u32 s14, s10, 0x200000
	s_addc_u32 s15, s11, 0
	global_store_short v213, v209, s[14:15] nt
	s_add_u32 s14, s10, 0x400000
	s_addc_u32 s15, s11, 0
	global_store_short v213, v210, s[14:15] nt
	s_add_u32 s14, s10, 0x600000
	s_addc_u32 s15, s11, 0
	global_store_short v213, v193, s[14:15] nt
	s_add_u32 s10, s10, 0x20000
	s_addc_u32 s11, s11, 0
	s_add_u32 s12, s12, 0x2000
	s_addc_u32 s13, s13, 0
	s_cmp_eq_u32 s22, 1
	s_cbranch_scc1 .Ltk1_noload
	global_load_dwordx4 v[160:163], v212, s[8:9] offset:0 nt
	global_load_dwordx4 v[164:167], v212, s[8:9] offset:1024 nt
	global_load_dwordx4 v[168:171], v212, s[8:9] offset:2048 nt
	global_load_dwordx4 v[172:175], v212, s[8:9] offset:3072 nt
	s_add_u32 s8, s8, 0x800000
	s_addc_u32 s9, s9, 0
